# plus: v_mov_b64 accumulator zeroing; 1.0/x division sequences in the GLU epilogue and retention output stage replaced by v_rcp_f32
# speedup vs baseline: 1.0272x; 1.0071x over previous
; template <class Epi, class Sched>
; __device__ __forceinline__ void gemm_phase(LAS unsigned char* lds, const Sched& S, const Epi& E) {
;     ...
;     f32x4 acc[2][2][4][2];
; #pragma unroll
;     for (int a = 0; a < 2; ++a)
; #pragma unroll
;         for (int b = 0; b < 2; ++b)
; #pragma unroll
;             for (int m = 0; m < 4; ++m)
; #pragma unroll
;                 for (int n = 0; n < 2; ++n) acc[a][b][m][n] = (f32x4){0.f, 0.f, 0.f, 0.f};
;     ...
; #pragma unroll
;         for (int a = 0; a < 2; ++a)
; #pragma unroll
;             for (int b = 0; b < 2; ++b)
; #pragma unroll
;                 for (int m = 0; m < 4; ++m)
; #pragma unroll
;                     for (int n = 0; n < 2; ++n) acc[a][b][m][n] = (f32x4){0.f, 0.f, 0.f, 0.f};
.LBB0_297:
	s_add_u32 s15, s30, 0x100
	s_addc_u32 s17, s31, 0
	s_add_u32 s28, s28, 0x40080
	v_mov_b32_e32 v2, 0
	s_addc_u32 s29, s29, 0
	s_mov_b32 s57, -2
	v_mov_b32_e32 v3, 0
	v_mov_b64_e32 v[4:5], 0
	v_mov_b64_e32 v[6:7], 0
	v_mov_b64_e32 v[8:9], 0
	v_mov_b64_e32 v[10:11], 0
	v_mov_b64_e32 v[12:13], 0
	v_mov_b64_e32 v[14:15], 0
	v_mov_b64_e32 v[16:17], 0
	v_mov_b64_e32 v[18:19], 0
	v_mov_b64_e32 v[20:21], 0
	v_mov_b64_e32 v[22:23], 0
	v_mov_b64_e32 v[24:25], 0
	v_mov_b64_e32 v[26:27], 0
	v_mov_b64_e32 v[28:29], 0
	v_mov_b64_e32 v[30:31], 0
	v_mov_b64_e32 v[32:33], 0
	v_mov_b64_e32 v[34:35], 0
	v_mov_b64_e32 v[36:37], 0
	v_mov_b64_e32 v[38:39], 0
	v_mov_b64_e32 v[40:41], 0
	v_mov_b64_e32 v[42:43], 0
	v_mov_b64_e32 v[44:45], 0
	v_mov_b64_e32 v[46:47], 0
	v_mov_b64_e32 v[48:49], 0
	v_mov_b64_e32 v[50:51], 0
	v_mov_b64_e32 v[52:53], 0
	v_mov_b64_e32 v[54:55], 0
	v_mov_b64_e32 v[56:57], 0
	v_mov_b64_e32 v[58:59], 0
	v_mov_b64_e32 v[60:61], 0
	v_mov_b64_e32 v[62:63], 0
	v_mov_b64_e32 v[64:65], 0
	v_mov_b64_e32 v[66:67], 0
	v_mov_b64_e32 v[68:69], 0
	v_mov_b64_e32 v[70:71], 0
	v_mov_b64_e32 v[72:73], 0
	v_mov_b64_e32 v[74:75], 0
	v_mov_b64_e32 v[76:77], 0
	v_mov_b64_e32 v[78:79], 0
	v_mov_b64_e32 v[80:81], 0
	v_mov_b64_e32 v[82:83], 0
	v_mov_b64_e32 v[84:85], 0
	v_mov_b64_e32 v[86:87], 0
	v_mov_b64_e32 v[88:89], 0
	v_mov_b64_e32 v[90:91], 0
	v_mov_b64_e32 v[92:93], 0
	v_mov_b64_e32 v[94:95], 0
	v_mov_b64_e32 v[96:97], 0
	v_mov_b64_e32 v[98:99], 0
	v_mov_b64_e32 v[100:101], 0
	v_mov_b64_e32 v[102:103], 0
	v_mov_b64_e32 v[104:105], 0
	v_mov_b64_e32 v[106:107], 0
	v_mov_b64_e32 v[108:109], 0
	v_mov_b64_e32 v[110:111], 0
	v_mov_b64_e32 v[112:113], 0
	v_mov_b64_e32 v[114:115], 0
	v_mov_b64_e32 v[116:117], 0
	v_mov_b64_e32 v[118:119], 0
	v_mov_b64_e32 v[120:121], 0
	v_mov_b64_e32 v[122:123], 0
	v_mov_b64_e32 v[124:125], 0
	v_mov_b64_e32 v[126:127], 0
	v_mov_b64_e32 v[128:129], 0

; #define LAS __attribute__((address_space(3)))
; __device__ __forceinline__ void ph_ret_chunk(unsigned char* lds_, bf16_t* Z, const bf16_t* KVF, const bf16_t* KVB, const float* decay_logit, const float* gn_w, int with_ctx, int u0, int ustep, unsigned* kvc, unsigned* barw) { PH_IDS;
;     ...
;     for (int u = u0; u < nunits; u += ustep) {
;         const bool lat = u < 256; const int bh = lat ? (u >> 3) : (u - 256), qb = lat ? (u & 7) : 0, b = bh >> 2, h = bh & 3;
;         const float lgf = -log1pf(__expf(-decay_logit[h])) * 1.4426950408889634f, lgb = -log1pf(__expf(-decay_logit[4 + h])) * 1.4426950408889634f;
;         const int qw0 = qb * 256 + wid * 32, qpos = qw0 + r32;
;         const int qrow = (lat ? b * 2048 : RL + b * 256) + qpos;
;         bf16_t* zq = Z + (size_t)qrow * ZW;
;         u32x4 sK[4], sV[4]; bf16x8 qf[4];
;         { const size_t rb = (lat ? (size_t)b * 2048 + qb * 256 : (size_t)RL + b * 256);
; #pragma unroll
;           for (int j = 0; j < 4; ++j) { const bf16_t* zr = Z + (rb + 64 * j + prow) * ZW + h * 64 + pc * 8; sK[j] = *(const u32x4*)(zr + C_RK); sV[j] = *(const u32x4*)(zr + C_RV); } }
; #pragma unroll
;         for (int st = 0; st < 4; ++st) qf[st] = *(const bf16x8*)(zq + C_RQ + h * 64 + 16 * st + 8 * hi);
;         if (kvc != nullptr && tid_ == 0) dep_spin(kvc, (unsigned)G_, barw);
;         __syncthreads();
; #pragma unroll
;         for (int j = 0; j < 4; ++j) { *(LAS u32x4*)(sm + j * BUF_R + koff) = sK[j]; *(LAS u32x4*)(sm + j * BUF_R + voff) = sV[j]; }
.LBB0_764:
	s_or_b64 exec, exec, s[10:11]
	s_movk_i32 s11, 0x90
	v_mul_lo_u32 v71, v36, s11
	v_lshlrev_b32_e32 v37, 10, v41
	v_lshlrev_b32_e32 v76, 6, v36
	v_lshlrev_b32_e32 v36, 3, v43
	v_and_b32_e32 v75, 0x1000, v37
	v_ashrrev_i32_e32 v37, 31, v36
	v_lshlrev_b64 v[46:47], 1, v[36:37]
	s_waitcnt vmcnt(13)
	v_mul_f32_e32 v37, 0xbfb8aa3b, v40
	v_exp_f32_e32 v37, v37
	v_lshl_add_u64 v[48:49], s[6:7], 0, v[46:47]
	v_lshl_add_u64 v[40:41], s[8:9], 0, v[46:47]
	s_waitcnt vmcnt(12)
	v_mul_f32_e32 v45, 0xbfb8aa3b, v45
	v_add_f32_e32 v50, 1.0, v37
	v_add_f32_e32 v46, -1.0, v50
	v_sub_f32_e32 v47, v46, v50
	v_add_f32_e32 v47, 1.0, v47
	v_sub_f32_e32 v46, v37, v46
	v_add_f32_e32 v51, v46, v47
	v_frexp_mant_f32_e32 v52, v50
	v_cvt_f64_f32_e32 v[46:47], v50
	s_mov_b32 s6, 0x3f2aaaab
	v_exp_f32_e32 v45, v45
	v_frexp_exp_i32_f64_e32 v46, v[46:47]
	v_cmp_gt_f32_e32 vcc, s6, v52
	v_lshlrev_b32_e32 v39, 4, v43
	v_and_b32_e32 v77, 48, v39
	v_subbrev_co_u32_e32 v78, vcc, 0, v46, vcc
	v_sub_u32_e32 v47, 0, v78
	v_ldexp_f32 v46, v50, v47
	v_ldexp_f32 v50, v51, v47
	v_add_f32_e32 v47, 1.0, v45
	v_add_f32_e32 v51, -1.0, v47
	v_sub_f32_e32 v52, v51, v47
	v_add_f32_e32 v52, 1.0, v52
	v_sub_f32_e32 v51, v45, v51
	v_add_f32_e32 v51, v51, v52
	v_frexp_mant_f32_e32 v54, v47
	v_cvt_f64_f32_e32 v[52:53], v47
	v_frexp_exp_i32_f64_e32 v52, v[52:53]
	v_cmp_gt_f32_e32 vcc, s6, v54
	s_mov_b32 s6, 0x3e9b6dac
	s_nop 0
	v_subbrev_co_u32_e32 v79, vcc, 0, v52, vcc
	v_sub_u32_e32 v52, 0, v79
	v_ldexp_f32 v47, v47, v52
	v_ldexp_f32 v51, v51, v52
	v_pk_add_f32 v[52:53], v[46:47], 1.0 op_sel_hi:[1,0]
	v_pk_add_f32 v[60:61], v[46:47], -1.0 op_sel_hi:[1,0]
	v_pk_add_f32 v[54:55], v[52:53], -1.0 op_sel_hi:[1,0]
	v_pk_add_f32 v[62:63], v[60:61], 1.0 op_sel_hi:[1,0]
	v_pk_add_f32 v[54:55], v[46:47], v[54:55] neg_lo:[0,1] neg_hi:[0,1]
	v_pk_add_f32 v[46:47], v[46:47], v[62:63] neg_lo:[0,1] neg_hi:[0,1]
	v_pk_add_f32 v[54:55], v[50:51], v[54:55]
	v_pk_add_f32 v[46:47], v[50:51], v[46:47]
	v_pk_add_f32 v[56:57], v[52:53], v[54:55]
	v_pk_add_f32 v[50:51], v[60:61], v[46:47]
	v_rcp_f32_e32 v58, v56
	v_rcp_f32_e32 v59, v57
	v_pk_add_f32 v[52:53], v[56:57], v[52:53] neg_lo:[0,1] neg_hi:[0,1]
	v_pk_add_f32 v[60:61], v[50:51], v[60:61] neg_lo:[0,1] neg_hi:[0,1]
	v_pk_add_f32 v[52:53], v[54:55], v[52:53] neg_lo:[0,1] neg_hi:[0,1]
	v_pk_mul_f32 v[54:55], v[50:51], v[58:59]
	v_pk_add_f32 v[46:47], v[46:47], v[60:61] neg_lo:[0,1] neg_hi:[0,1]
	v_pk_mul_f32 v[60:61], v[56:57], v[54:55]
	s_barrier
	v_pk_fma_f32 v[62:63], v[54:55], v[56:57], v[60:61] neg_lo:[0,0,1] neg_hi:[0,0,1]
	s_nop 0
	v_pk_fma_f32 v[62:63], v[54:55], v[52:53], v[62:63]
	s_mul_i32 s56, s21, 0x12000
	v_pk_add_f32 v[64:65], v[60:61], v[62:63]
	s_add_i32 s8, 0, 0x11000
	v_pk_add_f32 v[72:73], v[50:51], v[64:65] neg_lo:[0,1] neg_hi:[0,1]
	v_pk_add_f32 v[60:61], v[64:65], v[60:61] neg_lo:[0,1] neg_hi:[0,1]
	v_pk_add_f32 v[50:51], v[50:51], v[72:73] neg_lo:[0,1] neg_hi:[0,1]
	v_and_b32_e32 v44, 31, v43
	v_pk_add_f32 v[50:51], v[50:51], v[64:65] neg_lo:[0,1] neg_hi:[0,1]
	s_lshl_b32 s10, s22, 6
	v_pk_add_f32 v[46:47], v[46:47], v[50:51]
	v_pk_add_f32 v[50:51], v[60:61], v[62:63] neg_lo:[0,1] neg_hi:[0,1]
	s_lshl_b32 s10, s10, 2
	v_pk_add_f32 v[46:47], v[50:51], v[46:47]
	v_lshlrev_b32_e32 v43, 1, v43
	v_pk_add_f32 v[50:51], v[72:73], v[46:47]
	s_nop 0
	v_pk_mul_f32 v[60:61], v[58:59], v[50:51]
	s_nop 0
	v_pk_mul_f32 v[62:63], v[56:57], v[60:61]
	s_nop 0
	v_pk_fma_f32 v[56:57], v[60:61], v[56:57], v[62:63] neg_lo:[0,0,1] neg_hi:[0,0,1]
	s_nop 0
	v_pk_fma_f32 v[52:53], v[60:61], v[52:53], v[56:57]
	v_pk_add_f32 v[56:57], v[72:73], v[50:51] neg_lo:[0,1] neg_hi:[0,1]
	s_nop 0
	v_pk_add_f32 v[46:47], v[46:47], v[56:57]
	v_pk_add_f32 v[56:57], v[62:63], v[52:53]
	s_nop 0
	v_pk_add_f32 v[64:65], v[50:51], v[56:57] neg_lo:[0,1] neg_hi:[0,1]
	v_pk_add_f32 v[62:63], v[56:57], v[62:63] neg_lo:[0,1] neg_hi:[0,1]
	v_pk_add_f32 v[50:51], v[50:51], v[64:65] neg_lo:[0,1] neg_hi:[0,1]
	s_nop 0
	v_pk_add_f32 v[50:51], v[50:51], v[56:57] neg_lo:[0,1] neg_hi:[0,1]
	s_nop 0
	v_pk_add_f32 v[46:47], v[46:47], v[50:51]
	v_pk_add_f32 v[50:51], v[62:63], v[52:53] neg_lo:[0,1] neg_hi:[0,1]
	s_nop 0
	v_pk_add_f32 v[46:47], v[50:51], v[46:47]
	v_pk_add_f32 v[50:51], v[54:55], v[60:61]
	v_pk_add_f32 v[46:47], v[64:65], v[46:47]
	v_pk_add_f32 v[52:53], v[50:51], v[54:55] neg_lo:[0,1] neg_hi:[0,1]
	v_pk_mul_f32 v[46:47], v[58:59], v[46:47]
	v_pk_add_f32 v[52:53], v[60:61], v[52:53] neg_lo:[0,1] neg_hi:[0,1]
	v_cvt_f32_i32_e32 v59, v79
	v_pk_add_f32 v[46:47], v[52:53], v[46:47]
	v_cvt_f32_i32_e32 v58, v78
	v_pk_add_f32 v[52:53], v[50:51], v[46:47]
	s_nop 0
	v_pk_mul_f32 v[54:55], v[52:53], v[52:53]
	v_pk_add_f32 v[50:51], v[52:53], v[50:51] neg_lo:[0,1] neg_hi:[0,1]
	v_pk_fma_f32 v[56:57], v[54:55], s[6:7], v[182:183] op_sel_hi:[1,0,0]
	s_mov_b32 s6, 0x3f2aaada
	v_pk_add_f32 v[46:47], v[46:47], v[50:51] neg_lo:[0,1] neg_hi:[0,1]
	v_pk_fma_f32 v[56:57], v[54:55], v[56:57], s[6:7] op_sel_hi:[1,1,0]
	s_mov_b32 s6, 0x3f317218
	v_ldexp_f32 v50, v52, 1
	v_ldexp_f32 v51, v53, 1
	v_ldexp_f32 v61, v47, 1
	v_pk_mul_f32 v[52:53], v[52:53], v[54:55]
	v_pk_mul_f32 v[54:55], v[58:59], s[6:7] op_sel_hi:[1,0]
	v_add3_u32 v47, 0, v71, v38
	v_pk_fma_f32 v[62:63], v[58:59], s[6:7], v[54:55] op_sel_hi:[1,0,1] neg_lo:[0,0,1] neg_hi:[0,0,1]
	s_mov_b32 s6, 0xb102e308
	s_waitcnt vmcnt(11)
	ds_write_b128 v47, v[6:9]
	v_add_u32_e32 v6, 0, v75
	v_pk_fma_f32 v[58:59], v[58:59], s[6:7], v[62:63] op_sel_hi:[1,0,1]
	v_add3_u32 v6, v6, v76, v77
	s_lshl_b64 s[6:7], s[56:57], 1
	s_waitcnt vmcnt(10)
	ds_write_b128 v6, v[2:5] offset:9216
	s_waitcnt vmcnt(9)
	ds_write_b128 v47, v[10:13] offset:17408
	s_waitcnt vmcnt(8)
; #define LAS __attribute__((address_space(3)))
; #define ST_PUT(k) (*(LAS u32x4*)(sto + (k) * ST_SZ) = pack8(sa, sb))
; #define ST_STEP(ptr, ci_, g_) do { unpack8(*(const u32x4*)((ptr) + (size_t)(ci_) * 4096), ta, tb); sa = sa * (g_) + ta; sb = sb * (g_) + tb; } while (0)
; #define ST_PUTB(k) (*(LAS u32x4*)(sto + (k) * ST_SZ) = pack8(sc, sd))
; __device__ __forceinline__ void ph_ret_chunk(unsigned char* lds_, bf16_t* Z, const bf16_t* KVF, const bf16_t* KVB, const float* decay_logit, const float* gn_w, int with_ctx, int u0, int ustep, unsigned* kvc, unsigned* barw) { PH_IDS;
;     ...
;         {
;             const float g128f = __builtin_amdgcn_exp2f(lgf * 128.f), g128b = __builtin_amdgcn_exp2f(lgb * 128.f);
;             const bf16_t* kf = KVF + (size_t)bh * 18 * 4096 + tid_ * 8; const bf16_t* kb = KVB + (size_t)bh * 18 * 4096 + tid_ * 8;
;             LAS char* sto = sm + ST_OFF + (tid_ >> 3) * KP_R + (tid_ & 7) * 16;
;             f32x4 sa = (f32x4){0.f, 0.f, 0.f, 0.f}, sb = sa, ta, tb;
;     ...
;             if (lat) {
;                 const int cA = 2 * qb, n1 = 2 + cA, nb = 16 - cA;
;                 u32x4 Lq[9], Lr[9]; f32x4 sc = (f32x4){0.f, 0.f, 0.f, 0.f}, sd = sc;
;     ...
; #pragma unroll
;                 for (int hf = 0; hf < 2; ++hf) {
; #pragma unroll
;                     for (int k = 0; k < 9; ++k) { const int kk = 9 * hf + k;
;                         if (kk <= n1 && kk < 17) Lq[k] = *(const u32x4*)(kf + (size_t)kk * 4096);
;                         if (kk <= nb && kk < 17) Lr[k] = *(const u32x4*)(kb + (size_t)(kk == 0 ? 1 : (kk == 1 ? 0 : 19 - kk)) * 4096); }
; #pragma unroll
;                     for (int k = 0; k < 9; ++k) { const int kk = 9 * hf + k;
;                         if (kk == n1) ST_PUT(0); if (kk <= n1 && kk < 17) { unpack8(Lq[k], ta, tb); sa = sa * g128f + ta; sb = sb * g128f + tb; }
;                         if (kk == nb) ST_PUTB(3); if (kk <= nb && kk < 17) { unpack8(Lr[k], ta, tb); sc = sc * g128b + ta; sd = sd * g128b + tb; } }
;                     asm volatile("" ::: "memory"); }
;                 ST_PUT(1); ST_PUTB(2);
;     ...
;             } else {
;                 ST_PUT(0); ST_PUT(3);
;                 ST_STEP(kf, 0, g128f); ST_PUT(1);
;                 sa = (f32x4){0.f, 0.f, 0.f, 0.f}; sb = sa; ST_STEP(kb, 1, g128b); ST_PUT(2);
;             }
;     ...
;         }
;         __syncthreads();
	ds_write_b128 v6, v[14:17] offset:26624
	s_waitcnt vmcnt(7)
	ds_write_b128 v47, v[18:21] offset:34816
	s_waitcnt vmcnt(6)
	ds_write_b128 v6, v[22:25] offset:44032
	s_waitcnt vmcnt(5)
	ds_write_b128 v47, v[26:29] offset:52224
	s_waitcnt vmcnt(4)
	ds_write_b128 v6, v[30:33] offset:61440
	v_lshl_add_u64 v[6:7], v[48:49], 0, s[6:7]
	v_add3_u32 v32, s8, v71, v38
	s_mov_b32 s8, 0x380000
	v_add_co_u32_e32 v6, vcc, s8, v6
	v_cvt_pk_bf16_f32 v2, v130, v130
	v_cvt_pk_bf16_f32 v3, v130, v130
	v_cvt_pk_bf16_f32 v4, v130, v130
	v_cvt_pk_bf16_f32 v5, v130, v130
	s_nop 1
	v_addc_co_u32_e32 v7, vcc, 0, v7, vcc
	ds_write_b128 v32, v[2:5]
	v_cvt_pk_bf16_f32 v2, v130, v130
	v_cvt_pk_bf16_f32 v3, v130, v130
	v_cvt_pk_bf16_f32 v4, v130, v130
	v_cvt_pk_bf16_f32 v5, v130, v130
	global_load_dwordx4 v[6:9], v[6:7], off
	v_pk_mul_f32 v[52:53], v[52:53], v[56:57]
	v_ldexp_f32 v46, v46, 1
	v_pk_add_f32 v[56:57], v[50:51], v[52:53]
	v_mov_b32_e32 v47, v61
	v_pk_add_f32 v[50:51], v[56:57], v[50:51] neg_lo:[0,1] neg_hi:[0,1]
	v_pk_add_f32 v[62:63], v[54:55], v[58:59]
	v_pk_add_f32 v[50:51], v[52:53], v[50:51] neg_lo:[0,1] neg_hi:[0,1]
	v_mov_b32_e32 v26, v56
	v_pk_add_f32 v[12:13], v[46:47], v[50:51]
	v_mov_b32_e32 v27, v63
	v_pk_add_f32 v[16:17], v[56:57], v[12:13]
	v_mov_b32_e32 v21, v63
	v_pk_add_f32 v[18:19], v[62:63], v[16:17]
	v_mov_b32_e32 v24, v16
	v_mov_b32_e32 v25, v19
	v_pk_add_f32 v[24:25], v[24:25], v[26:27] neg_lo:[0,1] neg_hi:[0,1]
	v_mov_b32_e32 v20, v18
	v_mov_b32_e32 v22, v62
	v_mov_b32_e32 v23, v55
	v_mov_b32_e32 v26, v62
	v_mov_b32_e32 v27, v19
	v_mov_b32_e32 v55, v25
	v_pk_add_f32 v[20:21], v[20:21], v[22:23] neg_lo:[0,1] neg_hi:[0,1]
	v_mov_b32_e32 v22, v16
	v_mov_b32_e32 v23, v59
	v_pk_add_f32 v[26:27], v[26:27], v[54:55] neg_lo:[0,1] neg_hi:[0,1]
	v_mov_b32_e32 v52, v54
	v_mov_b32_e32 v53, v51
	v_mov_b32_e32 v60, v58
	v_mov_b32_e32 v47, v13
	v_mov_b32_e32 v51, v57
	v_pk_add_f32 v[22:23], v[22:23], v[20:21] neg_lo:[0,1] neg_hi:[0,1]
	v_mov_b32_e32 v28, v26
	v_mov_b32_e32 v29, v21
	v_mov_b32_e32 v30, v18
	v_mov_b32_e32 v31, v17
	v_mov_b32_e32 v21, v57
	v_pk_add_f32 v[10:11], v[52:53], v[60:61]
	v_pk_add_f32 v[14:15], v[46:47], v[50:51]
	v_pk_add_f32 v[28:29], v[58:59], v[28:29] neg_lo:[0,1] neg_hi:[0,1]
	v_pk_add_f32 v[20:21], v[30:31], v[20:21] neg_lo:[0,1] neg_hi:[0,1]
	v_pk_add_f32 v[16:17], v[16:17], v[56:57] neg_lo:[0,1] neg_hi:[0,1]
	v_mov_b32_e32 v59, v63
	v_pk_add_f32 v[10:11], v[10:11], v[20:21] neg_lo:[0,1] neg_hi:[0,1]
	v_pk_add_f32 v[12:13], v[12:13], v[16:17] neg_lo:[0,1] neg_hi:[0,1]
	v_pk_add_f32 v[16:17], v[58:59], v[26:27] neg_lo:[0,1] neg_hi:[0,1]
	v_pk_add_f32 v[14:15], v[14:15], v[24:25] neg_lo:[0,1] neg_hi:[0,1]
	v_pk_add_f32 v[24:25], v[22:23], v[10:11]
	v_pk_add_f32 v[20:21], v[14:15], v[16:17]
	v_mov_b32_e32 v17, v23
	v_mov_b32_e32 v15, v11
	v_pk_add_f32 v[10:11], v[16:17], v[14:15]
	v_mov_b32_e32 v14, v20
	v_pk_add_f32 v[10:11], v[10:11], v[28:29] neg_lo:[0,1] neg_hi:[0,1]
	v_mov_b32_e32 v15, v25
	v_pk_add_f32 v[14:15], v[14:15], v[10:11] neg_lo:[0,1] neg_hi:[0,1]
	v_pk_add_f32 v[10:11], v[12:13], v[10:11] neg_lo:[0,1] neg_hi:[0,1]
	v_pk_add_f32 v[14:15], v[16:17], v[14:15] neg_lo:[0,1] neg_hi:[0,1]
	v_pk_add_f32 v[12:13], v[24:25], v[20:21]
	v_pk_add_f32 v[10:11], v[10:11], v[14:15]
	v_pk_add_f32 v[14:15], v[18:19], v[12:13]
	v_cmp_neq_f32_e32 vcc, s95, v37
	v_pk_add_f32 v[16:17], v[14:15], v[18:19] neg_lo:[0,1] neg_hi:[0,1]
	s_mov_b32 s8, 0xbfb8aa3b
	v_pk_add_f32 v[12:13], v[12:13], v[16:17] neg_lo:[0,1] neg_hi:[0,1]
	ds_write_b128 v32, v[2:5] offset:27648
	v_pk_add_f32 v[10:11], v[10:11], v[12:13]
	v_mul_u32_u24_e32 v71, 0x90, v44
	v_pk_add_f32 v[10:11], v[14:15], v[10:11]
	v_and_b32_e32 v52, 0xc0, v39
	v_cndmask_b32_e32 v10, v209, v10, vcc
	v_cmp_neq_f32_e32 vcc, s95, v45
	v_mul_i32_i24_e32 v53, -4, v42
	s_waitcnt vmcnt(0)
	v_lshlrev_b32_e32 v2, 16, v6
	v_cndmask_b32_e32 v11, v209, v11, vcc
	v_cmp_ngt_f32_e32 vcc, -1.0, v45
	v_and_b32_e32 v3, 0xffff0000, v6
	v_lshlrev_b32_e32 v4, 16, v7
	v_cndmask_b32_e32 v11, v210, v11, vcc
	v_cmp_ngt_f32_e32 vcc, -1.0, v37
	v_and_b32_e32 v5, 0xffff0000, v7
	v_lshlrev_b32_e32 v6, 16, v8
	v_cndmask_b32_e32 v10, v210, v10, vcc
	v_cmp_neq_f32_e32 vcc, -1.0, v37
	v_and_b32_e32 v7, 0xffff0000, v8
	v_lshlrev_b32_e32 v8, 16, v9
	v_cndmask_b32_e32 v10, v211, v10, vcc
	v_cmp_neq_f32_e32 vcc, -1.0, v45
	v_and_b32_e32 v9, 0xffff0000, v9
	s_nop 0
	v_cndmask_b32_e32 v11, v211, v11, vcc
	v_cmp_lt_f32_e64 vcc, |v45|, s96
	s_nop 1
	v_cndmask_b32_e32 v11, v11, v45, vcc
	v_cmp_lt_f32_e64 vcc, |v37|, s96
	s_nop 1
	v_cndmask_b32_e32 v10, v10, v37, vcc
	v_pk_mul_f32 v[72:73], v[10:11], s[8:9] op_sel_hi:[1,0]
	v_lshlrev_b32_e32 v37, 8, v42
	v_mul_f32_e32 v10, 0x43000000, v72
	v_exp_f32_e32 v12, v10
	v_lshl_add_u64 v[10:11], v[40:41], 0, s[6:7]
	s_mov_b32 s6, 0x1602000
	s_ashr_i32 s7, s20, 8
	v_mul_f32_e32 v12, 0, v12
	v_pk_add_f32 v[4:5], v[12:13], v[4:5] op_sel_hi:[0,1]
	v_pk_add_f32 v[2:3], v[12:13], v[2:3] op_sel_hi:[0,1]
	v_pk_add_f32 v[6:7], v[12:13], v[6:7] op_sel_hi:[0,1]
	v_cvt_pk_bf16_f32 v2, v2, v3
	v_cvt_pk_bf16_f32 v3, v4, v5
	v_cvt_pk_bf16_f32 v4, v6, v7
	v_add_co_u32_e32 v6, vcc, s6, v10
	v_pk_add_f32 v[8:9], v[12:13], v[8:9] op_sel_hi:[0,1]
	s_nop 0
	v_addc_co_u32_e32 v7, vcc, 0, v11, vcc
	v_cvt_pk_bf16_f32 v5, v8, v9
	global_load_dwordx4 v[6:9], v[6:7], off
	v_mul_f32_e32 v10, 0x43000000, v73
	v_exp_f32_e32 v10, v10
	s_mul_i32 s6, s7, 0x8800
	ds_write_b128 v32, v[2:5] offset:9216
	s_add_i32 s9, s6, 0
	v_mul_f32_e32 v10, 0, v10
	v_add3_u32 v75, s9, v71, v70
	s_lshl_b32 s6, s7, 7
	s_mulk_i32 s7, 0x2400
	s_add_i32 s7, s7, 0
	s_add_i32 s8, s7, 0x11000
	s_add_i32 s7, s7, 0x15800
	s_add_u32 s4, s4, s10
	s_addc_u32 s5, s5, 0
	s_waitcnt vmcnt(0)
	v_lshlrev_b32_e32 v2, 16, v6
	v_and_b32_e32 v3, 0xffff0000, v6
	v_lshlrev_b32_e32 v4, 16, v7
	v_and_b32_e32 v5, 0xffff0000, v7
	v_lshlrev_b32_e32 v6, 16, v8
	v_and_b32_e32 v7, 0xffff0000, v8
	v_lshlrev_b32_e32 v8, 16, v9
	v_and_b32_e32 v9, 0xffff0000, v9
	v_pk_add_f32 v[4:5], v[10:11], v[4:5] op_sel_hi:[0,1]
	v_pk_add_f32 v[2:3], v[10:11], v[2:3] op_sel_hi:[0,1]
	v_pk_add_f32 v[8:9], v[10:11], v[8:9] op_sel_hi:[0,1]
	v_pk_add_f32 v[6:7], v[10:11], v[6:7] op_sel_hi:[0,1]
	v_cvt_pk_bf16_f32 v2, v2, v3
	v_cvt_pk_bf16_f32 v3, v4, v5
	v_cvt_pk_bf16_f32 v4, v6, v7
	v_cvt_pk_bf16_f32 v5, v8, v9
	ds_write_b128 v32, v[2:5] offset:18432
	s_waitcnt lgkmcnt(0)
	s_barrier
; #define LAS __attribute__((address_space(3)))
; __device__ __forceinline__ void ret_tile_gen(const LAS char* sm, int r32, int hi, int vrd, int buf, int kp0, int qpos, float lgf, float lgb, const bf16x8 (&qf)[4], fa::f32x16& o0, fa::f32x16& o1) {
;     using namespace fa;
;     const LAS char* kb = sm + buf + r32 * KP_R + 16 * hi;
;     f32x16 p0, p1;
; #pragma unroll
;     for (int r = 0; r < 16; ++r) { p0[r] = 0.f; p1[r] = 0.f; }
; #pragma unroll
;     for (int st = 0; st < 4; ++st) {
;         const bf16x8 k0 = *(const LAS bf16x8*)(kb + 32 * st), k1 = *(const LAS bf16x8*)(kb + 32 * KP_R + 32 * st);
;         p0 = __builtin_amdgcn_mfma_f32_32x32x16_bf16(k0, qf[st], p0, 0, 0, 0);
;         p1 = __builtin_amdgcn_mfma_f32_32x32x16_bf16(k1, qf[st], p1, 0, 0, 0);
;     }
;     int d0 = qpos - kp0 - 4 * hi;
;     asm volatile("" : "+v"(d0) : "v"(p0[15]), "v"(p1[15]));
; #pragma unroll
;     for (int r = 0; r < 16; ++r) {
;         const float f0 = (float)(d0 - ((r & 3) + 8 * (r >> 2))), f1 = f0 - 32.f;
;         const float w0 = __builtin_amdgcn_exp2f(lgf * fmaxf(f0, 0.f) + lgb * fmaxf(-f0, 0.f)) * (2.f - fminf(fabsf(f0), 1.f));
;         const float w1 = __builtin_amdgcn_exp2f(lgf * fmaxf(f1, 0.f) + lgb * fmaxf(-f1, 0.f)) * (2.f - fminf(fabsf(f1), 1.f));
;         p0[r] *= w0; p1[r] *= w1;
;     }
; __device__ __forceinline__ void ph_ret_chunk(unsigned char* lds_, bf16_t* Z, const bf16_t* KVF, const bf16_t* KVB, const float* decay_logit, const float* gn_w, int with_ctx, int u0, int ustep, unsigned* kvc, unsigned* barw) { PH_IDS;
;     ...
;         u32x2 gtv[8]; f32x4 gwv[8];
; #pragma unroll
;         for (int g = 0; g < 4; ++g)
; #pragma unroll
;             for (int blk = 0; blk < 2; ++blk) { const int d = blk * 32 + 8 * g + 4 * hi; gtv[2 * g + blk] = *(const u32x2*)(zq + C_RG + h * 64 + d); gwv[2 * g + blk] = *(const f32x4*)(gn_w + h * 64 + d); }
	ds_read_b128 v[2:5], v75
	ds_read_b128 v[44:47], v75 offset:32
	ds_read_b128 v[18:21], v75 offset:4608
	ds_read_b128 v[48:51], v75 offset:4640
	s_waitcnt lgkmcnt(3)
	v_mfma_f32_32x32x16_bf16 v[2:17], v[2:5], v[66:69], 0
	ds_read_b128 v[38:41], v75 offset:64
	s_waitcnt lgkmcnt(2)
	v_mfma_f32_32x32x16_bf16 v[18:33], v[18:21], v[66:69], 0
	v_mfma_f32_32x32x16_bf16 v[2:17], v[44:47], v[136:139], v[2:17]
	s_waitcnt lgkmcnt(1)
	v_mfma_f32_32x32x16_bf16 v[18:33], v[48:51], v[136:139], v[18:33]
	ds_read_b128 v[44:47], v75 offset:4672
	ds_read_b128 v[48:51], v75 offset:96
	s_waitcnt lgkmcnt(2)
	v_mfma_f32_32x32x16_bf16 v[2:17], v[38:41], v[132:135], v[2:17]
	v_lshlrev_b32_e32 v38, 3, v42
	v_mov_b32_e32 v39, v130
	v_lshl_add_u64 v[34:35], v[34:35], 0, v[38:39]
	ds_read_b128 v[38:41], v75 offset:4704
	global_load_dwordx4 v[122:125], v70, s[4:5]
	global_load_dwordx4 v[114:117], v70, s[4:5] offset:32
	global_load_dwordx4 v[118:121], v70, s[4:5] offset:128
	global_load_dwordx4 v[110:113], v70, s[4:5] offset:160
	global_load_dwordx2 v[144:145], v[34:35], off offset:3392
	global_load_dwordx2 v[148:149], v[34:35], off offset:3408
	global_load_dwordx2 v[152:153], v[34:35], off offset:3424
	global_load_dwordx2 v[156:157], v[34:35], off offset:3440
	global_load_dwordx4 v[106:109], v70, s[4:5] offset:64
	global_load_dwordx4 v[98:101], v70, s[4:5] offset:96
	global_load_dwordx2 v[146:147], v[34:35], off offset:3456
	global_load_dwordx2 v[150:151], v[34:35], off offset:3472
	global_load_dwordx2 v[154:155], v[34:35], off offset:3488
	global_load_dwordx2 v[142:143], v[34:35], off offset:3504
	global_load_dwordx4 v[102:105], v70, s[4:5] offset:192
	global_load_dwordx4 v[94:97], v70, s[4:5] offset:224
	v_subrev_u32_e32 v34, s6, v53
	s_waitcnt lgkmcnt(2)
	v_mfma_f32_32x32x16_bf16 v[18:33], v[44:47], v[132:135], v[18:33]
	v_add_u32_e32 v77, v34, v74
	v_and_b32_e32 v34, 24, v36
	v_and_or_b32 v34, v43, 32, v34
	v_or3_b32 v46, v37, v52, v34
	v_add_u32_e32 v76, s9, v46
	s_waitcnt lgkmcnt(0)
	v_mfma_f32_32x32x16_bf16 v[18:33], v[38:41], v[126:129], v[18:33]
	v_mov_b32_e32 v38, v77
	v_mfma_f32_32x32x16_bf16 v[2:17], v[48:51], v[126:129], v[2:17]
	s_nop 0
	v_cvt_f32_i32_e32 v39, v38
	v_max_f32_e32 v34, 0, v39
	v_max_f32_e64 v35, -v39, 0
	v_pk_mul_f32 v[34:35], v[72:73], v[34:35]
	v_add_f32_e32 v36, 0xc2000000, v39
	v_add_f32_e32 v34, v34, v35
	v_exp_f32_e32 v34, v34
	v_min_f32_e64 v35, |v39|, 1.0
	v_sub_f32_e32 v35, 2.0, v35
	v_mul_f32_e32 v37, v35, v34
	v_max_f32_e32 v34, 0, v36
	v_max_f32_e64 v35, -v36, 0
	v_pk_mul_f32 v[34:35], v[72:73], v[34:35]
	v_mul_f32_e32 v37, v2, v37
	v_add_f32_e32 v34, v34, v35
	v_exp_f32_e32 v34, v34
	v_min_f32_e64 v35, |v36|, 1.0
	v_add_u32_e32 v36, -1, v38
	v_cvt_f32_i32_e32 v36, v36
	v_sub_f32_e32 v35, 2.0, v35
	v_mul_f32_e32 v34, v35, v34
	v_mul_f32_e32 v39, v18, v34
	v_max_f32_e32 v34, 0, v36
	v_max_f32_e64 v35, -v36, 0
	v_pk_mul_f32 v[34:35], v[72:73], v[34:35]
	v_add_f32_e32 v18, 0xc2000000, v36
	v_add_f32_e32 v2, v34, v35
	v_exp_f32_e32 v2, v2
	v_min_f32_e64 v34, |v36|, 1.0
	v_sub_f32_e32 v34, 2.0, v34
	v_max_f32_e64 v35, -v18, 0
	v_mul_f32_e32 v2, v34, v2
	v_max_f32_e32 v34, 0, v18
	v_pk_mul_f32 v[34:35], v[72:73], v[34:35]
	v_min_f32_e64 v18, |v18|, 1.0
	v_add_f32_e32 v34, v34, v35
	v_add_u32_e32 v35, -2, v38
	v_exp_f32_e32 v34, v34
	v_cvt_f32_i32_e32 v35, v35
	v_sub_f32_e32 v18, 2.0, v18
	v_mul_f32_e32 v18, v18, v34
	v_mul_f32_e32 v34, v3, v2
	v_max_f32_e32 v2, 0, v35
	v_max_f32_e64 v3, -v35, 0
	v_pk_mul_f32 v[2:3], v[72:73], v[2:3]
	v_mul_f32_e32 v40, v19, v18
	v_add_f32_e32 v2, v2, v3
	v_exp_f32_e32 v2, v2
	v_min_f32_e64 v3, |v35|, 1.0
	v_add_f32_e32 v18, 0xc2000000, v35
	v_sub_f32_e32 v3, 2.0, v3
	v_mul_f32_e32 v19, v3, v2
	v_max_f32_e32 v2, 0, v18
	v_max_f32_e64 v3, -v18, 0
	v_pk_mul_f32 v[2:3], v[72:73], v[2:3]
	v_mul_f32_e32 v4, v4, v19
	v_add_f32_e32 v2, v2, v3
	v_exp_f32_e32 v2, v2
	v_min_f32_e64 v3, |v18|, 1.0
	v_add_u32_e32 v18, -3, v38
	v_cvt_f32_i32_e32 v18, v18
	v_sub_f32_e32 v3, 2.0, v3
	v_mul_f32_e32 v2, v3, v2
	v_mul_f32_e32 v41, v20, v2
	v_max_f32_e32 v2, 0, v18
	v_max_f32_e64 v3, -v18, 0
	v_pk_mul_f32 v[2:3], v[72:73], v[2:3]
	v_add_f32_e32 v19, 0xc2000000, v18
	v_add_f32_e32 v2, v2, v3
	v_exp_f32_e32 v2, v2
	v_min_f32_e64 v3, |v18|, 1.0
	v_sub_f32_e32 v3, 2.0, v3
	v_mul_f32_e32 v18, v3, v2
	v_max_f32_e32 v2, 0, v19
	v_max_f32_e64 v3, -v19, 0
	v_pk_mul_f32 v[2:3], v[72:73], v[2:3]
	v_mul_f32_e32 v5, v5, v18
	v_add_f32_e32 v2, v2, v3
	v_exp_f32_e32 v2, v2
	v_min_f32_e64 v3, |v19|, 1.0
	v_add_u32_e32 v19, -8, v38
	v_cvt_f32_i32_e32 v19, v19
	v_sub_f32_e32 v3, 2.0, v3
	v_mul_f32_e32 v2, v3, v2
	v_mul_f32_e32 v42, v21, v2
	v_max_f32_e32 v2, 0, v19
	v_max_f32_e64 v3, -v19, 0
	v_pk_mul_f32 v[2:3], v[72:73], v[2:3]
	v_add_f32_e32 v18, 0xc2000000, v19
	v_add_f32_e32 v2, v2, v3
	v_exp_f32_e32 v2, v2
	v_min_f32_e64 v3, |v19|, 1.0
	v_sub_f32_e32 v3, 2.0, v3
	v_mul_f32_e32 v19, v3, v2
	v_max_f32_e32 v2, 0, v18
	v_max_f32_e64 v3, -v18, 0
	v_pk_mul_f32 v[2:3], v[72:73], v[2:3]
	v_mul_f32_e32 v6, v6, v19
	v_add_f32_e32 v2, v2, v3
	v_exp_f32_e32 v2, v2
	v_min_f32_e64 v3, |v18|, 1.0
	v_add_u32_e32 v18, -9, v38
	v_cvt_f32_i32_e32 v18, v18
	v_sub_f32_e32 v3, 2.0, v3
	v_mul_f32_e32 v2, v3, v2
	v_mul_f32_e32 v22, v22, v2
	v_max_f32_e32 v2, 0, v18
	v_max_f32_e64 v3, -v18, 0
	v_pk_mul_f32 v[2:3], v[72:73], v[2:3]
	v_add_f32_e32 v19, 0xc2000000, v18
	v_add_f32_e32 v2, v2, v3
	v_exp_f32_e32 v2, v2
	v_min_f32_e64 v3, |v18|, 1.0
	v_sub_f32_e32 v3, 2.0, v3
	v_mul_f32_e32 v18, v3, v2
	v_max_f32_e32 v2, 0, v19
	v_max_f32_e64 v3, -v19, 0
	v_pk_mul_f32 v[2:3], v[72:73], v[2:3]
	v_mul_f32_e32 v7, v7, v18
	v_add_f32_e32 v2, v2, v3
	v_exp_f32_e32 v2, v2
; __device__ __forceinline__ bf16x8 pack_p(const f32x16& p, int base) { u32x4 w; w.x = pk2(p[base], p[base + 1]); w.y = pk2(p[base + 2], p[base + 3]); w.z = pk2(p[base + 4], p[base + 5]); w.w = pk2(p[base + 6], p[base + 7]); return __builtin_bit_cast(bf16x8, w); }
; __device__ __forceinline__ void ret_tile_gen(const LAS char* sm, int r32, int hi, int vrd, int buf, int kp0, int qpos, float lgf, float lgb, const bf16x8 (&qf)[4], fa::f32x16& o0, fa::f32x16& o1) {
;     ...
; #pragma unroll
;     for (int r = 0; r < 16; ++r) {
;         const float f0 = (float)(d0 - ((r & 3) + 8 * (r >> 2))), f1 = f0 - 32.f;
;         const float w0 = __builtin_amdgcn_exp2f(lgf * fmaxf(f0, 0.f) + lgb * fmaxf(-f0, 0.f)) * (2.f - fminf(fabsf(f0), 1.f));
;         const float w1 = __builtin_amdgcn_exp2f(lgf * fmaxf(f1, 0.f) + lgb * fmaxf(-f1, 0.f)) * (2.f - fminf(fabsf(f1), 1.f));
;         p0[r] *= w0; p1[r] *= w1;
;     }
;     bf16x8 pf[4]; pf[0] = pack_p(p0, 0); pf[1] = pack_p(p0, 8); pf[2] = pack_p(p1, 0); pf[3] = pack_p(p1, 8);
;     pv_tile(o0, o1, sm + buf + vrd, pf);
	v_min_f32_e64 v3, |v19|, 1.0
	v_add_u32_e32 v19, -10, v38
	v_cvt_f32_i32_e32 v19, v19
	v_sub_f32_e32 v3, 2.0, v3
	v_mul_f32_e32 v2, v3, v2
	v_mul_f32_e32 v23, v23, v2
	v_max_f32_e32 v2, 0, v19
	v_max_f32_e64 v3, -v19, 0
	v_pk_mul_f32 v[2:3], v[72:73], v[2:3]
	v_add_f32_e32 v18, 0xc2000000, v19
	v_add_f32_e32 v2, v2, v3
	v_exp_f32_e32 v2, v2
	v_min_f32_e64 v3, |v19|, 1.0
	v_sub_f32_e32 v3, 2.0, v3
	v_mul_f32_e32 v19, v3, v2
	v_max_f32_e32 v2, 0, v18
	v_max_f32_e64 v3, -v18, 0
	v_pk_mul_f32 v[2:3], v[72:73], v[2:3]
	v_mul_f32_e32 v8, v8, v19
	v_add_f32_e32 v2, v2, v3
	v_exp_f32_e32 v2, v2
	v_min_f32_e64 v3, |v18|, 1.0
	v_add_u32_e32 v18, -11, v38
	v_cvt_f32_i32_e32 v18, v18
	v_sub_f32_e32 v3, 2.0, v3
	v_mul_f32_e32 v2, v3, v2
	v_mul_f32_e32 v24, v24, v2
	v_max_f32_e32 v2, 0, v18
	v_max_f32_e64 v3, -v18, 0
	v_pk_mul_f32 v[2:3], v[72:73], v[2:3]
	v_add_f32_e32 v19, 0xc2000000, v18
	v_add_f32_e32 v2, v2, v3
	v_exp_f32_e32 v2, v2
	v_min_f32_e64 v3, |v18|, 1.0
	v_sub_f32_e32 v3, 2.0, v3
	v_mul_f32_e32 v18, v3, v2
	v_max_f32_e32 v2, 0, v19
	v_max_f32_e64 v3, -v19, 0
	v_pk_mul_f32 v[2:3], v[72:73], v[2:3]
	v_mul_f32_e32 v9, v9, v18
	v_add_f32_e32 v2, v2, v3
	v_exp_f32_e32 v2, v2
	v_min_f32_e64 v3, |v19|, 1.0
	v_add_u32_e32 v19, -16, v38
	v_cvt_f32_i32_e32 v19, v19
	v_sub_f32_e32 v3, 2.0, v3
	v_mul_f32_e32 v2, v3, v2
	v_mul_f32_e32 v25, v25, v2
	v_max_f32_e32 v2, 0, v19
	v_max_f32_e64 v3, -v19, 0
	v_pk_mul_f32 v[2:3], v[72:73], v[2:3]
	v_add_f32_e32 v18, 0xc2000000, v19
	v_add_f32_e32 v2, v2, v3
	v_exp_f32_e32 v2, v2
	v_min_f32_e64 v3, |v19|, 1.0
	v_sub_f32_e32 v3, 2.0, v3
	v_mul_f32_e32 v19, v3, v2
	v_max_f32_e32 v2, 0, v18
	v_max_f32_e64 v3, -v18, 0
	v_pk_mul_f32 v[2:3], v[72:73], v[2:3]
	v_mul_f32_e32 v10, v10, v19
	v_add_f32_e32 v2, v2, v3
	v_exp_f32_e32 v2, v2
	v_min_f32_e64 v3, |v18|, 1.0
	v_subrev_u32_e32 v18, 17, v38
	v_cvt_f32_i32_e32 v18, v18
	v_sub_f32_e32 v3, 2.0, v3
	v_mul_f32_e32 v2, v3, v2
	v_mul_f32_e32 v26, v26, v2
	v_max_f32_e32 v2, 0, v18
	v_max_f32_e64 v3, -v18, 0
	v_pk_mul_f32 v[2:3], v[72:73], v[2:3]
	v_add_f32_e32 v19, 0xc2000000, v18
	v_add_f32_e32 v2, v2, v3
	v_exp_f32_e32 v2, v2
	v_min_f32_e64 v3, |v18|, 1.0
	v_sub_f32_e32 v3, 2.0, v3
	v_mul_f32_e32 v18, v3, v2
	v_max_f32_e32 v2, 0, v19
	v_max_f32_e64 v3, -v19, 0
	v_pk_mul_f32 v[2:3], v[72:73], v[2:3]
	v_mul_f32_e32 v11, v11, v18
	v_add_f32_e32 v2, v2, v3
	v_exp_f32_e32 v2, v2
	v_min_f32_e64 v3, |v19|, 1.0
	v_subrev_u32_e32 v19, 18, v38
	v_cvt_f32_i32_e32 v19, v19
	v_sub_f32_e32 v3, 2.0, v3
	v_mul_f32_e32 v2, v3, v2
	v_mul_f32_e32 v27, v27, v2
	v_max_f32_e32 v2, 0, v19
	v_max_f32_e64 v3, -v19, 0
	v_pk_mul_f32 v[2:3], v[72:73], v[2:3]
	v_add_f32_e32 v18, 0xc2000000, v19
	v_add_f32_e32 v2, v2, v3
	v_exp_f32_e32 v2, v2
	v_min_f32_e64 v3, |v19|, 1.0
	v_sub_f32_e32 v3, 2.0, v3
	v_mul_f32_e32 v19, v3, v2
	v_max_f32_e32 v2, 0, v18
	v_max_f32_e64 v3, -v18, 0
	v_pk_mul_f32 v[2:3], v[72:73], v[2:3]
	v_mul_f32_e32 v12, v12, v19
	v_add_f32_e32 v2, v2, v3
	v_exp_f32_e32 v2, v2
	v_min_f32_e64 v3, |v18|, 1.0
	v_subrev_u32_e32 v18, 19, v38
	v_cvt_f32_i32_e32 v18, v18
	v_sub_f32_e32 v3, 2.0, v3
	v_mul_f32_e32 v2, v3, v2
	v_mul_f32_e32 v28, v28, v2
	v_max_f32_e32 v2, 0, v18
	v_max_f32_e64 v3, -v18, 0
	v_pk_mul_f32 v[2:3], v[72:73], v[2:3]
	v_add_f32_e32 v19, 0xc2000000, v18
	v_add_f32_e32 v2, v2, v3
	v_exp_f32_e32 v2, v2
	v_min_f32_e64 v3, |v18|, 1.0
	v_sub_f32_e32 v3, 2.0, v3
	v_mul_f32_e32 v18, v3, v2
	v_max_f32_e32 v2, 0, v19
	v_max_f32_e64 v3, -v19, 0
	v_pk_mul_f32 v[2:3], v[72:73], v[2:3]
	v_mul_f32_e32 v13, v13, v18
	v_add_f32_e32 v2, v2, v3
	v_exp_f32_e32 v2, v2
	v_min_f32_e64 v3, |v19|, 1.0
	v_subrev_u32_e32 v19, 24, v38
	v_cvt_f32_i32_e32 v19, v19
	v_sub_f32_e32 v3, 2.0, v3
	v_mul_f32_e32 v2, v3, v2
	v_mul_f32_e32 v29, v29, v2
	v_max_f32_e32 v2, 0, v19
	v_max_f32_e64 v3, -v19, 0
	v_pk_mul_f32 v[2:3], v[72:73], v[2:3]
	v_add_f32_e32 v18, 0xc2000000, v19
	v_add_f32_e32 v2, v2, v3
	v_exp_f32_e32 v2, v2
	v_min_f32_e64 v3, |v19|, 1.0
	v_sub_f32_e32 v3, 2.0, v3
	v_mul_f32_e32 v19, v3, v2
	v_max_f32_e32 v2, 0, v18
	v_max_f32_e64 v3, -v18, 0
	v_pk_mul_f32 v[2:3], v[72:73], v[2:3]
	v_mul_f32_e32 v14, v14, v19
	v_add_f32_e32 v2, v2, v3
	v_exp_f32_e32 v2, v2
	v_min_f32_e64 v3, |v18|, 1.0
	v_subrev_u32_e32 v18, 25, v38
	v_cvt_f32_i32_e32 v18, v18
	v_sub_f32_e32 v3, 2.0, v3
	v_mul_f32_e32 v2, v3, v2
	v_mul_f32_e32 v30, v30, v2
	v_max_f32_e32 v2, 0, v18
	v_max_f32_e64 v3, -v18, 0
	v_pk_mul_f32 v[2:3], v[72:73], v[2:3]
	v_add_f32_e32 v19, 0xc2000000, v18
	v_add_f32_e32 v2, v2, v3
	v_exp_f32_e32 v2, v2
	v_min_f32_e64 v3, |v18|, 1.0
	v_sub_f32_e32 v3, 2.0, v3
	v_mul_f32_e32 v18, v3, v2
	v_max_f32_e32 v2, 0, v19
	v_max_f32_e64 v3, -v19, 0
	v_pk_mul_f32 v[2:3], v[72:73], v[2:3]
	v_mul_f32_e32 v15, v15, v18
	v_add_f32_e32 v2, v2, v3
	v_exp_f32_e32 v2, v2
	v_min_f32_e64 v3, |v19|, 1.0
	v_subrev_u32_e32 v19, 26, v38
	v_cvt_f32_i32_e32 v19, v19
	v_sub_f32_e32 v3, 2.0, v3
	v_mul_f32_e32 v2, v3, v2
	v_mul_f32_e32 v31, v31, v2
	v_max_f32_e32 v2, 0, v19
	v_max_f32_e64 v3, -v19, 0
	v_pk_mul_f32 v[2:3], v[72:73], v[2:3]
	v_add_f32_e32 v18, 0xc2000000, v19
	v_add_f32_e32 v2, v2, v3
	v_exp_f32_e32 v2, v2
	v_min_f32_e64 v3, |v19|, 1.0
	v_sub_f32_e32 v3, 2.0, v3
	v_mul_f32_e32 v19, v3, v2
	v_max_f32_e32 v2, 0, v18
	v_max_f32_e64 v3, -v18, 0
	v_pk_mul_f32 v[2:3], v[72:73], v[2:3]
	v_mul_f32_e32 v16, v16, v19
	v_add_f32_e32 v2, v2, v3
	v_exp_f32_e32 v2, v2
	v_min_f32_e64 v3, |v18|, 1.0
	v_subrev_u32_e32 v18, 27, v38
	v_cvt_f32_i32_e32 v18, v18
	v_sub_f32_e32 v3, 2.0, v3
	v_mul_f32_e32 v2, v3, v2
	v_mul_f32_e32 v32, v32, v2
	v_max_f32_e32 v2, 0, v18
	v_max_f32_e64 v3, -v18, 0
	v_pk_mul_f32 v[2:3], v[72:73], v[2:3]
	v_add_f32_e32 v19, 0xc2000000, v18
	v_add_f32_e32 v2, v2, v3
	v_exp_f32_e32 v20, v2
	v_min_f32_e64 v2, |v18|, 1.0
	v_sub_f32_e32 v18, 2.0, v2
	v_max_f32_e32 v2, 0, v19
	v_max_f32_e64 v3, -v19, 0
	v_pk_mul_f32 v[2:3], v[72:73], v[2:3]
	s_nop 0
	v_add_f32_e32 v2, v2, v3
	v_exp_f32_e32 v2, v2
	v_mul_f32_e32 v3, v18, v20
	v_min_f32_e64 v18, |v19|, 1.0
	v_sub_f32_e32 v18, 2.0, v18
	v_mul_f32_e32 v2, v18, v2
	v_mul_f32_e32 v3, v17, v3
	v_mul_f32_e32 v2, v33, v2
	v_cvt_pk_bf16_f32 v18, v37, v34
	v_cvt_pk_bf16_f32 v19, v4, v5
	v_cvt_pk_bf16_f32 v20, v6, v7
	v_cvt_pk_bf16_f32 v21, v8, v9
	v_cvt_pk_bf16_f32 v34, v10, v11
	v_cvt_pk_bf16_f32 v35, v12, v13
	v_cvt_pk_bf16_f32 v36, v14, v15
	v_cvt_pk_bf16_f32 v37, v16, v3
	v_cvt_pk_bf16_f32 v38, v39, v40
	v_cvt_pk_bf16_f32 v39, v41, v42
	v_cvt_pk_bf16_f32 v40, v22, v23
	v_cvt_pk_bf16_f32 v41, v24, v25
	v_cvt_pk_bf16_f32 v42, v26, v27
	v_cvt_pk_bf16_f32 v43, v28, v29
	v_cvt_pk_bf16_f32 v44, v30, v31
	v_cvt_pk_bf16_f32 v45, v32, v2
	ds_read_b64_tr_b16 v[2:3], v76 offset:9216
	ds_read_b64_tr_b16 v[4:5], v76 offset:9728
	ds_read_b64_tr_b16 v[46:47], v76 offset:10240
	ds_read_b64_tr_b16 v[48:49], v76 offset:10752
	s_waitcnt lgkmcnt(2)
; #define LAS __attribute__((address_space(3)))
; __device__ __forceinline__ s16x4 vtr(const LAS char* p) { return __builtin_bit_cast(s16x4, __builtin_amdgcn_ds_read_tr16_b64_v4i16((LAS s16x4*)p)); }
; __device__ __forceinline__ void pv_tile(f32x16& o0, f32x16& o1, const LAS char* vb, const bf16x8 (&pf)[4]) {
; #pragma unroll
;     for (int ks = 0; ks < 4; ++ks) {
;         const s16x4 a0 = vtr(vb + ks * 1024), a1 = vtr(vb + ks * 1024 + 512), b0 = vtr(vb + 4096 + ks * 1024), b1 = vtr(vb + 4096 + ks * 1024 + 512);
;         const bf16x8 v0 = (bf16x8){a0[0], a0[1], a0[2], a0[3], a1[0], a1[1], a1[2], a1[3]}, v1 = (bf16x8){b0[0], b0[1], b0[2], b0[3], b1[0], b1[1], b1[2], b1[3]};
;         o0 = __builtin_amdgcn_mfma_f32_32x32x16_bf16(v0, pf[ks], o0, 0, 0, 0);
;         o1 = __builtin_amdgcn_mfma_f32_32x32x16_bf16(v1, pf[ks], o1, 0, 0, 0);
;     }
; }
; __device__ __forceinline__ void ret_tile_gen(const LAS char* sm, int r32, int hi, int vrd, int buf, int kp0, int qpos, float lgf, float lgb, const bf16x8 (&qf)[4], fa::f32x16& o0, fa::f32x16& o1) {
;     ...
;     for (int st = 0; st < 4; ++st) {
;         const bf16x8 k0 = *(const LAS bf16x8*)(kb + 32 * st), k1 = *(const LAS bf16x8*)(kb + 32 * KP_R + 32 * st);
;         p0 = __builtin_amdgcn_mfma_f32_32x32x16_bf16(k0, qf[st], p0, 0, 0, 0);
;         p1 = __builtin_amdgcn_mfma_f32_32x32x16_bf16(k1, qf[st], p1, 0, 0, 0);
;     }
;     int d0 = qpos - kp0 - 4 * hi;
;     asm volatile("" : "+v"(d0) : "v"(p0[15]), "v"(p1[15]));
; #pragma unroll
;     for (int r = 0; r < 16; ++r) {
;         const float f0 = (float)(d0 - ((r & 3) + 8 * (r >> 2))), f1 = f0 - 32.f;
;         const float w0 = __builtin_amdgcn_exp2f(lgf * fmaxf(f0, 0.f) + lgb * fmaxf(-f0, 0.f)) * (2.f - fminf(fabsf(f0), 1.f));
;         const float w1 = __builtin_amdgcn_exp2f(lgf * fmaxf(f1, 0.f) + lgb * fmaxf(-f1, 0.f)) * (2.f - fminf(fabsf(f1), 1.f));
;         p0[r] *= w0; p1[r] *= w1;
;     }
	v_mfma_f32_32x32x16_bf16 v[2:17], v[2:5], v[18:21], 0
	ds_read_b64_tr_b16 v[22:23], v76 offset:13312
	ds_read_b64_tr_b16 v[24:25], v76 offset:13824
	ds_read_b64_tr_b16 v[50:51], v76 offset:14336
	ds_read_b64_tr_b16 v[52:53], v76 offset:14848
	s_waitcnt lgkmcnt(2)
	v_mfma_f32_32x32x16_bf16 v[18:33], v[22:25], v[18:21], 0
	v_mfma_f32_32x32x16_bf16 v[2:17], v[46:49], v[34:37], v[2:17]
	s_waitcnt lgkmcnt(0)
	v_mfma_f32_32x32x16_bf16 v[18:33], v[50:53], v[34:37], v[18:33]
	ds_read_b64_tr_b16 v[34:35], v76 offset:11264
	ds_read_b64_tr_b16 v[36:37], v76 offset:11776
	ds_read_b64_tr_b16 v[46:47], v76 offset:12288
	ds_read_b64_tr_b16 v[48:49], v76 offset:12800
	s_waitcnt lgkmcnt(2)
	v_mfma_f32_32x32x16_bf16 v[2:17], v[34:37], v[38:41], v[2:17]
	ds_read_b64_tr_b16 v[34:35], v76 offset:15360
	ds_read_b64_tr_b16 v[36:37], v76 offset:15872
	ds_read_b64_tr_b16 v[50:51], v76 offset:16384
	ds_read_b64_tr_b16 v[52:53], v76 offset:16896
	s_waitcnt lgkmcnt(2)
	v_mfma_f32_32x32x16_bf16 v[18:33], v[34:37], v[38:41], v[18:33]
	v_mfma_f32_32x32x16_bf16 v[2:17], v[46:49], v[42:45], v[2:17]
	s_waitcnt lgkmcnt(0)
	v_mfma_f32_32x32x16_bf16 v[18:33], v[50:53], v[42:45], v[18:33]
	ds_read_b128 v[34:37], v75 offset:17408
	ds_read_b128 v[78:81], v75 offset:17440
	ds_read_b128 v[50:53], v75 offset:22016
	ds_read_b128 v[82:85], v75 offset:22048
	s_waitcnt lgkmcnt(3)
	v_mfma_f32_32x32x16_bf16 v[34:49], v[34:37], v[66:69], 0
	s_waitcnt lgkmcnt(1)
	v_mfma_f32_32x32x16_bf16 v[50:65], v[50:53], v[66:69], 0
	v_mfma_f32_32x32x16_bf16 v[34:49], v[78:81], v[136:139], v[34:49]
	s_waitcnt lgkmcnt(0)
	v_mfma_f32_32x32x16_bf16 v[50:65], v[82:85], v[136:139], v[50:65]
	ds_read_b128 v[78:81], v75 offset:17472
	ds_read_b128 v[82:85], v75 offset:17504
	s_waitcnt lgkmcnt(1)
	v_mfma_f32_32x32x16_bf16 v[34:49], v[78:81], v[132:135], v[34:49]
	ds_read_b128 v[78:81], v75 offset:22080
	ds_read_b128 v[86:89], v75 offset:22112
	v_subrev_u32_e32 v75, 64, v77
	s_waitcnt lgkmcnt(1)
	v_mfma_f32_32x32x16_bf16 v[50:65], v[78:81], v[132:135], v[50:65]
	v_mfma_f32_32x32x16_bf16 v[34:49], v[82:85], v[126:129], v[34:49]
	s_waitcnt lgkmcnt(0)
	v_mfma_f32_32x32x16_bf16 v[50:65], v[86:89], v[126:129], v[50:65]
	s_nop 0
	v_cvt_f32_i32_e32 v77, v75
	v_max_f32_e32 v78, 0, v77
	v_max_f32_e64 v79, -v77, 0
	v_pk_mul_f32 v[78:79], v[72:73], v[78:79]
	v_add_f32_e32 v80, 0xc2000000, v77
	v_add_f32_e32 v78, v78, v79
	v_exp_f32_e32 v78, v78
	v_min_f32_e64 v77, |v77|, 1.0
	v_sub_f32_e32 v77, 2.0, v77
	v_max_f32_e64 v79, -v80, 0
	v_mul_f32_e32 v77, v77, v78
	v_max_f32_e32 v78, 0, v80
	v_pk_mul_f32 v[78:79], v[72:73], v[78:79]
	v_mul_f32_e32 v77, v34, v77
	v_add_f32_e32 v78, v78, v79
	v_exp_f32_e32 v78, v78
	v_min_f32_e64 v79, |v80|, 1.0
	v_add_u32_e32 v80, -1, v75
	v_cvt_f32_i32_e32 v80, v80
	v_sub_f32_e32 v79, 2.0, v79
	v_mul_f32_e32 v78, v79, v78
	v_mul_f32_e32 v50, v50, v78
	v_max_f32_e32 v78, 0, v80
	v_max_f32_e64 v79, -v80, 0
	v_pk_mul_f32 v[78:79], v[72:73], v[78:79]
	v_add_f32_e32 v81, 0xc2000000, v80
	v_add_f32_e32 v34, v78, v79
	v_exp_f32_e32 v34, v34
	v_min_f32_e64 v78, |v80|, 1.0
	v_sub_f32_e32 v78, 2.0, v78
	v_max_f32_e64 v79, -v81, 0
	v_mul_f32_e32 v34, v78, v34
	v_max_f32_e32 v78, 0, v81
	v_pk_mul_f32 v[78:79], v[72:73], v[78:79]
	v_add_u32_e32 v80, -2, v75
	v_add_f32_e32 v78, v78, v79
	v_exp_f32_e32 v78, v78
	v_cvt_f32_i32_e32 v80, v80
	v_min_f32_e64 v79, |v81|, 1.0
	v_sub_f32_e32 v79, 2.0, v79
	v_mul_f32_e32 v78, v79, v78
	v_mul_f32_e32 v79, v35, v34
	v_max_f32_e32 v34, 0, v80
	v_max_f32_e64 v35, -v80, 0
	v_pk_mul_f32 v[34:35], v[72:73], v[34:35]
	v_mul_f32_e32 v51, v51, v78
	v_add_f32_e32 v34, v34, v35
	v_exp_f32_e32 v34, v34
	v_min_f32_e64 v35, |v80|, 1.0
	v_add_f32_e32 v78, 0xc2000000, v80
	v_sub_f32_e32 v35, 2.0, v35
	v_mul_f32_e32 v80, v35, v34
	v_max_f32_e32 v34, 0, v78
	v_max_f32_e64 v35, -v78, 0
	v_pk_mul_f32 v[34:35], v[72:73], v[34:35]
	v_mul_f32_e32 v36, v36, v80
	v_add_f32_e32 v34, v34, v35
	v_exp_f32_e32 v34, v34
	v_min_f32_e64 v35, |v78|, 1.0
	v_add_u32_e32 v78, -3, v75
	v_cvt_f32_i32_e32 v78, v78
	v_sub_f32_e32 v35, 2.0, v35
	v_mul_f32_e32 v34, v35, v34
	v_mul_f32_e32 v52, v52, v34
	v_max_f32_e32 v34, 0, v78
	v_max_f32_e64 v35, -v78, 0
	v_pk_mul_f32 v[34:35], v[72:73], v[34:35]
	v_add_f32_e32 v80, 0xc2000000, v78
	v_add_f32_e32 v34, v34, v35
	v_exp_f32_e32 v34, v34
	v_min_f32_e64 v35, |v78|, 1.0
	v_sub_f32_e32 v35, 2.0, v35
	v_mul_f32_e32 v78, v35, v34
	v_max_f32_e32 v34, 0, v80
	v_max_f32_e64 v35, -v80, 0
	v_pk_mul_f32 v[34:35], v[72:73], v[34:35]
	v_mul_f32_e32 v37, v37, v78
	v_add_f32_e32 v34, v34, v35
	v_exp_f32_e32 v34, v34
	v_min_f32_e64 v35, |v80|, 1.0
	v_add_u32_e32 v80, -8, v75
	v_cvt_f32_i32_e32 v80, v80
	v_sub_f32_e32 v35, 2.0, v35
	v_mul_f32_e32 v34, v35, v34
	v_mul_f32_e32 v53, v53, v34
	v_max_f32_e32 v34, 0, v80
	v_max_f32_e64 v35, -v80, 0
	v_pk_mul_f32 v[34:35], v[72:73], v[34:35]
	v_add_f32_e32 v78, 0xc2000000, v80
	v_add_f32_e32 v34, v34, v35
	v_exp_f32_e32 v34, v34
	v_min_f32_e64 v35, |v80|, 1.0
	v_sub_f32_e32 v35, 2.0, v35
	v_mul_f32_e32 v80, v35, v34
	v_max_f32_e32 v34, 0, v78
	v_max_f32_e64 v35, -v78, 0
	v_pk_mul_f32 v[34:35], v[72:73], v[34:35]
	v_mul_f32_e32 v38, v38, v80
	v_add_f32_e32 v34, v34, v35
	v_exp_f32_e32 v34, v34
	v_min_f32_e64 v35, |v78|, 1.0
	v_add_u32_e32 v78, -9, v75
	v_cvt_f32_i32_e32 v78, v78
	v_sub_f32_e32 v35, 2.0, v35
	v_mul_f32_e32 v34, v35, v34
	v_mul_f32_e32 v54, v54, v34
	v_max_f32_e32 v34, 0, v78
	v_max_f32_e64 v35, -v78, 0
	v_pk_mul_f32 v[34:35], v[72:73], v[34:35]
	v_add_f32_e32 v80, 0xc2000000, v78
	v_add_f32_e32 v34, v34, v35
	v_exp_f32_e32 v34, v34
	v_min_f32_e64 v35, |v78|, 1.0
	v_sub_f32_e32 v35, 2.0, v35
	v_mul_f32_e32 v78, v35, v34
; __device__ __forceinline__ void ret_tile_gen(const LAS char* sm, int r32, int hi, int vrd, int buf, int kp0, int qpos, float lgf, float lgb, const bf16x8 (&qf)[4], fa::f32x16& o0, fa::f32x16& o1) {
;     ...
; #pragma unroll
;     for (int r = 0; r < 16; ++r) {
;         const float f0 = (float)(d0 - ((r & 3) + 8 * (r >> 2))), f1 = f0 - 32.f;
;         const float w0 = __builtin_amdgcn_exp2f(lgf * fmaxf(f0, 0.f) + lgb * fmaxf(-f0, 0.f)) * (2.f - fminf(fabsf(f0), 1.f));
;         const float w1 = __builtin_amdgcn_exp2f(lgf * fmaxf(f1, 0.f) + lgb * fmaxf(-f1, 0.f)) * (2.f - fminf(fabsf(f1), 1.f));
;         p0[r] *= w0; p1[r] *= w1;
;     }
	v_max_f32_e32 v34, 0, v80
	v_max_f32_e64 v35, -v80, 0
	v_pk_mul_f32 v[34:35], v[72:73], v[34:35]
	v_mul_f32_e32 v39, v39, v78
	v_add_f32_e32 v34, v34, v35
	v_exp_f32_e32 v34, v34
	v_min_f32_e64 v35, |v80|, 1.0
	v_add_u32_e32 v80, -10, v75
	v_cvt_f32_i32_e32 v80, v80
	v_sub_f32_e32 v35, 2.0, v35
	v_mul_f32_e32 v34, v35, v34
	v_mul_f32_e32 v55, v55, v34
	v_max_f32_e32 v34, 0, v80
	v_max_f32_e64 v35, -v80, 0
	v_pk_mul_f32 v[34:35], v[72:73], v[34:35]
	v_add_f32_e32 v78, 0xc2000000, v80
	v_add_f32_e32 v34, v34, v35
	v_exp_f32_e32 v34, v34
	v_min_f32_e64 v35, |v80|, 1.0
	v_sub_f32_e32 v35, 2.0, v35
	v_mul_f32_e32 v80, v35, v34
	v_max_f32_e32 v34, 0, v78
	v_max_f32_e64 v35, -v78, 0
	v_pk_mul_f32 v[34:35], v[72:73], v[34:35]
	v_mul_f32_e32 v40, v40, v80
	v_add_f32_e32 v34, v34, v35
	v_exp_f32_e32 v34, v34
	v_min_f32_e64 v35, |v78|, 1.0
	v_add_u32_e32 v78, -11, v75
	v_cvt_f32_i32_e32 v78, v78
	v_sub_f32_e32 v35, 2.0, v35
	v_mul_f32_e32 v34, v35, v34
	v_mul_f32_e32 v56, v56, v34
	v_max_f32_e32 v34, 0, v78
	v_max_f32_e64 v35, -v78, 0
	v_pk_mul_f32 v[34:35], v[72:73], v[34:35]
	v_add_f32_e32 v80, 0xc2000000, v78
	v_add_f32_e32 v34, v34, v35
	v_exp_f32_e32 v34, v34
	v_min_f32_e64 v35, |v78|, 1.0
	v_sub_f32_e32 v35, 2.0, v35
	v_mul_f32_e32 v78, v35, v34
	v_max_f32_e32 v34, 0, v80
	v_max_f32_e64 v35, -v80, 0
	v_pk_mul_f32 v[34:35], v[72:73], v[34:35]
	v_mul_f32_e32 v41, v41, v78
	v_add_f32_e32 v34, v34, v35
	v_exp_f32_e32 v34, v34
	v_min_f32_e64 v35, |v80|, 1.0
	v_add_u32_e32 v80, -16, v75
	v_cvt_f32_i32_e32 v80, v80
	v_sub_f32_e32 v35, 2.0, v35
	v_mul_f32_e32 v34, v35, v34
	v_mul_f32_e32 v57, v57, v34
	v_max_f32_e32 v34, 0, v80
	v_max_f32_e64 v35, -v80, 0
	v_pk_mul_f32 v[34:35], v[72:73], v[34:35]
	v_add_f32_e32 v78, 0xc2000000, v80
	v_add_f32_e32 v34, v34, v35
	v_exp_f32_e32 v34, v34
	v_min_f32_e64 v35, |v80|, 1.0
	v_sub_f32_e32 v35, 2.0, v35
	v_mul_f32_e32 v80, v35, v34
	v_max_f32_e32 v34, 0, v78
	v_max_f32_e64 v35, -v78, 0
	v_pk_mul_f32 v[34:35], v[72:73], v[34:35]
	v_mul_f32_e32 v42, v42, v80
	v_add_f32_e32 v34, v34, v35
	v_exp_f32_e32 v34, v34
	v_min_f32_e64 v35, |v78|, 1.0
	v_subrev_u32_e32 v78, 17, v75
	v_cvt_f32_i32_e32 v78, v78
	v_sub_f32_e32 v35, 2.0, v35
	v_mul_f32_e32 v34, v35, v34
	v_mul_f32_e32 v58, v58, v34
	v_max_f32_e32 v34, 0, v78
	v_max_f32_e64 v35, -v78, 0
	v_pk_mul_f32 v[34:35], v[72:73], v[34:35]
	v_add_f32_e32 v80, 0xc2000000, v78
	v_add_f32_e32 v34, v34, v35
	v_exp_f32_e32 v34, v34
	v_min_f32_e64 v35, |v78|, 1.0
	v_sub_f32_e32 v35, 2.0, v35
	v_mul_f32_e32 v78, v35, v34
	v_max_f32_e32 v34, 0, v80
	v_max_f32_e64 v35, -v80, 0
	v_pk_mul_f32 v[34:35], v[72:73], v[34:35]
	v_mul_f32_e32 v43, v43, v78
	v_add_f32_e32 v34, v34, v35
	v_exp_f32_e32 v34, v34
	v_min_f32_e64 v35, |v80|, 1.0
	v_subrev_u32_e32 v80, 18, v75
	v_cvt_f32_i32_e32 v80, v80
	v_sub_f32_e32 v35, 2.0, v35
	v_mul_f32_e32 v34, v35, v34
	v_mul_f32_e32 v59, v59, v34
	v_max_f32_e32 v34, 0, v80
	v_max_f32_e64 v35, -v80, 0
	v_pk_mul_f32 v[34:35], v[72:73], v[34:35]
	v_add_f32_e32 v78, 0xc2000000, v80
	v_add_f32_e32 v34, v34, v35
	v_exp_f32_e32 v34, v34
	v_min_f32_e64 v35, |v80|, 1.0
	v_sub_f32_e32 v35, 2.0, v35
	v_mul_f32_e32 v80, v35, v34
	v_max_f32_e32 v34, 0, v78
	v_max_f32_e64 v35, -v78, 0
	v_pk_mul_f32 v[34:35], v[72:73], v[34:35]
	v_mul_f32_e32 v44, v44, v80
	v_add_f32_e32 v34, v34, v35
	v_exp_f32_e32 v34, v34
	v_min_f32_e64 v35, |v78|, 1.0
	v_subrev_u32_e32 v78, 19, v75
	v_cvt_f32_i32_e32 v78, v78
	v_sub_f32_e32 v35, 2.0, v35
	v_mul_f32_e32 v34, v35, v34
	v_mul_f32_e32 v60, v60, v34
	v_max_f32_e32 v34, 0, v78
	v_max_f32_e64 v35, -v78, 0
	v_pk_mul_f32 v[34:35], v[72:73], v[34:35]
	v_add_f32_e32 v80, 0xc2000000, v78
	v_add_f32_e32 v34, v34, v35
	v_exp_f32_e32 v34, v34
	v_min_f32_e64 v35, |v78|, 1.0
	v_sub_f32_e32 v35, 2.0, v35
	v_mul_f32_e32 v78, v35, v34
	v_max_f32_e32 v34, 0, v80
	v_max_f32_e64 v35, -v80, 0
	v_pk_mul_f32 v[34:35], v[72:73], v[34:35]
	v_mul_f32_e32 v45, v45, v78
	v_add_f32_e32 v34, v34, v35
	v_exp_f32_e32 v34, v34
	v_min_f32_e64 v35, |v80|, 1.0
	v_subrev_u32_e32 v80, 24, v75
	v_cvt_f32_i32_e32 v80, v80
	v_sub_f32_e32 v35, 2.0, v35
	v_mul_f32_e32 v34, v35, v34
	v_mul_f32_e32 v61, v61, v34
	v_max_f32_e32 v34, 0, v80
	v_max_f32_e64 v35, -v80, 0
	v_pk_mul_f32 v[34:35], v[72:73], v[34:35]
	v_add_f32_e32 v78, 0xc2000000, v80
	v_add_f32_e32 v34, v34, v35
	v_exp_f32_e32 v34, v34
	v_min_f32_e64 v35, |v80|, 1.0
	v_sub_f32_e32 v35, 2.0, v35
	v_mul_f32_e32 v80, v35, v34
	v_max_f32_e32 v34, 0, v78
	v_max_f32_e64 v35, -v78, 0
	v_pk_mul_f32 v[34:35], v[72:73], v[34:35]
	v_mul_f32_e32 v46, v46, v80
	v_add_f32_e32 v34, v34, v35
	v_exp_f32_e32 v34, v34
	v_min_f32_e64 v35, |v78|, 1.0
	v_subrev_u32_e32 v78, 25, v75
	v_cvt_f32_i32_e32 v78, v78
	v_sub_f32_e32 v35, 2.0, v35
	v_mul_f32_e32 v34, v35, v34
	v_mul_f32_e32 v62, v62, v34
	v_max_f32_e32 v34, 0, v78
	v_max_f32_e64 v35, -v78, 0
	v_pk_mul_f32 v[34:35], v[72:73], v[34:35]
	v_add_f32_e32 v80, 0xc2000000, v78
	v_add_f32_e32 v34, v34, v35
	v_exp_f32_e32 v34, v34
	v_min_f32_e64 v35, |v78|, 1.0
	v_sub_f32_e32 v35, 2.0, v35
	v_mul_f32_e32 v78, v35, v34
	v_max_f32_e32 v34, 0, v80
	v_max_f32_e64 v35, -v80, 0
	v_pk_mul_f32 v[34:35], v[72:73], v[34:35]
	v_mul_f32_e32 v47, v47, v78
	v_add_f32_e32 v34, v34, v35
	v_exp_f32_e32 v34, v34
	v_min_f32_e64 v35, |v80|, 1.0
	v_subrev_u32_e32 v80, 26, v75
	v_cvt_f32_i32_e32 v80, v80
	v_sub_f32_e32 v35, 2.0, v35
	v_mul_f32_e32 v34, v35, v34
	v_mul_f32_e32 v63, v63, v34
	v_max_f32_e32 v34, 0, v80
	v_max_f32_e64 v35, -v80, 0
	v_pk_mul_f32 v[34:35], v[72:73], v[34:35]
	v_add_f32_e32 v78, 0xc2000000, v80
	v_add_f32_e32 v34, v34, v35
	v_exp_f32_e32 v34, v34
	v_min_f32_e64 v35, |v80|, 1.0
; __device__ __forceinline__ float siluf_(float x) { return x * sigmoidf_(x); }
; __device__ __forceinline__ void ph_ret_chunk(unsigned char* lds_, bf16_t* Z, const bf16_t* KVF, const bf16_t* KVB, const float* decay_logit, const float* gn_w, int with_ctx, int u0, int ustep, unsigned* kvc, unsigned* barw) { PH_IDS;
;     ...
;         ret_tile_gen(sm, r32, hi, vrd, (2 * cl) * BUF_R, c0, qpos, lgf, lgb, qf, o0, o1);
;         __builtin_amdgcn_sched_barrier(0);
;         ret_tile_gen(sm, r32, hi, vrd, (2 * cl + 1) * BUF_R, c0 + 64, qpos, lgf, lgb, qf, o0, o1);
;         __builtin_amdgcn_sched_barrier(0);
;         { f32x16 p0, p1;
;           ret_qk(sm, r32, hi, ST_OFF + cl * ST_SZ, qf, p0, p1);
;           const float sf = __builtin_amdgcn_exp2f(lgf * (float)(qpos - c0 + 1));
; #pragma unroll
;           for (int r = 0; r < 16; ++r) { o0[r] += p0[r] * sf; o1[r] += p1[r] * sf; }
;           ret_qk(sm, r32, hi, ST_OFF + (2 + cl) * ST_SZ, qf, p0, p1);
;           const float sbk = __builtin_amdgcn_exp2f(lgb * (float)(c0 + 128 - qpos));
; #pragma unroll
;           for (int r = 0; r < 16; ++r) { o0[r] += p0[r] * sbk; o1[r] += p1[r] * sbk; } }
;     ...
;                 for (int q = 0; q < 4; ++q) { const float ov = blk ? o1[4 * g + q] : o0[4 * g + q]; const unsigned gb = q < 2 ? gt.x : gt.y; const float gv = __uint_as_float((q & 1) ? (gb & 0xffff0000u) : (gb << 16));
;                     y[q] = siluf_(gv) * ((ov - mu) * rstd * gw[q]); }
	v_sub_f32_e32 v35, 2.0, v35
	v_subrev_u32_e32 v75, 27, v75
	v_mul_f32_e32 v80, v35, v34
	v_max_f32_e32 v34, 0, v78
	v_max_f32_e64 v35, -v78, 0
	v_pk_mul_f32 v[34:35], v[72:73], v[34:35]
	v_cvt_f32_i32_e32 v75, v75
	v_add_f32_e32 v34, v34, v35
	v_exp_f32_e32 v34, v34
	v_min_f32_e64 v35, |v78|, 1.0
	v_sub_f32_e32 v35, 2.0, v35
	v_mul_f32_e32 v48, v48, v80
	v_mul_f32_e32 v34, v35, v34
	v_mul_f32_e32 v64, v64, v34
	v_max_f32_e32 v34, 0, v75
	v_max_f32_e64 v35, -v75, 0
	v_pk_mul_f32 v[34:35], v[72:73], v[34:35]
	v_add_f32_e32 v78, 0xc2000000, v75
	v_add_f32_e32 v34, v34, v35
	v_exp_f32_e32 v80, v34
	v_min_f32_e64 v34, |v75|, 1.0
	v_sub_f32_e32 v75, 2.0, v34
	v_max_f32_e32 v34, 0, v78
	v_max_f32_e64 v35, -v78, 0
	v_pk_mul_f32 v[34:35], v[72:73], v[34:35]
	s_nop 0
	v_add_f32_e32 v34, v34, v35
	v_exp_f32_e32 v34, v34
	v_mul_f32_e32 v35, v75, v80
	v_min_f32_e64 v75, |v78|, 1.0
	v_sub_f32_e32 v75, 2.0, v75
	v_mul_f32_e32 v34, v75, v34
	v_mul_f32_e32 v49, v49, v35
	v_mul_f32_e32 v65, v65, v34
	v_cvt_pk_bf16_f32 v34, v77, v79
	v_cvt_pk_bf16_f32 v35, v36, v37
	v_cvt_pk_bf16_f32 v36, v38, v39
	v_cvt_pk_bf16_f32 v37, v40, v41
	v_cvt_pk_bf16_f32 v38, v42, v43
	v_cvt_pk_bf16_f32 v39, v44, v45
	v_cvt_pk_bf16_f32 v40, v46, v47
	v_cvt_pk_bf16_f32 v41, v48, v49
	v_cvt_pk_bf16_f32 v42, v50, v51
	v_cvt_pk_bf16_f32 v43, v52, v53
	v_cvt_pk_bf16_f32 v44, v54, v55
	v_cvt_pk_bf16_f32 v45, v56, v57
	v_cvt_pk_bf16_f32 v46, v58, v59
	v_cvt_pk_bf16_f32 v47, v60, v61
	v_cvt_pk_bf16_f32 v48, v62, v63
	v_cvt_pk_bf16_f32 v49, v64, v65
	ds_read_b64_tr_b16 v[50:51], v76 offset:26624
	ds_read_b64_tr_b16 v[52:53], v76 offset:27136
	ds_read_b64_tr_b16 v[54:55], v76 offset:27648
	ds_read_b64_tr_b16 v[56:57], v76 offset:28160
	s_waitcnt lgkmcnt(2)
	v_mfma_f32_32x32x16_bf16 v[2:17], v[50:53], v[34:37], v[2:17]
	ds_read_b64_tr_b16 v[50:51], v76 offset:30720
	ds_read_b64_tr_b16 v[52:53], v76 offset:31232
	ds_read_b64_tr_b16 v[58:59], v76 offset:31744
	ds_read_b64_tr_b16 v[60:61], v76 offset:32256
	s_waitcnt lgkmcnt(2)
	v_mfma_f32_32x32x16_bf16 v[18:33], v[50:53], v[34:37], v[18:33]
	v_mfma_f32_32x32x16_bf16 v[2:17], v[54:57], v[38:41], v[2:17]
	s_waitcnt lgkmcnt(0)
	v_mfma_f32_32x32x16_bf16 v[18:33], v[58:61], v[38:41], v[18:33]
	ds_read_b64_tr_b16 v[34:35], v76 offset:28672
	ds_read_b64_tr_b16 v[36:37], v76 offset:29184
	ds_read_b64_tr_b16 v[38:39], v76 offset:29696
	ds_read_b64_tr_b16 v[40:41], v76 offset:30208
	s_waitcnt lgkmcnt(2)
	v_mfma_f32_32x32x16_bf16 v[2:17], v[34:37], v[42:45], v[2:17]
	ds_read_b64_tr_b16 v[34:35], v76 offset:32768
	ds_read_b64_tr_b16 v[36:37], v76 offset:33280
	ds_read_b64_tr_b16 v[50:51], v76 offset:33792
	ds_read_b64_tr_b16 v[52:53], v76 offset:34304
	s_waitcnt lgkmcnt(2)
	v_mfma_f32_32x32x16_bf16 v[18:33], v[34:37], v[42:45], v[18:33]
	v_mfma_f32_32x32x16_bf16 v[2:17], v[38:41], v[46:49], v[2:17]
	s_waitcnt lgkmcnt(0)
	v_mfma_f32_32x32x16_bf16 v[18:33], v[50:53], v[46:49], v[18:33]
	v_add3_u32 v75, s8, v71, v70
	ds_read_b128 v[34:37], v75
	ds_read_b128 v[76:79], v75 offset:32
	ds_read_b128 v[50:53], v75 offset:4608
	ds_read_b128 v[80:83], v75 offset:4640
	v_add3_u32 v70, s7, v71, v70
	s_waitcnt lgkmcnt(1)
	v_mfma_f32_32x32x16_bf16 v[50:65], v[50:53], v[66:69], 0
	v_mfma_f32_32x32x16_bf16 v[34:49], v[34:37], v[66:69], 0
	s_waitcnt lgkmcnt(0)
	v_mfma_f32_32x32x16_bf16 v[50:65], v[80:83], v[136:139], v[50:65]
	v_mfma_f32_32x32x16_bf16 v[34:49], v[76:79], v[136:139], v[34:49]
	ds_read_b128 v[76:79], v75 offset:4672
	ds_read_b128 v[80:83], v75 offset:4704
	ds_read_b128 v[162:165], v75 offset:64
	ds_read_b128 v[166:169], v75 offset:96
	v_subrev_u32_e32 v75, s6, v74
	v_add_u32_e32 v75, 1, v75
	v_cvt_f32_i32_e32 v75, v75
	v_mul_f32_e32 v71, v72, v75
	s_waitcnt lgkmcnt(3)
	v_mfma_f32_32x32x16_bf16 v[50:65], v[76:79], v[132:135], v[50:65]
	ds_read_b128 v[76:79], v70 offset:4608
	ds_read_b128 v[170:173], v70
	ds_read_b128 v[174:177], v70 offset:32
	ds_read_b128 v[178:181], v70 offset:4640
	v_exp_f32_e32 v158, v71
	v_sub_u32_e32 v71, s6, v74
	v_add_u32_e32 v71, 0x80, v71
	v_cvt_f32_i32_e32 v71, v71
	v_xor_b32_e32 v72, 32, v1
	s_waitcnt lgkmcnt(6)
	v_mfma_f32_32x32x16_bf16 v[50:65], v[80:83], v[126:129], v[50:65]
	s_waitcnt lgkmcnt(3)
	v_mfma_f32_32x32x16_bf16 v[78:93], v[76:79], v[66:69], 0
	ds_read_b128 v[184:187], v70 offset:64
	ds_read_b128 v[188:191], v70 offset:96
	ds_read_b128 v[74:77], v70 offset:4672
	ds_read_b128 v[192:195], v70 offset:4704
	v_mul_f32_e32 v70, v73, v71
	v_exp_f32_e32 v160, v70
	v_and_b32_e32 v70, 64, v1
	v_add_u32_e32 v73, 64, v70
	s_nop 1
	v_pk_fma_f32 v[32:33], v[158:159], v[64:65], v[32:33] op_sel_hi:[0,1,1]
	v_pk_fma_f32 v[30:31], v[158:159], v[62:63], v[30:31] op_sel_hi:[0,1,1]
	s_waitcnt lgkmcnt(4)
	v_mfma_f32_32x32x16_bf16 v[78:93], v[178:181], v[136:139], v[78:93]
	s_waitcnt vmcnt(2)
	v_lshlrev_b32_e32 v178, 16, v142
	v_and_b32_e32 v179, 0xffff0000, v142
	v_mul_f32_e32 v70, 0xbfb8aa3b, v178
	v_mul_f32_e32 v71, 0xbfb8aa3b, v179
	v_exp_f32_e32 v70, v70
	v_exp_f32_e32 v71, v71
	v_cmp_lt_i32_e32 vcc, v72, v73
	s_waitcnt lgkmcnt(1)
	v_mfma_f32_32x32x16_bf16 v[78:93], v[74:77], v[132:135], v[78:93]
	v_add_f32_e64 v180, v70, 1.0
	v_add_f32_e64 v181, v71, 1.0
	v_div_scale_f32 v64, s[4:5], v181, v181, 1.0
	v_rcp_f32_e32 v65, v64
	v_cndmask_b32_e32 v72, v1, v72, vcc
	v_lshlrev_b32_e32 v131, 2, v72
	s_waitcnt lgkmcnt(0)
; __device__ __forceinline__ float siluf_(float x) { return x * sigmoidf_(x); }
; __device__ __forceinline__ void ph_ret_chunk(unsigned char* lds_, bf16_t* Z, const bf16_t* KVF, const bf16_t* KVB, const float* decay_logit, const float* gn_w, int with_ctx, int u0, int ustep, unsigned* kvc, unsigned* barw) { PH_IDS;
;     ...
;         { f32x16 p0, p1;
;           ret_qk(sm, r32, hi, ST_OFF + cl * ST_SZ, qf, p0, p1);
;           const float sf = __builtin_amdgcn_exp2f(lgf * (float)(qpos - c0 + 1));
; #pragma unroll
;           for (int r = 0; r < 16; ++r) { o0[r] += p0[r] * sf; o1[r] += p1[r] * sf; }
;           ret_qk(sm, r32, hi, ST_OFF + (2 + cl) * ST_SZ, qf, p0, p1);
;           const float sbk = __builtin_amdgcn_exp2f(lgb * (float)(c0 + 128 - qpos));
; #pragma unroll
;           for (int r = 0; r < 16; ++r) { o0[r] += p0[r] * sbk; o1[r] += p1[r] * sbk; } }
;         float s1 = 0.f;
; #pragma unroll
;         for (int r = 0; r < 16; ++r) s1 += o0[r] + o1[r];
;         s1 += __shfl_xor(s1, 32);
;         const float mu = s1 * (1.f / 64);
;         float s2 = 0.f;
; #pragma unroll
;         for (int r = 0; r < 16; ++r) { const float a = o0[r] - mu, c = o1[r] - mu; s2 += a * a + c * c; }
;         s2 += __shfl_xor(s2, 32);
;         const float rstd = rsqrtf(s2 * (1.f / 64) + EPS);
;         u32x2 wv[2][4];
; #pragma unroll
;         for (int g = 0; g < 4; ++g)
; #pragma unroll
;             for (int blk = 0; blk < 2; ++blk) {
;                 const int d = blk * 32 + 8 * g + 4 * hi;
;                 const u32x2 gt = gtv[2 * g + blk];
;                 const f32x4 gw = gwv[2 * g + blk];
;                 float y[4];
; #pragma unroll
;                 for (int q = 0; q < 4; ++q) { const float ov = blk ? o1[4 * g + q] : o0[4 * g + q]; const unsigned gb = q < 2 ? gt.x : gt.y; const float gv = __uint_as_float((q & 1) ? (gb & 0xffff0000u) : (gb << 16));
;                     y[q] = siluf_(gv) * ((ov - mu) * rstd * gw[q]); }
	v_mfma_f32_32x32x16_bf16 v[78:93], v[192:195], v[126:129], v[78:93]
	v_mfma_f32_32x32x16_bf16 v[34:49], v[162:165], v[132:135], v[34:49]
	s_nop 10
	v_fma_f32 v90, v160, v90, v30
	v_fma_f32 v91, v160, v91, v31
	v_fma_f32 v30, -v64, v65, 1.0
	v_fmac_f32_e32 v65, v30, v65
	v_div_scale_f32 v30, vcc, 1.0, v181, 1.0
	v_mul_f32_e32 v31, v30, v65
	v_fma_f32 v62, -v64, v31, v30
	v_mfma_f32_32x32x16_bf16 v[62:77], v[170:173], v[66:69], 0
	v_fma_f32 v32, v160, v92, v32
	v_fma_f32 v33, v160, v93, v33
	v_div_scale_f32 v92, s[4:5], v180, v180, 1.0
	v_rcp_f32_e32 v93, v92
	v_rcp_f32_e32 v31, v181
	v_fma_f32 v30, -v92, v93, 1.0
	v_mfma_f32_32x32x16_bf16 v[62:77], v[174:177], v[136:139], v[62:77]
	v_fmac_f32_e32 v93, v30, v93
	v_div_scale_f32 v30, vcc, 1.0, v180, 1.0
	v_mul_f32_e32 v142, v30, v93
	v_fma_f32 v159, -v92, v142, v30
	v_mfma_f32_32x32x16_bf16 v[62:77], v[184:187], v[132:135], v[62:77]
	v_lshlrev_b32_e32 v92, 16, v157
	v_and_b32_e32 v93, 0xffff0000, v157
	v_mul_f32_e32 v136, 0xbfb8aa3b, v92
	v_mul_f32_e32 v137, 0xbfb8aa3b, v93
	v_exp_f32_e32 v136, v136
	v_exp_f32_e32 v137, v137
	v_mfma_f32_32x32x16_bf16 v[34:49], v[166:169], v[126:129], v[34:49]
	v_fma_f32 v28, v158, v60, v28
	v_fma_f32 v29, v158, v61, v29
	v_fma_f32 v60, v160, v88, v28
	v_fma_f32 v61, v160, v89, v29
	v_add_f32_e64 v132, v136, 1.0
	v_add_f32_e64 v133, v137, 1.0
	v_pk_fma_f32 v[26:27], v[158:159], v[58:59], v[26:27] op_sel_hi:[0,1,1]
	v_mfma_f32_32x32x16_bf16 v[62:77], v[188:191], v[126:129], v[62:77]
	s_nop 1
	s_nop 1
	v_fma_f32 v16, v158, v48, v16
	v_fma_f32 v17, v158, v49, v17
	v_lshlrev_b32_e32 v126, 16, v156
	v_and_b32_e32 v127, 0xffff0000, v156
	v_fma_f32 v14, v158, v46, v14
	v_fma_f32 v15, v158, v47, v15
	v_pk_fma_f32 v[58:59], v[160:161], v[86:87], v[26:27] op_sel_hi:[0,1,1]
	v_pk_fma_f32 v[12:13], v[158:159], v[44:45], v[12:13] op_sel_hi:[0,1,1]
	v_pk_fma_f32 v[10:11], v[158:159], v[42:43], v[10:11] op_sel_hi:[0,1,1]
	s_nop 0
	v_pk_fma_f32 v[48:49], v[160:161], v[76:77], v[16:17] op_sel_hi:[0,1,1]
	v_rcp_f32_e32 v17, v133
	v_mul_f32_e32 v76, 0xbfb8aa3b, v126
	v_mul_f32_e32 v77, 0xbfb8aa3b, v127
	v_exp_f32_e32 v76, v76
	v_exp_f32_e32 v77, v77
	v_rcp_f32_e32 v16, v132
	s_nop 0
	v_pk_mul_f32 v[16:17], v[16:17], v[92:93]
	v_pk_add_f32 v[92:93], v[76:77], 1.0 op_sel_hi:[1,0]
	v_pk_fma_f32 v[46:47], v[160:161], v[74:75], v[14:15] op_sel_hi:[0,1,1]
	v_pk_fma_f32 v[44:45], v[160:161], v[72:73], v[12:13] op_sel_hi:[0,1,1]
	v_pk_fma_f32 v[42:43], v[160:161], v[70:71], v[10:11] op_sel_hi:[0,1,1]
	v_pk_fma_f32 v[24:25], v[158:159], v[56:57], v[24:25] op_sel_hi:[0,1,1]
	v_rcp_f32_e32 v15, v93
	v_lshlrev_b32_e32 v128, 16, v155
	v_and_b32_e32 v129, 0xffff0000, v155
	v_mul_f32_e32 v74, 0xbfb8aa3b, v128
	v_mul_f32_e32 v75, 0xbfb8aa3b, v129
	v_exp_f32_e32 v74, v74
	v_exp_f32_e32 v75, v75
	v_rcp_f32_e32 v14, v92
	s_nop 0
	v_pk_mul_f32 v[14:15], v[14:15], v[126:127]
	v_pk_add_f32 v[92:93], v[74:75], 1.0 op_sel_hi:[1,0]
	v_pk_fma_f32 v[56:57], v[160:161], v[84:85], v[24:25] op_sel_hi:[0,1,1]
	v_pk_fma_f32 v[22:23], v[158:159], v[54:55], v[22:23] op_sel_hi:[0,1,1]
	v_pk_fma_f32 v[54:55], v[160:161], v[82:83], v[22:23] op_sel_hi:[0,1,1]
	v_pk_fma_f32 v[8:9], v[158:159], v[40:41], v[8:9] op_sel_hi:[0,1,1]
	v_rcp_f32_e32 v29, v93
	v_lshlrev_b32_e32 v88, 16, v154
	v_and_b32_e32 v89, 0xffff0000, v154
	v_mul_f32_e32 v126, 0xbfb8aa3b, v88
	v_mul_f32_e32 v127, 0xbfb8aa3b, v89
	v_exp_f32_e32 v126, v126
	v_exp_f32_e32 v127, v127
	v_rcp_f32_e32 v28, v92
	s_nop 0
	v_pk_mul_f32 v[28:29], v[28:29], v[128:129]
	v_pk_add_f32 v[92:93], v[126:127], 1.0 op_sel_hi:[1,0]
	v_pk_fma_f32 v[40:41], v[160:161], v[68:69], v[8:9] op_sel_hi:[0,1,1]
	v_pk_fma_f32 v[6:7], v[158:159], v[38:39], v[6:7] op_sel_hi:[0,1,1]
	v_pk_fma_f32 v[38:39], v[160:161], v[66:67], v[6:7] op_sel_hi:[0,1,1]
	v_pk_fma_f32 v[20:21], v[158:159], v[52:53], v[20:21] op_sel_hi:[0,1,1]
	v_rcp_f32_e32 v27, v93
	v_lshlrev_b32_e32 v86, 16, v153
	v_and_b32_e32 v87, 0xffff0000, v153
	v_mul_f32_e32 v126, 0xbfb8aa3b, v86
	v_mul_f32_e32 v127, 0xbfb8aa3b, v87
	v_exp_f32_e32 v126, v126
	v_exp_f32_e32 v127, v127
	v_rcp_f32_e32 v26, v92
	s_nop 0
	v_pk_mul_f32 v[26:27], v[26:27], v[88:89]
	v_pk_add_f32 v[92:93], v[126:127], 1.0 op_sel_hi:[1,0]
	v_lshlrev_b32_e32 v88, 16, v152
	v_and_b32_e32 v89, 0xffff0000, v152
	v_pk_fma_f32 v[20:21], v[160:161], v[80:81], v[20:21] op_sel_hi:[0,1,1]
	v_pk_fma_f32 v[18:19], v[158:159], v[50:51], v[18:19] op_sel_hi:[0,1,1]
	v_rcp_f32_e32 v13, v93
	v_pk_fma_f32 v[18:19], v[160:161], v[78:79], v[18:19] op_sel_hi:[0,1,1]
	v_mul_f32_e32 v72, 0xbfb8aa3b, v88
	v_mul_f32_e32 v73, 0xbfb8aa3b, v89
	v_exp_f32_e32 v72, v72
	v_exp_f32_e32 v73, v73
	v_rcp_f32_e32 v12, v92
	s_nop 0
	v_pk_mul_f32 v[12:13], v[12:13], v[86:87]
	v_pk_add_f32 v[86:87], v[72:73], 1.0 op_sel_hi:[1,0]
	v_pk_fma_f32 v[4:5], v[158:159], v[36:37], v[4:5] op_sel_hi:[0,1,1]
	v_pk_fma_f32 v[4:5], v[160:161], v[64:65], v[4:5] op_sel_hi:[0,1,1]
	v_pk_fma_f32 v[2:3], v[158:159], v[34:35], v[2:3] op_sel_hi:[0,1,1]
	v_pk_fma_f32 v[2:3], v[160:161], v[62:63], v[2:3] op_sel_hi:[0,1,1]
	v_rcp_f32_e32 v11, v87
	v_lshlrev_b32_e32 v92, 16, v151
	v_and_b32_e32 v93, 0xffff0000, v151
	v_mul_f32_e32 v70, 0xbfb8aa3b, v92
	v_mul_f32_e32 v71, 0xbfb8aa3b, v93
	v_exp_f32_e32 v70, v70
	v_exp_f32_e32 v71, v71
	v_rcp_f32_e32 v10, v86
	s_nop 0
	v_pk_mul_f32 v[10:11], v[10:11], v[88:89]
	v_pk_add_f32 v[86:87], v[70:71], 1.0 op_sel_hi:[1,0]
	v_pk_add_f32 v[70:71], v[42:43], v[58:59]
	v_pk_add_f32 v[72:73], v[44:45], v[60:61]
	v_pk_add_f32 v[74:75], v[46:47], v[90:91]
	v_pk_add_f32 v[76:77], v[48:49], v[32:33]
	v_rcp_f32_e32 v25, v87
	v_lshlrev_b32_e32 v84, 16, v150
	v_and_b32_e32 v85, 0xffff0000, v150
; __device__ __forceinline__ float siluf_(float x) { return x * sigmoidf_(x); }
; __device__ __forceinline__ void ph_ret_chunk(unsigned char* lds_, bf16_t* Z, const bf16_t* KVF, const bf16_t* KVB, const float* decay_logit, const float* gn_w, int with_ctx, int u0, int ustep, unsigned* kvc, unsigned* barw) { PH_IDS;
;     ...
;         float s1 = 0.f;
; #pragma unroll
;         for (int r = 0; r < 16; ++r) s1 += o0[r] + o1[r];
;         s1 += __shfl_xor(s1, 32);
;         const float mu = s1 * (1.f / 64);
;         float s2 = 0.f;
; #pragma unroll
;         for (int r = 0; r < 16; ++r) { const float a = o0[r] - mu, c = o1[r] - mu; s2 += a * a + c * c; }
;         s2 += __shfl_xor(s2, 32);
;         const float rstd = rsqrtf(s2 * (1.f / 64) + EPS);
;         u32x2 wv[2][4];
; #pragma unroll
;         for (int g = 0; g < 4; ++g)
; #pragma unroll
;             for (int blk = 0; blk < 2; ++blk) {
;                 const int d = blk * 32 + 8 * g + 4 * hi;
;                 const u32x2 gt = gtv[2 * g + blk];
;                 const f32x4 gw = gwv[2 * g + blk];
;                 float y[4];
; #pragma unroll
;                 for (int q = 0; q < 4; ++q) { const float ov = blk ? o1[4 * g + q] : o0[4 * g + q]; const unsigned gb = q < 2 ? gt.x : gt.y; const float gv = __uint_as_float((q & 1) ? (gb & 0xffff0000u) : (gb << 16));
;                     y[q] = siluf_(gv) * ((ov - mu) * rstd * gw[q]); }
	v_mul_f32_e32 v88, 0xbfb8aa3b, v84
	v_mul_f32_e32 v89, 0xbfb8aa3b, v85
	v_exp_f32_e32 v88, v88
	v_exp_f32_e32 v89, v89
	v_rcp_f32_e32 v24, v86
	s_nop 0
	v_pk_mul_f32 v[24:25], v[24:25], v[92:93]
	v_pk_add_f32 v[86:87], v[88:89], 1.0 op_sel_hi:[1,0]
	v_rcp_f32_e32 v30, v180
	s_nop 0
	v_pk_mul_f32 v[30:31], v[30:31], v[178:179]
	v_rcp_f32_e32 v23, v87
	v_lshlrev_b32_e32 v82, 16, v149
	v_and_b32_e32 v83, 0xffff0000, v149
	v_mul_f32_e32 v88, 0xbfb8aa3b, v82
	v_mul_f32_e32 v89, 0xbfb8aa3b, v83
	v_exp_f32_e32 v88, v88
	v_exp_f32_e32 v89, v89
	v_rcp_f32_e32 v22, v86
	s_nop 0
	v_pk_mul_f32 v[22:23], v[22:23], v[84:85]
	v_pk_add_f32 v[86:87], v[88:89], 1.0 op_sel_hi:[1,0]
	v_lshlrev_b32_e32 v84, 16, v148
	v_and_b32_e32 v85, 0xffff0000, v148
	v_rcp_f32_e32 v9, v87
	v_mul_f32_e32 v68, 0xbfb8aa3b, v84
	v_mul_f32_e32 v69, 0xbfb8aa3b, v85
	v_exp_f32_e32 v68, v68
	v_exp_f32_e32 v69, v69
	v_rcp_f32_e32 v8, v86
	s_nop 0
	v_pk_mul_f32 v[8:9], v[8:9], v[82:83]
	v_pk_add_f32 v[82:83], v[68:69], 1.0 op_sel_hi:[1,0]
	v_pk_add_f32 v[68:69], v[40:41], v[56:57]
	s_nop 0
	v_rcp_f32_e32 v7, v83
	v_lshlrev_b32_e32 v66, 16, v147
	v_and_b32_e32 v67, 0xffff0000, v147
	v_mul_f32_e32 v86, 0xbfb8aa3b, v66
	v_mul_f32_e32 v87, 0xbfb8aa3b, v67
	v_exp_f32_e32 v86, v86
	v_exp_f32_e32 v87, v87
	v_rcp_f32_e32 v6, v82
	s_nop 0
	v_pk_mul_f32 v[6:7], v[6:7], v[84:85]
	v_pk_add_f32 v[82:83], v[86:87], 1.0 op_sel_hi:[1,0]
	v_pk_add_f32 v[84:85], v[38:39], v[54:55]
	s_nop 0
	v_rcp_f32_e32 v53, v83
	v_lshlrev_b32_e32 v80, 16, v146
	v_and_b32_e32 v81, 0xffff0000, v146
	v_mul_f32_e32 v86, 0xbfb8aa3b, v80
	v_mul_f32_e32 v87, 0xbfb8aa3b, v81
	v_exp_f32_e32 v86, v86
	v_exp_f32_e32 v87, v87
	v_rcp_f32_e32 v52, v82
	s_nop 0
	v_pk_mul_f32 v[52:53], v[52:53], v[66:67]
	v_pk_add_f32 v[82:83], v[86:87], 1.0 op_sel_hi:[1,0]
	s_nop 0
	s_nop 0
	v_rcp_f32_e32 v51, v83
	v_lshlrev_b32_e32 v66, 16, v145
	v_and_b32_e32 v67, 0xffff0000, v145
	v_mul_f32_e32 v78, 0xbfb8aa3b, v66
	v_mul_f32_e32 v79, 0xbfb8aa3b, v67
	v_exp_f32_e32 v78, v78
	v_exp_f32_e32 v79, v79
	v_rcp_f32_e32 v50, v82
	s_nop 0
	v_pk_mul_f32 v[50:51], v[50:51], v[80:81]
	v_pk_add_f32 v[78:79], v[78:79], 1.0 op_sel_hi:[1,0]
	s_nop 0
	s_nop 0
	v_rcp_f32_e32 v37, v79
	v_lshlrev_b32_e32 v64, 16, v144
	v_and_b32_e32 v65, 0xffff0000, v144
	v_mul_f32_e32 v80, 0xbfb8aa3b, v64
	v_mul_f32_e32 v81, 0xbfb8aa3b, v65
	v_exp_f32_e32 v80, v80
	v_exp_f32_e32 v81, v81
	v_rcp_f32_e32 v36, v78
	s_nop 0
	v_pk_mul_f32 v[36:37], v[36:37], v[66:67]
	v_pk_add_f32 v[66:67], v[80:81], 1.0 op_sel_hi:[1,0]
	v_pk_add_f32 v[78:79], v[4:5], v[20:21]
	s_nop 0
	v_pk_add_f32 v[62:63], v[2:3], v[18:19]
	v_rcp_f32_e32 v35, v67
	v_add_f32_e32 v34, 0, v62
	v_add_f32_e32 v34, v63, v34
	v_add_f32_e32 v34, v78, v34
	v_add_f32_e32 v34, v79, v34
	v_add_f32_e32 v34, v84, v34
	v_add_f32_e32 v34, v85, v34
	v_add_f32_e32 v34, v68, v34
	v_add_f32_e32 v34, v69, v34
	v_add_f32_e32 v34, v70, v34
	v_add_f32_e32 v34, v71, v34
	v_add_f32_e32 v34, v72, v34
	v_add_f32_e32 v34, v73, v34
	v_add_f32_e32 v34, v74, v34
	v_add_f32_e32 v34, v75, v34
	v_add_f32_e32 v34, v76, v34
	v_add_f32_e32 v34, v77, v34
	ds_bpermute_b32 v62, v131, v34
	s_mov_b32 s4, 0x800000
	s_waitcnt lgkmcnt(0)
	v_add_f32_e32 v34, v34, v62
	v_mul_f32_e32 v34, 0x3c800000, v34
	v_pk_add_f32 v[18:19], v[18:19], v[34:35] op_sel_hi:[1,0] neg_lo:[0,1] neg_hi:[0,1]
	v_pk_add_f32 v[2:3], v[2:3], v[34:35] op_sel_hi:[1,0] neg_lo:[0,1] neg_hi:[0,1]
	v_pk_mul_f32 v[62:63], v[18:19], v[18:19]
	v_pk_add_f32 v[20:21], v[20:21], v[34:35] op_sel_hi:[1,0] neg_lo:[0,1] neg_hi:[0,1]
	v_pk_fma_f32 v[62:63], v[2:3], v[2:3], v[62:63]
	v_pk_add_f32 v[4:5], v[4:5], v[34:35] op_sel_hi:[1,0] neg_lo:[0,1] neg_hi:[0,1]
	v_pk_mul_f32 v[68:69], v[20:21], v[20:21]
	v_pk_add_f32 v[38:39], v[38:39], v[34:35] op_sel_hi:[1,0] neg_lo:[0,1] neg_hi:[0,1]
	v_pk_fma_f32 v[68:69], v[4:5], v[4:5], v[68:69]
	v_pk_add_f32 v[54:55], v[54:55], v[34:35] op_sel_hi:[1,0] neg_lo:[0,1] neg_hi:[0,1]
	v_pk_add_f32 v[40:41], v[40:41], v[34:35] op_sel_hi:[1,0] neg_lo:[0,1] neg_hi:[0,1]
	v_pk_add_f32 v[56:57], v[56:57], v[34:35] op_sel_hi:[1,0] neg_lo:[0,1] neg_hi:[0,1]
	v_pk_add_f32 v[42:43], v[42:43], v[34:35] op_sel_hi:[1,0] neg_lo:[0,1] neg_hi:[0,1]
	v_pk_add_f32 v[58:59], v[58:59], v[34:35] op_sel_hi:[1,0] neg_lo:[0,1] neg_hi:[0,1]
	v_pk_add_f32 v[44:45], v[44:45], v[34:35] op_sel_hi:[1,0] neg_lo:[0,1] neg_hi:[0,1]
	v_pk_add_f32 v[60:61], v[60:61], v[34:35] op_sel_hi:[1,0] neg_lo:[0,1] neg_hi:[0,1]
	v_pk_add_f32 v[46:47], v[46:47], v[34:35] op_sel_hi:[1,0] neg_lo:[0,1] neg_hi:[0,1]
	v_pk_add_f32 v[78:79], v[90:91], v[34:35] op_sel_hi:[1,0] neg_lo:[0,1] neg_hi:[0,1]
	v_pk_add_f32 v[48:49], v[48:49], v[34:35] op_sel_hi:[1,0] neg_lo:[0,1] neg_hi:[0,1]
	v_pk_add_f32 v[32:33], v[32:33], v[34:35] op_sel_hi:[1,0] neg_lo:[0,1] neg_hi:[0,1]
	v_add_f32_e32 v34, v62, v63
	v_pk_mul_f32 v[70:71], v[54:55], v[54:55]
	v_add_f32_e32 v34, v68, v34
	v_pk_fma_f32 v[70:71], v[38:39], v[38:39], v[70:71]
	v_add_f32_e32 v34, v69, v34
	v_pk_mul_f32 v[72:73], v[56:57], v[56:57]
	v_add_f32_e32 v34, v70, v34
	v_pk_fma_f32 v[72:73], v[40:41], v[40:41], v[72:73]
	v_add_f32_e32 v34, v71, v34
	v_pk_mul_f32 v[74:75], v[58:59], v[58:59]
	v_add_f32_e32 v34, v72, v34
	v_pk_fma_f32 v[74:75], v[42:43], v[42:43], v[74:75]
	v_add_f32_e32 v34, v73, v34
	v_pk_mul_f32 v[76:77], v[60:61], v[60:61]
	v_add_f32_e32 v34, v74, v34
	v_pk_fma_f32 v[76:77], v[44:45], v[44:45], v[76:77]
	v_add_f32_e32 v34, v75, v34
	v_pk_mul_f32 v[80:81], v[78:79], v[78:79]
	v_add_f32_e32 v34, v76, v34
	v_pk_fma_f32 v[80:81], v[46:47], v[46:47], v[80:81]
	v_add_f32_e32 v34, v77, v34
	v_pk_mul_f32 v[82:83], v[32:33], v[32:33]
	v_add_f32_e32 v34, v80, v34
	v_pk_fma_f32 v[82:83], v[48:49], v[48:49], v[82:83]
	v_add_f32_e32 v34, v81, v34
	v_add_f32_e32 v34, v82, v34
	v_add_f32_e32 v34, v83, v34
	ds_bpermute_b32 v62, v131, v34
	s_waitcnt lgkmcnt(0)
; __device__ __forceinline__ float siluf_(float x) { return x * sigmoidf_(x); }
; __device__ __forceinline__ unsigned pk2n(float lo, float hi) { return __builtin_bit_cast(unsigned, __builtin_convertvector((f32v2_t){lo, hi}, bf16v2_t)); }
; __device__ __forceinline__ void ph_ret_chunk(unsigned char* lds_, bf16_t* Z, const bf16_t* KVF, const bf16_t* KVB, const float* decay_logit, const float* gn_w, int with_ctx, int u0, int ustep, unsigned* kvc, unsigned* barw) { PH_IDS;
;     ...
;         const float rstd = rsqrtf(s2 * (1.f / 64) + EPS);
;         u32x2 wv[2][4];
; #pragma unroll
;         for (int g = 0; g < 4; ++g)
; #pragma unroll
;             for (int blk = 0; blk < 2; ++blk) {
;                 const int d = blk * 32 + 8 * g + 4 * hi;
;                 const u32x2 gt = gtv[2 * g + blk];
;                 const f32x4 gw = gwv[2 * g + blk];
;                 float y[4];
; #pragma unroll
;                 for (int q = 0; q < 4; ++q) { const float ov = blk ? o1[4 * g + q] : o0[4 * g + q]; const unsigned gb = q < 2 ? gt.x : gt.y; const float gv = __uint_as_float((q & 1) ? (gb & 0xffff0000u) : (gb << 16));
;                     y[q] = siluf_(gv) * ((ov - mu) * rstd * gw[q]); }
;                 wv[blk][g].x = pk2n(y[0], y[1]); wv[blk][g].y = pk2n(y[2], y[3]);
;             }
; #pragma unroll
;         for (int blk = 0; blk < 2; ++blk)
; #pragma unroll
;             for (int g = 0; g < 4; g += 2) {
;                 auto rx = __builtin_amdgcn_permlane32_swap(wv[blk][g].x, wv[blk][g + 1].x, false, false), ry = __builtin_amdgcn_permlane32_swap(wv[blk][g].y, wv[blk][g + 1].y, false, false);
;                 *(u32x4*)(zq + C_RQ + h * 64 + blk * 32 + 8 * g + 8 * hi) = (u32x4){(unsigned)rx[0], (unsigned)ry[0], (unsigned)rx[1], (unsigned)ry[1]};
;             }
	v_add_f32_e32 v34, v34, v62
	v_fmamk_f32 v34, v34, 0x3c800000, v207
	v_mul_f32_e32 v62, 0x4b800000, v34
	v_cmp_gt_f32_e64 s[4:5], s4, v34
	v_cndmask_b32_e64 v34, v34, v62, s[4:5]
	v_rsq_f32_e32 v62, v34
	v_rcp_f32_e32 v34, v66
	s_nop 0
	v_pk_mul_f32 v[34:35], v[34:35], v[64:65]
	v_mul_f32_e32 v63, 0x45800000, v62
	v_cndmask_b32_e64 v62, v62, v63, s[4:5]
	v_pk_mul_f32 v[2:3], v[2:3], v[62:63] op_sel_hi:[1,0]
	v_pk_mul_f32 v[4:5], v[4:5], v[62:63] op_sel_hi:[1,0]
	v_pk_mul_f32 v[2:3], v[122:123], v[2:3]
	v_pk_mul_f32 v[4:5], v[124:125], v[4:5]
	v_pk_mul_f32 v[2:3], v[34:35], v[2:3]
	v_pk_mul_f32 v[4:5], v[36:37], v[4:5]
	v_cvt_pk_bf16_f32 v2, v2, v3
	v_cvt_pk_bf16_f32 v3, v4, v5
	v_pk_mul_f32 v[4:5], v[18:19], v[62:63] op_sel_hi:[1,0]
	v_pk_mul_f32 v[18:19], v[20:21], v[62:63] op_sel_hi:[1,0]
	v_pk_mul_f32 v[4:5], v[118:119], v[4:5]
	v_pk_mul_f32 v[18:19], v[120:121], v[18:19]
	v_pk_mul_f32 v[4:5], v[50:51], v[4:5]
	v_pk_mul_f32 v[20:21], v[52:53], v[18:19]
	v_cvt_pk_bf16_f32 v18, v4, v5
	v_pk_mul_f32 v[4:5], v[38:39], v[62:63] op_sel_hi:[1,0]
	v_cvt_pk_bf16_f32 v19, v20, v21
	v_pk_mul_f32 v[4:5], v[114:115], v[4:5]
	s_nop 0
	v_pk_mul_f32 v[4:5], v[6:7], v[4:5]
	v_pk_mul_f32 v[6:7], v[40:41], v[62:63] op_sel_hi:[1,0]
	v_cvt_pk_bf16_f32 v4, v4, v5
	v_pk_mul_f32 v[6:7], v[116:117], v[6:7]
	s_nop 0
	v_permlane32_swap_b32_e32 v2, v4
	v_pk_mul_f32 v[6:7], v[8:9], v[6:7]
	v_pk_mul_f32 v[8:9], v[56:57], v[62:63] op_sel_hi:[1,0]
	v_cvt_pk_bf16_f32 v5, v6, v7
	v_pk_mul_f32 v[6:7], v[54:55], v[62:63] op_sel_hi:[1,0]
	v_pk_mul_f32 v[8:9], v[112:113], v[8:9]
	v_pk_mul_f32 v[6:7], v[110:111], v[6:7]
	v_pk_mul_f32 v[8:9], v[24:25], v[8:9]
	v_pk_mul_f32 v[6:7], v[22:23], v[6:7]
	v_cvt_pk_bf16_f32 v21, v8, v9
	v_cvt_pk_bf16_f32 v20, v6, v7
	v_pk_mul_f32 v[6:7], v[42:43], v[62:63] op_sel_hi:[1,0]
	v_pk_mul_f32 v[8:9], v[44:45], v[62:63] op_sel_hi:[1,0]
	v_pk_mul_f32 v[6:7], v[106:107], v[6:7]
	v_pk_mul_f32 v[8:9], v[108:109], v[8:9]
	v_pk_mul_f32 v[6:7], v[10:11], v[6:7]
	v_pk_mul_f32 v[8:9], v[12:13], v[8:9]
	v_cvt_pk_bf16_f32 v6, v6, v7
	v_cvt_pk_bf16_f32 v7, v8, v9
	v_pk_mul_f32 v[8:9], v[58:59], v[62:63] op_sel_hi:[1,0]
	v_pk_mul_f32 v[10:11], v[60:61], v[62:63] op_sel_hi:[1,0]
	s_waitcnt vmcnt(1)
	v_pk_mul_f32 v[8:9], v[102:103], v[8:9]
	v_pk_mul_f32 v[10:11], v[104:105], v[10:11]
	v_pk_mul_f32 v[8:9], v[26:27], v[8:9]
	v_pk_mul_f32 v[12:13], v[28:29], v[10:11]
	v_cvt_pk_bf16_f32 v10, v8, v9
	v_pk_mul_f32 v[8:9], v[46:47], v[62:63] op_sel_hi:[1,0]
	v_cvt_pk_bf16_f32 v11, v12, v13
	v_pk_mul_f32 v[8:9], v[98:99], v[8:9]
	v_pk_mul_f32 v[12:13], v[48:49], v[62:63] op_sel_hi:[1,0]
	v_pk_mul_f32 v[8:9], v[14:15], v[8:9]
	v_lshlrev_b32_e32 v14, 16, v143
	v_and_b32_e32 v15, 0xffff0000, v143
	v_mul_f32_e32 v22, 0xbfb8aa3b, v14
	v_mul_f32_e32 v23, 0xbfb8aa3b, v15
	v_exp_f32_e32 v22, v22
	v_exp_f32_e32 v23, v23
	v_pk_mul_f32 v[12:13], v[100:101], v[12:13]
	v_cvt_pk_bf16_f32 v8, v8, v9
	v_pk_mul_f32 v[12:13], v[16:17], v[12:13]
	v_pk_mul_f32 v[16:17], v[78:79], v[62:63] op_sel_hi:[1,0]
	v_cvt_pk_bf16_f32 v9, v12, v13
	v_pk_add_f32 v[12:13], v[22:23], 1.0 op_sel_hi:[1,0]
	s_waitcnt vmcnt(0)
	v_pk_mul_f32 v[16:17], v[94:95], v[16:17]
	v_pk_mul_f32 v[16:17], v[30:31], v[16:17]
	v_permlane32_swap_b32_e32 v3, v5
	v_rcp_f32_e32 v13, v13
	v_permlane32_swap_b32_e32 v6, v8
	v_rcp_f32_e32 v12, v12
	s_nop 0
	v_pk_mul_f32 v[12:13], v[12:13], v[14:15]
	v_pk_mul_f32 v[14:15], v[32:33], v[62:63] op_sel_hi:[1,0]
	v_permlane32_swap_b32_e32 v7, v9
	v_pk_mul_f32 v[14:15], v[96:97], v[14:15]
	v_permlane32_swap_b32_e32 v18, v20
	v_pk_mul_f32 v[14:15], v[12:13], v[14:15]
	v_cvt_pk_bf16_f32 v12, v16, v17
	v_cvt_pk_bf16_f32 v13, v14, v15
	v_permlane32_swap_b32_e32 v19, v21
	v_permlane32_swap_b32_e32 v10, v12
	v_permlane32_swap_b32_e32 v11, v13
	global_store_dwordx4 v[140:141], v[2:5], off offset:2880
	global_store_dwordx4 v[140:141], v[6:9], off offset:2912
	global_store_dwordx4 v[140:141], v[18:21], off offset:2944
	global_store_dwordx4 v[140:141], v[10:13], off offset:2976
	s_barrier
	s_mov_b64 s[4:5], 0

; #define LAS __attribute__((address_space(3)))
; __device__ __forceinline__ void ret_tile_gen(const LAS char* sm, int r32, int hi, int vrd, int buf, int kp0, int qpos, float lgf, float lgb, const bf16x8 (&qf)[4], fa::f32x16& o0, fa::f32x16& o1) {
;     using namespace fa;
;     const LAS char* kb = sm + buf + r32 * KP_R + 16 * hi;
;     f32x16 p0, p1;
; #pragma unroll
;     for (int r = 0; r < 16; ++r) { p0[r] = 0.f; p1[r] = 0.f; }
; #pragma unroll
;     for (int st = 0; st < 4; ++st) {
;         const bf16x8 k0 = *(const LAS bf16x8*)(kb + 32 * st), k1 = *(const LAS bf16x8*)(kb + 32 * KP_R + 32 * st);
;         p0 = __builtin_amdgcn_mfma_f32_32x32x16_bf16(k0, qf[st], p0, 0, 0, 0);
;         p1 = __builtin_amdgcn_mfma_f32_32x32x16_bf16(k1, qf[st], p1, 0, 0, 0);
;     }
;     int d0 = qpos - kp0 - 4 * hi;
;     asm volatile("" : "+v"(d0) : "v"(p0[15]), "v"(p1[15]));
; #pragma unroll
;     for (int r = 0; r < 16; ++r) {
;         const float f0 = (float)(d0 - ((r & 3) + 8 * (r >> 2))), f1 = f0 - 32.f;
;         const float w0 = __builtin_amdgcn_exp2f(lgf * fmaxf(f0, 0.f) + lgb * fmaxf(-f0, 0.f)) * (2.f - fminf(fabsf(f0), 1.f));
;         const float w1 = __builtin_amdgcn_exp2f(lgf * fmaxf(f1, 0.f) + lgb * fmaxf(-f1, 0.f)) * (2.f - fminf(fabsf(f1), 1.f));
;         p0[r] *= w0; p1[r] *= w1;
;     }
;     bf16x8 pf[4]; pf[0] = pack_p(p0, 0); pf[1] = pack_p(p0, 8); pf[2] = pack_p(p1, 0); pf[3] = pack_p(p1, 8);
;     pv_tile(o0, o1, sm + buf + vrd, pf);
; __device__ __forceinline__ void ph_ret_chunk(unsigned char* lds_, bf16_t* Z, const bf16_t* KVF, const bf16_t* KVB, const float* decay_logit, const float* gn_w, int with_ctx, int u0, int ustep, unsigned* kvc, unsigned* barw) { PH_IDS;
;     ...
;                 ST_PUT(1); ST_PUTB(2);
;     ...
;             } else {
;                 ST_PUT(0); ST_PUT(3);
;                 ST_STEP(kf, 0, g128f); ST_PUT(1);
;                 sa = (f32x4){0.f, 0.f, 0.f, 0.f}; sb = sa; ST_STEP(kb, 1, g128b); ST_PUT(2);
;             }
;     ...
;         }
;         __syncthreads();
;         u32x2 gtv[8]; f32x4 gwv[8];
; #pragma unroll
;         for (int g = 0; g < 4; ++g)
; #pragma unroll
;             for (int blk = 0; blk < 2; ++blk) { const int d = blk * 32 + 8 * g + 4 * hi; gtv[2 * g + blk] = *(const u32x2*)(zq + C_RG + h * 64 + d); gwv[2 * g + blk] = *(const f32x4*)(gn_w + h * 64 + d); }
.LBB0_1240:
	s_ashr_i32 s5, s39, 8
	s_mul_i32 s4, s5, 0x8800
	v_mul_u32_u24_e32 v70, 0x90, v79
	s_add_i32 s8, s4, 0
	s_waitcnt vmcnt(0)
	v_cvt_pk_bf16_f32 v2, v90, v91
	v_cvt_pk_bf16_f32 v3, v88, v89
	v_cvt_pk_bf16_f32 v4, v106, v107
	v_cvt_pk_bf16_f32 v5, v92, v93
	ds_write_b128 v124, v[2:5] offset:9216
	v_cvt_pk_bf16_f32 v2, v110, v111
	v_cvt_pk_bf16_f32 v3, v108, v109
	v_cvt_pk_bf16_f32 v4, v114, v115
	v_cvt_pk_bf16_f32 v5, v112, v113
	v_add3_u32 v72, s8, v70, v78
	ds_write_b128 v124, v[2:5] offset:18432
	s_waitcnt lgkmcnt(0)
	s_barrier
	ds_read_b128 v[2:5], v72
	ds_read_b128 v[34:37], v72 offset:32
	ds_read_b128 v[18:21], v72 offset:4608
	ds_read_b128 v[38:41], v72 offset:4640
	s_waitcnt lgkmcnt(3)
	v_mfma_f32_32x32x16_bf16 v[2:17], v[2:5], v[66:69], 0
	s_lshl_b32 s4, s5, 7
	s_mulk_i32 s5, 0x2400
	s_add_i32 s5, s5, 0
	s_add_i32 s7, s5, 0x11000
	s_add_i32 s5, s5, 0x15800
	s_lshl_b32 s6, s42, 2
	s_add_u32 s10, s20, s6
	s_waitcnt lgkmcnt(1)
	v_mfma_f32_32x32x16_bf16 v[18:33], v[18:21], v[66:69], 0
	s_addc_u32 s11, s21, 0
	v_mul_i32_i24_e32 v51, -4, v122
	s_add_i32 s6, s4, s38
	v_lshlrev_b32_e32 v48, 8, v122
	v_lshlrev_b32_e32 v50, 1, v123
	v_and_b32_e32 v49, 0xc0, v83
	v_mfma_f32_32x32x16_bf16 v[2:17], v[34:37], v[102:105], v[2:17]
	ds_read_b128 v[34:37], v72 offset:64
	s_waitcnt lgkmcnt(1)
	v_mfma_f32_32x32x16_bf16 v[18:33], v[38:41], v[102:105], v[18:33]
	ds_read_b128 v[38:41], v72 offset:4672
	ds_read_b128 v[42:45], v72 offset:96
	global_load_dwordx4 v[136:139], v78, s[10:11]
	global_load_dwordx4 v[126:129], v78, s[10:11] offset:32
	s_waitcnt lgkmcnt(2)
	v_mfma_f32_32x32x16_bf16 v[2:17], v[34:37], v[98:101], v[2:17]
	v_lshlrev_b32_e32 v34, 3, v122
	v_mov_b32_e32 v35, v130
	v_lshl_add_u64 v[46:47], v[80:81], 0, v[34:35]
	ds_read_b128 v[34:37], v72 offset:4704
	global_load_dwordx4 v[132:135], v78, s[10:11] offset:128
	global_load_dwordx4 v[122:125], v78, s[10:11] offset:160
	global_load_dwordx2 v[146:147], v[46:47], off offset:3392
	global_load_dwordx2 v[150:151], v[46:47], off offset:3408
	global_load_dwordx2 v[154:155], v[46:47], off offset:3424
	global_load_dwordx2 v[158:159], v[46:47], off offset:3440
	global_load_dwordx4 v[118:121], v78, s[10:11] offset:64
	global_load_dwordx4 v[110:113], v78, s[10:11] offset:96
	global_load_dwordx2 v[148:149], v[46:47], off offset:3456
	global_load_dwordx2 v[152:153], v[46:47], off offset:3472
	global_load_dwordx2 v[156:157], v[46:47], off offset:3488
	global_load_dwordx2 v[144:145], v[46:47], off offset:3504
	global_load_dwordx4 v[114:117], v78, s[10:11] offset:192
	global_load_dwordx4 v[106:109], v78, s[10:11] offset:224
	s_waitcnt lgkmcnt(2)
	v_mfma_f32_32x32x16_bf16 v[18:33], v[38:41], v[98:101], v[18:33]
	s_waitcnt lgkmcnt(0)
	v_mfma_f32_32x32x16_bf16 v[18:33], v[34:37], v[94:97], v[18:33]
	v_subrev_u32_e32 v34, s6, v51
	v_add_u32_e32 v73, v34, v131
	v_mov_b32_e32 v36, v73
	v_and_b32_e32 v34, 24, v82
	v_and_or_b32 v34, v50, 32, v34
	v_or3_b32 v46, v48, v49, v34
	v_add_u32_e32 v71, s8, v46
	v_mfma_f32_32x32x16_bf16 v[2:17], v[42:45], v[94:97], v[2:17]
	s_nop 0
	v_cvt_f32_i32_e32 v37, v36
	v_max_f32_e32 v34, 0, v37
	v_max_f32_e64 v35, -v37, 0
	v_pk_mul_f32 v[34:35], v[142:143], v[34:35]
	v_add_f32_e32 v38, 0xc2000000, v37
	v_add_f32_e32 v34, v34, v35
	v_exp_f32_e32 v34, v34
	v_min_f32_e64 v35, |v37|, 1.0
	v_sub_f32_e32 v35, 2.0, v35
	v_mul_f32_e32 v37, v35, v34
	v_max_f32_e32 v34, 0, v38
	v_max_f32_e64 v35, -v38, 0
	v_pk_mul_f32 v[34:35], v[142:143], v[34:35]
	v_mul_f32_e32 v37, v2, v37
	v_add_f32_e32 v34, v34, v35
	v_exp_f32_e32 v34, v34
	v_min_f32_e64 v35, |v38|, 1.0
	v_add_u32_e32 v38, -1, v36
	v_cvt_f32_i32_e32 v38, v38
	v_sub_f32_e32 v35, 2.0, v35
	v_mul_f32_e32 v34, v35, v34
	v_mul_f32_e32 v39, v18, v34
	v_max_f32_e32 v34, 0, v38
	v_max_f32_e64 v35, -v38, 0
	v_pk_mul_f32 v[34:35], v[142:143], v[34:35]
	v_add_f32_e32 v18, 0xc2000000, v38
	v_add_f32_e32 v2, v34, v35
	v_exp_f32_e32 v2, v2
	v_min_f32_e64 v34, |v38|, 1.0
	v_sub_f32_e32 v34, 2.0, v34
	v_max_f32_e64 v35, -v18, 0
	v_mul_f32_e32 v2, v34, v2
	v_max_f32_e32 v34, 0, v18
	v_pk_mul_f32 v[34:35], v[142:143], v[34:35]
	v_min_f32_e64 v18, |v18|, 1.0
	v_add_f32_e32 v34, v34, v35
	v_add_u32_e32 v35, -2, v36
	v_exp_f32_e32 v34, v34
	v_cvt_f32_i32_e32 v35, v35
	v_sub_f32_e32 v18, 2.0, v18
	v_mul_f32_e32 v18, v18, v34
	v_mul_f32_e32 v34, v3, v2
	v_max_f32_e32 v2, 0, v35
	v_max_f32_e64 v3, -v35, 0
	v_pk_mul_f32 v[2:3], v[142:143], v[2:3]
	v_mul_f32_e32 v38, v19, v18
	v_add_f32_e32 v2, v2, v3
	v_exp_f32_e32 v2, v2
	v_min_f32_e64 v3, |v35|, 1.0
	v_add_f32_e32 v18, 0xc2000000, v35
	v_sub_f32_e32 v3, 2.0, v3
	v_mul_f32_e32 v19, v3, v2
	v_max_f32_e32 v2, 0, v18
	v_max_f32_e64 v3, -v18, 0
	v_pk_mul_f32 v[2:3], v[142:143], v[2:3]
	v_mul_f32_e32 v4, v4, v19
	v_add_f32_e32 v2, v2, v3
	v_exp_f32_e32 v2, v2
	v_min_f32_e64 v3, |v18|, 1.0
	v_add_u32_e32 v18, -3, v36
	v_cvt_f32_i32_e32 v18, v18
	v_sub_f32_e32 v3, 2.0, v3
	v_mul_f32_e32 v2, v3, v2
	v_mul_f32_e32 v40, v20, v2
	v_max_f32_e32 v2, 0, v18
	v_max_f32_e64 v3, -v18, 0
	v_pk_mul_f32 v[2:3], v[142:143], v[2:3]
	v_add_f32_e32 v19, 0xc2000000, v18
	v_add_f32_e32 v2, v2, v3
	v_exp_f32_e32 v2, v2
	v_min_f32_e64 v3, |v18|, 1.0
	v_sub_f32_e32 v3, 2.0, v3
	v_mul_f32_e32 v18, v3, v2
	v_max_f32_e32 v2, 0, v19
	v_max_f32_e64 v3, -v19, 0
	v_pk_mul_f32 v[2:3], v[142:143], v[2:3]
	v_mul_f32_e32 v5, v5, v18
	v_add_f32_e32 v2, v2, v3
	v_exp_f32_e32 v2, v2
	v_min_f32_e64 v3, |v19|, 1.0
	v_add_u32_e32 v19, -8, v36
	v_cvt_f32_i32_e32 v19, v19
	v_sub_f32_e32 v3, 2.0, v3
	v_mul_f32_e32 v2, v3, v2
	v_mul_f32_e32 v41, v21, v2
	v_max_f32_e32 v2, 0, v19
	v_max_f32_e64 v3, -v19, 0
	v_pk_mul_f32 v[2:3], v[142:143], v[2:3]
; __device__ __forceinline__ void ret_tile_gen(const LAS char* sm, int r32, int hi, int vrd, int buf, int kp0, int qpos, float lgf, float lgb, const bf16x8 (&qf)[4], fa::f32x16& o0, fa::f32x16& o1) {
;     ...
;     int d0 = qpos - kp0 - 4 * hi;
;     asm volatile("" : "+v"(d0) : "v"(p0[15]), "v"(p1[15]));
; #pragma unroll
;     for (int r = 0; r < 16; ++r) {
;         const float f0 = (float)(d0 - ((r & 3) + 8 * (r >> 2))), f1 = f0 - 32.f;
;         const float w0 = __builtin_amdgcn_exp2f(lgf * fmaxf(f0, 0.f) + lgb * fmaxf(-f0, 0.f)) * (2.f - fminf(fabsf(f0), 1.f));
;         const float w1 = __builtin_amdgcn_exp2f(lgf * fmaxf(f1, 0.f) + lgb * fmaxf(-f1, 0.f)) * (2.f - fminf(fabsf(f1), 1.f));
;         p0[r] *= w0; p1[r] *= w1;
;     }
	v_add_f32_e32 v18, 0xc2000000, v19
	v_add_f32_e32 v2, v2, v3
	v_exp_f32_e32 v2, v2
	v_min_f32_e64 v3, |v19|, 1.0
	v_sub_f32_e32 v3, 2.0, v3
	v_mul_f32_e32 v19, v3, v2
	v_max_f32_e32 v2, 0, v18
	v_max_f32_e64 v3, -v18, 0
	v_pk_mul_f32 v[2:3], v[142:143], v[2:3]
	v_mul_f32_e32 v6, v6, v19
	v_add_f32_e32 v2, v2, v3
	v_exp_f32_e32 v2, v2
	v_min_f32_e64 v3, |v18|, 1.0
	v_add_u32_e32 v18, -9, v36
	v_cvt_f32_i32_e32 v18, v18
	v_sub_f32_e32 v3, 2.0, v3
	v_mul_f32_e32 v2, v3, v2
	v_mul_f32_e32 v22, v22, v2
	v_max_f32_e32 v2, 0, v18
	v_max_f32_e64 v3, -v18, 0
	v_pk_mul_f32 v[2:3], v[142:143], v[2:3]
	v_add_f32_e32 v19, 0xc2000000, v18
	v_add_f32_e32 v2, v2, v3
	v_exp_f32_e32 v2, v2
	v_min_f32_e64 v3, |v18|, 1.0
	v_sub_f32_e32 v3, 2.0, v3
	v_mul_f32_e32 v18, v3, v2
	v_max_f32_e32 v2, 0, v19
	v_max_f32_e64 v3, -v19, 0
	v_pk_mul_f32 v[2:3], v[142:143], v[2:3]
	v_mul_f32_e32 v7, v7, v18
	v_add_f32_e32 v2, v2, v3
	v_exp_f32_e32 v2, v2
	v_min_f32_e64 v3, |v19|, 1.0
	v_add_u32_e32 v19, -10, v36
	v_cvt_f32_i32_e32 v19, v19
	v_sub_f32_e32 v3, 2.0, v3
	v_mul_f32_e32 v2, v3, v2
	v_mul_f32_e32 v23, v23, v2
	v_max_f32_e32 v2, 0, v19
	v_max_f32_e64 v3, -v19, 0
	v_pk_mul_f32 v[2:3], v[142:143], v[2:3]
	v_add_f32_e32 v18, 0xc2000000, v19
	v_add_f32_e32 v2, v2, v3
	v_exp_f32_e32 v2, v2
	v_min_f32_e64 v3, |v19|, 1.0
	v_sub_f32_e32 v3, 2.0, v3
	v_mul_f32_e32 v19, v3, v2
	v_max_f32_e32 v2, 0, v18
	v_max_f32_e64 v3, -v18, 0
	v_pk_mul_f32 v[2:3], v[142:143], v[2:3]
	v_mul_f32_e32 v8, v8, v19
	v_add_f32_e32 v2, v2, v3
	v_exp_f32_e32 v2, v2
	v_min_f32_e64 v3, |v18|, 1.0
	v_add_u32_e32 v18, -11, v36
	v_cvt_f32_i32_e32 v18, v18
	v_sub_f32_e32 v3, 2.0, v3
	v_mul_f32_e32 v2, v3, v2
	v_mul_f32_e32 v24, v24, v2
	v_max_f32_e32 v2, 0, v18
	v_max_f32_e64 v3, -v18, 0
	v_pk_mul_f32 v[2:3], v[142:143], v[2:3]
	v_add_f32_e32 v19, 0xc2000000, v18
	v_add_f32_e32 v2, v2, v3
	v_exp_f32_e32 v2, v2
	v_min_f32_e64 v3, |v18|, 1.0
	v_sub_f32_e32 v3, 2.0, v3
	v_mul_f32_e32 v18, v3, v2
	v_max_f32_e32 v2, 0, v19
	v_max_f32_e64 v3, -v19, 0
	v_pk_mul_f32 v[2:3], v[142:143], v[2:3]
	v_mul_f32_e32 v9, v9, v18
	v_add_f32_e32 v2, v2, v3
	v_exp_f32_e32 v2, v2
	v_min_f32_e64 v3, |v19|, 1.0
	v_add_u32_e32 v19, -16, v36
	v_cvt_f32_i32_e32 v19, v19
	v_sub_f32_e32 v3, 2.0, v3
	v_mul_f32_e32 v2, v3, v2
	v_mul_f32_e32 v25, v25, v2
	v_max_f32_e32 v2, 0, v19
	v_max_f32_e64 v3, -v19, 0
	v_pk_mul_f32 v[2:3], v[142:143], v[2:3]
	v_add_f32_e32 v18, 0xc2000000, v19
	v_add_f32_e32 v2, v2, v3
	v_exp_f32_e32 v2, v2
	v_min_f32_e64 v3, |v19|, 1.0
	v_sub_f32_e32 v3, 2.0, v3
	v_mul_f32_e32 v19, v3, v2
	v_max_f32_e32 v2, 0, v18
	v_max_f32_e64 v3, -v18, 0
	v_pk_mul_f32 v[2:3], v[142:143], v[2:3]
	v_mul_f32_e32 v10, v10, v19
	v_add_f32_e32 v2, v2, v3
	v_exp_f32_e32 v2, v2
	v_min_f32_e64 v3, |v18|, 1.0
	v_subrev_u32_e32 v18, 17, v36
	v_cvt_f32_i32_e32 v18, v18
	v_sub_f32_e32 v3, 2.0, v3
	v_mul_f32_e32 v2, v3, v2
	v_mul_f32_e32 v26, v26, v2
	v_max_f32_e32 v2, 0, v18
	v_max_f32_e64 v3, -v18, 0
	v_pk_mul_f32 v[2:3], v[142:143], v[2:3]
	v_add_f32_e32 v19, 0xc2000000, v18
	v_add_f32_e32 v2, v2, v3
	v_exp_f32_e32 v2, v2
	v_min_f32_e64 v3, |v18|, 1.0
	v_sub_f32_e32 v3, 2.0, v3
	v_mul_f32_e32 v18, v3, v2
	v_max_f32_e32 v2, 0, v19
	v_max_f32_e64 v3, -v19, 0
	v_pk_mul_f32 v[2:3], v[142:143], v[2:3]
	v_mul_f32_e32 v11, v11, v18
	v_add_f32_e32 v2, v2, v3
	v_exp_f32_e32 v2, v2
	v_min_f32_e64 v3, |v19|, 1.0
	v_subrev_u32_e32 v19, 18, v36
	v_cvt_f32_i32_e32 v19, v19
	v_sub_f32_e32 v3, 2.0, v3
	v_mul_f32_e32 v2, v3, v2
	v_mul_f32_e32 v27, v27, v2
	v_max_f32_e32 v2, 0, v19
	v_max_f32_e64 v3, -v19, 0
	v_pk_mul_f32 v[2:3], v[142:143], v[2:3]
	v_add_f32_e32 v18, 0xc2000000, v19
	v_add_f32_e32 v2, v2, v3
	v_exp_f32_e32 v2, v2
	v_min_f32_e64 v3, |v19|, 1.0
	v_sub_f32_e32 v3, 2.0, v3
	v_mul_f32_e32 v19, v3, v2
	v_max_f32_e32 v2, 0, v18
	v_max_f32_e64 v3, -v18, 0
	v_pk_mul_f32 v[2:3], v[142:143], v[2:3]
	v_mul_f32_e32 v12, v12, v19
	v_add_f32_e32 v2, v2, v3
	v_exp_f32_e32 v2, v2
	v_min_f32_e64 v3, |v18|, 1.0
	v_subrev_u32_e32 v18, 19, v36
	v_cvt_f32_i32_e32 v18, v18
	v_sub_f32_e32 v3, 2.0, v3
	v_mul_f32_e32 v2, v3, v2
	v_mul_f32_e32 v28, v28, v2
	v_max_f32_e32 v2, 0, v18
	v_max_f32_e64 v3, -v18, 0
	v_pk_mul_f32 v[2:3], v[142:143], v[2:3]
	v_add_f32_e32 v19, 0xc2000000, v18
	v_add_f32_e32 v2, v2, v3
	v_exp_f32_e32 v2, v2
	v_min_f32_e64 v3, |v18|, 1.0
	v_sub_f32_e32 v3, 2.0, v3
	v_mul_f32_e32 v18, v3, v2
	v_max_f32_e32 v2, 0, v19
	v_max_f32_e64 v3, -v19, 0
	v_pk_mul_f32 v[2:3], v[142:143], v[2:3]
	v_mul_f32_e32 v13, v13, v18
	v_add_f32_e32 v2, v2, v3
	v_exp_f32_e32 v2, v2
	v_min_f32_e64 v3, |v19|, 1.0
	v_subrev_u32_e32 v19, 24, v36
	v_cvt_f32_i32_e32 v19, v19
	v_sub_f32_e32 v3, 2.0, v3
	v_mul_f32_e32 v2, v3, v2
	v_mul_f32_e32 v29, v29, v2
	v_max_f32_e32 v2, 0, v19
	v_max_f32_e64 v3, -v19, 0
	v_pk_mul_f32 v[2:3], v[142:143], v[2:3]
	v_add_f32_e32 v18, 0xc2000000, v19
	v_add_f32_e32 v2, v2, v3
	v_exp_f32_e32 v2, v2
	v_min_f32_e64 v3, |v19|, 1.0
	v_sub_f32_e32 v3, 2.0, v3
	v_mul_f32_e32 v19, v3, v2
	v_max_f32_e32 v2, 0, v18
	v_max_f32_e64 v3, -v18, 0
	v_pk_mul_f32 v[2:3], v[142:143], v[2:3]
	v_mul_f32_e32 v14, v14, v19
	v_add_f32_e32 v2, v2, v3
	v_exp_f32_e32 v2, v2
	v_min_f32_e64 v3, |v18|, 1.0
	v_subrev_u32_e32 v18, 25, v36
	v_cvt_f32_i32_e32 v18, v18
	v_sub_f32_e32 v3, 2.0, v3
	v_mul_f32_e32 v2, v3, v2
	v_mul_f32_e32 v30, v30, v2
	v_max_f32_e32 v2, 0, v18
	v_max_f32_e64 v3, -v18, 0
	v_pk_mul_f32 v[2:3], v[142:143], v[2:3]
	v_add_f32_e32 v19, 0xc2000000, v18
	v_add_f32_e32 v2, v2, v3
	v_exp_f32_e32 v2, v2
	v_min_f32_e64 v3, |v18|, 1.0
	v_sub_f32_e32 v3, 2.0, v3
	v_mul_f32_e32 v18, v3, v2
	v_max_f32_e32 v2, 0, v19
	v_max_f32_e64 v3, -v19, 0
; __device__ __forceinline__ bf16x8 pack_p(const f32x16& p, int base) { u32x4 w; w.x = pk2(p[base], p[base + 1]); w.y = pk2(p[base + 2], p[base + 3]); w.z = pk2(p[base + 4], p[base + 5]); w.w = pk2(p[base + 6], p[base + 7]); return __builtin_bit_cast(bf16x8, w); }
; __device__ __forceinline__ void ret_tile_gen(const LAS char* sm, int r32, int hi, int vrd, int buf, int kp0, int qpos, float lgf, float lgb, const bf16x8 (&qf)[4], fa::f32x16& o0, fa::f32x16& o1) {
;     ...
;     int d0 = qpos - kp0 - 4 * hi;
;     asm volatile("" : "+v"(d0) : "v"(p0[15]), "v"(p1[15]));
; #pragma unroll
;     for (int r = 0; r < 16; ++r) {
;         const float f0 = (float)(d0 - ((r & 3) + 8 * (r >> 2))), f1 = f0 - 32.f;
;         const float w0 = __builtin_amdgcn_exp2f(lgf * fmaxf(f0, 0.f) + lgb * fmaxf(-f0, 0.f)) * (2.f - fminf(fabsf(f0), 1.f));
;         const float w1 = __builtin_amdgcn_exp2f(lgf * fmaxf(f1, 0.f) + lgb * fmaxf(-f1, 0.f)) * (2.f - fminf(fabsf(f1), 1.f));
;         p0[r] *= w0; p1[r] *= w1;
;     }
;     bf16x8 pf[4]; pf[0] = pack_p(p0, 0); pf[1] = pack_p(p0, 8); pf[2] = pack_p(p1, 0); pf[3] = pack_p(p1, 8);
;     pv_tile(o0, o1, sm + buf + vrd, pf);
	v_pk_mul_f32 v[2:3], v[142:143], v[2:3]
	v_mul_f32_e32 v15, v15, v18
	v_add_f32_e32 v2, v2, v3
	v_exp_f32_e32 v2, v2
	v_min_f32_e64 v3, |v19|, 1.0
	v_subrev_u32_e32 v19, 26, v36
	v_cvt_f32_i32_e32 v19, v19
	v_sub_f32_e32 v3, 2.0, v3
	v_mul_f32_e32 v2, v3, v2
	v_mul_f32_e32 v31, v31, v2
	v_max_f32_e32 v2, 0, v19
	v_max_f32_e64 v3, -v19, 0
	v_pk_mul_f32 v[2:3], v[142:143], v[2:3]
	v_add_f32_e32 v18, 0xc2000000, v19
	v_add_f32_e32 v2, v2, v3
	v_exp_f32_e32 v2, v2
	v_min_f32_e64 v3, |v19|, 1.0
	v_sub_f32_e32 v3, 2.0, v3
	v_mul_f32_e32 v19, v3, v2
	v_max_f32_e32 v2, 0, v18
	v_max_f32_e64 v3, -v18, 0
	v_pk_mul_f32 v[2:3], v[142:143], v[2:3]
	v_mul_f32_e32 v16, v16, v19
	v_add_f32_e32 v2, v2, v3
	v_exp_f32_e32 v2, v2
	v_min_f32_e64 v3, |v18|, 1.0
	v_subrev_u32_e32 v18, 27, v36
	v_cvt_f32_i32_e32 v18, v18
	v_sub_f32_e32 v3, 2.0, v3
	v_mul_f32_e32 v2, v3, v2
	v_mul_f32_e32 v32, v32, v2
	v_max_f32_e32 v2, 0, v18
	v_max_f32_e64 v3, -v18, 0
	v_pk_mul_f32 v[2:3], v[142:143], v[2:3]
	v_add_f32_e32 v19, 0xc2000000, v18
	v_add_f32_e32 v2, v2, v3
	v_exp_f32_e32 v20, v2
	v_min_f32_e64 v2, |v18|, 1.0
	v_sub_f32_e32 v18, 2.0, v2
	v_max_f32_e32 v2, 0, v19
	v_max_f32_e64 v3, -v19, 0
	v_pk_mul_f32 v[2:3], v[142:143], v[2:3]
	s_nop 0
	v_add_f32_e32 v2, v2, v3
	v_exp_f32_e32 v2, v2
	v_mul_f32_e32 v3, v18, v20
	v_min_f32_e64 v18, |v19|, 1.0
	v_sub_f32_e32 v18, 2.0, v18
	v_mul_f32_e32 v2, v18, v2
	v_mul_f32_e32 v3, v17, v3
	v_mul_f32_e32 v2, v33, v2
	v_cvt_pk_bf16_f32 v18, v37, v34
	v_cvt_pk_bf16_f32 v19, v4, v5
	v_cvt_pk_bf16_f32 v20, v6, v7
	v_cvt_pk_bf16_f32 v21, v8, v9
	v_cvt_pk_bf16_f32 v34, v10, v11
	v_cvt_pk_bf16_f32 v35, v12, v13
	v_cvt_pk_bf16_f32 v36, v14, v15
	v_cvt_pk_bf16_f32 v37, v16, v3
	v_cvt_pk_bf16_f32 v38, v39, v38
	v_cvt_pk_bf16_f32 v39, v40, v41
	v_cvt_pk_bf16_f32 v40, v22, v23
	v_cvt_pk_bf16_f32 v41, v24, v25
	v_cvt_pk_bf16_f32 v42, v26, v27
	v_cvt_pk_bf16_f32 v43, v28, v29
	v_cvt_pk_bf16_f32 v44, v30, v31
	v_cvt_pk_bf16_f32 v45, v32, v2
	ds_read_b64_tr_b16 v[2:3], v71 offset:9216
	ds_read_b64_tr_b16 v[4:5], v71 offset:9728
	ds_read_b64_tr_b16 v[46:47], v71 offset:10240
	ds_read_b64_tr_b16 v[48:49], v71 offset:10752
	s_waitcnt lgkmcnt(2)
	v_mfma_f32_32x32x16_bf16 v[2:17], v[2:5], v[18:21], 0
	ds_read_b64_tr_b16 v[22:23], v71 offset:13312
	ds_read_b64_tr_b16 v[24:25], v71 offset:13824
	ds_read_b64_tr_b16 v[50:51], v71 offset:14336
	ds_read_b64_tr_b16 v[52:53], v71 offset:14848
	s_waitcnt lgkmcnt(2)
	v_mfma_f32_32x32x16_bf16 v[18:33], v[22:25], v[18:21], 0
	v_mfma_f32_32x32x16_bf16 v[2:17], v[46:49], v[34:37], v[2:17]
	s_waitcnt lgkmcnt(0)
	v_mfma_f32_32x32x16_bf16 v[18:33], v[50:53], v[34:37], v[18:33]
	ds_read_b64_tr_b16 v[34:35], v71 offset:11264
	ds_read_b64_tr_b16 v[36:37], v71 offset:11776
	ds_read_b64_tr_b16 v[46:47], v71 offset:12288
	ds_read_b64_tr_b16 v[48:49], v71 offset:12800
	s_waitcnt lgkmcnt(2)
	v_mfma_f32_32x32x16_bf16 v[2:17], v[34:37], v[38:41], v[2:17]
	ds_read_b64_tr_b16 v[34:35], v71 offset:15360
	ds_read_b64_tr_b16 v[36:37], v71 offset:15872
	ds_read_b64_tr_b16 v[50:51], v71 offset:16384
	ds_read_b64_tr_b16 v[52:53], v71 offset:16896
	s_waitcnt lgkmcnt(2)
	v_mfma_f32_32x32x16_bf16 v[18:33], v[34:37], v[38:41], v[18:33]
	v_mfma_f32_32x32x16_bf16 v[2:17], v[46:49], v[42:45], v[2:17]
	s_waitcnt lgkmcnt(0)
	v_mfma_f32_32x32x16_bf16 v[18:33], v[50:53], v[42:45], v[18:33]
	ds_read_b128 v[34:37], v72 offset:17408
	ds_read_b128 v[74:77], v72 offset:17440
	ds_read_b128 v[50:53], v72 offset:22016
	ds_read_b128 v[80:83], v72 offset:22048
	s_waitcnt lgkmcnt(3)
	v_mfma_f32_32x32x16_bf16 v[34:49], v[34:37], v[66:69], 0
	s_waitcnt lgkmcnt(1)
	v_mfma_f32_32x32x16_bf16 v[50:65], v[50:53], v[66:69], 0
	v_mfma_f32_32x32x16_bf16 v[34:49], v[74:77], v[102:105], v[34:49]
	s_waitcnt lgkmcnt(0)
	v_mfma_f32_32x32x16_bf16 v[50:65], v[80:83], v[102:105], v[50:65]
	ds_read_b128 v[74:77], v72 offset:17472
	ds_read_b128 v[80:83], v72 offset:17504
	s_waitcnt lgkmcnt(1)
	v_mfma_f32_32x32x16_bf16 v[34:49], v[74:77], v[98:101], v[34:49]
	ds_read_b128 v[74:77], v72 offset:22080
	ds_read_b128 v[84:87], v72 offset:22112
	s_waitcnt lgkmcnt(1)
	v_mfma_f32_32x32x16_bf16 v[50:65], v[74:77], v[98:101], v[50:65]
	v_subrev_u32_e32 v74, 64, v73
	v_mfma_f32_32x32x16_bf16 v[34:49], v[80:83], v[94:97], v[34:49]
	s_waitcnt lgkmcnt(0)
; __device__ __forceinline__ void ret_tile_gen(const LAS char* sm, int r32, int hi, int vrd, int buf, int kp0, int qpos, float lgf, float lgb, const bf16x8 (&qf)[4], fa::f32x16& o0, fa::f32x16& o1) {
;     ...
;     int d0 = qpos - kp0 - 4 * hi;
;     asm volatile("" : "+v"(d0) : "v"(p0[15]), "v"(p1[15]));
; #pragma unroll
;     for (int r = 0; r < 16; ++r) {
;         const float f0 = (float)(d0 - ((r & 3) + 8 * (r >> 2))), f1 = f0 - 32.f;
;         const float w0 = __builtin_amdgcn_exp2f(lgf * fmaxf(f0, 0.f) + lgb * fmaxf(-f0, 0.f)) * (2.f - fminf(fabsf(f0), 1.f));
;         const float w1 = __builtin_amdgcn_exp2f(lgf * fmaxf(f1, 0.f) + lgb * fmaxf(-f1, 0.f)) * (2.f - fminf(fabsf(f1), 1.f));
;         p0[r] *= w0; p1[r] *= w1;
;     }
	v_mfma_f32_32x32x16_bf16 v[50:65], v[84:87], v[94:97], v[50:65]
	s_nop 0
	v_cvt_f32_i32_e32 v75, v74
	v_max_f32_e32 v72, 0, v75
	v_max_f32_e64 v73, -v75, 0
	v_pk_mul_f32 v[72:73], v[142:143], v[72:73]
	v_add_f32_e32 v76, 0xc2000000, v75
	v_add_f32_e32 v72, v72, v73
	v_exp_f32_e32 v72, v72
	v_min_f32_e64 v73, |v75|, 1.0
	v_sub_f32_e32 v73, 2.0, v73
	v_mul_f32_e32 v75, v73, v72
	v_max_f32_e32 v72, 0, v76
	v_max_f32_e64 v73, -v76, 0
	v_pk_mul_f32 v[72:73], v[142:143], v[72:73]
	v_mul_f32_e32 v75, v34, v75
	v_add_f32_e32 v72, v72, v73
	v_exp_f32_e32 v72, v72
	v_min_f32_e64 v73, |v76|, 1.0
	v_add_u32_e32 v76, -1, v74
	v_cvt_f32_i32_e32 v76, v76
	v_sub_f32_e32 v73, 2.0, v73
	v_mul_f32_e32 v72, v73, v72
	v_mul_f32_e32 v50, v50, v72
	v_max_f32_e32 v72, 0, v76
	v_max_f32_e64 v73, -v76, 0
	v_pk_mul_f32 v[72:73], v[142:143], v[72:73]
	v_add_f32_e32 v77, 0xc2000000, v76
	v_add_f32_e32 v34, v72, v73
	v_exp_f32_e32 v34, v34
	v_min_f32_e64 v72, |v76|, 1.0
	v_sub_f32_e32 v72, 2.0, v72
	v_max_f32_e64 v73, -v77, 0
	v_mul_f32_e32 v34, v72, v34
	v_max_f32_e32 v72, 0, v77
	v_pk_mul_f32 v[72:73], v[142:143], v[72:73]
	v_add_u32_e32 v76, -2, v74
	v_add_f32_e32 v72, v72, v73
	v_exp_f32_e32 v72, v72
	v_cvt_f32_i32_e32 v76, v76
	v_min_f32_e64 v73, |v77|, 1.0
	v_sub_f32_e32 v73, 2.0, v73
	v_mul_f32_e32 v72, v73, v72
	v_mul_f32_e32 v73, v35, v34
	v_max_f32_e32 v34, 0, v76
	v_max_f32_e64 v35, -v76, 0
	v_pk_mul_f32 v[34:35], v[142:143], v[34:35]
	v_mul_f32_e32 v51, v51, v72
	v_add_f32_e32 v34, v34, v35
	v_exp_f32_e32 v34, v34
	v_min_f32_e64 v35, |v76|, 1.0
	v_add_f32_e32 v72, 0xc2000000, v76
	v_sub_f32_e32 v35, 2.0, v35
	v_mul_f32_e32 v76, v35, v34
	v_max_f32_e32 v34, 0, v72
	v_max_f32_e64 v35, -v72, 0
	v_pk_mul_f32 v[34:35], v[142:143], v[34:35]
	v_mul_f32_e32 v36, v36, v76
	v_add_f32_e32 v34, v34, v35
	v_exp_f32_e32 v34, v34
	v_min_f32_e64 v35, |v72|, 1.0
	v_add_u32_e32 v72, -3, v74
	v_cvt_f32_i32_e32 v72, v72
	v_sub_f32_e32 v35, 2.0, v35
	v_mul_f32_e32 v34, v35, v34
	v_mul_f32_e32 v52, v52, v34
	v_max_f32_e32 v34, 0, v72
	v_max_f32_e64 v35, -v72, 0
	v_pk_mul_f32 v[34:35], v[142:143], v[34:35]
	v_add_f32_e32 v76, 0xc2000000, v72
	v_add_f32_e32 v34, v34, v35
	v_exp_f32_e32 v34, v34
	v_min_f32_e64 v35, |v72|, 1.0
	v_sub_f32_e32 v35, 2.0, v35
	v_mul_f32_e32 v72, v35, v34
	v_max_f32_e32 v34, 0, v76
	v_max_f32_e64 v35, -v76, 0
	v_pk_mul_f32 v[34:35], v[142:143], v[34:35]
	v_mul_f32_e32 v37, v37, v72
	v_add_f32_e32 v34, v34, v35
	v_exp_f32_e32 v34, v34
	v_min_f32_e64 v35, |v76|, 1.0
	v_add_u32_e32 v76, -8, v74
	v_cvt_f32_i32_e32 v76, v76
	v_sub_f32_e32 v35, 2.0, v35
	v_mul_f32_e32 v34, v35, v34
	v_mul_f32_e32 v53, v53, v34
	v_max_f32_e32 v34, 0, v76
	v_max_f32_e64 v35, -v76, 0
	v_pk_mul_f32 v[34:35], v[142:143], v[34:35]
	v_add_f32_e32 v72, 0xc2000000, v76
	v_add_f32_e32 v34, v34, v35
	v_exp_f32_e32 v34, v34
	v_min_f32_e64 v35, |v76|, 1.0
	v_sub_f32_e32 v35, 2.0, v35
	v_mul_f32_e32 v76, v35, v34
	v_max_f32_e32 v34, 0, v72
	v_max_f32_e64 v35, -v72, 0
	v_pk_mul_f32 v[34:35], v[142:143], v[34:35]
	v_mul_f32_e32 v38, v38, v76
	v_add_f32_e32 v34, v34, v35
	v_exp_f32_e32 v34, v34
	v_min_f32_e64 v35, |v72|, 1.0
	v_add_u32_e32 v72, -9, v74
	v_cvt_f32_i32_e32 v72, v72
	v_sub_f32_e32 v35, 2.0, v35
	v_mul_f32_e32 v34, v35, v34
	v_mul_f32_e32 v54, v54, v34
	v_max_f32_e32 v34, 0, v72
	v_max_f32_e64 v35, -v72, 0
	v_pk_mul_f32 v[34:35], v[142:143], v[34:35]
	v_add_f32_e32 v76, 0xc2000000, v72
	v_add_f32_e32 v34, v34, v35
	v_exp_f32_e32 v34, v34
	v_min_f32_e64 v35, |v72|, 1.0
	v_sub_f32_e32 v35, 2.0, v35
	v_mul_f32_e32 v72, v35, v34
	v_max_f32_e32 v34, 0, v76
	v_max_f32_e64 v35, -v76, 0
	v_pk_mul_f32 v[34:35], v[142:143], v[34:35]
	v_mul_f32_e32 v39, v39, v72
	v_add_f32_e32 v34, v34, v35
	v_exp_f32_e32 v34, v34
	v_min_f32_e64 v35, |v76|, 1.0
	v_add_u32_e32 v76, -10, v74
	v_cvt_f32_i32_e32 v76, v76
	v_sub_f32_e32 v35, 2.0, v35
	v_mul_f32_e32 v34, v35, v34
	v_mul_f32_e32 v55, v55, v34
	v_max_f32_e32 v34, 0, v76
	v_max_f32_e64 v35, -v76, 0
	v_pk_mul_f32 v[34:35], v[142:143], v[34:35]
	v_add_f32_e32 v72, 0xc2000000, v76
	v_add_f32_e32 v34, v34, v35
	v_exp_f32_e32 v34, v34
	v_min_f32_e64 v35, |v76|, 1.0
	v_sub_f32_e32 v35, 2.0, v35
	v_mul_f32_e32 v76, v35, v34
	v_max_f32_e32 v34, 0, v72
	v_max_f32_e64 v35, -v72, 0
	v_pk_mul_f32 v[34:35], v[142:143], v[34:35]
	v_mul_f32_e32 v40, v40, v76
	v_add_f32_e32 v34, v34, v35
	v_exp_f32_e32 v34, v34
	v_min_f32_e64 v35, |v72|, 1.0
	v_add_u32_e32 v72, -11, v74
	v_cvt_f32_i32_e32 v72, v72
	v_sub_f32_e32 v35, 2.0, v35
	v_mul_f32_e32 v34, v35, v34
	v_mul_f32_e32 v56, v56, v34
	v_max_f32_e32 v34, 0, v72
	v_max_f32_e64 v35, -v72, 0
	v_pk_mul_f32 v[34:35], v[142:143], v[34:35]
	v_add_f32_e32 v76, 0xc2000000, v72
	v_add_f32_e32 v34, v34, v35
	v_exp_f32_e32 v34, v34
	v_min_f32_e64 v35, |v72|, 1.0
	v_sub_f32_e32 v35, 2.0, v35
	v_mul_f32_e32 v72, v35, v34
	v_max_f32_e32 v34, 0, v76
	v_max_f32_e64 v35, -v76, 0
	v_pk_mul_f32 v[34:35], v[142:143], v[34:35]
	v_mul_f32_e32 v41, v41, v72
	v_add_f32_e32 v34, v34, v35
	v_exp_f32_e32 v34, v34
	v_min_f32_e64 v35, |v76|, 1.0
	v_add_u32_e32 v76, -16, v74
	v_cvt_f32_i32_e32 v76, v76
	v_sub_f32_e32 v35, 2.0, v35
	v_mul_f32_e32 v34, v35, v34
	v_mul_f32_e32 v57, v57, v34
	v_max_f32_e32 v34, 0, v76
	v_max_f32_e64 v35, -v76, 0
	v_pk_mul_f32 v[34:35], v[142:143], v[34:35]
	v_add_f32_e32 v72, 0xc2000000, v76
	v_add_f32_e32 v34, v34, v35
	v_exp_f32_e32 v34, v34
	v_min_f32_e64 v35, |v76|, 1.0
	v_sub_f32_e32 v35, 2.0, v35
	v_mul_f32_e32 v76, v35, v34
	v_max_f32_e32 v34, 0, v72
	v_max_f32_e64 v35, -v72, 0
	v_pk_mul_f32 v[34:35], v[142:143], v[34:35]
	v_mul_f32_e32 v42, v42, v76
	v_add_f32_e32 v34, v34, v35
	v_exp_f32_e32 v34, v34
; __device__ __forceinline__ bf16x8 pack_p(const f32x16& p, int base) { u32x4 w; w.x = pk2(p[base], p[base + 1]); w.y = pk2(p[base + 2], p[base + 3]); w.z = pk2(p[base + 4], p[base + 5]); w.w = pk2(p[base + 6], p[base + 7]); return __builtin_bit_cast(bf16x8, w); }
; __device__ __forceinline__ void ret_tile_gen(const LAS char* sm, int r32, int hi, int vrd, int buf, int kp0, int qpos, float lgf, float lgb, const bf16x8 (&qf)[4], fa::f32x16& o0, fa::f32x16& o1) {
;     ...
;     int d0 = qpos - kp0 - 4 * hi;
;     asm volatile("" : "+v"(d0) : "v"(p0[15]), "v"(p1[15]));
; #pragma unroll
;     for (int r = 0; r < 16; ++r) {
;         const float f0 = (float)(d0 - ((r & 3) + 8 * (r >> 2))), f1 = f0 - 32.f;
;         const float w0 = __builtin_amdgcn_exp2f(lgf * fmaxf(f0, 0.f) + lgb * fmaxf(-f0, 0.f)) * (2.f - fminf(fabsf(f0), 1.f));
;         const float w1 = __builtin_amdgcn_exp2f(lgf * fmaxf(f1, 0.f) + lgb * fmaxf(-f1, 0.f)) * (2.f - fminf(fabsf(f1), 1.f));
;         p0[r] *= w0; p1[r] *= w1;
;     }
;     bf16x8 pf[4]; pf[0] = pack_p(p0, 0); pf[1] = pack_p(p0, 8); pf[2] = pack_p(p1, 0); pf[3] = pack_p(p1, 8);
;     pv_tile(o0, o1, sm + buf + vrd, pf);
	v_min_f32_e64 v35, |v72|, 1.0
	v_subrev_u32_e32 v72, 17, v74
	v_cvt_f32_i32_e32 v72, v72
	v_sub_f32_e32 v35, 2.0, v35
	v_mul_f32_e32 v34, v35, v34
	v_mul_f32_e32 v58, v58, v34
	v_max_f32_e32 v34, 0, v72
	v_max_f32_e64 v35, -v72, 0
	v_pk_mul_f32 v[34:35], v[142:143], v[34:35]
	v_add_f32_e32 v76, 0xc2000000, v72
	v_add_f32_e32 v34, v34, v35
	v_exp_f32_e32 v34, v34
	v_min_f32_e64 v35, |v72|, 1.0
	v_sub_f32_e32 v35, 2.0, v35
	v_mul_f32_e32 v72, v35, v34
	v_max_f32_e32 v34, 0, v76
	v_max_f32_e64 v35, -v76, 0
	v_pk_mul_f32 v[34:35], v[142:143], v[34:35]
	v_mul_f32_e32 v43, v43, v72
	v_add_f32_e32 v34, v34, v35
	v_exp_f32_e32 v34, v34
	v_min_f32_e64 v35, |v76|, 1.0
	v_subrev_u32_e32 v76, 18, v74
	v_cvt_f32_i32_e32 v76, v76
	v_sub_f32_e32 v35, 2.0, v35
	v_mul_f32_e32 v34, v35, v34
	v_mul_f32_e32 v59, v59, v34
	v_max_f32_e32 v34, 0, v76
	v_max_f32_e64 v35, -v76, 0
	v_pk_mul_f32 v[34:35], v[142:143], v[34:35]
	v_add_f32_e32 v72, 0xc2000000, v76
	v_add_f32_e32 v34, v34, v35
	v_exp_f32_e32 v34, v34
	v_min_f32_e64 v35, |v76|, 1.0
	v_sub_f32_e32 v35, 2.0, v35
	v_mul_f32_e32 v76, v35, v34
	v_max_f32_e32 v34, 0, v72
	v_max_f32_e64 v35, -v72, 0
	v_pk_mul_f32 v[34:35], v[142:143], v[34:35]
	v_mul_f32_e32 v44, v44, v76
	v_add_f32_e32 v34, v34, v35
	v_exp_f32_e32 v34, v34
	v_min_f32_e64 v35, |v72|, 1.0
	v_subrev_u32_e32 v72, 19, v74
	v_cvt_f32_i32_e32 v72, v72
	v_sub_f32_e32 v35, 2.0, v35
	v_mul_f32_e32 v34, v35, v34
	v_mul_f32_e32 v60, v60, v34
	v_max_f32_e32 v34, 0, v72
	v_max_f32_e64 v35, -v72, 0
	v_pk_mul_f32 v[34:35], v[142:143], v[34:35]
	v_add_f32_e32 v76, 0xc2000000, v72
	v_add_f32_e32 v34, v34, v35
	v_exp_f32_e32 v34, v34
	v_min_f32_e64 v35, |v72|, 1.0
	v_sub_f32_e32 v35, 2.0, v35
	v_mul_f32_e32 v72, v35, v34
	v_max_f32_e32 v34, 0, v76
	v_max_f32_e64 v35, -v76, 0
	v_pk_mul_f32 v[34:35], v[142:143], v[34:35]
	v_mul_f32_e32 v45, v45, v72
	v_add_f32_e32 v34, v34, v35
	v_exp_f32_e32 v34, v34
	v_min_f32_e64 v35, |v76|, 1.0
	v_subrev_u32_e32 v76, 24, v74
	v_cvt_f32_i32_e32 v76, v76
	v_sub_f32_e32 v35, 2.0, v35
	v_mul_f32_e32 v34, v35, v34
	v_mul_f32_e32 v61, v61, v34
	v_max_f32_e32 v34, 0, v76
	v_max_f32_e64 v35, -v76, 0
	v_pk_mul_f32 v[34:35], v[142:143], v[34:35]
	v_add_f32_e32 v72, 0xc2000000, v76
	v_add_f32_e32 v34, v34, v35
	v_exp_f32_e32 v34, v34
	v_min_f32_e64 v35, |v76|, 1.0
	v_sub_f32_e32 v35, 2.0, v35
	v_mul_f32_e32 v76, v35, v34
	v_max_f32_e32 v34, 0, v72
	v_max_f32_e64 v35, -v72, 0
	v_pk_mul_f32 v[34:35], v[142:143], v[34:35]
	v_mul_f32_e32 v46, v46, v76
	v_add_f32_e32 v34, v34, v35
	v_exp_f32_e32 v34, v34
	v_min_f32_e64 v35, |v72|, 1.0
	v_subrev_u32_e32 v72, 25, v74
	v_cvt_f32_i32_e32 v72, v72
	v_sub_f32_e32 v35, 2.0, v35
	v_mul_f32_e32 v34, v35, v34
	v_mul_f32_e32 v62, v62, v34
	v_max_f32_e32 v34, 0, v72
	v_max_f32_e64 v35, -v72, 0
	v_pk_mul_f32 v[34:35], v[142:143], v[34:35]
	v_add_f32_e32 v76, 0xc2000000, v72
	v_add_f32_e32 v34, v34, v35
	v_exp_f32_e32 v34, v34
	v_min_f32_e64 v35, |v72|, 1.0
	v_sub_f32_e32 v35, 2.0, v35
	v_mul_f32_e32 v72, v35, v34
	v_max_f32_e32 v34, 0, v76
	v_max_f32_e64 v35, -v76, 0
	v_pk_mul_f32 v[34:35], v[142:143], v[34:35]
	v_mul_f32_e32 v47, v47, v72
	v_add_f32_e32 v34, v34, v35
	v_exp_f32_e32 v34, v34
	v_min_f32_e64 v35, |v76|, 1.0
	v_subrev_u32_e32 v76, 26, v74
	v_cvt_f32_i32_e32 v76, v76
	v_sub_f32_e32 v35, 2.0, v35
	v_mul_f32_e32 v34, v35, v34
	v_mul_f32_e32 v63, v63, v34
	v_max_f32_e32 v34, 0, v76
	v_max_f32_e64 v35, -v76, 0
	v_pk_mul_f32 v[34:35], v[142:143], v[34:35]
	v_add_f32_e32 v72, 0xc2000000, v76
	v_add_f32_e32 v34, v34, v35
	v_exp_f32_e32 v34, v34
	v_min_f32_e64 v35, |v76|, 1.0
	v_sub_f32_e32 v35, 2.0, v35
	v_mul_f32_e32 v76, v35, v34
	v_max_f32_e32 v34, 0, v72
	v_max_f32_e64 v35, -v72, 0
	v_pk_mul_f32 v[34:35], v[142:143], v[34:35]
	v_mul_f32_e32 v48, v48, v76
	v_add_f32_e32 v34, v34, v35
	v_exp_f32_e32 v34, v34
	v_min_f32_e64 v35, |v72|, 1.0
	v_subrev_u32_e32 v72, 27, v74
	v_cvt_f32_i32_e32 v72, v72
	v_sub_f32_e32 v35, 2.0, v35
	v_mul_f32_e32 v34, v35, v34
	v_mul_f32_e32 v64, v64, v34
	v_max_f32_e32 v34, 0, v72
	v_max_f32_e64 v35, -v72, 0
	v_pk_mul_f32 v[34:35], v[142:143], v[34:35]
	v_add_f32_e32 v74, 0xc2000000, v72
	v_add_f32_e32 v34, v34, v35
	v_exp_f32_e32 v76, v34
	v_min_f32_e64 v34, |v72|, 1.0
	v_sub_f32_e32 v72, 2.0, v34
	v_max_f32_e32 v34, 0, v74
	v_max_f32_e64 v35, -v74, 0
	v_pk_mul_f32 v[34:35], v[142:143], v[34:35]
	s_nop 0
	v_add_f32_e32 v34, v34, v35
	v_exp_f32_e32 v34, v34
	v_mul_f32_e32 v35, v72, v76
	v_min_f32_e64 v72, |v74|, 1.0
	v_sub_f32_e32 v72, 2.0, v72
	v_mul_f32_e32 v34, v72, v34
	v_mul_f32_e32 v49, v49, v35
	v_mul_f32_e32 v65, v65, v34
	v_cvt_pk_bf16_f32 v34, v75, v73
	v_cvt_pk_bf16_f32 v35, v36, v37
	v_cvt_pk_bf16_f32 v36, v38, v39
	v_cvt_pk_bf16_f32 v37, v40, v41
	v_cvt_pk_bf16_f32 v38, v42, v43
	v_cvt_pk_bf16_f32 v39, v44, v45
	v_cvt_pk_bf16_f32 v40, v46, v47
	v_cvt_pk_bf16_f32 v41, v48, v49
	v_cvt_pk_bf16_f32 v42, v50, v51
	v_cvt_pk_bf16_f32 v43, v52, v53
	v_cvt_pk_bf16_f32 v44, v54, v55
	v_cvt_pk_bf16_f32 v45, v56, v57
	v_cvt_pk_bf16_f32 v46, v58, v59
	v_cvt_pk_bf16_f32 v47, v60, v61
	v_cvt_pk_bf16_f32 v48, v62, v63
	v_cvt_pk_bf16_f32 v49, v64, v65
	ds_read_b64_tr_b16 v[50:51], v71 offset:26624
	ds_read_b64_tr_b16 v[52:53], v71 offset:27136
	ds_read_b64_tr_b16 v[54:55], v71 offset:27648
	ds_read_b64_tr_b16 v[56:57], v71 offset:28160
	s_waitcnt lgkmcnt(2)
	v_mfma_f32_32x32x16_bf16 v[2:17], v[50:53], v[34:37], v[2:17]
	ds_read_b64_tr_b16 v[50:51], v71 offset:30720
	ds_read_b64_tr_b16 v[52:53], v71 offset:31232
	ds_read_b64_tr_b16 v[58:59], v71 offset:31744
	ds_read_b64_tr_b16 v[60:61], v71 offset:32256
	s_waitcnt lgkmcnt(2)
; __device__ __forceinline__ float siluf_(float x) { return x * sigmoidf_(x); }
; __device__ __forceinline__ unsigned pk2n(float lo, float hi) { return __builtin_bit_cast(unsigned, __builtin_convertvector((f32v2_t){lo, hi}, bf16v2_t)); }
; __device__ __forceinline__ void ph_ret_chunk(unsigned char* lds_, bf16_t* Z, const bf16_t* KVF, const bf16_t* KVB, const float* decay_logit, const float* gn_w, int with_ctx, int u0, int ustep, unsigned* kvc, unsigned* barw) { PH_IDS;
;     ...
;         { f32x16 p0, p1;
;           ret_qk(sm, r32, hi, ST_OFF + cl * ST_SZ, qf, p0, p1);
;           const float sf = __builtin_amdgcn_exp2f(lgf * (float)(qpos - c0 + 1));
; #pragma unroll
;           for (int r = 0; r < 16; ++r) { o0[r] += p0[r] * sf; o1[r] += p1[r] * sf; }
;           ret_qk(sm, r32, hi, ST_OFF + (2 + cl) * ST_SZ, qf, p0, p1);
;           const float sbk = __builtin_amdgcn_exp2f(lgb * (float)(c0 + 128 - qpos));
; #pragma unroll
;           for (int r = 0; r < 16; ++r) { o0[r] += p0[r] * sbk; o1[r] += p1[r] * sbk; } }
;         float s1 = 0.f;
; #pragma unroll
;         for (int r = 0; r < 16; ++r) s1 += o0[r] + o1[r];
;         s1 += __shfl_xor(s1, 32);
;         const float mu = s1 * (1.f / 64);
;         float s2 = 0.f;
; #pragma unroll
;         for (int r = 0; r < 16; ++r) { const float a = o0[r] - mu, c = o1[r] - mu; s2 += a * a + c * c; }
;         s2 += __shfl_xor(s2, 32);
;         const float rstd = rsqrtf(s2 * (1.f / 64) + EPS);
;         u32x2 wv[2][4];
; #pragma unroll
;         for (int g = 0; g < 4; ++g)
; #pragma unroll
;             for (int blk = 0; blk < 2; ++blk) {
;                 const int d = blk * 32 + 8 * g + 4 * hi;
;                 const u32x2 gt = gtv[2 * g + blk];
;                 const f32x4 gw = gwv[2 * g + blk];
;                 float y[4];
; #pragma unroll
;                 for (int q = 0; q < 4; ++q) { const float ov = blk ? o1[4 * g + q] : o0[4 * g + q]; const unsigned gb = q < 2 ? gt.x : gt.y; const float gv = __uint_as_float((q & 1) ? (gb & 0xffff0000u) : (gb << 16));
;                     y[q] = siluf_(gv) * ((ov - mu) * rstd * gw[q]); }
;                 wv[blk][g].x = pk2n(y[0], y[1]); wv[blk][g].y = pk2n(y[2], y[3]);
;             }
	v_mfma_f32_32x32x16_bf16 v[18:33], v[50:53], v[34:37], v[18:33]
	v_mfma_f32_32x32x16_bf16 v[2:17], v[54:57], v[38:41], v[2:17]
	s_waitcnt lgkmcnt(0)
	v_mfma_f32_32x32x16_bf16 v[18:33], v[58:61], v[38:41], v[18:33]
	ds_read_b64_tr_b16 v[34:35], v71 offset:28672
	ds_read_b64_tr_b16 v[36:37], v71 offset:29184
	ds_read_b64_tr_b16 v[38:39], v71 offset:29696
	ds_read_b64_tr_b16 v[40:41], v71 offset:30208
	s_waitcnt lgkmcnt(2)
	v_mfma_f32_32x32x16_bf16 v[2:17], v[34:37], v[42:45], v[2:17]
	ds_read_b64_tr_b16 v[34:35], v71 offset:32768
	ds_read_b64_tr_b16 v[36:37], v71 offset:33280
	ds_read_b64_tr_b16 v[50:51], v71 offset:33792
	ds_read_b64_tr_b16 v[52:53], v71 offset:34304
	s_waitcnt lgkmcnt(2)
	v_mfma_f32_32x32x16_bf16 v[18:33], v[34:37], v[42:45], v[18:33]
	v_mfma_f32_32x32x16_bf16 v[2:17], v[38:41], v[46:49], v[2:17]
	s_waitcnt lgkmcnt(0)
	v_mfma_f32_32x32x16_bf16 v[18:33], v[50:53], v[46:49], v[18:33]
	v_add3_u32 v71, s7, v70, v78
	ds_read_b128 v[34:37], v71
	ds_read_b128 v[72:75], v71 offset:32
	ds_read_b128 v[50:53], v71 offset:4608
	ds_read_b128 v[80:83], v71 offset:4640
	v_add3_u32 v70, s5, v70, v78
	s_waitcnt lgkmcnt(1)
	v_mfma_f32_32x32x16_bf16 v[50:65], v[50:53], v[66:69], 0
	v_mfma_f32_32x32x16_bf16 v[34:49], v[34:37], v[66:69], 0
	s_waitcnt lgkmcnt(0)
	v_mfma_f32_32x32x16_bf16 v[50:65], v[80:83], v[102:105], v[50:65]
	v_mfma_f32_32x32x16_bf16 v[34:49], v[72:75], v[102:105], v[34:49]
	ds_read_b128 v[72:75], v71 offset:4672
	ds_read_b128 v[80:83], v71 offset:4704
	s_waitcnt lgkmcnt(1)
	v_mfma_f32_32x32x16_bf16 v[50:65], v[72:75], v[98:101], v[50:65]
	ds_read_b128 v[72:75], v71 offset:64
	ds_read_b128 v[162:165], v71 offset:96
	ds_read_b128 v[76:79], v70 offset:4608
	ds_read_b128 v[166:169], v70
	ds_read_b128 v[170:173], v70 offset:32
	ds_read_b128 v[174:177], v70 offset:4640
	v_subrev_u32_e32 v71, s4, v160
	v_add_u32_e32 v71, 1, v71
	v_cvt_f32_i32_e32 v71, v71
	ds_read_b128 v[178:181], v70 offset:64
	ds_read_b128 v[184:187], v70 offset:96
	ds_read_b128 v[188:191], v70 offset:4672
	ds_read_b128 v[192:195], v70 offset:4704
	s_waitcnt lgkmcnt(10)
	v_mfma_f32_32x32x16_bf16 v[50:65], v[80:83], v[94:97], v[50:65]
	v_mul_f32_e32 v71, v142, v71
	v_exp_f32_e32 v142, v71
	v_sub_u32_e32 v71, s6, v131
	v_add_u32_e32 v71, 0x80, v71
	v_cvt_f32_i32_e32 v71, v71
	s_waitcnt lgkmcnt(7)
	v_mfma_f32_32x32x16_bf16 v[78:93], v[76:79], v[66:69], 0
	s_nop 4
	v_fma_f32 v32, v142, v64, v32
	v_fma_f32 v33, v142, v65, v33
	v_mul_f32_e32 v70, v143, v71
	v_exp_f32_e32 v160, v70
	v_and_b32_e32 v70, 64, v1
	v_add_u32_e32 v77, 64, v70
	v_xor_b32_e32 v76, 32, v1
	v_pk_fma_f32 v[30:31], v[142:143], v[62:63], v[30:31] op_sel_hi:[0,1,1]
	s_waitcnt lgkmcnt(4)
	v_mfma_f32_32x32x16_bf16 v[78:93], v[174:177], v[102:105], v[78:93]
	s_waitcnt vmcnt(2)
	v_lshlrev_b32_e32 v174, 16, v144
	v_and_b32_e32 v175, 0xffff0000, v144
	v_mul_f32_e32 v70, 0xbfb8aa3b, v174
	v_mul_f32_e32 v71, 0xbfb8aa3b, v175
	v_exp_f32_e32 v70, v70
	v_exp_f32_e32 v71, v71
	v_cmp_lt_i32_e32 vcc, v76, v77
	s_waitcnt lgkmcnt(1)
	v_mfma_f32_32x32x16_bf16 v[78:93], v[188:191], v[98:101], v[78:93]
	v_add_f32_e64 v176, v70, 1.0
	v_add_f32_e64 v177, v71, 1.0
	v_div_scale_f32 v64, s[4:5], v177, v177, 1.0
	v_rcp_f32_e32 v65, v64
	v_cndmask_b32_e32 v76, v1, v76, vcc
	v_lshlrev_b32_e32 v131, 2, v76
	s_waitcnt lgkmcnt(0)
	v_mfma_f32_32x32x16_bf16 v[78:93], v[192:195], v[94:97], v[78:93]
	v_mfma_f32_32x32x16_bf16 v[34:49], v[72:75], v[98:101], v[34:49]
	s_nop 10
	v_fma_f32 v90, v160, v90, v30
	v_fma_f32 v91, v160, v91, v31
	v_fma_f32 v30, -v64, v65, 1.0
	v_fmac_f32_e32 v65, v30, v65
	v_div_scale_f32 v30, vcc, 1.0, v177, 1.0
	v_mul_f32_e32 v31, v30, v65
	v_fma_f32 v62, -v64, v31, v30
	v_mfma_f32_32x32x16_bf16 v[62:77], v[166:169], v[66:69], 0
	v_fma_f32 v32, v160, v92, v32
	v_fma_f32 v33, v160, v93, v33
	v_div_scale_f32 v92, s[4:5], v176, v176, 1.0
	v_rcp_f32_e32 v93, v92
	v_rcp_f32_e32 v31, v177
	v_fma_f32 v30, -v92, v93, 1.0
	v_mfma_f32_32x32x16_bf16 v[62:77], v[170:173], v[102:105], v[62:77]
	v_fmac_f32_e32 v93, v30, v93
	v_div_scale_f32 v30, vcc, 1.0, v176, 1.0
	v_mul_f32_e32 v143, v30, v93
	v_fma_f32 v144, -v92, v143, v30
	v_fmac_f32_e32 v143, v144, v93
	v_mfma_f32_32x32x16_bf16 v[62:77], v[178:181], v[98:101], v[62:77]
	v_lshlrev_b32_e32 v92, 16, v159
	v_and_b32_e32 v93, 0xffff0000, v159
	v_mul_f32_e32 v102, 0xbfb8aa3b, v92
	v_mul_f32_e32 v103, 0xbfb8aa3b, v93
	v_exp_f32_e32 v102, v102
	v_exp_f32_e32 v103, v103
	v_mfma_f32_32x32x16_bf16 v[34:49], v[162:165], v[94:97], v[34:49]
	v_fma_f32 v28, v142, v60, v28
	v_fma_f32 v29, v142, v61, v29
	v_fma_f32 v60, v160, v88, v28
	v_fma_f32 v61, v160, v89, v29
	v_add_f32_e64 v98, v102, 1.0
	v_add_f32_e64 v99, v103, 1.0
	v_pk_fma_f32 v[26:27], v[142:143], v[58:59], v[26:27] op_sel_hi:[0,1,1]
	v_mfma_f32_32x32x16_bf16 v[62:77], v[184:187], v[94:97], v[62:77]
	s_nop 1
	s_nop 1
	v_fma_f32 v16, v142, v48, v16
	v_fma_f32 v17, v142, v49, v17
	v_lshlrev_b32_e32 v94, 16, v158
	v_and_b32_e32 v95, 0xffff0000, v158
	v_fma_f32 v14, v142, v46, v14
	v_fma_f32 v15, v142, v47, v15
	v_pk_fma_f32 v[58:59], v[160:161], v[86:87], v[26:27] op_sel_hi:[0,1,1]
	v_pk_fma_f32 v[12:13], v[142:143], v[44:45], v[12:13] op_sel_hi:[0,1,1]
	v_pk_fma_f32 v[10:11], v[142:143], v[42:43], v[10:11] op_sel_hi:[0,1,1]
	s_nop 0
	v_pk_fma_f32 v[48:49], v[160:161], v[76:77], v[16:17] op_sel_hi:[0,1,1]
	v_rcp_f32_e32 v17, v99
	v_mul_f32_e32 v76, 0xbfb8aa3b, v94
	v_mul_f32_e32 v77, 0xbfb8aa3b, v95
	v_exp_f32_e32 v76, v76
	v_exp_f32_e32 v77, v77
	v_rcp_f32_e32 v16, v98
	s_nop 0
	v_pk_mul_f32 v[16:17], v[16:17], v[92:93]
	v_pk_add_f32 v[92:93], v[76:77], 1.0 op_sel_hi:[1,0]
	v_pk_fma_f32 v[46:47], v[160:161], v[74:75], v[14:15] op_sel_hi:[0,1,1]
; __device__ __forceinline__ void ph_ret_chunk(unsigned char* lds_, bf16_t* Z, const bf16_t* KVF, const bf16_t* KVB, const float* decay_logit, const float* gn_w, int with_ctx, int u0, int ustep, unsigned* kvc, unsigned* barw) { PH_IDS;
;     ...
;         u32x2 gtv[8]; f32x4 gwv[8];
; #pragma unroll
;         for (int g = 0; g < 4; ++g)
; #pragma unroll
;             for (int blk = 0; blk < 2; ++blk) { const int d = blk * 32 + 8 * g + 4 * hi; gtv[2 * g + blk] = *(const u32x2*)(zq + C_RG + h * 64 + d); gwv[2 * g + blk] = *(const f32x4*)(gn_w + h * 64 + d); }
;         f32x16 o0, o1;
; #pragma unroll
;         for (int r = 0; r < 16; ++r) { o0[r] = 0.f; o1[r] = 0.f; }
;         const int cl = wid >> 2, c0 = qb * 256 + 128 * cl;
;         ret_tile_gen(sm, r32, hi, vrd, (2 * cl) * BUF_R, c0, qpos, lgf, lgb, qf, o0, o1);
;         __builtin_amdgcn_sched_barrier(0);
;         ret_tile_gen(sm, r32, hi, vrd, (2 * cl + 1) * BUF_R, c0 + 64, qpos, lgf, lgb, qf, o0, o1);
;         __builtin_amdgcn_sched_barrier(0);
;         { f32x16 p0, p1;
;           ret_qk(sm, r32, hi, ST_OFF + cl * ST_SZ, qf, p0, p1);
;           const float sf = __builtin_amdgcn_exp2f(lgf * (float)(qpos - c0 + 1));
; #pragma unroll
;           for (int r = 0; r < 16; ++r) { o0[r] += p0[r] * sf; o1[r] += p1[r] * sf; }
;           ret_qk(sm, r32, hi, ST_OFF + (2 + cl) * ST_SZ, qf, p0, p1);
;           const float sbk = __builtin_amdgcn_exp2f(lgb * (float)(c0 + 128 - qpos));
; #pragma unroll
;           for (int r = 0; r < 16; ++r) { o0[r] += p0[r] * sbk; o1[r] += p1[r] * sbk; } }
;         float s1 = 0.f;
; #pragma unroll
;         for (int r = 0; r < 16; ++r) s1 += o0[r] + o1[r];
;         s1 += __shfl_xor(s1, 32);
;         const float mu = s1 * (1.f / 64);
;         float s2 = 0.f;
; #pragma unroll
;         for (int r = 0; r < 16; ++r) { const float a = o0[r] - mu, c = o1[r] - mu; s2 += a * a + c * c; }
;         s2 += __shfl_xor(s2, 32);
;         const float rstd = rsqrtf(s2 * (1.f / 64) + EPS);
;         u32x2 wv[2][4];
; #pragma unroll
;         for (int g = 0; g < 4; ++g)
; #pragma unroll
;             for (int blk = 0; blk < 2; ++blk) {
;                 const int d = blk * 32 + 8 * g + 4 * hi;
;                 const u32x2 gt = gtv[2 * g + blk];
;                 const f32x4 gw = gwv[2 * g + blk];
;                 float y[4];
; #pragma unroll
	v_pk_fma_f32 v[44:45], v[160:161], v[72:73], v[12:13] op_sel_hi:[0,1,1]
	v_pk_fma_f32 v[42:43], v[160:161], v[70:71], v[10:11] op_sel_hi:[0,1,1]
	v_pk_fma_f32 v[24:25], v[142:143], v[56:57], v[24:25] op_sel_hi:[0,1,1]
	v_rcp_f32_e32 v15, v93
	v_lshlrev_b32_e32 v96, 16, v157
	v_and_b32_e32 v97, 0xffff0000, v157
	v_mul_f32_e32 v74, 0xbfb8aa3b, v96
	v_mul_f32_e32 v75, 0xbfb8aa3b, v97
	v_exp_f32_e32 v74, v74
	v_exp_f32_e32 v75, v75
	v_rcp_f32_e32 v14, v92
	s_nop 0
	v_pk_mul_f32 v[14:15], v[14:15], v[94:95]
	v_pk_add_f32 v[92:93], v[74:75], 1.0 op_sel_hi:[1,0]
	v_pk_fma_f32 v[56:57], v[160:161], v[84:85], v[24:25] op_sel_hi:[0,1,1]
	v_pk_fma_f32 v[22:23], v[142:143], v[54:55], v[22:23] op_sel_hi:[0,1,1]
	v_pk_fma_f32 v[54:55], v[160:161], v[82:83], v[22:23] op_sel_hi:[0,1,1]
	v_pk_fma_f32 v[8:9], v[142:143], v[40:41], v[8:9] op_sel_hi:[0,1,1]
	v_rcp_f32_e32 v29, v93
	v_lshlrev_b32_e32 v88, 16, v156
	v_and_b32_e32 v89, 0xffff0000, v156
	v_mul_f32_e32 v94, 0xbfb8aa3b, v88
	v_mul_f32_e32 v95, 0xbfb8aa3b, v89
	v_exp_f32_e32 v94, v94
	v_exp_f32_e32 v95, v95
	v_rcp_f32_e32 v28, v92
	s_nop 0
	v_pk_mul_f32 v[28:29], v[28:29], v[96:97]
	v_pk_add_f32 v[92:93], v[94:95], 1.0 op_sel_hi:[1,0]
	v_pk_fma_f32 v[40:41], v[160:161], v[68:69], v[8:9] op_sel_hi:[0,1,1]
	v_pk_fma_f32 v[6:7], v[142:143], v[38:39], v[6:7] op_sel_hi:[0,1,1]
	v_pk_fma_f32 v[38:39], v[160:161], v[66:67], v[6:7] op_sel_hi:[0,1,1]
	v_pk_fma_f32 v[20:21], v[142:143], v[52:53], v[20:21] op_sel_hi:[0,1,1]
	v_rcp_f32_e32 v27, v93
	v_lshlrev_b32_e32 v86, 16, v155
	v_and_b32_e32 v87, 0xffff0000, v155
	v_mul_f32_e32 v94, 0xbfb8aa3b, v86
	v_mul_f32_e32 v95, 0xbfb8aa3b, v87
	v_exp_f32_e32 v94, v94
	v_exp_f32_e32 v95, v95
	v_rcp_f32_e32 v26, v92
	s_nop 0
	v_pk_mul_f32 v[26:27], v[26:27], v[88:89]
	v_pk_add_f32 v[92:93], v[94:95], 1.0 op_sel_hi:[1,0]
	v_lshlrev_b32_e32 v88, 16, v154
	v_and_b32_e32 v89, 0xffff0000, v154
	v_pk_fma_f32 v[20:21], v[160:161], v[80:81], v[20:21] op_sel_hi:[0,1,1]
	v_pk_fma_f32 v[18:19], v[142:143], v[50:51], v[18:19] op_sel_hi:[0,1,1]
	v_rcp_f32_e32 v13, v93
	v_pk_fma_f32 v[18:19], v[160:161], v[78:79], v[18:19] op_sel_hi:[0,1,1]
	v_mul_f32_e32 v72, 0xbfb8aa3b, v88
	v_mul_f32_e32 v73, 0xbfb8aa3b, v89
	v_exp_f32_e32 v72, v72
	v_exp_f32_e32 v73, v73
	v_rcp_f32_e32 v12, v92
	s_nop 0
	v_pk_mul_f32 v[12:13], v[12:13], v[86:87]
	v_pk_add_f32 v[86:87], v[72:73], 1.0 op_sel_hi:[1,0]
	v_pk_fma_f32 v[4:5], v[142:143], v[36:37], v[4:5] op_sel_hi:[0,1,1]
	v_pk_fma_f32 v[4:5], v[160:161], v[64:65], v[4:5] op_sel_hi:[0,1,1]
	v_pk_fma_f32 v[2:3], v[142:143], v[34:35], v[2:3] op_sel_hi:[0,1,1]
	v_pk_fma_f32 v[2:3], v[160:161], v[62:63], v[2:3] op_sel_hi:[0,1,1]
	v_rcp_f32_e32 v11, v87
	v_lshlrev_b32_e32 v92, 16, v153
	v_and_b32_e32 v93, 0xffff0000, v153
	v_mul_f32_e32 v70, 0xbfb8aa3b, v92
	v_mul_f32_e32 v71, 0xbfb8aa3b, v93
	v_exp_f32_e32 v70, v70
	v_exp_f32_e32 v71, v71
	v_rcp_f32_e32 v10, v86
	s_nop 0
	v_pk_mul_f32 v[10:11], v[10:11], v[88:89]
	v_pk_add_f32 v[86:87], v[70:71], 1.0 op_sel_hi:[1,0]
	v_pk_add_f32 v[70:71], v[42:43], v[58:59]
	v_pk_add_f32 v[72:73], v[44:45], v[60:61]
	v_pk_add_f32 v[74:75], v[46:47], v[90:91]
	v_pk_add_f32 v[76:77], v[48:49], v[32:33]
	v_rcp_f32_e32 v25, v87
	v_lshlrev_b32_e32 v84, 16, v152
	v_and_b32_e32 v85, 0xffff0000, v152
	v_mul_f32_e32 v88, 0xbfb8aa3b, v84
	v_mul_f32_e32 v89, 0xbfb8aa3b, v85
	v_exp_f32_e32 v88, v88
	v_exp_f32_e32 v89, v89
	v_rcp_f32_e32 v24, v86
	s_nop 0
	v_pk_mul_f32 v[24:25], v[24:25], v[92:93]
	v_pk_add_f32 v[86:87], v[88:89], 1.0 op_sel_hi:[1,0]
	v_rcp_f32_e32 v30, v176
	s_nop 0
	v_pk_mul_f32 v[30:31], v[30:31], v[174:175]
	v_rcp_f32_e32 v23, v87
	v_lshlrev_b32_e32 v82, 16, v151
	v_and_b32_e32 v83, 0xffff0000, v151
	v_mul_f32_e32 v88, 0xbfb8aa3b, v82
	v_mul_f32_e32 v89, 0xbfb8aa3b, v83
	v_exp_f32_e32 v88, v88
	v_exp_f32_e32 v89, v89
	v_rcp_f32_e32 v22, v86
	s_nop 0
	v_pk_mul_f32 v[22:23], v[22:23], v[84:85]
	v_pk_add_f32 v[86:87], v[88:89], 1.0 op_sel_hi:[1,0]
	v_lshlrev_b32_e32 v84, 16, v150
	v_and_b32_e32 v85, 0xffff0000, v150
	v_rcp_f32_e32 v9, v87
	v_mul_f32_e32 v68, 0xbfb8aa3b, v84
	v_mul_f32_e32 v69, 0xbfb8aa3b, v85
	v_exp_f32_e32 v68, v68
	v_exp_f32_e32 v69, v69
	v_rcp_f32_e32 v8, v86
	s_nop 0
	v_pk_mul_f32 v[8:9], v[8:9], v[82:83]
	v_pk_add_f32 v[82:83], v[68:69], 1.0 op_sel_hi:[1,0]
	v_pk_add_f32 v[68:69], v[40:41], v[56:57]
	s_nop 0
	v_rcp_f32_e32 v7, v83
	v_lshlrev_b32_e32 v66, 16, v149
	v_and_b32_e32 v67, 0xffff0000, v149
	v_mul_f32_e32 v86, 0xbfb8aa3b, v66
	v_mul_f32_e32 v87, 0xbfb8aa3b, v67
	v_exp_f32_e32 v86, v86
	v_exp_f32_e32 v87, v87
	v_rcp_f32_e32 v6, v82
	s_nop 0
	v_pk_mul_f32 v[6:7], v[6:7], v[84:85]
	v_pk_add_f32 v[82:83], v[86:87], 1.0 op_sel_hi:[1,0]
	v_pk_add_f32 v[84:85], v[38:39], v[54:55]
	s_nop 0
	v_rcp_f32_e32 v53, v83
	v_lshlrev_b32_e32 v80, 16, v148
	v_and_b32_e32 v81, 0xffff0000, v148
	v_mul_f32_e32 v86, 0xbfb8aa3b, v80
	v_mul_f32_e32 v87, 0xbfb8aa3b, v81
	v_exp_f32_e32 v86, v86
	v_exp_f32_e32 v87, v87
	v_rcp_f32_e32 v52, v82
	s_nop 0
	v_pk_mul_f32 v[52:53], v[52:53], v[66:67]
	v_pk_add_f32 v[82:83], v[86:87], 1.0 op_sel_hi:[1,0]
	s_nop 0
	s_nop 0
	v_rcp_f32_e32 v51, v83
	v_lshlrev_b32_e32 v66, 16, v147
	v_and_b32_e32 v67, 0xffff0000, v147
	v_mul_f32_e32 v78, 0xbfb8aa3b, v66
	v_mul_f32_e32 v79, 0xbfb8aa3b, v67
	v_exp_f32_e32 v78, v78
	v_exp_f32_e32 v79, v79
	v_rcp_f32_e32 v50, v82
	s_nop 0
	v_pk_mul_f32 v[50:51], v[50:51], v[80:81]
	v_pk_add_f32 v[78:79], v[78:79], 1.0 op_sel_hi:[1,0]
	s_nop 0
	s_nop 0
	v_rcp_f32_e32 v37, v79
	v_lshlrev_b32_e32 v64, 16, v146
	v_and_b32_e32 v65, 0xffff0000, v146
	v_mul_f32_e32 v80, 0xbfb8aa3b, v64
	v_mul_f32_e32 v81, 0xbfb8aa3b, v65
	v_exp_f32_e32 v80, v80
	v_exp_f32_e32 v81, v81
	v_rcp_f32_e32 v36, v78
	s_nop 0
	v_pk_mul_f32 v[36:37], v[36:37], v[66:67]
	v_pk_add_f32 v[66:67], v[80:81], 1.0 op_sel_hi:[1,0]
	v_pk_add_f32 v[78:79], v[4:5], v[20:21]
	s_nop 0
	v_pk_add_f32 v[62:63], v[2:3], v[18:19]
	v_rcp_f32_e32 v35, v67
	v_add_f32_e32 v34, 0, v62
	v_add_f32_e32 v34, v63, v34
	v_add_f32_e32 v34, v78, v34
	v_add_f32_e32 v34, v79, v34
	v_add_f32_e32 v34, v84, v34
	v_add_f32_e32 v34, v85, v34
	v_add_f32_e32 v34, v68, v34
	v_add_f32_e32 v34, v69, v34
	v_add_f32_e32 v34, v70, v34
	v_add_f32_e32 v34, v71, v34
	v_add_f32_e32 v34, v72, v34
	v_add_f32_e32 v34, v73, v34
	v_add_f32_e32 v34, v74, v34
	v_add_f32_e32 v34, v75, v34
	v_add_f32_e32 v34, v76, v34
	v_add_f32_e32 v34, v77, v34
	ds_bpermute_b32 v62, v131, v34
	s_mov_b32 s4, 0x800000
	s_waitcnt lgkmcnt(0)
; __device__ __forceinline__ float siluf_(float x) { return x * sigmoidf_(x); }
; __device__ __forceinline__ unsigned pk2n(float lo, float hi) { return __builtin_bit_cast(unsigned, __builtin_convertvector((f32v2_t){lo, hi}, bf16v2_t)); }
; __device__ __forceinline__ void ph_ret_chunk(unsigned char* lds_, bf16_t* Z, const bf16_t* KVF, const bf16_t* KVB, const float* decay_logit, const float* gn_w, int with_ctx, int u0, int ustep, unsigned* kvc, unsigned* barw) { PH_IDS;
;     ...
;         float s1 = 0.f;
; #pragma unroll
;         for (int r = 0; r < 16; ++r) s1 += o0[r] + o1[r];
;         s1 += __shfl_xor(s1, 32);
;         const float mu = s1 * (1.f / 64);
;         float s2 = 0.f;
; #pragma unroll
;         for (int r = 0; r < 16; ++r) { const float a = o0[r] - mu, c = o1[r] - mu; s2 += a * a + c * c; }
;         s2 += __shfl_xor(s2, 32);
;         const float rstd = rsqrtf(s2 * (1.f / 64) + EPS);
;         u32x2 wv[2][4];
; #pragma unroll
;         for (int g = 0; g < 4; ++g)
; #pragma unroll
;             for (int blk = 0; blk < 2; ++blk) {
;                 const int d = blk * 32 + 8 * g + 4 * hi;
;                 const u32x2 gt = gtv[2 * g + blk];
;                 const f32x4 gw = gwv[2 * g + blk];
;                 float y[4];
; #pragma unroll
;                 for (int q = 0; q < 4; ++q) { const float ov = blk ? o1[4 * g + q] : o0[4 * g + q]; const unsigned gb = q < 2 ? gt.x : gt.y; const float gv = __uint_as_float((q & 1) ? (gb & 0xffff0000u) : (gb << 16));
;                     y[q] = siluf_(gv) * ((ov - mu) * rstd * gw[q]); }
;                 wv[blk][g].x = pk2n(y[0], y[1]); wv[blk][g].y = pk2n(y[2], y[3]);
;             }
; #pragma unroll
;         for (int blk = 0; blk < 2; ++blk)
; #pragma unroll
;             for (int g = 0; g < 4; g += 2) {
;                 auto rx = __builtin_amdgcn_permlane32_swap(wv[blk][g].x, wv[blk][g + 1].x, false, false), ry = __builtin_amdgcn_permlane32_swap(wv[blk][g].y, wv[blk][g + 1].y, false, false);
;                 *(u32x4*)(zq + C_RQ + h * 64 + blk * 32 + 8 * g + 8 * hi) = (u32x4){(unsigned)rx[0], (unsigned)ry[0], (unsigned)rx[1], (unsigned)ry[1]};
;             }
	v_add_f32_e32 v34, v34, v62
	v_mul_f32_e32 v34, 0x3c800000, v34
	v_pk_add_f32 v[18:19], v[18:19], v[34:35] op_sel_hi:[1,0] neg_lo:[0,1] neg_hi:[0,1]
	v_pk_add_f32 v[2:3], v[2:3], v[34:35] op_sel_hi:[1,0] neg_lo:[0,1] neg_hi:[0,1]
	v_pk_mul_f32 v[62:63], v[18:19], v[18:19]
	v_pk_add_f32 v[20:21], v[20:21], v[34:35] op_sel_hi:[1,0] neg_lo:[0,1] neg_hi:[0,1]
	v_pk_fma_f32 v[62:63], v[2:3], v[2:3], v[62:63]
	v_pk_add_f32 v[4:5], v[4:5], v[34:35] op_sel_hi:[1,0] neg_lo:[0,1] neg_hi:[0,1]
	v_pk_mul_f32 v[68:69], v[20:21], v[20:21]
	v_pk_add_f32 v[38:39], v[38:39], v[34:35] op_sel_hi:[1,0] neg_lo:[0,1] neg_hi:[0,1]
	v_pk_fma_f32 v[68:69], v[4:5], v[4:5], v[68:69]
	v_pk_add_f32 v[54:55], v[54:55], v[34:35] op_sel_hi:[1,0] neg_lo:[0,1] neg_hi:[0,1]
	v_pk_add_f32 v[40:41], v[40:41], v[34:35] op_sel_hi:[1,0] neg_lo:[0,1] neg_hi:[0,1]
	v_pk_add_f32 v[56:57], v[56:57], v[34:35] op_sel_hi:[1,0] neg_lo:[0,1] neg_hi:[0,1]
	v_pk_add_f32 v[42:43], v[42:43], v[34:35] op_sel_hi:[1,0] neg_lo:[0,1] neg_hi:[0,1]
	v_pk_add_f32 v[58:59], v[58:59], v[34:35] op_sel_hi:[1,0] neg_lo:[0,1] neg_hi:[0,1]
	v_pk_add_f32 v[44:45], v[44:45], v[34:35] op_sel_hi:[1,0] neg_lo:[0,1] neg_hi:[0,1]
	v_pk_add_f32 v[60:61], v[60:61], v[34:35] op_sel_hi:[1,0] neg_lo:[0,1] neg_hi:[0,1]
	v_pk_add_f32 v[46:47], v[46:47], v[34:35] op_sel_hi:[1,0] neg_lo:[0,1] neg_hi:[0,1]
	v_pk_add_f32 v[78:79], v[90:91], v[34:35] op_sel_hi:[1,0] neg_lo:[0,1] neg_hi:[0,1]
	v_pk_add_f32 v[48:49], v[48:49], v[34:35] op_sel_hi:[1,0] neg_lo:[0,1] neg_hi:[0,1]
	v_pk_add_f32 v[32:33], v[32:33], v[34:35] op_sel_hi:[1,0] neg_lo:[0,1] neg_hi:[0,1]
	v_add_f32_e32 v34, v62, v63
	v_pk_mul_f32 v[70:71], v[54:55], v[54:55]
	v_add_f32_e32 v34, v68, v34
	v_pk_fma_f32 v[70:71], v[38:39], v[38:39], v[70:71]
	v_add_f32_e32 v34, v69, v34
	v_pk_mul_f32 v[72:73], v[56:57], v[56:57]
	v_add_f32_e32 v34, v70, v34
	v_pk_fma_f32 v[72:73], v[40:41], v[40:41], v[72:73]
	v_add_f32_e32 v34, v71, v34
	v_pk_mul_f32 v[74:75], v[58:59], v[58:59]
	v_add_f32_e32 v34, v72, v34
	v_pk_fma_f32 v[74:75], v[42:43], v[42:43], v[74:75]
	v_add_f32_e32 v34, v73, v34
	v_pk_mul_f32 v[76:77], v[60:61], v[60:61]
	v_add_f32_e32 v34, v74, v34
	v_pk_fma_f32 v[76:77], v[44:45], v[44:45], v[76:77]
	v_add_f32_e32 v34, v75, v34
	v_pk_mul_f32 v[80:81], v[78:79], v[78:79]
	v_add_f32_e32 v34, v76, v34
	v_pk_fma_f32 v[80:81], v[46:47], v[46:47], v[80:81]
	v_add_f32_e32 v34, v77, v34
	v_pk_mul_f32 v[82:83], v[32:33], v[32:33]
	v_add_f32_e32 v34, v80, v34
	v_pk_fma_f32 v[82:83], v[48:49], v[48:49], v[82:83]
	v_add_f32_e32 v34, v81, v34
	v_add_f32_e32 v34, v82, v34
	v_add_f32_e32 v34, v83, v34
	ds_bpermute_b32 v62, v131, v34
	s_waitcnt lgkmcnt(0)
	v_add_f32_e32 v34, v34, v62
	v_fmamk_f32 v34, v34, 0x3c800000, v207
	v_mul_f32_e32 v62, 0x4b800000, v34
	v_cmp_gt_f32_e64 s[4:5], s4, v34
	v_cndmask_b32_e64 v34, v34, v62, s[4:5]
	v_rsq_f32_e32 v62, v34
	v_rcp_f32_e32 v34, v66
	s_nop 0
	v_pk_mul_f32 v[34:35], v[34:35], v[64:65]
	v_mul_f32_e32 v63, 0x45800000, v62
	v_cndmask_b32_e64 v62, v62, v63, s[4:5]
	v_pk_mul_f32 v[2:3], v[2:3], v[62:63] op_sel_hi:[1,0]
	v_pk_mul_f32 v[4:5], v[4:5], v[62:63] op_sel_hi:[1,0]
	v_pk_mul_f32 v[2:3], v[136:137], v[2:3]
	v_pk_mul_f32 v[4:5], v[138:139], v[4:5]
	v_pk_mul_f32 v[2:3], v[34:35], v[2:3]
	v_pk_mul_f32 v[4:5], v[36:37], v[4:5]
	v_cvt_pk_bf16_f32 v2, v2, v3
	v_cvt_pk_bf16_f32 v3, v4, v5
	v_pk_mul_f32 v[4:5], v[18:19], v[62:63] op_sel_hi:[1,0]
	v_pk_mul_f32 v[18:19], v[20:21], v[62:63] op_sel_hi:[1,0]
	v_pk_mul_f32 v[4:5], v[132:133], v[4:5]
	v_pk_mul_f32 v[18:19], v[134:135], v[18:19]
	v_pk_mul_f32 v[4:5], v[50:51], v[4:5]
	v_pk_mul_f32 v[20:21], v[52:53], v[18:19]
	v_cvt_pk_bf16_f32 v18, v4, v5
	v_pk_mul_f32 v[4:5], v[38:39], v[62:63] op_sel_hi:[1,0]
	v_cvt_pk_bf16_f32 v19, v20, v21
	v_pk_mul_f32 v[4:5], v[126:127], v[4:5]
	s_nop 0
	v_pk_mul_f32 v[4:5], v[6:7], v[4:5]
	v_pk_mul_f32 v[6:7], v[40:41], v[62:63] op_sel_hi:[1,0]
	v_cvt_pk_bf16_f32 v4, v4, v5
	v_pk_mul_f32 v[6:7], v[128:129], v[6:7]
	s_nop 0
	v_permlane32_swap_b32_e32 v2, v4
	v_pk_mul_f32 v[6:7], v[8:9], v[6:7]
	v_pk_mul_f32 v[8:9], v[56:57], v[62:63] op_sel_hi:[1,0]
	v_cvt_pk_bf16_f32 v5, v6, v7
	v_pk_mul_f32 v[6:7], v[54:55], v[62:63] op_sel_hi:[1,0]
	v_pk_mul_f32 v[8:9], v[124:125], v[8:9]
	v_pk_mul_f32 v[6:7], v[122:123], v[6:7]
	v_pk_mul_f32 v[8:9], v[24:25], v[8:9]
	v_pk_mul_f32 v[6:7], v[22:23], v[6:7]
	v_cvt_pk_bf16_f32 v21, v8, v9
	v_cvt_pk_bf16_f32 v20, v6, v7
	v_pk_mul_f32 v[6:7], v[42:43], v[62:63] op_sel_hi:[1,0]
	v_pk_mul_f32 v[8:9], v[44:45], v[62:63] op_sel_hi:[1,0]
	v_pk_mul_f32 v[6:7], v[118:119], v[6:7]
	v_pk_mul_f32 v[8:9], v[120:121], v[8:9]
	v_pk_mul_f32 v[6:7], v[10:11], v[6:7]
	v_pk_mul_f32 v[8:9], v[12:13], v[8:9]
	v_cvt_pk_bf16_f32 v6, v6, v7
	v_cvt_pk_bf16_f32 v7, v8, v9
	v_pk_mul_f32 v[8:9], v[58:59], v[62:63] op_sel_hi:[1,0]
	v_pk_mul_f32 v[10:11], v[60:61], v[62:63] op_sel_hi:[1,0]
	s_waitcnt vmcnt(1)
	v_pk_mul_f32 v[8:9], v[114:115], v[8:9]
	v_pk_mul_f32 v[10:11], v[116:117], v[10:11]
	v_pk_mul_f32 v[8:9], v[26:27], v[8:9]
	v_pk_mul_f32 v[12:13], v[28:29], v[10:11]
	v_cvt_pk_bf16_f32 v10, v8, v9
	v_pk_mul_f32 v[8:9], v[46:47], v[62:63] op_sel_hi:[1,0]
	v_cvt_pk_bf16_f32 v11, v12, v13
	v_pk_mul_f32 v[8:9], v[110:111], v[8:9]
	v_pk_mul_f32 v[12:13], v[48:49], v[62:63] op_sel_hi:[1,0]
	v_pk_mul_f32 v[8:9], v[14:15], v[8:9]
	v_lshlrev_b32_e32 v14, 16, v145
	v_and_b32_e32 v15, 0xffff0000, v145
	v_mul_f32_e32 v22, 0xbfb8aa3b, v14
	v_mul_f32_e32 v23, 0xbfb8aa3b, v15
	v_exp_f32_e32 v22, v22
	v_exp_f32_e32 v23, v23
	v_pk_mul_f32 v[12:13], v[112:113], v[12:13]
	v_cvt_pk_bf16_f32 v8, v8, v9
	v_pk_mul_f32 v[12:13], v[16:17], v[12:13]
	v_pk_mul_f32 v[16:17], v[78:79], v[62:63] op_sel_hi:[1,0]
	v_cvt_pk_bf16_f32 v9, v12, v13
	v_pk_add_f32 v[12:13], v[22:23], 1.0 op_sel_hi:[1,0]
	s_waitcnt vmcnt(0)
	v_pk_mul_f32 v[16:17], v[106:107], v[16:17]
	v_pk_mul_f32 v[16:17], v[30:31], v[16:17]
	v_permlane32_swap_b32_e32 v3, v5
	v_rcp_f32_e32 v13, v13
	v_permlane32_swap_b32_e32 v6, v8
	v_rcp_f32_e32 v12, v12
	s_nop 0
	v_pk_mul_f32 v[12:13], v[12:13], v[14:15]
	v_pk_mul_f32 v[14:15], v[32:33], v[62:63] op_sel_hi:[1,0]
	v_permlane32_swap_b32_e32 v7, v9
	v_pk_mul_f32 v[14:15], v[108:109], v[14:15]
	v_permlane32_swap_b32_e32 v18, v20
	v_pk_mul_f32 v[14:15], v[12:13], v[14:15]
	v_cvt_pk_bf16_f32 v12, v16, v17
	v_cvt_pk_bf16_f32 v13, v14, v15
	v_permlane32_swap_b32_e32 v19, v21
	v_permlane32_swap_b32_e32 v10, v12
	v_permlane32_swap_b32_e32 v11, v13
	global_store_dwordx4 v[140:141], v[2:5], off offset:2880
	global_store_dwordx4 v[140:141], v[6:9], off offset:2912
	global_store_dwordx4 v[140:141], v[18:21], off offset:2944
	global_store_dwordx4 v[140:141], v[10:13], off offset:2976
	s_barrier
	s_cbranch_execz .LBB0_778
	s_branch .LBB0_1012

; __device__ __forceinline__ float sigmoidf_(float x) { return 1.f / (1.f + __expf(-x)); }
; __device__ __forceinline__ pg8::u32x4 pack8(const f32x4 a, const f32x4 b) { pg8::u32x4 w; w.x = pg8::cvt_pk_bf16(a[0], a[1]); w.y = pg8::cvt_pk_bf16(a[2], a[3]); w.z = pg8::cvt_pk_bf16(b[0], b[1]); w.w = pg8::cvt_pk_bf16(b[2], b[3]); return w; }
;     __device__ __forceinline__ void operator()(const f32x4 (&acc)[2][2][4][2], const pg8::Unit& u, int wr, int wc, int fr, int fq) const {
; #pragma unroll
;         for (int ai = 0; ai < 2; ++ai)
; #pragma unroll
;             for (int m = 0; m < 4; ++m) {
;                 const int row = u.pm * 256 + ai * 128 + wr * 64 + m * 16 + fr, col = u.pn * 128 + wc * 32 + 8 * fq;
;                 f32x4 a, b;
; #pragma unroll
;                 for (int q = 0; q < 4; ++q) { a[q] = acc[ai][0][m][0][q] * sigmoidf_(acc[ai][1][m][0][q]); b[q] = acc[ai][0][m][1][q] * sigmoidf_(acc[ai][1][m][1][q]); }
;                 *(pg8::u32x4*)(OCp + (size_t)row * 256 + col) = pack8(a, b);
;             }
;     }
.LBB0_1274:
	v_mul_f32_e32 v126, 0xbfb8aa3b, v126
	v_exp_f32_e32 v147, v126
	v_mul_f32_e32 v122, 0xbfb8aa3b, v122
	v_exp_f32_e32 v122, v122
	v_mul_f32_e32 v127, 0xbfb8aa3b, v127
	v_add_f32_e32 v148, 1.0, v147
	v_add_f32_e32 v122, 1.0, v122
	v_rcp_f32_e32 v148, v148
	v_exp_f32_e32 v127, v127
	v_mul_f32_e32 v118, v118, v148
	v_add_f32_e32 v127, 1.0, v127
	v_mul_f32_e32 v123, 0xbfb8aa3b, v123
	v_rcp_f32_e32 v122, v122
	v_exp_f32_e32 v123, v123
	v_mul_f32_e32 v114, v114, v122
	v_add_f32_e32 v123, 1.0, v123
	v_mul_f32_e32 v128, 0xbfb8aa3b, v128
	v_rcp_f32_e32 v122, v127
	v_exp_f32_e32 v128, v128
	v_mul_f32_e32 v119, v119, v122
	v_add_f32_e32 v128, 1.0, v128
	v_mul_f32_e32 v124, 0xbfb8aa3b, v124
	v_rcp_f32_e32 v122, v123
	v_exp_f32_e32 v124, v124
	v_mul_f32_e32 v115, v115, v122
	v_add_f32_e32 v124, 1.0, v124
	v_rcp_f32_e32 v122, v128
	s_nop 0
	v_mul_f32_e32 v120, v120, v122
	v_mul_f32_e32 v128, 0xbfb8aa3b, v129
	v_exp_f32_e32 v128, v128
	s_nop 0
	v_add_f32_e32 v127, 1.0, v128
	v_rcp_f32_e32 v122, v124
	v_mul_f32_e32 v124, 0xbfb8aa3b, v125
	v_exp_f32_e32 v124, v124
	v_mul_f32_e32 v122, v116, v122
	v_add_f32_e32 v124, 1.0, v124
	v_rcp_f32_e32 v116, v127
	s_nop 0
	v_mul_f32_e32 v121, v121, v116
	v_mul_f32_e32 v110, 0xbfb8aa3b, v110
	v_exp_f32_e32 v110, v110
	v_rcp_f32_e32 v116, v124
	v_add_f32_e32 v110, 1.0, v110
	v_lshl_add_u32 v126, s26, 8, v138
	v_mul_f32_e32 v123, v117, v116
	v_cvt_pk_bf16_f32 v116, v118, v119
	v_cvt_pk_bf16_f32 v117, v120, v121
	v_cvt_pk_bf16_f32 v118, v114, v115
	v_cvt_pk_bf16_f32 v119, v122, v123
	v_lshl_or_b32 v146, s60, 7, v139
	v_ashrrev_i32_e32 v127, 31, v126
	v_ashrrev_i32_e32 v147, 31, v146
	v_lshlrev_b64 v[114:115], 9, v[126:127]
	v_lshl_add_u64 v[120:121], s[10:11], 0, v[114:115]
	v_lshlrev_b64 v[114:115], 1, v[146:147]
	v_mul_f32_e32 v106, 0xbfb8aa3b, v106
	v_lshl_add_u64 v[120:121], v[120:121], 0, v[114:115]
	v_exp_f32_e32 v106, v106
	global_store_dwordx4 v[120:121], v[116:119], off
	v_mul_f32_e32 v111, 0xbfb8aa3b, v111
	v_exp_f32_e32 v111, v111
	v_add_f32_e32 v106, 1.0, v106
	v_rcp_f32_e32 v110, v110
	s_nop 0
	v_mul_f32_e32 v110, v102, v110
	v_add_f32_e32 v111, 1.0, v111
	v_mul_f32_e32 v107, 0xbfb8aa3b, v107
	v_rcp_f32_e32 v102, v106
	v_exp_f32_e32 v107, v107
	v_mul_f32_e32 v106, v98, v102
	v_add_f32_e32 v107, 1.0, v107
	v_rcp_f32_e32 v98, v111
	v_mul_f32_e32 v111, 0xbfb8aa3b, v112
	v_exp_f32_e32 v111, v111
	v_mul_f32_e32 v98, v103, v98
	v_add_f32_e32 v111, 1.0, v111
	v_rcp_f32_e32 v102, v107
	v_mul_f32_e32 v107, 0xbfb8aa3b, v108
	v_exp_f32_e32 v107, v107
	v_mul_f32_e32 v103, v99, v102
	v_add_f32_e32 v107, 1.0, v107
	v_rcp_f32_e32 v99, v111
	v_mul_f32_e32 v111, 0xbfb8aa3b, v113
	v_exp_f32_e32 v111, v111
	v_mul_f32_e32 v99, v104, v99
	v_add_f32_e32 v108, 1.0, v111
	v_rcp_f32_e32 v102, v107
	v_mul_f32_e32 v107, 0xbfb8aa3b, v109
	v_exp_f32_e32 v107, v107
	v_mul_f32_e32 v104, v100, v102
	v_add_f32_e32 v107, 1.0, v107
	v_rcp_f32_e32 v100, v108
	s_nop 0
	v_mul_f32_e32 v100, v105, v100
	v_mul_f32_e32 v94, 0xbfb8aa3b, v94
	v_exp_f32_e32 v94, v94
	v_rcp_f32_e32 v102, v107
	s_nop 0
	v_mul_f32_e32 v101, v101, v102
	v_add_f32_e32 v94, 1.0, v94
	v_or_b32_e32 v102, 16, v126
	v_cvt_pk_bf16_f32 v98, v110, v98
	v_cvt_pk_bf16_f32 v99, v99, v100
	v_cvt_pk_bf16_f32 v100, v106, v103
	v_cvt_pk_bf16_f32 v101, v104, v101
	v_ashrrev_i32_e32 v103, 31, v102
	v_lshlrev_b64 v[102:103], 9, v[102:103]
	v_lshl_add_u64 v[102:103], s[10:11], 0, v[102:103]
	v_mul_f32_e32 v90, 0xbfb8aa3b, v90
	v_lshl_add_u64 v[102:103], v[102:103], 0, v[114:115]
	v_exp_f32_e32 v90, v90
	global_store_dwordx4 v[102:103], v[98:101], off
	v_mul_f32_e32 v95, 0xbfb8aa3b, v95
	v_exp_f32_e32 v95, v95
	v_add_f32_e32 v90, 1.0, v90
	v_rcp_f32_e32 v94, v94
	s_nop 0
	v_mul_f32_e32 v94, v86, v94
	v_add_f32_e32 v95, 1.0, v95
	v_mul_f32_e32 v91, 0xbfb8aa3b, v91
	v_rcp_f32_e32 v86, v90
	v_exp_f32_e32 v91, v91
	v_mul_f32_e32 v90, v82, v86
	v_add_f32_e32 v91, 1.0, v91
	v_rcp_f32_e32 v82, v95
	v_mul_f32_e32 v95, 0xbfb8aa3b, v96
	v_exp_f32_e32 v95, v95
	v_mul_f32_e32 v82, v87, v82
	v_add_f32_e32 v95, 1.0, v95
	v_rcp_f32_e32 v86, v91
	v_mul_f32_e32 v91, 0xbfb8aa3b, v92
	v_exp_f32_e32 v91, v91
	v_mul_f32_e32 v87, v83, v86
	v_add_f32_e32 v91, 1.0, v91
	v_rcp_f32_e32 v83, v95
	v_mul_f32_e32 v95, 0xbfb8aa3b, v97
	v_exp_f32_e32 v95, v95
	v_mul_f32_e32 v83, v88, v83
	v_add_f32_e32 v92, 1.0, v95
	v_rcp_f32_e32 v86, v91
	v_mul_f32_e32 v91, 0xbfb8aa3b, v93
	v_exp_f32_e32 v91, v91
	v_mul_f32_e32 v88, v84, v86
	v_add_f32_e32 v91, 1.0, v91
	v_rcp_f32_e32 v84, v92
	s_nop 0
	v_mul_f32_e32 v84, v89, v84
	v_mul_f32_e32 v78, 0xbfb8aa3b, v78
	v_exp_f32_e32 v78, v78
	v_rcp_f32_e32 v86, v91
	s_nop 0
	v_mul_f32_e32 v85, v85, v86
	v_add_f32_e32 v78, 1.0, v78
	v_or_b32_e32 v86, 32, v126
	v_cvt_pk_bf16_f32 v82, v94, v82
	v_cvt_pk_bf16_f32 v83, v83, v84
	v_cvt_pk_bf16_f32 v84, v90, v87
	v_cvt_pk_bf16_f32 v85, v88, v85
	v_ashrrev_i32_e32 v87, 31, v86
	v_lshlrev_b64 v[86:87], 9, v[86:87]
	v_lshl_add_u64 v[86:87], s[10:11], 0, v[86:87]
	v_mul_f32_e32 v74, 0xbfb8aa3b, v74
	v_lshl_add_u64 v[86:87], v[86:87], 0, v[114:115]
	v_exp_f32_e32 v74, v74
	global_store_dwordx4 v[86:87], v[82:85], off
	v_mul_f32_e32 v79, 0xbfb8aa3b, v79
	v_exp_f32_e32 v79, v79
	v_add_f32_e32 v74, 1.0, v74
	v_rcp_f32_e32 v78, v78
	s_nop 0
	v_mul_f32_e32 v78, v70, v78
	v_add_f32_e32 v79, 1.0, v79
	v_mul_f32_e32 v75, 0xbfb8aa3b, v75
	v_rcp_f32_e32 v70, v74
	v_exp_f32_e32 v75, v75
	v_mul_f32_e32 v74, v66, v70
	v_add_f32_e32 v75, 1.0, v75
	v_rcp_f32_e32 v66, v79
	v_mul_f32_e32 v79, 0xbfb8aa3b, v80
	v_exp_f32_e32 v79, v79
	v_mul_f32_e32 v66, v71, v66
	v_add_f32_e32 v79, 1.0, v79
	v_rcp_f32_e32 v70, v75
	v_mul_f32_e32 v75, 0xbfb8aa3b, v76
; __device__ __forceinline__ float sigmoidf_(float x) { return 1.f / (1.f + __expf(-x)); }
; __device__ __forceinline__ pg8::u32x4 pack8(const f32x4 a, const f32x4 b) { pg8::u32x4 w; w.x = pg8::cvt_pk_bf16(a[0], a[1]); w.y = pg8::cvt_pk_bf16(a[2], a[3]); w.z = pg8::cvt_pk_bf16(b[0], b[1]); w.w = pg8::cvt_pk_bf16(b[2], b[3]); return w; }
;     __device__ __forceinline__ void operator()(const f32x4 (&acc)[2][2][4][2], const pg8::Unit& u, int wr, int wc, int fr, int fq) const {
; #pragma unroll
;         for (int ai = 0; ai < 2; ++ai)
; #pragma unroll
;             for (int m = 0; m < 4; ++m) {
;                 const int row = u.pm * 256 + ai * 128 + wr * 64 + m * 16 + fr, col = u.pn * 128 + wc * 32 + 8 * fq;
;                 f32x4 a, b;
; #pragma unroll
;                 for (int q = 0; q < 4; ++q) { a[q] = acc[ai][0][m][0][q] * sigmoidf_(acc[ai][1][m][0][q]); b[q] = acc[ai][0][m][1][q] * sigmoidf_(acc[ai][1][m][1][q]); }
;                 *(pg8::u32x4*)(OCp + (size_t)row * 256 + col) = pack8(a, b);
;             }
;     }
	v_exp_f32_e32 v75, v75
	v_mul_f32_e32 v71, v67, v70
	v_add_f32_e32 v75, 1.0, v75
	v_rcp_f32_e32 v67, v79
	v_mul_f32_e32 v79, 0xbfb8aa3b, v81
	v_exp_f32_e32 v79, v79
	v_mul_f32_e32 v67, v72, v67
	v_add_f32_e32 v76, 1.0, v79
	v_rcp_f32_e32 v70, v75
	v_mul_f32_e32 v75, 0xbfb8aa3b, v77
	v_exp_f32_e32 v75, v75
	v_mul_f32_e32 v72, v68, v70
	v_add_f32_e32 v75, 1.0, v75
	v_rcp_f32_e32 v68, v76
	s_nop 0
	v_mul_f32_e32 v68, v73, v68
	v_mul_f32_e32 v62, 0xbfb8aa3b, v62
	v_exp_f32_e32 v62, v62
	v_rcp_f32_e32 v70, v75
	s_nop 0
	v_mul_f32_e32 v69, v69, v70
	v_cvt_pk_bf16_f32 v66, v78, v66
	v_cvt_pk_bf16_f32 v67, v67, v68
	v_cvt_pk_bf16_f32 v68, v74, v71
	v_cvt_pk_bf16_f32 v69, v72, v69
	v_add_f32_e32 v72, 1.0, v62
	v_or_b32_e32 v70, 48, v126
	v_ashrrev_i32_e32 v71, 31, v70
	v_lshlrev_b64 v[70:71], 9, v[70:71]
	v_lshl_add_u64 v[70:71], s[10:11], 0, v[70:71]
	v_mul_f32_e32 v58, 0xbfb8aa3b, v58
	v_lshl_add_u64 v[70:71], v[70:71], 0, v[114:115]
	v_exp_f32_e32 v58, v58
	global_store_dwordx4 v[70:71], v[66:69], off
	v_mul_f32_e32 v63, 0xbfb8aa3b, v63
	v_exp_f32_e32 v63, v63
	v_add_f32_e32 v58, 1.0, v58
	v_rcp_f32_e32 v66, v72
	s_nop 0
	v_mul_f32_e32 v54, v54, v66
	v_add_f32_e32 v63, 1.0, v63
	v_mul_f32_e32 v59, 0xbfb8aa3b, v59
	v_rcp_f32_e32 v58, v58
	v_exp_f32_e32 v59, v59
	v_mul_f32_e32 v58, v50, v58
	v_add_f32_e32 v59, 1.0, v59
	v_mul_f32_e32 v64, 0xbfb8aa3b, v64
	v_rcp_f32_e32 v50, v63
	v_exp_f32_e32 v64, v64
	v_mul_f32_e32 v50, v55, v50
	v_add_f32_e32 v64, 1.0, v64
	v_mul_f32_e32 v60, 0xbfb8aa3b, v60
	v_rcp_f32_e32 v55, v59
	v_exp_f32_e32 v60, v60
	v_mul_f32_e32 v55, v51, v55
	v_add_f32_e32 v60, 1.0, v60
	v_rcp_f32_e32 v51, v64
	s_nop 0
	v_mul_f32_e32 v51, v56, v51
	v_mul_f32_e32 v64, 0xbfb8aa3b, v65
	v_exp_f32_e32 v64, v64
	s_nop 0
	v_add_f32_e32 v63, 1.0, v64
	v_rcp_f32_e32 v56, v60
	v_mul_f32_e32 v60, 0xbfb8aa3b, v61
	v_exp_f32_e32 v60, v60
	v_mul_f32_e32 v56, v52, v56
	v_add_f32_e32 v60, 1.0, v60
	v_rcp_f32_e32 v52, v63
	s_nop 0
	v_mul_f32_e32 v52, v57, v52
	v_mul_f32_e32 v46, 0xbfb8aa3b, v46
	v_exp_f32_e32 v46, v46
	v_rcp_f32_e32 v57, v60
	s_nop 0
	v_mul_f32_e32 v53, v53, v57
	v_add_f32_e32 v46, 1.0, v46
	v_add_u32_e32 v62, 0x80, v126
	v_cvt_pk_bf16_f32 v50, v54, v50
	v_cvt_pk_bf16_f32 v51, v51, v52
	v_cvt_pk_bf16_f32 v52, v58, v55
	v_cvt_pk_bf16_f32 v53, v56, v53
	v_ashrrev_i32_e32 v63, 31, v62
	v_lshlrev_b64 v[54:55], 9, v[62:63]
	v_lshl_add_u64 v[54:55], s[10:11], 0, v[54:55]
	v_mul_f32_e32 v42, 0xbfb8aa3b, v42
	v_lshl_add_u64 v[54:55], v[54:55], 0, v[114:115]
	v_exp_f32_e32 v42, v42
	global_store_dwordx4 v[54:55], v[50:53], off
	v_mul_f32_e32 v47, 0xbfb8aa3b, v47
	v_exp_f32_e32 v47, v47
	v_add_f32_e32 v42, 1.0, v42
	v_rcp_f32_e32 v46, v46
	s_nop 0
	v_mul_f32_e32 v46, v38, v46
	v_add_f32_e32 v47, 1.0, v47
	v_mul_f32_e32 v43, 0xbfb8aa3b, v43
	v_rcp_f32_e32 v38, v42
	v_exp_f32_e32 v43, v43
	v_mul_f32_e32 v42, v34, v38
	v_add_f32_e32 v43, 1.0, v43
	v_rcp_f32_e32 v34, v47
	v_mul_f32_e32 v47, 0xbfb8aa3b, v48
	v_exp_f32_e32 v47, v47
	v_mul_f32_e32 v34, v39, v34
	v_add_f32_e32 v47, 1.0, v47
	v_rcp_f32_e32 v38, v43
	v_mul_f32_e32 v43, 0xbfb8aa3b, v44
	v_exp_f32_e32 v43, v43
	v_mul_f32_e32 v39, v35, v38
	v_add_f32_e32 v43, 1.0, v43
	v_rcp_f32_e32 v35, v47
	v_mul_f32_e32 v47, 0xbfb8aa3b, v49
	v_exp_f32_e32 v47, v47
	v_mul_f32_e32 v35, v40, v35
	v_add_f32_e32 v44, 1.0, v47
	v_rcp_f32_e32 v38, v43
	v_mul_f32_e32 v43, 0xbfb8aa3b, v45
	v_exp_f32_e32 v43, v43
	v_mul_f32_e32 v40, v36, v38
	v_add_f32_e32 v43, 1.0, v43
	v_rcp_f32_e32 v36, v44
	s_nop 0
	v_mul_f32_e32 v36, v41, v36
	v_mul_f32_e32 v30, 0xbfb8aa3b, v30
	v_exp_f32_e32 v30, v30
; __device__ __forceinline__ float sigmoidf_(float x) { return 1.f / (1.f + __expf(-x)); }
; __device__ __forceinline__ pg8::u32x4 pack8(const f32x4 a, const f32x4 b) { pg8::u32x4 w; w.x = pg8::cvt_pk_bf16(a[0], a[1]); w.y = pg8::cvt_pk_bf16(a[2], a[3]); w.z = pg8::cvt_pk_bf16(b[0], b[1]); w.w = pg8::cvt_pk_bf16(b[2], b[3]); return w; }
;     __device__ __forceinline__ void operator()(const f32x4 (&acc)[2][2][4][2], const pg8::Unit& u, int wr, int wc, int fr, int fq) const {
; #pragma unroll
;         for (int ai = 0; ai < 2; ++ai)
; #pragma unroll
;             for (int m = 0; m < 4; ++m) {
;                 const int row = u.pm * 256 + ai * 128 + wr * 64 + m * 16 + fr, col = u.pn * 128 + wc * 32 + 8 * fq;
;                 f32x4 a, b;
; #pragma unroll
;                 for (int q = 0; q < 4; ++q) { a[q] = acc[ai][0][m][0][q] * sigmoidf_(acc[ai][1][m][0][q]); b[q] = acc[ai][0][m][1][q] * sigmoidf_(acc[ai][1][m][1][q]); }
;                 *(pg8::u32x4*)(OCp + (size_t)row * 256 + col) = pack8(a, b);
;             }
;     }
	v_rcp_f32_e32 v38, v43
	s_nop 0
	v_mul_f32_e32 v37, v37, v38
	v_add_f32_e32 v30, 1.0, v30
	v_add_u32_e32 v38, 0x90, v126
	v_cvt_pk_bf16_f32 v34, v46, v34
	v_cvt_pk_bf16_f32 v35, v35, v36
	v_cvt_pk_bf16_f32 v36, v42, v39
	v_cvt_pk_bf16_f32 v37, v40, v37
	v_ashrrev_i32_e32 v39, 31, v38
	v_lshlrev_b64 v[38:39], 9, v[38:39]
	v_lshl_add_u64 v[38:39], s[10:11], 0, v[38:39]
	v_mul_f32_e32 v26, 0xbfb8aa3b, v26
	v_lshl_add_u64 v[38:39], v[38:39], 0, v[114:115]
	v_exp_f32_e32 v26, v26
	global_store_dwordx4 v[38:39], v[34:37], off
	v_mul_f32_e32 v31, 0xbfb8aa3b, v31
	v_exp_f32_e32 v31, v31
	v_add_f32_e32 v26, 1.0, v26
	v_rcp_f32_e32 v30, v30
	s_nop 0
	v_mul_f32_e32 v30, v22, v30
	v_add_f32_e32 v31, 1.0, v31
	v_mul_f32_e32 v27, 0xbfb8aa3b, v27
	v_rcp_f32_e32 v22, v26
	v_exp_f32_e32 v27, v27
	v_mul_f32_e32 v26, v18, v22
	v_add_f32_e32 v27, 1.0, v27
	v_rcp_f32_e32 v18, v31
	v_mul_f32_e32 v31, 0xbfb8aa3b, v32
	v_exp_f32_e32 v31, v31
	v_mul_f32_e32 v18, v23, v18
	v_add_f32_e32 v31, 1.0, v31
	v_rcp_f32_e32 v22, v27
	v_mul_f32_e32 v27, 0xbfb8aa3b, v28
	v_exp_f32_e32 v27, v27
	v_mul_f32_e32 v23, v19, v22
	v_add_f32_e32 v27, 1.0, v27
	v_rcp_f32_e32 v19, v31
	v_mul_f32_e32 v31, 0xbfb8aa3b, v33
	v_exp_f32_e32 v31, v31
	v_mul_f32_e32 v19, v24, v19
	v_add_f32_e32 v28, 1.0, v31
	v_rcp_f32_e32 v22, v27
	v_mul_f32_e32 v27, 0xbfb8aa3b, v29
	v_exp_f32_e32 v27, v27
	v_mul_f32_e32 v24, v20, v22
	v_add_f32_e32 v27, 1.0, v27
	v_rcp_f32_e32 v20, v28
	s_nop 0
	v_mul_f32_e32 v20, v25, v20
	v_mul_f32_e32 v14, 0xbfb8aa3b, v14
	v_exp_f32_e32 v14, v14
	v_rcp_f32_e32 v22, v27
	s_nop 0
	v_mul_f32_e32 v21, v21, v22
	v_add_f32_e32 v14, 1.0, v14
	v_add_u32_e32 v22, 0xa0, v126
	v_cvt_pk_bf16_f32 v18, v30, v18
	v_cvt_pk_bf16_f32 v19, v19, v20
	v_cvt_pk_bf16_f32 v20, v26, v23
	v_cvt_pk_bf16_f32 v21, v24, v21
	v_ashrrev_i32_e32 v23, 31, v22
	v_lshlrev_b64 v[22:23], 9, v[22:23]
	v_lshl_add_u64 v[22:23], s[10:11], 0, v[22:23]
	v_mul_f32_e32 v10, 0xbfb8aa3b, v10
	v_lshl_add_u64 v[22:23], v[22:23], 0, v[114:115]
	v_exp_f32_e32 v10, v10
	global_store_dwordx4 v[22:23], v[18:21], off
	v_mul_f32_e32 v15, 0xbfb8aa3b, v15
	v_exp_f32_e32 v15, v15
	v_add_f32_e32 v10, 1.0, v10
	v_rcp_f32_e32 v14, v14
	s_nop 0
	v_mul_f32_e32 v14, v6, v14
	v_add_f32_e32 v15, 1.0, v15
	v_mul_f32_e32 v11, 0xbfb8aa3b, v11
	v_rcp_f32_e32 v6, v10
	v_exp_f32_e32 v11, v11
	v_mul_f32_e32 v10, v2, v6
	v_add_f32_e32 v11, 1.0, v11
	v_rcp_f32_e32 v2, v15
	v_mul_f32_e32 v15, 0xbfb8aa3b, v16
	v_exp_f32_e32 v15, v15
	v_mul_f32_e32 v2, v7, v2
	v_add_f32_e32 v15, 1.0, v15
	v_rcp_f32_e32 v6, v11
	v_mul_f32_e32 v11, 0xbfb8aa3b, v12
	v_exp_f32_e32 v11, v11
	v_mul_f32_e32 v7, v3, v6
	v_add_f32_e32 v11, 1.0, v11
	v_rcp_f32_e32 v3, v15
	v_mul_f32_e32 v15, 0xbfb8aa3b, v17
	v_exp_f32_e32 v15, v15
	v_mul_f32_e32 v3, v8, v3
	v_add_f32_e32 v12, 1.0, v15
	v_rcp_f32_e32 v6, v11
	v_mul_f32_e32 v11, 0xbfb8aa3b, v13
	v_exp_f32_e32 v11, v11
	v_mul_f32_e32 v8, v4, v6
	v_add_f32_e32 v11, 1.0, v11
	v_rcp_f32_e32 v4, v12
	s_nop 0
	v_mul_f32_e32 v4, v9, v4
	v_rcp_f32_e32 v6, v11
	s_nop 0
	v_mul_f32_e32 v5, v5, v6
	v_add_u32_e32 v6, 0xb0, v126
	v_cvt_pk_bf16_f32 v2, v14, v2
	v_cvt_pk_bf16_f32 v3, v3, v4
	v_cvt_pk_bf16_f32 v4, v10, v7
	v_ashrrev_i32_e32 v7, 31, v6
	v_lshlrev_b64 v[6:7], 9, v[6:7]
	v_lshl_add_u64 v[6:7], s[10:11], 0, v[6:7]
	v_lshl_add_u64 v[6:7], v[6:7], 0, v[114:115]
	s_andn2_b64 vcc, exec, s[24:25]
	s_mov_b64 s[24:25], -1
	v_cvt_pk_bf16_f32 v5, v8, v5
	global_store_dwordx4 v[6:7], v[2:5], off
	s_cbranch_vccnz .LBB0_1265
	s_andn2_b64 vcc, exec, s[8:9]
	s_cbranch_vccnz .LBB0_1264
	s_barrier
	s_branch .LBB0_1264

; template <class Epi, class Sched>
; __device__ __forceinline__ void gemm_phase(LAS unsigned char* lds, const Sched& S, const Epi& E) {
;     ...
; #pragma unroll
;         for (int a = 0; a < 2; ++a)
; #pragma unroll
;             for (int b = 0; b < 2; ++b)
; #pragma unroll
;                 for (int m = 0; m < 4; ++m)
; #pragma unroll
;                     for (int n = 0; n < 2; ++n) acc[a][b][m][n] = (f32x4){0.f, 0.f, 0.f, 0.f};
.LBB0_1352:
	s_and_b64 s[30:31], s[28:29], exec
	s_cselect_b32 s36, s25, s11
	s_cselect_b32 s37, s24, s10
	s_cselect_b32 s89, s27, s9
	s_cselect_b32 s91, s26, s8
	s_ashr_i32 s7, s6, 31
	s_add_i32 s92, s5, -2
	s_lshl_b64 s[30:31], s[6:7], 7
	s_add_u32 s7, s8, 0x100
	s_addc_u32 s93, s9, 0
	v_mad_u64_u32 v[2:3], s[34:35], s6, v131, v[130:131]
	s_add_u32 s8, s10, 0x80
	s_addc_u32 s9, s11, 0
	v_mad_u64_u32 v[4:5], s[10:11], v152, s6, v[134:135]
	v_mov_b32_e32 v3, v133
	v_mov_b32_e32 v5, v133
	v_lshl_add_u64 v[138:139], s[30:31], 0, v[2:3]
	v_mov_b32_e32 v2, 0
	v_lshl_add_u64 v[136:137], s[30:31], 0, v[4:5]
	s_mov_b32 s10, 0
	v_mov_b32_e32 v3, 0
	v_mov_b64_e32 v[4:5], 0
	v_mov_b64_e32 v[6:7], 0
	v_mov_b64_e32 v[8:9], 0
	v_mov_b64_e32 v[10:11], 0
	v_mov_b64_e32 v[12:13], 0
	v_mov_b64_e32 v[14:15], 0
	v_mov_b64_e32 v[16:17], 0
	v_mov_b64_e32 v[18:19], 0
	v_mov_b64_e32 v[20:21], 0
	v_mov_b64_e32 v[22:23], 0
	v_mov_b64_e32 v[24:25], 0
	v_mov_b64_e32 v[26:27], 0
	v_mov_b64_e32 v[28:29], 0
	v_mov_b64_e32 v[30:31], 0
	v_mov_b64_e32 v[32:33], 0
	v_mov_b64_e32 v[34:35], 0
	v_mov_b64_e32 v[36:37], 0
	v_mov_b64_e32 v[38:39], 0
	v_mov_b64_e32 v[40:41], 0
	v_mov_b64_e32 v[42:43], 0
	v_mov_b64_e32 v[44:45], 0
	v_mov_b64_e32 v[46:47], 0
	v_mov_b64_e32 v[48:49], 0
	v_mov_b64_e32 v[50:51], 0
	v_mov_b64_e32 v[52:53], 0
	v_mov_b64_e32 v[54:55], 0
	v_mov_b64_e32 v[56:57], 0
	v_mov_b64_e32 v[58:59], 0
	v_mov_b64_e32 v[60:61], 0
	v_mov_b64_e32 v[62:63], 0
	v_mov_b64_e32 v[64:65], 0
	v_mov_b64_e32 v[66:67], 0
	v_mov_b64_e32 v[68:69], 0
	v_mov_b64_e32 v[70:71], 0
	v_mov_b64_e32 v[72:73], 0
	v_mov_b64_e32 v[74:75], 0
	v_mov_b64_e32 v[76:77], 0
	v_mov_b64_e32 v[78:79], 0
	v_mov_b64_e32 v[80:81], 0
	v_mov_b64_e32 v[82:83], 0
	v_mov_b64_e32 v[84:85], 0
	v_mov_b64_e32 v[86:87], 0
	v_mov_b64_e32 v[88:89], 0
	v_mov_b64_e32 v[90:91], 0
	v_mov_b64_e32 v[92:93], 0
	v_mov_b64_e32 v[94:95], 0
	v_mov_b64_e32 v[96:97], 0
	v_mov_b64_e32 v[98:99], 0
	v_mov_b64_e32 v[100:101], 0
	v_mov_b64_e32 v[102:103], 0
	v_mov_b64_e32 v[104:105], 0
	v_mov_b64_e32 v[106:107], 0
	v_mov_b64_e32 v[108:109], 0
	v_mov_b64_e32 v[110:111], 0
	v_mov_b64_e32 v[112:113], 0
	v_mov_b64_e32 v[114:115], 0
	v_mov_b64_e32 v[116:117], 0
	v_mov_b64_e32 v[118:119], 0
	v_mov_b64_e32 v[120:121], 0
	v_mov_b64_e32 v[122:123], 0
	v_mov_b64_e32 v[124:125], 0
	v_mov_b64_e32 v[126:127], 0
	v_mov_b64_e32 v[128:129], 0

; template <class Epi, class Sched>
; __device__ __forceinline__ void gemm_phase(LAS unsigned char* lds, const Sched& S, const Epi& E) {
;     ...
; #pragma unroll
;         for (int a = 0; a < 2; ++a)
; #pragma unroll
;             for (int b = 0; b < 2; ++b)
; #pragma unroll
;                 for (int m = 0; m < 4; ++m)
; #pragma unroll
;                     for (int n = 0; n < 2; ++n) acc[a][b][m][n] = (f32x4){0.f, 0.f, 0.f, 0.f};
.LBB0_1554:
	v_mov_b32_e32 v2, 0
	s_mov_b32 s10, s42
	s_mov_b32 s16, s48
	s_mov_b64 s[56:57], s[50:51]
	s_mov_b64 s[18:19], s[46:47]
	v_mov_b32_e32 v3, 0
	v_mov_b64_e32 v[4:5], 0
	v_mov_b64_e32 v[6:7], 0
	v_mov_b64_e32 v[8:9], 0
	v_mov_b64_e32 v[10:11], 0
	v_mov_b64_e32 v[12:13], 0
	v_mov_b64_e32 v[14:15], 0
	v_mov_b64_e32 v[16:17], 0
	v_mov_b64_e32 v[18:19], 0
	v_mov_b64_e32 v[20:21], 0
	v_mov_b64_e32 v[22:23], 0
	v_mov_b64_e32 v[24:25], 0
	v_mov_b64_e32 v[26:27], 0
	v_mov_b64_e32 v[28:29], 0
	v_mov_b64_e32 v[30:31], 0
	v_mov_b64_e32 v[32:33], 0
	v_mov_b64_e32 v[34:35], 0
	v_mov_b64_e32 v[36:37], 0
	v_mov_b64_e32 v[38:39], 0
	v_mov_b64_e32 v[40:41], 0
	v_mov_b64_e32 v[42:43], 0
	v_mov_b64_e32 v[44:45], 0
	v_mov_b64_e32 v[46:47], 0
	v_mov_b64_e32 v[48:49], 0
	v_mov_b64_e32 v[50:51], 0
	v_mov_b64_e32 v[52:53], 0
	v_mov_b64_e32 v[54:55], 0
	v_mov_b64_e32 v[56:57], 0
	v_mov_b64_e32 v[58:59], 0
	v_mov_b64_e32 v[60:61], 0
	v_mov_b64_e32 v[62:63], 0
	v_mov_b64_e32 v[64:65], 0
	v_mov_b64_e32 v[66:67], 0
	v_mov_b64_e32 v[68:69], 0
	v_mov_b64_e32 v[70:71], 0
	v_mov_b64_e32 v[72:73], 0
	v_mov_b64_e32 v[74:75], 0
	v_mov_b64_e32 v[76:77], 0
	v_mov_b64_e32 v[78:79], 0
	v_mov_b64_e32 v[80:81], 0
	v_mov_b64_e32 v[82:83], 0
	v_mov_b64_e32 v[84:85], 0
	v_mov_b64_e32 v[86:87], 0
	v_mov_b64_e32 v[88:89], 0
	v_mov_b64_e32 v[90:91], 0
	v_mov_b64_e32 v[92:93], 0
	v_mov_b64_e32 v[94:95], 0
	v_mov_b64_e32 v[96:97], 0
	v_mov_b64_e32 v[98:99], 0
	v_mov_b64_e32 v[100:101], 0
	v_mov_b64_e32 v[102:103], 0
	v_mov_b64_e32 v[104:105], 0
	v_mov_b64_e32 v[106:107], 0
	v_mov_b64_e32 v[108:109], 0
	v_mov_b64_e32 v[110:111], 0
	v_mov_b64_e32 v[112:113], 0
	v_mov_b64_e32 v[114:115], 0
	v_mov_b64_e32 v[116:117], 0
	v_mov_b64_e32 v[118:119], 0
	v_mov_b64_e32 v[120:121], 0
	v_mov_b64_e32 v[122:123], 0
	v_mov_b64_e32 v[124:125], 0
	v_mov_b64_e32 v[126:127], 0
	v_mov_b64_e32 v[128:129], 0
	s_mov_b32 s92, s93

; template <class Epi, class Sched>
; __device__ __forceinline__ void gemm_phase(LAS unsigned char* lds, const Sched& S, const Epi& E) {
;     ...
; #pragma unroll
;         for (int a = 0; a < 2; ++a)
; #pragma unroll
;             for (int b = 0; b < 2; ++b)
; #pragma unroll
;                 for (int m = 0; m < 4; ++m)
; #pragma unroll
;                     for (int n = 0; n < 2; ++n) acc[a][b][m][n] = (f32x4){0.f, 0.f, 0.f, 0.f};
.LBB0_1808:
	s_add_u32 s19, s30, 0x100
	s_addc_u32 s21, s31, 0
	s_add_u32 s28, s28, 0x100080
	v_mov_b32_e32 v2, 0
	s_addc_u32 s29, s29, 0
	s_mov_b32 s64, -2
	v_mov_b32_e32 v3, 0
	v_mov_b64_e32 v[4:5], 0
	v_mov_b64_e32 v[6:7], 0
	v_mov_b64_e32 v[8:9], 0
	v_mov_b64_e32 v[10:11], 0
	v_mov_b64_e32 v[12:13], 0
	v_mov_b64_e32 v[14:15], 0
	v_mov_b64_e32 v[16:17], 0
	v_mov_b64_e32 v[18:19], 0
	v_mov_b64_e32 v[20:21], 0
	v_mov_b64_e32 v[22:23], 0
	v_mov_b64_e32 v[24:25], 0
	v_mov_b64_e32 v[26:27], 0
	v_mov_b64_e32 v[28:29], 0
	v_mov_b64_e32 v[30:31], 0
	v_mov_b64_e32 v[32:33], 0
	v_mov_b64_e32 v[34:35], 0
	v_mov_b64_e32 v[36:37], 0
	v_mov_b64_e32 v[38:39], 0
	v_mov_b64_e32 v[40:41], 0
	v_mov_b64_e32 v[42:43], 0
	v_mov_b64_e32 v[44:45], 0
	v_mov_b64_e32 v[46:47], 0
	v_mov_b64_e32 v[48:49], 0
	v_mov_b64_e32 v[50:51], 0
	v_mov_b64_e32 v[52:53], 0
	v_mov_b64_e32 v[54:55], 0
	v_mov_b64_e32 v[56:57], 0
	v_mov_b64_e32 v[58:59], 0
	v_mov_b64_e32 v[60:61], 0
	v_mov_b64_e32 v[62:63], 0
	v_mov_b64_e32 v[64:65], 0
	v_mov_b64_e32 v[66:67], 0
	v_mov_b64_e32 v[68:69], 0
	v_mov_b64_e32 v[70:71], 0
	v_mov_b64_e32 v[72:73], 0
	v_mov_b64_e32 v[74:75], 0
	v_mov_b64_e32 v[76:77], 0
	v_mov_b64_e32 v[78:79], 0
	v_mov_b64_e32 v[80:81], 0
	v_mov_b64_e32 v[82:83], 0
	v_mov_b64_e32 v[84:85], 0
	v_mov_b64_e32 v[86:87], 0
	v_mov_b64_e32 v[88:89], 0
	v_mov_b64_e32 v[90:91], 0
	v_mov_b64_e32 v[92:93], 0
	v_mov_b64_e32 v[94:95], 0
	v_mov_b64_e32 v[96:97], 0
	v_mov_b64_e32 v[98:99], 0
	v_mov_b64_e32 v[100:101], 0
	v_mov_b64_e32 v[102:103], 0
	v_mov_b64_e32 v[104:105], 0
	v_mov_b64_e32 v[106:107], 0
	v_mov_b64_e32 v[108:109], 0
	v_mov_b64_e32 v[110:111], 0
	v_mov_b64_e32 v[112:113], 0
	v_mov_b64_e32 v[114:115], 0
	v_mov_b64_e32 v[116:117], 0
	v_mov_b64_e32 v[118:119], 0
	v_mov_b64_e32 v[120:121], 0
	v_mov_b64_e32 v[122:123], 0
	v_mov_b64_e32 v[124:125], 0
	v_mov_b64_e32 v[126:127], 0
	v_mov_b64_e32 v[128:129], 0

; template <class Epi, class Sched>
; __device__ __forceinline__ void gemm_phase(LAS unsigned char* lds, const Sched& S, const Epi& E) {
;     ...
; #pragma unroll
;         for (int a = 0; a < 2; ++a)
; #pragma unroll
;             for (int b = 0; b < 2; ++b)
; #pragma unroll
;                 for (int m = 0; m < 4; ++m)
; #pragma unroll
;                     for (int n = 0; n < 2; ++n) acc[a][b][m][n] = (f32x4){0.f, 0.f, 0.f, 0.f};
.LBB0_1845:
	s_and_b64 s[36:37], s[28:29], exec
	s_cselect_b32 s38, s25, s31
	s_cselect_b32 s39, s24, s30
	s_cselect_b32 s75, s27, s35
	s_cselect_b32 s76, s26, s34
	s_add_i32 s77, s5, -2
	s_add_u32 s78, s34, 0x100
	s_addc_u32 s79, s35, 0
	s_add_u32 s30, s30, 0x100080
	v_mov_b32_e32 v2, 0
	s_addc_u32 s31, s31, 0
	s_mov_b32 s34, 0
	v_mov_b32_e32 v3, 0
	v_mov_b64_e32 v[4:5], 0
	v_mov_b64_e32 v[6:7], 0
	v_mov_b64_e32 v[8:9], 0
	v_mov_b64_e32 v[10:11], 0
	v_mov_b64_e32 v[12:13], 0
	v_mov_b64_e32 v[14:15], 0
	v_mov_b64_e32 v[16:17], 0
	v_mov_b64_e32 v[18:19], 0
	v_mov_b64_e32 v[20:21], 0
	v_mov_b64_e32 v[22:23], 0
	v_mov_b64_e32 v[24:25], 0
	v_mov_b64_e32 v[26:27], 0
	v_mov_b64_e32 v[28:29], 0
	v_mov_b64_e32 v[30:31], 0
	v_mov_b64_e32 v[32:33], 0
	v_mov_b64_e32 v[34:35], 0
	v_mov_b64_e32 v[36:37], 0
	v_mov_b64_e32 v[38:39], 0
	v_mov_b64_e32 v[40:41], 0
	v_mov_b64_e32 v[42:43], 0
	v_mov_b64_e32 v[44:45], 0
	v_mov_b64_e32 v[46:47], 0
	v_mov_b64_e32 v[48:49], 0
	v_mov_b64_e32 v[50:51], 0
	v_mov_b64_e32 v[52:53], 0
	v_mov_b64_e32 v[54:55], 0
	v_mov_b64_e32 v[56:57], 0
	v_mov_b64_e32 v[58:59], 0
	v_mov_b64_e32 v[60:61], 0
	v_mov_b64_e32 v[62:63], 0
	v_mov_b64_e32 v[64:65], 0
	v_mov_b64_e32 v[66:67], 0
	v_mov_b64_e32 v[68:69], 0
	v_mov_b64_e32 v[70:71], 0
	v_mov_b64_e32 v[72:73], 0
	v_mov_b64_e32 v[74:75], 0
	v_mov_b64_e32 v[76:77], 0
	v_mov_b64_e32 v[78:79], 0
	v_mov_b64_e32 v[80:81], 0
	v_mov_b64_e32 v[82:83], 0
	v_mov_b64_e32 v[84:85], 0
	v_mov_b64_e32 v[86:87], 0
	v_mov_b64_e32 v[88:89], 0
	v_mov_b64_e32 v[90:91], 0
	v_mov_b64_e32 v[92:93], 0
	v_mov_b64_e32 v[94:95], 0
	v_mov_b64_e32 v[96:97], 0
	v_mov_b64_e32 v[98:99], 0
	v_mov_b64_e32 v[100:101], 0
	v_mov_b64_e32 v[102:103], 0
	v_mov_b64_e32 v[104:105], 0
	v_mov_b64_e32 v[106:107], 0
	v_mov_b64_e32 v[108:109], 0
	v_mov_b64_e32 v[110:111], 0
	v_mov_b64_e32 v[112:113], 0
	v_mov_b64_e32 v[114:115], 0
	v_mov_b64_e32 v[116:117], 0
	v_mov_b64_e32 v[118:119], 0
	v_mov_b64_e32 v[120:121], 0
	v_mov_b64_e32 v[122:123], 0
	v_mov_b64_e32 v[124:125], 0
	v_mov_b64_e32 v[126:127], 0
	v_mov_b64_e32 v[128:129], 0

; template <class Epi, class Sched>
; __device__ __forceinline__ void gemm_phase(LAS unsigned char* lds, const Sched& S, const Epi& E) {
;     ...
; #pragma unroll
;         for (int a = 0; a < 2; ++a)
; #pragma unroll
;             for (int b = 0; b < 2; ++b)
; #pragma unroll
;                 for (int m = 0; m < 4; ++m)
; #pragma unroll
;                     for (int n = 0; n < 2; ++n) acc[a][b][m][n] = (f32x4){0.f, 0.f, 0.f, 0.f};
.LBB0_2128:
	s_and_b64 s[30:31], s[4:5], exec
	s_cselect_b32 s23, s15, s27
	s_cselect_b32 s25, s14, s26
	s_cselect_b32 s52, s17, s29
	s_cselect_b32 s53, s16, s28
	s_add_u32 s54, s28, 0x100
	s_addc_u32 s55, s29, 0
	s_add_u32 s26, s26, 0x40080
	v_mov_b32_e32 v2, 0
	s_addc_u32 s27, s27, 0
	s_mov_b32 s56, -2
	v_mov_b32_e32 v3, 0
	v_mov_b64_e32 v[4:5], 0
	v_mov_b64_e32 v[6:7], 0
	v_mov_b64_e32 v[8:9], 0
	v_mov_b64_e32 v[10:11], 0
	v_mov_b64_e32 v[12:13], 0
	v_mov_b64_e32 v[14:15], 0
	v_mov_b64_e32 v[16:17], 0
	v_mov_b64_e32 v[18:19], 0
	v_mov_b64_e32 v[20:21], 0
	v_mov_b64_e32 v[22:23], 0
	v_mov_b64_e32 v[24:25], 0
	v_mov_b64_e32 v[26:27], 0
	v_mov_b64_e32 v[28:29], 0
	v_mov_b64_e32 v[30:31], 0
	v_mov_b64_e32 v[32:33], 0
	v_mov_b64_e32 v[34:35], 0
	v_mov_b64_e32 v[36:37], 0
	v_mov_b64_e32 v[38:39], 0
	v_mov_b64_e32 v[40:41], 0
	v_mov_b64_e32 v[42:43], 0
	v_mov_b64_e32 v[44:45], 0
	v_mov_b64_e32 v[46:47], 0
	v_mov_b64_e32 v[48:49], 0
	v_mov_b64_e32 v[50:51], 0
	v_mov_b64_e32 v[52:53], 0
	v_mov_b64_e32 v[54:55], 0
	v_mov_b64_e32 v[56:57], 0
	v_mov_b64_e32 v[58:59], 0
	v_mov_b64_e32 v[60:61], 0
	v_mov_b64_e32 v[62:63], 0
	v_mov_b64_e32 v[64:65], 0
	v_mov_b64_e32 v[66:67], 0
	v_mov_b64_e32 v[68:69], 0
	v_mov_b64_e32 v[70:71], 0
	v_mov_b64_e32 v[72:73], 0
	v_mov_b64_e32 v[74:75], 0
	v_mov_b64_e32 v[76:77], 0
	v_mov_b64_e32 v[78:79], 0
	v_mov_b64_e32 v[80:81], 0
	v_mov_b64_e32 v[82:83], 0
	v_mov_b64_e32 v[84:85], 0
	v_mov_b64_e32 v[86:87], 0
	v_mov_b64_e32 v[88:89], 0
	v_mov_b64_e32 v[90:91], 0
	v_mov_b64_e32 v[92:93], 0
	v_mov_b64_e32 v[94:95], 0
	v_mov_b64_e32 v[96:97], 0
	v_mov_b64_e32 v[98:99], 0
	v_mov_b64_e32 v[100:101], 0
	v_mov_b64_e32 v[102:103], 0
	v_mov_b64_e32 v[104:105], 0
	v_mov_b64_e32 v[106:107], 0
	v_mov_b64_e32 v[108:109], 0
	v_mov_b64_e32 v[110:111], 0
	v_mov_b64_e32 v[112:113], 0
	v_mov_b64_e32 v[114:115], 0
	v_mov_b64_e32 v[116:117], 0
	v_mov_b64_e32 v[118:119], 0
	v_mov_b64_e32 v[120:121], 0
	v_mov_b64_e32 v[122:123], 0
	v_mov_b64_e32 v[124:125], 0
	v_mov_b64_e32 v[126:127], 0
	v_mov_b64_e32 v[128:129], 0

; #define LAS __attribute__((address_space(3)))
; __device__ __forceinline__ void ret_tile_gen(const LAS char* sm, int r32, int hi, int vrd, int buf, int kp0, int qpos, float lgf, float lgb, const bf16x8 (&qf)[4], fa::f32x16& o0, fa::f32x16& o1) {
;     using namespace fa;
;     const LAS char* kb = sm + buf + r32 * KP_R + 16 * hi;
;     f32x16 p0, p1;
; #pragma unroll
;     for (int r = 0; r < 16; ++r) { p0[r] = 0.f; p1[r] = 0.f; }
; #pragma unroll
;     for (int st = 0; st < 4; ++st) {
;         const bf16x8 k0 = *(const LAS bf16x8*)(kb + 32 * st), k1 = *(const LAS bf16x8*)(kb + 32 * KP_R + 32 * st);
;         p0 = __builtin_amdgcn_mfma_f32_32x32x16_bf16(k0, qf[st], p0, 0, 0, 0);
;         p1 = __builtin_amdgcn_mfma_f32_32x32x16_bf16(k1, qf[st], p1, 0, 0, 0);
;     }
;     int d0 = qpos - kp0 - 4 * hi;
;     asm volatile("" : "+v"(d0) : "v"(p0[15]), "v"(p1[15]));
; #pragma unroll
;     for (int r = 0; r < 16; ++r) {
;         const float f0 = (float)(d0 - ((r & 3) + 8 * (r >> 2))), f1 = f0 - 32.f;
;         const float w0 = __builtin_amdgcn_exp2f(lgf * fmaxf(f0, 0.f) + lgb * fmaxf(-f0, 0.f)) * (2.f - fminf(fabsf(f0), 1.f));
;         const float w1 = __builtin_amdgcn_exp2f(lgf * fmaxf(f1, 0.f) + lgb * fmaxf(-f1, 0.f)) * (2.f - fminf(fabsf(f1), 1.f));
;         p0[r] *= w0; p1[r] *= w1;
;     }
;     bf16x8 pf[4]; pf[0] = pack_p(p0, 0); pf[1] = pack_p(p0, 8); pf[2] = pack_p(p1, 0); pf[3] = pack_p(p1, 8);
;     pv_tile(o0, o1, sm + buf + vrd, pf);
; __device__ __forceinline__ void ph_ret_chunk(unsigned char* lds_, bf16_t* Z, const bf16_t* KVF, const bf16_t* KVB, const float* decay_logit, const float* gn_w, int with_ctx, int u0, int ustep, unsigned* kvc, unsigned* barw) { PH_IDS;
;     ...
;                 ST_PUT(1); ST_PUTB(2);
;     ...
;             } else {
;                 ST_PUT(0); ST_PUT(3);
;                 ST_STEP(kf, 0, g128f); ST_PUT(1);
;                 sa = (f32x4){0.f, 0.f, 0.f, 0.f}; sb = sa; ST_STEP(kb, 1, g128b); ST_PUT(2);
;             }
;     ...
;         }
;         __syncthreads();
;         u32x2 gtv[8]; f32x4 gwv[8];
; #pragma unroll
;         for (int g = 0; g < 4; ++g)
; #pragma unroll
;             for (int blk = 0; blk < 2; ++blk) { const int d = blk * 32 + 8 * g + 4 * hi; gtv[2 * g + blk] = *(const u32x2*)(zq + C_RG + h * 64 + d); gwv[2 * g + blk] = *(const f32x4*)(gn_w + h * 64 + d); }
.LBB0_2730:
	s_ashr_i32 s4, s42, 8
	s_mul_i32 s5, s4, 0x8800
	v_mul_u32_u24_e32 v70, 0x90, v79
	s_add_i32 s9, s5, 0
	s_waitcnt vmcnt(0)
	v_cvt_pk_bf16_f32 v2, v90, v91
	v_cvt_pk_bf16_f32 v3, v88, v89
	v_cvt_pk_bf16_f32 v4, v106, v107
	v_cvt_pk_bf16_f32 v5, v92, v93
	ds_write_b128 v124, v[2:5] offset:9216
	v_cvt_pk_bf16_f32 v2, v110, v111
	v_cvt_pk_bf16_f32 v3, v108, v109
	v_cvt_pk_bf16_f32 v4, v114, v115
	v_cvt_pk_bf16_f32 v5, v112, v113
	v_add3_u32 v71, s9, v70, v78
	ds_write_b128 v124, v[2:5] offset:18432
	s_waitcnt lgkmcnt(0)
	s_barrier
	ds_read_b128 v[2:5], v71
	ds_read_b128 v[34:37], v71 offset:32
	ds_read_b128 v[18:21], v71 offset:4608
	ds_read_b128 v[38:41], v71 offset:4640
	s_waitcnt lgkmcnt(3)
	v_mfma_f32_32x32x16_bf16 v[2:17], v[2:5], v[66:69], 0
	s_lshl_b32 s6, s4, 7
	s_mulk_i32 s4, 0x2400
	s_add_i32 s7, s4, 0
	s_add_i32 s8, s7, 0x11000
	s_add_i32 s7, s7, 0x15800
	s_lshl_b32 s4, s39, 2
	s_add_u32 s4, s20, s4
	s_waitcnt lgkmcnt(1)
	v_mfma_f32_32x32x16_bf16 v[18:33], v[18:21], v[66:69], 0
	s_addc_u32 s5, s21, 0
	v_lshlrev_b32_e32 v48, 8, v122
	v_lshlrev_b32_e32 v50, 1, v123
	v_mul_i32_i24_e32 v51, -4, v122
	v_and_b32_e32 v49, 0xc0, v83
	v_mfma_f32_32x32x16_bf16 v[2:17], v[34:37], v[102:105], v[2:17]
	ds_read_b128 v[34:37], v71 offset:64
	s_waitcnt lgkmcnt(1)
	v_mfma_f32_32x32x16_bf16 v[18:33], v[38:41], v[102:105], v[18:33]
	ds_read_b128 v[38:41], v71 offset:4672
	ds_read_b128 v[42:45], v71 offset:96
	global_load_dwordx4 v[126:129], v78, s[4:5] offset:1024
	global_load_dwordx4 v[114:117], v78, s[4:5] offset:1056
	s_waitcnt lgkmcnt(2)
	v_mfma_f32_32x32x16_bf16 v[2:17], v[34:37], v[98:101], v[2:17]
	v_lshlrev_b32_e32 v34, 3, v122
	v_mov_b32_e32 v35, v130
	v_lshl_add_u64 v[46:47], v[80:81], 0, v[34:35]
	ds_read_b128 v[34:37], v71 offset:4704
	global_load_dwordx4 v[136:139], v78, s[4:5] offset:1152
	global_load_dwordx4 v[122:125], v78, s[4:5] offset:1184
	global_load_dwordx2 v[146:147], v[46:47], off offset:3392
	global_load_dwordx2 v[150:151], v[46:47], off offset:3408
	global_load_dwordx2 v[154:155], v[46:47], off offset:3424
	global_load_dwordx2 v[158:159], v[46:47], off offset:3440
	global_load_dwordx4 v[118:121], v78, s[4:5] offset:1088
	global_load_dwordx4 v[110:113], v78, s[4:5] offset:1120
	global_load_dwordx2 v[148:149], v[46:47], off offset:3456
	global_load_dwordx2 v[152:153], v[46:47], off offset:3472
	global_load_dwordx2 v[156:157], v[46:47], off offset:3488
	global_load_dwordx2 v[144:145], v[46:47], off offset:3504
	global_load_dwordx4 v[132:135], v78, s[4:5] offset:1216
	global_load_dwordx4 v[106:109], v78, s[4:5] offset:1248
	s_add_i32 s4, s6, s38
	s_waitcnt lgkmcnt(2)
	v_mfma_f32_32x32x16_bf16 v[18:33], v[38:41], v[98:101], v[18:33]
	s_waitcnt lgkmcnt(0)
	v_mfma_f32_32x32x16_bf16 v[18:33], v[34:37], v[94:97], v[18:33]
	v_subrev_u32_e32 v34, s4, v51
	v_add_u32_e32 v72, v34, v131
	v_mov_b32_e32 v35, v72
	v_and_b32_e32 v34, 24, v82
	v_and_or_b32 v34, v50, 32, v34
	v_or3_b32 v34, v48, v49, v34
	v_add_u32_e32 v73, s9, v34
	v_mfma_f32_32x32x16_bf16 v[2:17], v[42:45], v[94:97], v[2:17]
	s_nop 0
	v_cvt_f32_i32_e32 v38, v35
	v_max_f32_e32 v36, 0, v38
	v_max_f32_e64 v37, -v38, 0
	v_pk_mul_f32 v[36:37], v[142:143], v[36:37]
	v_add_f32_e32 v39, 0xc2000000, v38
	v_add_f32_e32 v36, v36, v37
	v_exp_f32_e32 v36, v36
	v_min_f32_e64 v37, |v38|, 1.0
	v_sub_f32_e32 v37, 2.0, v37
	v_mul_f32_e32 v38, v37, v36
	v_max_f32_e32 v36, 0, v39
	v_max_f32_e64 v37, -v39, 0
	v_pk_mul_f32 v[36:37], v[142:143], v[36:37]
	s_nop 0
	v_add_f32_e32 v36, v36, v37
	v_min_f32_e64 v37, |v39|, 1.0
	v_add_u32_e32 v39, -1, v35
	v_exp_f32_e32 v36, v36
	v_cvt_f32_i32_e32 v40, v39
	v_sub_f32_e32 v37, 2.0, v37
	v_mul_f32_e32 v37, v37, v36
	v_mul_f32_e32 v36, v2, v38
	v_max_f32_e32 v38, 0, v40
	v_max_f32_e64 v39, -v40, 0
	v_pk_mul_f32 v[38:39], v[142:143], v[38:39]
	v_mul_f32_e32 v2, v18, v37
	v_add_f32_e32 v18, v38, v39
	v_exp_f32_e32 v18, v18
	v_min_f32_e64 v38, |v40|, 1.0
	v_add_f32_e32 v37, 0xc2000000, v40
	v_sub_f32_e32 v38, 2.0, v38
	v_mul_f32_e32 v18, v38, v18
	v_max_f32_e32 v38, 0, v37
	v_max_f32_e64 v39, -v37, 0
	v_pk_mul_f32 v[38:39], v[142:143], v[38:39]
	v_min_f32_e64 v37, |v37|, 1.0
	v_add_f32_e32 v38, v38, v39
	v_add_u32_e32 v39, -2, v35
	v_exp_f32_e32 v38, v38
	v_cvt_f32_i32_e32 v40, v39
	v_sub_f32_e32 v37, 2.0, v37
	v_mul_f32_e32 v18, v3, v18
	v_mul_f32_e32 v37, v37, v38
	v_max_f32_e32 v38, 0, v40
	v_max_f32_e64 v39, -v40, 0
	v_pk_mul_f32 v[38:39], v[142:143], v[38:39]
	v_mul_f32_e32 v3, v19, v37
	v_add_f32_e32 v19, v38, v39
	v_exp_f32_e32 v19, v19
	v_min_f32_e64 v38, |v40|, 1.0
	v_add_f32_e32 v37, 0xc2000000, v40
	v_sub_f32_e32 v38, 2.0, v38
	v_mul_f32_e32 v19, v38, v19
	v_max_f32_e32 v38, 0, v37
	v_max_f32_e64 v39, -v37, 0
	v_pk_mul_f32 v[38:39], v[142:143], v[38:39]
	v_min_f32_e64 v37, |v37|, 1.0
	v_add_f32_e32 v38, v38, v39
	v_add_u32_e32 v39, -3, v35
	v_exp_f32_e32 v38, v38
	v_cvt_f32_i32_e32 v40, v39
	v_sub_f32_e32 v37, 2.0, v37
	v_mul_f32_e32 v19, v4, v19
	v_mul_f32_e32 v37, v37, v38
	v_max_f32_e32 v38, 0, v40
	v_max_f32_e64 v39, -v40, 0
	v_pk_mul_f32 v[38:39], v[142:143], v[38:39]
	v_mul_f32_e32 v4, v20, v37
	v_add_f32_e32 v20, v38, v39
	v_exp_f32_e32 v20, v20
	v_min_f32_e64 v38, |v40|, 1.0
	v_add_f32_e32 v37, 0xc2000000, v40
	v_sub_f32_e32 v38, 2.0, v38
	v_mul_f32_e32 v20, v38, v20
	v_max_f32_e32 v38, 0, v37
	v_max_f32_e64 v39, -v37, 0
	v_pk_mul_f32 v[38:39], v[142:143], v[38:39]
	v_min_f32_e64 v37, |v37|, 1.0
	v_add_f32_e32 v38, v38, v39
	v_add_u32_e32 v39, -8, v35
	v_exp_f32_e32 v38, v38
	v_cvt_f32_i32_e32 v40, v39
	v_sub_f32_e32 v37, 2.0, v37
	v_mul_f32_e32 v20, v5, v20
	v_mul_f32_e32 v37, v37, v38
	v_max_f32_e32 v38, 0, v40
; __device__ __forceinline__ void ret_tile_gen(const LAS char* sm, int r32, int hi, int vrd, int buf, int kp0, int qpos, float lgf, float lgb, const bf16x8 (&qf)[4], fa::f32x16& o0, fa::f32x16& o1) {
;     ...
;     int d0 = qpos - kp0 - 4 * hi;
;     asm volatile("" : "+v"(d0) : "v"(p0[15]), "v"(p1[15]));
; #pragma unroll
;     for (int r = 0; r < 16; ++r) {
;         const float f0 = (float)(d0 - ((r & 3) + 8 * (r >> 2))), f1 = f0 - 32.f;
;         const float w0 = __builtin_amdgcn_exp2f(lgf * fmaxf(f0, 0.f) + lgb * fmaxf(-f0, 0.f)) * (2.f - fminf(fabsf(f0), 1.f));
;         const float w1 = __builtin_amdgcn_exp2f(lgf * fmaxf(f1, 0.f) + lgb * fmaxf(-f1, 0.f)) * (2.f - fminf(fabsf(f1), 1.f));
;         p0[r] *= w0; p1[r] *= w1;
;     }
	v_max_f32_e64 v39, -v40, 0
	v_pk_mul_f32 v[38:39], v[142:143], v[38:39]
	v_mul_f32_e32 v5, v21, v37
	v_add_f32_e32 v21, v38, v39
	v_exp_f32_e32 v21, v21
	v_min_f32_e64 v38, |v40|, 1.0
	v_add_f32_e32 v37, 0xc2000000, v40
	v_sub_f32_e32 v38, 2.0, v38
	v_mul_f32_e32 v21, v38, v21
	v_max_f32_e32 v38, 0, v37
	v_max_f32_e64 v39, -v37, 0
	v_pk_mul_f32 v[38:39], v[142:143], v[38:39]
	v_min_f32_e64 v37, |v37|, 1.0
	v_add_f32_e32 v38, v38, v39
	v_add_u32_e32 v39, -9, v35
	v_exp_f32_e32 v38, v38
	v_cvt_f32_i32_e32 v40, v39
	v_sub_f32_e32 v37, 2.0, v37
	v_mul_f32_e32 v21, v6, v21
	v_mul_f32_e32 v37, v37, v38
	v_max_f32_e32 v38, 0, v40
	v_max_f32_e64 v39, -v40, 0
	v_pk_mul_f32 v[38:39], v[142:143], v[38:39]
	v_mul_f32_e32 v6, v22, v37
	v_add_f32_e32 v22, v38, v39
	v_exp_f32_e32 v22, v22
	v_min_f32_e64 v38, |v40|, 1.0
	v_add_f32_e32 v37, 0xc2000000, v40
	v_sub_f32_e32 v38, 2.0, v38
	v_mul_f32_e32 v22, v38, v22
	v_max_f32_e32 v38, 0, v37
	v_max_f32_e64 v39, -v37, 0
	v_pk_mul_f32 v[38:39], v[142:143], v[38:39]
	v_min_f32_e64 v37, |v37|, 1.0
	v_add_f32_e32 v38, v38, v39
	v_add_u32_e32 v39, -10, v35
	v_exp_f32_e32 v38, v38
	v_cvt_f32_i32_e32 v40, v39
	v_sub_f32_e32 v37, 2.0, v37
	v_mul_f32_e32 v22, v7, v22
	v_mul_f32_e32 v37, v37, v38
	v_max_f32_e32 v38, 0, v40
	v_max_f32_e64 v39, -v40, 0
	v_pk_mul_f32 v[38:39], v[142:143], v[38:39]
	v_mul_f32_e32 v7, v23, v37
	v_add_f32_e32 v23, v38, v39
	v_exp_f32_e32 v23, v23
	v_min_f32_e64 v38, |v40|, 1.0
	v_add_f32_e32 v37, 0xc2000000, v40
	v_sub_f32_e32 v38, 2.0, v38
	v_mul_f32_e32 v23, v38, v23
	v_max_f32_e32 v38, 0, v37
	v_max_f32_e64 v39, -v37, 0
	v_pk_mul_f32 v[38:39], v[142:143], v[38:39]
	v_min_f32_e64 v37, |v37|, 1.0
	v_add_f32_e32 v38, v38, v39
	v_add_u32_e32 v39, -11, v35
	v_exp_f32_e32 v38, v38
	v_cvt_f32_i32_e32 v40, v39
	v_sub_f32_e32 v37, 2.0, v37
	v_mul_f32_e32 v23, v8, v23
	v_mul_f32_e32 v37, v37, v38
	v_max_f32_e32 v38, 0, v40
	v_max_f32_e64 v39, -v40, 0
	v_pk_mul_f32 v[38:39], v[142:143], v[38:39]
	v_mul_f32_e32 v24, v24, v37
	v_add_f32_e32 v8, v38, v39
	v_exp_f32_e32 v8, v8
	v_min_f32_e64 v38, |v40|, 1.0
	v_add_f32_e32 v37, 0xc2000000, v40
	v_sub_f32_e32 v38, 2.0, v38
	v_mul_f32_e32 v8, v38, v8
	v_max_f32_e32 v38, 0, v37
	v_max_f32_e64 v39, -v37, 0
	v_pk_mul_f32 v[38:39], v[142:143], v[38:39]
	v_min_f32_e64 v37, |v37|, 1.0
	v_add_f32_e32 v38, v38, v39
	v_add_u32_e32 v39, -16, v35
	v_exp_f32_e32 v38, v38
	v_cvt_f32_i32_e32 v39, v39
	v_sub_f32_e32 v37, 2.0, v37
	v_cvt_pk_bf16_f32 v18, v36, v18
	v_mul_f32_e32 v37, v37, v38
	v_mul_f32_e32 v38, v9, v8
	v_max_f32_e32 v8, 0, v39
	v_max_f32_e64 v9, -v39, 0
	v_pk_mul_f32 v[8:9], v[142:143], v[8:9]
	v_mul_f32_e32 v25, v25, v37
	v_add_f32_e32 v8, v8, v9
	v_exp_f32_e32 v8, v8
	v_min_f32_e64 v9, |v39|, 1.0
	v_add_f32_e32 v37, 0xc2000000, v39
	v_sub_f32_e32 v9, 2.0, v9
	v_mul_f32_e32 v39, v9, v8
	v_max_f32_e32 v8, 0, v37
	v_max_f32_e64 v9, -v37, 0
	v_pk_mul_f32 v[8:9], v[142:143], v[8:9]
	v_mul_f32_e32 v10, v10, v39
	v_add_f32_e32 v8, v8, v9
	v_exp_f32_e32 v8, v8
	v_min_f32_e64 v9, |v37|, 1.0
	v_subrev_u32_e32 v37, 17, v35
	v_cvt_f32_i32_e32 v37, v37
	v_sub_f32_e32 v9, 2.0, v9
	v_mul_f32_e32 v8, v9, v8
	v_mul_f32_e32 v26, v26, v8
	v_max_f32_e32 v8, 0, v37
	v_max_f32_e64 v9, -v37, 0
	v_pk_mul_f32 v[8:9], v[142:143], v[8:9]
	v_add_f32_e32 v39, 0xc2000000, v37
	v_add_f32_e32 v8, v8, v9
	v_exp_f32_e32 v8, v8
	v_min_f32_e64 v9, |v37|, 1.0
	v_sub_f32_e32 v9, 2.0, v9
	v_cvt_pk_bf16_f32 v19, v19, v20
	v_mul_f32_e32 v37, v9, v8
	v_max_f32_e32 v8, 0, v39
	v_max_f32_e64 v9, -v39, 0
	v_pk_mul_f32 v[8:9], v[142:143], v[8:9]
	v_mul_f32_e32 v11, v11, v37
	v_add_f32_e32 v8, v8, v9
	v_exp_f32_e32 v8, v8
	v_min_f32_e64 v9, |v39|, 1.0
	v_subrev_u32_e32 v39, 18, v35
	v_cvt_f32_i32_e32 v39, v39
	v_sub_f32_e32 v9, 2.0, v9
	v_mul_f32_e32 v8, v9, v8
	v_mul_f32_e32 v27, v27, v8
	v_max_f32_e32 v8, 0, v39
	v_max_f32_e64 v9, -v39, 0
	v_pk_mul_f32 v[8:9], v[142:143], v[8:9]
	v_add_f32_e32 v37, 0xc2000000, v39
	v_add_f32_e32 v8, v8, v9
	v_exp_f32_e32 v8, v8
	v_min_f32_e64 v9, |v39|, 1.0
	v_sub_f32_e32 v9, 2.0, v9
	v_cvt_pk_bf16_f32 v20, v21, v22
	v_mul_f32_e32 v39, v9, v8
	v_max_f32_e32 v8, 0, v37
	v_max_f32_e64 v9, -v37, 0
	v_pk_mul_f32 v[8:9], v[142:143], v[8:9]
	v_mul_f32_e32 v12, v12, v39
	v_add_f32_e32 v8, v8, v9
	v_exp_f32_e32 v8, v8
	v_min_f32_e64 v9, |v37|, 1.0
	v_subrev_u32_e32 v37, 19, v35
	v_cvt_f32_i32_e32 v37, v37
	v_sub_f32_e32 v9, 2.0, v9
	v_mul_f32_e32 v8, v9, v8
	v_mul_f32_e32 v28, v28, v8
	v_max_f32_e32 v8, 0, v37
	v_max_f32_e64 v9, -v37, 0
	v_pk_mul_f32 v[8:9], v[142:143], v[8:9]
	v_add_f32_e32 v39, 0xc2000000, v37
	v_add_f32_e32 v8, v8, v9
	v_exp_f32_e32 v8, v8
	v_min_f32_e64 v9, |v37|, 1.0
	v_sub_f32_e32 v9, 2.0, v9
	v_cvt_pk_bf16_f32 v21, v23, v38
	v_mul_f32_e32 v37, v9, v8
	v_max_f32_e32 v8, 0, v39
	v_max_f32_e64 v9, -v39, 0
	v_pk_mul_f32 v[8:9], v[142:143], v[8:9]
	v_mul_f32_e32 v13, v13, v37
	v_add_f32_e32 v8, v8, v9
	v_exp_f32_e32 v8, v8
	v_min_f32_e64 v9, |v39|, 1.0
	v_subrev_u32_e32 v39, 24, v35
	v_cvt_f32_i32_e32 v39, v39
	v_sub_f32_e32 v9, 2.0, v9
	v_mul_f32_e32 v8, v9, v8
	v_mul_f32_e32 v29, v29, v8
	v_max_f32_e32 v8, 0, v39
	v_max_f32_e64 v9, -v39, 0
	v_pk_mul_f32 v[8:9], v[142:143], v[8:9]
	v_add_f32_e32 v37, 0xc2000000, v39
	v_add_f32_e32 v8, v8, v9
	v_exp_f32_e32 v8, v8
	v_min_f32_e64 v9, |v39|, 1.0
	v_sub_f32_e32 v9, 2.0, v9
	v_cvt_pk_bf16_f32 v36, v10, v11
	v_mul_f32_e32 v39, v9, v8
	v_max_f32_e32 v8, 0, v37
	v_max_f32_e64 v9, -v37, 0
	v_pk_mul_f32 v[8:9], v[142:143], v[8:9]
	v_mul_f32_e32 v14, v14, v39
	v_add_f32_e32 v8, v8, v9
	v_exp_f32_e32 v8, v8
	v_min_f32_e64 v9, |v37|, 1.0
	v_subrev_u32_e32 v37, 25, v35
	v_cvt_f32_i32_e32 v37, v37
; __device__ __forceinline__ bf16x8 pack_p(const f32x16& p, int base) { u32x4 w; w.x = pk2(p[base], p[base + 1]); w.y = pk2(p[base + 2], p[base + 3]); w.z = pk2(p[base + 4], p[base + 5]); w.w = pk2(p[base + 6], p[base + 7]); return __builtin_bit_cast(bf16x8, w); }
; __device__ __forceinline__ void ret_tile_gen(const LAS char* sm, int r32, int hi, int vrd, int buf, int kp0, int qpos, float lgf, float lgb, const bf16x8 (&qf)[4], fa::f32x16& o0, fa::f32x16& o1) {
;     ...
;     int d0 = qpos - kp0 - 4 * hi;
;     asm volatile("" : "+v"(d0) : "v"(p0[15]), "v"(p1[15]));
; #pragma unroll
;     for (int r = 0; r < 16; ++r) {
;         const float f0 = (float)(d0 - ((r & 3) + 8 * (r >> 2))), f1 = f0 - 32.f;
;         const float w0 = __builtin_amdgcn_exp2f(lgf * fmaxf(f0, 0.f) + lgb * fmaxf(-f0, 0.f)) * (2.f - fminf(fabsf(f0), 1.f));
;         const float w1 = __builtin_amdgcn_exp2f(lgf * fmaxf(f1, 0.f) + lgb * fmaxf(-f1, 0.f)) * (2.f - fminf(fabsf(f1), 1.f));
;         p0[r] *= w0; p1[r] *= w1;
;     }
;     bf16x8 pf[4]; pf[0] = pack_p(p0, 0); pf[1] = pack_p(p0, 8); pf[2] = pack_p(p1, 0); pf[3] = pack_p(p1, 8);
;     pv_tile(o0, o1, sm + buf + vrd, pf);
	v_sub_f32_e32 v9, 2.0, v9
	v_mul_f32_e32 v8, v9, v8
	v_mul_f32_e32 v30, v30, v8
	v_max_f32_e32 v8, 0, v37
	v_max_f32_e64 v9, -v37, 0
	v_pk_mul_f32 v[8:9], v[142:143], v[8:9]
	v_add_f32_e32 v39, 0xc2000000, v37
	v_add_f32_e32 v8, v8, v9
	v_exp_f32_e32 v8, v8
	v_min_f32_e64 v9, |v37|, 1.0
	v_sub_f32_e32 v9, 2.0, v9
	v_mul_f32_e32 v37, v9, v8
	v_max_f32_e32 v8, 0, v39
	v_max_f32_e64 v9, -v39, 0
	v_pk_mul_f32 v[8:9], v[142:143], v[8:9]
	v_mul_f32_e32 v15, v15, v37
	v_add_f32_e32 v8, v8, v9
	v_exp_f32_e32 v8, v8
	v_min_f32_e64 v9, |v39|, 1.0
	v_subrev_u32_e32 v39, 26, v35
	v_cvt_f32_i32_e32 v39, v39
	v_sub_f32_e32 v9, 2.0, v9
	v_mul_f32_e32 v8, v9, v8
	v_mul_f32_e32 v31, v31, v8
	v_max_f32_e32 v8, 0, v39
	v_max_f32_e64 v9, -v39, 0
	v_pk_mul_f32 v[8:9], v[142:143], v[8:9]
	v_add_f32_e32 v37, 0xc2000000, v39
	v_add_f32_e32 v8, v8, v9
	v_exp_f32_e32 v8, v8
	v_min_f32_e64 v9, |v39|, 1.0
	v_sub_f32_e32 v9, 2.0, v9
	v_subrev_u32_e32 v35, 27, v35
	v_mul_f32_e32 v39, v9, v8
	v_max_f32_e32 v8, 0, v37
	v_max_f32_e64 v9, -v37, 0
	v_pk_mul_f32 v[8:9], v[142:143], v[8:9]
	v_cvt_f32_i32_e32 v35, v35
	v_add_f32_e32 v8, v8, v9
	v_exp_f32_e32 v8, v8
	v_min_f32_e64 v9, |v37|, 1.0
	v_sub_f32_e32 v9, 2.0, v9
	v_mul_f32_e32 v16, v16, v39
	v_mul_f32_e32 v8, v9, v8
	v_mul_f32_e32 v32, v32, v8
	v_max_f32_e32 v8, 0, v35
	v_max_f32_e64 v9, -v35, 0
	v_pk_mul_f32 v[8:9], v[142:143], v[8:9]
	v_add_f32_e32 v37, 0xc2000000, v35
	v_add_f32_e32 v8, v8, v9
	v_exp_f32_e32 v39, v8
	v_min_f32_e64 v8, |v35|, 1.0
	v_sub_f32_e32 v35, 2.0, v8
	v_max_f32_e32 v8, 0, v37
	v_max_f32_e64 v9, -v37, 0
	v_pk_mul_f32 v[8:9], v[142:143], v[8:9]
	s_nop 0
	v_add_f32_e32 v8, v8, v9
	v_exp_f32_e32 v8, v8
	v_mul_f32_e32 v9, v35, v39
	v_min_f32_e64 v35, |v37|, 1.0
	v_sub_f32_e32 v35, 2.0, v35
	v_mul_f32_e32 v8, v35, v8
	v_mul_f32_e32 v9, v17, v9
	v_mul_f32_e32 v8, v33, v8
	v_cvt_pk_bf16_f32 v37, v12, v13
	v_cvt_pk_bf16_f32 v38, v14, v15
	v_cvt_pk_bf16_f32 v39, v16, v9
	v_cvt_pk_bf16_f32 v40, v2, v3
	v_cvt_pk_bf16_f32 v41, v4, v5
	v_cvt_pk_bf16_f32 v42, v6, v7
	v_cvt_pk_bf16_f32 v43, v24, v25
	v_cvt_pk_bf16_f32 v44, v26, v27
	v_cvt_pk_bf16_f32 v45, v28, v29
	v_cvt_pk_bf16_f32 v46, v30, v31
	v_cvt_pk_bf16_f32 v47, v32, v8
	ds_read_b64_tr_b16 v[2:3], v73 offset:9216
	ds_read_b64_tr_b16 v[4:5], v73 offset:9728
	ds_read_b64_tr_b16 v[48:49], v73 offset:10240
	ds_read_b64_tr_b16 v[50:51], v73 offset:10752
	s_waitcnt lgkmcnt(2)
	v_mfma_f32_32x32x16_bf16 v[2:17], v[2:5], v[18:21], 0
	ds_read_b64_tr_b16 v[22:23], v73 offset:13312
	ds_read_b64_tr_b16 v[24:25], v73 offset:13824
	ds_read_b64_tr_b16 v[52:53], v73 offset:14336
	ds_read_b64_tr_b16 v[54:55], v73 offset:14848
	s_waitcnt lgkmcnt(2)
	v_mfma_f32_32x32x16_bf16 v[18:33], v[22:25], v[18:21], 0
	v_mfma_f32_32x32x16_bf16 v[2:17], v[48:51], v[36:39], v[2:17]
	s_waitcnt lgkmcnt(0)
	v_mfma_f32_32x32x16_bf16 v[18:33], v[52:55], v[36:39], v[18:33]
	ds_read_b64_tr_b16 v[34:35], v73 offset:11264
	ds_read_b64_tr_b16 v[36:37], v73 offset:11776
	ds_read_b64_tr_b16 v[48:49], v73 offset:12288
	ds_read_b64_tr_b16 v[50:51], v73 offset:12800
	s_waitcnt lgkmcnt(2)
	v_mfma_f32_32x32x16_bf16 v[2:17], v[34:37], v[40:43], v[2:17]
	ds_read_b64_tr_b16 v[34:35], v73 offset:15360
	ds_read_b64_tr_b16 v[36:37], v73 offset:15872
	ds_read_b64_tr_b16 v[52:53], v73 offset:16384
	ds_read_b64_tr_b16 v[54:55], v73 offset:16896
	s_waitcnt lgkmcnt(2)
	v_mfma_f32_32x32x16_bf16 v[18:33], v[34:37], v[40:43], v[18:33]
	v_mfma_f32_32x32x16_bf16 v[2:17], v[48:51], v[44:47], v[2:17]
	s_waitcnt lgkmcnt(0)
	v_mfma_f32_32x32x16_bf16 v[18:33], v[52:55], v[44:47], v[18:33]
	ds_read_b128 v[34:37], v71 offset:17408
	ds_read_b128 v[74:77], v71 offset:17440
	ds_read_b128 v[50:53], v71 offset:22016
	ds_read_b128 v[80:83], v71 offset:22048
	s_waitcnt lgkmcnt(3)
	v_mfma_f32_32x32x16_bf16 v[34:49], v[34:37], v[66:69], 0
	s_waitcnt lgkmcnt(1)
	v_mfma_f32_32x32x16_bf16 v[50:65], v[50:53], v[66:69], 0
	v_mfma_f32_32x32x16_bf16 v[34:49], v[74:77], v[102:105], v[34:49]
	s_waitcnt lgkmcnt(0)
	v_mfma_f32_32x32x16_bf16 v[50:65], v[80:83], v[102:105], v[50:65]
	ds_read_b128 v[74:77], v71 offset:17472
	ds_read_b128 v[80:83], v71 offset:17504
	s_waitcnt lgkmcnt(1)
	v_mfma_f32_32x32x16_bf16 v[34:49], v[74:77], v[98:101], v[34:49]
	ds_read_b128 v[74:77], v71 offset:22080
	ds_read_b128 v[84:87], v71 offset:22112
	v_subrev_u32_e32 v71, 64, v72
	s_waitcnt lgkmcnt(1)
	v_mfma_f32_32x32x16_bf16 v[50:65], v[74:77], v[98:101], v[50:65]
	v_mfma_f32_32x32x16_bf16 v[34:49], v[80:83], v[94:97], v[34:49]
	s_waitcnt lgkmcnt(0)
; __device__ __forceinline__ void ret_tile_gen(const LAS char* sm, int r32, int hi, int vrd, int buf, int kp0, int qpos, float lgf, float lgb, const bf16x8 (&qf)[4], fa::f32x16& o0, fa::f32x16& o1) {
;     ...
;     int d0 = qpos - kp0 - 4 * hi;
;     asm volatile("" : "+v"(d0) : "v"(p0[15]), "v"(p1[15]));
; #pragma unroll
;     for (int r = 0; r < 16; ++r) {
;         const float f0 = (float)(d0 - ((r & 3) + 8 * (r >> 2))), f1 = f0 - 32.f;
;         const float w0 = __builtin_amdgcn_exp2f(lgf * fmaxf(f0, 0.f) + lgb * fmaxf(-f0, 0.f)) * (2.f - fminf(fabsf(f0), 1.f));
;         const float w1 = __builtin_amdgcn_exp2f(lgf * fmaxf(f1, 0.f) + lgb * fmaxf(-f1, 0.f)) * (2.f - fminf(fabsf(f1), 1.f));
;         p0[r] *= w0; p1[r] *= w1;
;     }
	v_mfma_f32_32x32x16_bf16 v[50:65], v[84:87], v[94:97], v[50:65]
	s_nop 0
	v_cvt_f32_i32_e32 v72, v71
	v_max_f32_e32 v74, 0, v72
	v_max_f32_e64 v75, -v72, 0
	v_pk_mul_f32 v[74:75], v[142:143], v[74:75]
	v_add_f32_e32 v76, 0xc2000000, v72
	v_add_f32_e32 v74, v74, v75
	v_exp_f32_e32 v74, v74
	v_min_f32_e64 v72, |v72|, 1.0
	v_sub_f32_e32 v72, 2.0, v72
	v_max_f32_e64 v75, -v76, 0
	v_mul_f32_e32 v72, v72, v74
	v_max_f32_e32 v74, 0, v76
	v_pk_mul_f32 v[74:75], v[142:143], v[74:75]
	v_mul_f32_e32 v72, v34, v72
	v_add_f32_e32 v74, v74, v75
	v_exp_f32_e32 v74, v74
	v_min_f32_e64 v75, |v76|, 1.0
	v_add_u32_e32 v76, -1, v71
	v_cvt_f32_i32_e32 v76, v76
	v_sub_f32_e32 v75, 2.0, v75
	v_mul_f32_e32 v74, v75, v74
	v_mul_f32_e32 v50, v50, v74
	v_max_f32_e32 v74, 0, v76
	v_max_f32_e64 v75, -v76, 0
	v_pk_mul_f32 v[74:75], v[142:143], v[74:75]
	v_add_f32_e32 v77, 0xc2000000, v76
	v_add_f32_e32 v34, v74, v75
	v_exp_f32_e32 v34, v34
	v_min_f32_e64 v74, |v76|, 1.0
	v_sub_f32_e32 v74, 2.0, v74
	v_max_f32_e64 v75, -v77, 0
	v_mul_f32_e32 v34, v74, v34
	v_max_f32_e32 v74, 0, v77
	v_pk_mul_f32 v[74:75], v[142:143], v[74:75]
	v_add_u32_e32 v76, -2, v71
	v_add_f32_e32 v74, v74, v75
	v_exp_f32_e32 v74, v74
	v_cvt_f32_i32_e32 v76, v76
	v_min_f32_e64 v75, |v77|, 1.0
	v_sub_f32_e32 v75, 2.0, v75
	v_mul_f32_e32 v74, v75, v74
	v_mul_f32_e32 v75, v35, v34
	v_max_f32_e32 v34, 0, v76
	v_max_f32_e64 v35, -v76, 0
	v_pk_mul_f32 v[34:35], v[142:143], v[34:35]
	v_mul_f32_e32 v51, v51, v74
	v_add_f32_e32 v34, v34, v35
	v_exp_f32_e32 v34, v34
	v_min_f32_e64 v35, |v76|, 1.0
	v_add_f32_e32 v74, 0xc2000000, v76
	v_sub_f32_e32 v35, 2.0, v35
	v_mul_f32_e32 v76, v35, v34
	v_max_f32_e32 v34, 0, v74
	v_max_f32_e64 v35, -v74, 0
	v_pk_mul_f32 v[34:35], v[142:143], v[34:35]
	v_mul_f32_e32 v36, v36, v76
	v_add_f32_e32 v34, v34, v35
	v_exp_f32_e32 v34, v34
	v_min_f32_e64 v35, |v74|, 1.0
	v_add_u32_e32 v74, -3, v71
	v_cvt_f32_i32_e32 v74, v74
	v_sub_f32_e32 v35, 2.0, v35
	v_mul_f32_e32 v34, v35, v34
	v_mul_f32_e32 v52, v52, v34
	v_max_f32_e32 v34, 0, v74
	v_max_f32_e64 v35, -v74, 0
	v_pk_mul_f32 v[34:35], v[142:143], v[34:35]
	v_add_f32_e32 v76, 0xc2000000, v74
	v_add_f32_e32 v34, v34, v35
	v_exp_f32_e32 v34, v34
	v_min_f32_e64 v35, |v74|, 1.0
	v_sub_f32_e32 v35, 2.0, v35
	v_mul_f32_e32 v74, v35, v34
	v_max_f32_e32 v34, 0, v76
	v_max_f32_e64 v35, -v76, 0
	v_pk_mul_f32 v[34:35], v[142:143], v[34:35]
	v_mul_f32_e32 v37, v37, v74
	v_add_f32_e32 v34, v34, v35
	v_exp_f32_e32 v34, v34
	v_min_f32_e64 v35, |v76|, 1.0
	v_add_u32_e32 v76, -8, v71
	v_cvt_f32_i32_e32 v76, v76
	v_sub_f32_e32 v35, 2.0, v35
	v_mul_f32_e32 v34, v35, v34
	v_mul_f32_e32 v53, v53, v34
	v_max_f32_e32 v34, 0, v76
	v_max_f32_e64 v35, -v76, 0
	v_pk_mul_f32 v[34:35], v[142:143], v[34:35]
	v_add_f32_e32 v74, 0xc2000000, v76
	v_add_f32_e32 v34, v34, v35
	v_exp_f32_e32 v34, v34
	v_min_f32_e64 v35, |v76|, 1.0
	v_sub_f32_e32 v35, 2.0, v35
	v_mul_f32_e32 v76, v35, v34
	v_max_f32_e32 v34, 0, v74
	v_max_f32_e64 v35, -v74, 0
	v_pk_mul_f32 v[34:35], v[142:143], v[34:35]
	v_mul_f32_e32 v38, v38, v76
	v_add_f32_e32 v34, v34, v35
	v_exp_f32_e32 v34, v34
	v_min_f32_e64 v35, |v74|, 1.0
	v_add_u32_e32 v74, -9, v71
	v_cvt_f32_i32_e32 v74, v74
	v_sub_f32_e32 v35, 2.0, v35
	v_mul_f32_e32 v34, v35, v34
	v_mul_f32_e32 v54, v54, v34
	v_max_f32_e32 v34, 0, v74
	v_max_f32_e64 v35, -v74, 0
	v_pk_mul_f32 v[34:35], v[142:143], v[34:35]
	v_add_f32_e32 v76, 0xc2000000, v74
	v_add_f32_e32 v34, v34, v35
	v_exp_f32_e32 v34, v34
	v_min_f32_e64 v35, |v74|, 1.0
	v_sub_f32_e32 v35, 2.0, v35
	v_mul_f32_e32 v74, v35, v34
	v_max_f32_e32 v34, 0, v76
	v_max_f32_e64 v35, -v76, 0
	v_pk_mul_f32 v[34:35], v[142:143], v[34:35]
	v_mul_f32_e32 v39, v39, v74
	v_add_f32_e32 v34, v34, v35
	v_exp_f32_e32 v34, v34
	v_min_f32_e64 v35, |v76|, 1.0
	v_add_u32_e32 v76, -10, v71
	v_cvt_f32_i32_e32 v76, v76
	v_sub_f32_e32 v35, 2.0, v35
	v_mul_f32_e32 v34, v35, v34
	v_mul_f32_e32 v55, v55, v34
	v_max_f32_e32 v34, 0, v76
	v_max_f32_e64 v35, -v76, 0
	v_pk_mul_f32 v[34:35], v[142:143], v[34:35]
	v_add_f32_e32 v74, 0xc2000000, v76
	v_add_f32_e32 v34, v34, v35
	v_exp_f32_e32 v34, v34
	v_min_f32_e64 v35, |v76|, 1.0
	v_sub_f32_e32 v35, 2.0, v35
	v_mul_f32_e32 v76, v35, v34
	v_max_f32_e32 v34, 0, v74
	v_max_f32_e64 v35, -v74, 0
	v_pk_mul_f32 v[34:35], v[142:143], v[34:35]
	v_mul_f32_e32 v40, v40, v76
	v_add_f32_e32 v34, v34, v35
	v_exp_f32_e32 v34, v34
	v_min_f32_e64 v35, |v74|, 1.0
	v_add_u32_e32 v74, -11, v71
	v_cvt_f32_i32_e32 v74, v74
	v_sub_f32_e32 v35, 2.0, v35
	v_mul_f32_e32 v34, v35, v34
	v_mul_f32_e32 v56, v56, v34
	v_max_f32_e32 v34, 0, v74
	v_max_f32_e64 v35, -v74, 0
	v_pk_mul_f32 v[34:35], v[142:143], v[34:35]
	v_add_f32_e32 v76, 0xc2000000, v74
	v_add_f32_e32 v34, v34, v35
	v_exp_f32_e32 v34, v34
	v_min_f32_e64 v35, |v74|, 1.0
	v_sub_f32_e32 v35, 2.0, v35
	v_mul_f32_e32 v74, v35, v34
	v_max_f32_e32 v34, 0, v76
	v_max_f32_e64 v35, -v76, 0
	v_pk_mul_f32 v[34:35], v[142:143], v[34:35]
	v_mul_f32_e32 v41, v41, v74
	v_add_f32_e32 v34, v34, v35
	v_exp_f32_e32 v34, v34
	v_min_f32_e64 v35, |v76|, 1.0
	v_add_u32_e32 v76, -16, v71
	v_cvt_f32_i32_e32 v76, v76
	v_sub_f32_e32 v35, 2.0, v35
	v_mul_f32_e32 v34, v35, v34
	v_mul_f32_e32 v57, v57, v34
	v_max_f32_e32 v34, 0, v76
	v_max_f32_e64 v35, -v76, 0
	v_pk_mul_f32 v[34:35], v[142:143], v[34:35]
	v_add_f32_e32 v74, 0xc2000000, v76
	v_add_f32_e32 v34, v34, v35
	v_exp_f32_e32 v34, v34
	v_min_f32_e64 v35, |v76|, 1.0
	v_sub_f32_e32 v35, 2.0, v35
	v_mul_f32_e32 v76, v35, v34
	v_max_f32_e32 v34, 0, v74
	v_max_f32_e64 v35, -v74, 0
	v_pk_mul_f32 v[34:35], v[142:143], v[34:35]
	v_mul_f32_e32 v42, v42, v76
	v_add_f32_e32 v34, v34, v35
	v_exp_f32_e32 v34, v34
; #define LAS __attribute__((address_space(3)))
; __device__ __forceinline__ s16x4 vtr(const LAS char* p) { return __builtin_bit_cast(s16x4, __builtin_amdgcn_ds_read_tr16_b64_v4i16((LAS s16x4*)p)); }
; __device__ __forceinline__ bf16x8 pack_p(const f32x16& p, int base) { u32x4 w; w.x = pk2(p[base], p[base + 1]); w.y = pk2(p[base + 2], p[base + 3]); w.z = pk2(p[base + 4], p[base + 5]); w.w = pk2(p[base + 6], p[base + 7]); return __builtin_bit_cast(bf16x8, w); }
; __device__ __forceinline__ void pv_tile(f32x16& o0, f32x16& o1, const LAS char* vb, const bf16x8 (&pf)[4]) {
; #pragma unroll
;     for (int ks = 0; ks < 4; ++ks) {
;         const s16x4 a0 = vtr(vb + ks * 1024), a1 = vtr(vb + ks * 1024 + 512), b0 = vtr(vb + 4096 + ks * 1024), b1 = vtr(vb + 4096 + ks * 1024 + 512);
;         const bf16x8 v0 = (bf16x8){a0[0], a0[1], a0[2], a0[3], a1[0], a1[1], a1[2], a1[3]}, v1 = (bf16x8){b0[0], b0[1], b0[2], b0[3], b1[0], b1[1], b1[2], b1[3]};
;         o0 = __builtin_amdgcn_mfma_f32_32x32x16_bf16(v0, pf[ks], o0, 0, 0, 0);
;         o1 = __builtin_amdgcn_mfma_f32_32x32x16_bf16(v1, pf[ks], o1, 0, 0, 0);
;     }
; }
; __device__ __forceinline__ void ret_tile_gen(const LAS char* sm, int r32, int hi, int vrd, int buf, int kp0, int qpos, float lgf, float lgb, const bf16x8 (&qf)[4], fa::f32x16& o0, fa::f32x16& o1) {
;     ...
;     for (int r = 0; r < 16; ++r) {
;         const float f0 = (float)(d0 - ((r & 3) + 8 * (r >> 2))), f1 = f0 - 32.f;
;         const float w0 = __builtin_amdgcn_exp2f(lgf * fmaxf(f0, 0.f) + lgb * fmaxf(-f0, 0.f)) * (2.f - fminf(fabsf(f0), 1.f));
;         const float w1 = __builtin_amdgcn_exp2f(lgf * fmaxf(f1, 0.f) + lgb * fmaxf(-f1, 0.f)) * (2.f - fminf(fabsf(f1), 1.f));
;         p0[r] *= w0; p1[r] *= w1;
;     }
;     bf16x8 pf[4]; pf[0] = pack_p(p0, 0); pf[1] = pack_p(p0, 8); pf[2] = pack_p(p1, 0); pf[3] = pack_p(p1, 8);
;     pv_tile(o0, o1, sm + buf + vrd, pf);
	v_min_f32_e64 v35, |v74|, 1.0
	v_subrev_u32_e32 v74, 17, v71
	v_cvt_f32_i32_e32 v74, v74
	v_sub_f32_e32 v35, 2.0, v35
	v_mul_f32_e32 v34, v35, v34
	v_mul_f32_e32 v58, v58, v34
	v_max_f32_e32 v34, 0, v74
	v_max_f32_e64 v35, -v74, 0
	v_pk_mul_f32 v[34:35], v[142:143], v[34:35]
	v_add_f32_e32 v76, 0xc2000000, v74
	v_add_f32_e32 v34, v34, v35
	v_exp_f32_e32 v34, v34
	v_min_f32_e64 v35, |v74|, 1.0
	v_sub_f32_e32 v35, 2.0, v35
	v_mul_f32_e32 v74, v35, v34
	v_max_f32_e32 v34, 0, v76
	v_max_f32_e64 v35, -v76, 0
	v_pk_mul_f32 v[34:35], v[142:143], v[34:35]
	v_mul_f32_e32 v43, v43, v74
	v_add_f32_e32 v34, v34, v35
	v_exp_f32_e32 v34, v34
	v_min_f32_e64 v35, |v76|, 1.0
	v_subrev_u32_e32 v76, 18, v71
	v_cvt_f32_i32_e32 v76, v76
	v_sub_f32_e32 v35, 2.0, v35
	v_mul_f32_e32 v34, v35, v34
	v_mul_f32_e32 v59, v59, v34
	v_max_f32_e32 v34, 0, v76
	v_max_f32_e64 v35, -v76, 0
	v_pk_mul_f32 v[34:35], v[142:143], v[34:35]
	v_add_f32_e32 v74, 0xc2000000, v76
	v_add_f32_e32 v34, v34, v35
	v_exp_f32_e32 v34, v34
	v_min_f32_e64 v35, |v76|, 1.0
	v_sub_f32_e32 v35, 2.0, v35
	v_mul_f32_e32 v76, v35, v34
	v_max_f32_e32 v34, 0, v74
	v_max_f32_e64 v35, -v74, 0
	v_pk_mul_f32 v[34:35], v[142:143], v[34:35]
	v_mul_f32_e32 v44, v44, v76
	v_add_f32_e32 v34, v34, v35
	v_exp_f32_e32 v34, v34
	v_min_f32_e64 v35, |v74|, 1.0
	v_subrev_u32_e32 v74, 19, v71
	v_cvt_f32_i32_e32 v74, v74
	v_sub_f32_e32 v35, 2.0, v35
	v_mul_f32_e32 v34, v35, v34
	v_mul_f32_e32 v60, v60, v34
	v_max_f32_e32 v34, 0, v74
	v_max_f32_e64 v35, -v74, 0
	v_pk_mul_f32 v[34:35], v[142:143], v[34:35]
	v_add_f32_e32 v76, 0xc2000000, v74
	v_add_f32_e32 v34, v34, v35
	v_exp_f32_e32 v34, v34
	v_min_f32_e64 v35, |v74|, 1.0
	v_sub_f32_e32 v35, 2.0, v35
	v_mul_f32_e32 v74, v35, v34
	v_max_f32_e32 v34, 0, v76
	v_max_f32_e64 v35, -v76, 0
	v_pk_mul_f32 v[34:35], v[142:143], v[34:35]
	v_mul_f32_e32 v45, v45, v74
	v_add_f32_e32 v34, v34, v35
	v_exp_f32_e32 v34, v34
	v_min_f32_e64 v35, |v76|, 1.0
	v_subrev_u32_e32 v76, 24, v71
	v_cvt_f32_i32_e32 v76, v76
	v_sub_f32_e32 v35, 2.0, v35
	v_mul_f32_e32 v34, v35, v34
	v_mul_f32_e32 v61, v61, v34
	v_max_f32_e32 v34, 0, v76
	v_max_f32_e64 v35, -v76, 0
	v_pk_mul_f32 v[34:35], v[142:143], v[34:35]
	v_add_f32_e32 v74, 0xc2000000, v76
	v_add_f32_e32 v34, v34, v35
	v_exp_f32_e32 v34, v34
	v_min_f32_e64 v35, |v76|, 1.0
	v_sub_f32_e32 v35, 2.0, v35
	v_mul_f32_e32 v76, v35, v34
	v_max_f32_e32 v34, 0, v74
	v_max_f32_e64 v35, -v74, 0
	v_pk_mul_f32 v[34:35], v[142:143], v[34:35]
	v_mul_f32_e32 v46, v46, v76
	v_add_f32_e32 v34, v34, v35
	v_exp_f32_e32 v34, v34
	v_min_f32_e64 v35, |v74|, 1.0
	v_subrev_u32_e32 v74, 25, v71
	v_cvt_f32_i32_e32 v74, v74
	v_sub_f32_e32 v35, 2.0, v35
	v_mul_f32_e32 v34, v35, v34
	v_mul_f32_e32 v62, v62, v34
	v_max_f32_e32 v34, 0, v74
	v_max_f32_e64 v35, -v74, 0
	v_pk_mul_f32 v[34:35], v[142:143], v[34:35]
	v_add_f32_e32 v76, 0xc2000000, v74
	v_add_f32_e32 v34, v34, v35
	v_exp_f32_e32 v34, v34
	v_min_f32_e64 v35, |v74|, 1.0
	v_sub_f32_e32 v35, 2.0, v35
	v_mul_f32_e32 v74, v35, v34
	v_max_f32_e32 v34, 0, v76
	v_max_f32_e64 v35, -v76, 0
	v_pk_mul_f32 v[34:35], v[142:143], v[34:35]
	v_mul_f32_e32 v47, v47, v74
	v_add_f32_e32 v34, v34, v35
	v_exp_f32_e32 v34, v34
	v_min_f32_e64 v35, |v76|, 1.0
	v_subrev_u32_e32 v76, 26, v71
	v_cvt_f32_i32_e32 v76, v76
	v_sub_f32_e32 v35, 2.0, v35
	v_mul_f32_e32 v34, v35, v34
	v_mul_f32_e32 v63, v63, v34
	v_max_f32_e32 v34, 0, v76
	v_max_f32_e64 v35, -v76, 0
	v_pk_mul_f32 v[34:35], v[142:143], v[34:35]
	v_add_f32_e32 v74, 0xc2000000, v76
	v_add_f32_e32 v34, v34, v35
	v_exp_f32_e32 v34, v34
	v_min_f32_e64 v35, |v76|, 1.0
	v_sub_f32_e32 v35, 2.0, v35
	v_subrev_u32_e32 v71, 27, v71
	v_mul_f32_e32 v76, v35, v34
	v_max_f32_e32 v34, 0, v74
	v_max_f32_e64 v35, -v74, 0
	v_pk_mul_f32 v[34:35], v[142:143], v[34:35]
	v_cvt_f32_i32_e32 v71, v71
	v_add_f32_e32 v34, v34, v35
	v_exp_f32_e32 v34, v34
	v_min_f32_e64 v35, |v74|, 1.0
	v_sub_f32_e32 v35, 2.0, v35
	v_mul_f32_e32 v48, v48, v76
	v_mul_f32_e32 v34, v35, v34
	v_mul_f32_e32 v64, v64, v34
	v_max_f32_e32 v34, 0, v71
	v_max_f32_e64 v35, -v71, 0
	v_pk_mul_f32 v[34:35], v[142:143], v[34:35]
	v_add_f32_e32 v74, 0xc2000000, v71
	v_add_f32_e32 v34, v34, v35
	v_exp_f32_e32 v76, v34
	v_min_f32_e64 v34, |v71|, 1.0
	v_sub_f32_e32 v71, 2.0, v34
	v_max_f32_e32 v34, 0, v74
	v_max_f32_e64 v35, -v74, 0
	v_pk_mul_f32 v[34:35], v[142:143], v[34:35]
	s_nop 0
	v_add_f32_e32 v34, v34, v35
	v_exp_f32_e32 v34, v34
	v_mul_f32_e32 v35, v71, v76
	v_min_f32_e64 v71, |v74|, 1.0
	v_sub_f32_e32 v71, 2.0, v71
	v_mul_f32_e32 v34, v71, v34
	v_mul_f32_e32 v49, v49, v35
	v_mul_f32_e32 v65, v65, v34
	v_cvt_pk_bf16_f32 v34, v72, v75
	v_cvt_pk_bf16_f32 v35, v36, v37
	v_cvt_pk_bf16_f32 v36, v38, v39
	v_cvt_pk_bf16_f32 v37, v40, v41
	v_cvt_pk_bf16_f32 v38, v42, v43
	v_cvt_pk_bf16_f32 v39, v44, v45
	v_cvt_pk_bf16_f32 v40, v46, v47
	v_cvt_pk_bf16_f32 v41, v48, v49
	v_cvt_pk_bf16_f32 v42, v50, v51
	v_cvt_pk_bf16_f32 v43, v52, v53
	v_cvt_pk_bf16_f32 v44, v54, v55
	v_cvt_pk_bf16_f32 v45, v56, v57
	v_cvt_pk_bf16_f32 v46, v58, v59
	v_cvt_pk_bf16_f32 v47, v60, v61
	v_cvt_pk_bf16_f32 v48, v62, v63
	v_cvt_pk_bf16_f32 v49, v64, v65
	ds_read_b64_tr_b16 v[50:51], v73 offset:26624
	ds_read_b64_tr_b16 v[52:53], v73 offset:27136
	ds_read_b64_tr_b16 v[54:55], v73 offset:27648
	ds_read_b64_tr_b16 v[56:57], v73 offset:28160
	s_waitcnt lgkmcnt(2)
	v_mfma_f32_32x32x16_bf16 v[2:17], v[50:53], v[34:37], v[2:17]
	ds_read_b64_tr_b16 v[50:51], v73 offset:30720
	ds_read_b64_tr_b16 v[52:53], v73 offset:31232
	ds_read_b64_tr_b16 v[58:59], v73 offset:31744
	ds_read_b64_tr_b16 v[60:61], v73 offset:32256
	s_waitcnt lgkmcnt(2)
; __device__ __forceinline__ float siluf_(float x) { return x * sigmoidf_(x); }
; __device__ __forceinline__ void ph_ret_chunk(unsigned char* lds_, bf16_t* Z, const bf16_t* KVF, const bf16_t* KVB, const float* decay_logit, const float* gn_w, int with_ctx, int u0, int ustep, unsigned* kvc, unsigned* barw) { PH_IDS;
;     ...
;         ret_tile_gen(sm, r32, hi, vrd, (2 * cl) * BUF_R, c0, qpos, lgf, lgb, qf, o0, o1);
;         __builtin_amdgcn_sched_barrier(0);
;         ret_tile_gen(sm, r32, hi, vrd, (2 * cl + 1) * BUF_R, c0 + 64, qpos, lgf, lgb, qf, o0, o1);
;         __builtin_amdgcn_sched_barrier(0);
;         { f32x16 p0, p1;
;           ret_qk(sm, r32, hi, ST_OFF + cl * ST_SZ, qf, p0, p1);
;           const float sf = __builtin_amdgcn_exp2f(lgf * (float)(qpos - c0 + 1));
; #pragma unroll
;           for (int r = 0; r < 16; ++r) { o0[r] += p0[r] * sf; o1[r] += p1[r] * sf; }
;           ret_qk(sm, r32, hi, ST_OFF + (2 + cl) * ST_SZ, qf, p0, p1);
;           const float sbk = __builtin_amdgcn_exp2f(lgb * (float)(c0 + 128 - qpos));
; #pragma unroll
;           for (int r = 0; r < 16; ++r) { o0[r] += p0[r] * sbk; o1[r] += p1[r] * sbk; } }
;         float s1 = 0.f;
; #pragma unroll
;         for (int r = 0; r < 16; ++r) s1 += o0[r] + o1[r];
;         s1 += __shfl_xor(s1, 32);
;         const float mu = s1 * (1.f / 64);
;         float s2 = 0.f;
; #pragma unroll
;         for (int r = 0; r < 16; ++r) { const float a = o0[r] - mu, c = o1[r] - mu; s2 += a * a + c * c; }
;         s2 += __shfl_xor(s2, 32);
;         const float rstd = rsqrtf(s2 * (1.f / 64) + EPS);
;         u32x2 wv[2][4];
; #pragma unroll
;         for (int g = 0; g < 4; ++g)
; #pragma unroll
;             for (int blk = 0; blk < 2; ++blk) {
;                 const int d = blk * 32 + 8 * g + 4 * hi;
;                 const u32x2 gt = gtv[2 * g + blk];
;                 const f32x4 gw = gwv[2 * g + blk];
;                 float y[4];
; #pragma unroll
;                 for (int q = 0; q < 4; ++q) { const float ov = blk ? o1[4 * g + q] : o0[4 * g + q]; const unsigned gb = q < 2 ? gt.x : gt.y; const float gv = __uint_as_float((q & 1) ? (gb & 0xffff0000u) : (gb << 16));
;                     y[q] = siluf_(gv) * ((ov - mu) * rstd * gw[q]); }
	v_mfma_f32_32x32x16_bf16 v[18:33], v[50:53], v[34:37], v[18:33]
	v_mfma_f32_32x32x16_bf16 v[2:17], v[54:57], v[38:41], v[2:17]
	s_waitcnt lgkmcnt(0)
	v_mfma_f32_32x32x16_bf16 v[18:33], v[58:61], v[38:41], v[18:33]
	ds_read_b64_tr_b16 v[34:35], v73 offset:28672
	ds_read_b64_tr_b16 v[36:37], v73 offset:29184
	ds_read_b64_tr_b16 v[38:39], v73 offset:29696
	ds_read_b64_tr_b16 v[40:41], v73 offset:30208
	s_waitcnt lgkmcnt(2)
	v_mfma_f32_32x32x16_bf16 v[2:17], v[34:37], v[42:45], v[2:17]
	ds_read_b64_tr_b16 v[34:35], v73 offset:32768
	ds_read_b64_tr_b16 v[36:37], v73 offset:33280
	ds_read_b64_tr_b16 v[50:51], v73 offset:33792
	ds_read_b64_tr_b16 v[52:53], v73 offset:34304
	s_waitcnt lgkmcnt(2)
	v_mfma_f32_32x32x16_bf16 v[18:33], v[34:37], v[42:45], v[18:33]
	v_mfma_f32_32x32x16_bf16 v[2:17], v[38:41], v[46:49], v[2:17]
	s_waitcnt lgkmcnt(0)
	v_mfma_f32_32x32x16_bf16 v[18:33], v[50:53], v[46:49], v[18:33]
	v_add3_u32 v71, s8, v70, v78
	ds_read_b128 v[34:37], v71
	ds_read_b128 v[72:75], v71 offset:32
	ds_read_b128 v[50:53], v71 offset:4608
	ds_read_b128 v[80:83], v71 offset:4640
	v_add3_u32 v70, s7, v70, v78
	s_waitcnt lgkmcnt(1)
	v_mfma_f32_32x32x16_bf16 v[50:65], v[50:53], v[66:69], 0
	v_mfma_f32_32x32x16_bf16 v[34:49], v[34:37], v[66:69], 0
	s_waitcnt lgkmcnt(0)
	v_mfma_f32_32x32x16_bf16 v[50:65], v[80:83], v[102:105], v[50:65]
	v_mfma_f32_32x32x16_bf16 v[34:49], v[72:75], v[102:105], v[34:49]
	ds_read_b128 v[72:75], v71 offset:4672
	ds_read_b128 v[80:83], v71 offset:4704
	s_waitcnt lgkmcnt(1)
	v_mfma_f32_32x32x16_bf16 v[50:65], v[72:75], v[98:101], v[50:65]
	ds_read_b128 v[72:75], v71 offset:64
	ds_read_b128 v[162:165], v71 offset:96
	ds_read_b128 v[76:79], v70 offset:4608
	ds_read_b128 v[166:169], v70
	ds_read_b128 v[170:173], v70 offset:32
	ds_read_b128 v[174:177], v70 offset:4640
	v_subrev_u32_e32 v71, s6, v160
	v_add_u32_e32 v71, 1, v71
	v_cvt_f32_i32_e32 v71, v71
	ds_read_b128 v[178:181], v70 offset:64
	ds_read_b128 v[184:187], v70 offset:96
	ds_read_b128 v[188:191], v70 offset:4672
	ds_read_b128 v[192:195], v70 offset:4704
	s_waitcnt lgkmcnt(10)
	v_mfma_f32_32x32x16_bf16 v[50:65], v[80:83], v[94:97], v[50:65]
	s_mov_b64 s[6:7], 0
	v_mul_f32_e32 v71, v142, v71
	v_exp_f32_e32 v142, v71
	v_sub_u32_e32 v71, s4, v131
	v_add_u32_e32 v71, 0x80, v71
	v_cvt_f32_i32_e32 v71, v71
	s_nop 5
	v_pk_fma_f32 v[32:33], v[142:143], v[64:65], v[32:33] op_sel_hi:[0,1,1]
	s_waitcnt lgkmcnt(7)
	v_mfma_f32_32x32x16_bf16 v[78:93], v[76:79], v[66:69], 0
	v_mul_f32_e32 v70, v143, v71
	v_exp_f32_e32 v160, v70
	v_and_b32_e32 v70, 64, v1
	v_add_u32_e32 v77, 64, v70
	v_xor_b32_e32 v76, 32, v1
	v_pk_fma_f32 v[30:31], v[142:143], v[62:63], v[30:31] op_sel_hi:[0,1,1]
	v_cmp_lt_i32_e32 vcc, v76, v77
	s_waitcnt lgkmcnt(4)
	v_mfma_f32_32x32x16_bf16 v[78:93], v[174:177], v[102:105], v[78:93]
	s_waitcnt vmcnt(2)
	v_lshlrev_b32_e32 v174, 16, v144
	v_and_b32_e32 v175, 0xffff0000, v144
	v_mul_f32_e32 v70, 0xbfb8aa3b, v174
	v_mul_f32_e32 v71, 0xbfb8aa3b, v175
	v_exp_f32_e32 v70, v70
	v_exp_f32_e32 v71, v71
	v_cndmask_b32_e32 v76, v1, v76, vcc
	s_waitcnt lgkmcnt(1)
	v_mfma_f32_32x32x16_bf16 v[78:93], v[188:191], v[98:101], v[78:93]
	v_lshlrev_b32_e32 v131, 2, v76
	v_add_f32_e64 v176, v70, 1.0
	v_add_f32_e64 v177, v71, 1.0
	v_div_scale_f32 v64, s[4:5], v177, v177, 1.0
	v_rcp_f32_e32 v65, v64
	s_waitcnt lgkmcnt(0)
	v_mfma_f32_32x32x16_bf16 v[78:93], v[192:195], v[94:97], v[78:93]
	v_mfma_f32_32x32x16_bf16 v[34:49], v[72:75], v[98:101], v[34:49]
	s_nop 10
	v_fma_f32 v90, v160, v90, v30
	v_fma_f32 v91, v160, v91, v31
	v_fma_f32 v30, -v64, v65, 1.0
	v_fmac_f32_e32 v65, v30, v65
	v_div_scale_f32 v30, vcc, 1.0, v177, 1.0
	v_mul_f32_e32 v31, v30, v65
	v_fma_f32 v62, -v64, v31, v30
	v_mfma_f32_32x32x16_bf16 v[62:77], v[166:169], v[66:69], 0
	v_fma_f32 v32, v160, v92, v32
	v_fma_f32 v33, v160, v93, v33
	v_div_scale_f32 v92, s[4:5], v176, v176, 1.0
	v_rcp_f32_e32 v93, v92
	v_rcp_f32_e32 v31, v177
	v_fma_f32 v30, -v92, v93, 1.0
	v_mfma_f32_32x32x16_bf16 v[62:77], v[170:173], v[102:105], v[62:77]
	v_fmac_f32_e32 v93, v30, v93
	v_div_scale_f32 v30, vcc, 1.0, v176, 1.0
	v_mul_f32_e32 v143, v30, v93
	v_fma_f32 v144, -v92, v143, v30
	v_fmac_f32_e32 v143, v144, v93
	v_mfma_f32_32x32x16_bf16 v[62:77], v[178:181], v[98:101], v[62:77]
	v_lshlrev_b32_e32 v92, 16, v159
	v_and_b32_e32 v93, 0xffff0000, v159
	v_mul_f32_e32 v102, 0xbfb8aa3b, v92
	v_mul_f32_e32 v103, 0xbfb8aa3b, v93
	v_exp_f32_e32 v102, v102
	v_exp_f32_e32 v103, v103
	v_mfma_f32_32x32x16_bf16 v[34:49], v[162:165], v[94:97], v[34:49]
	v_fma_f32 v28, v142, v60, v28
	v_fma_f32 v29, v142, v61, v29
	v_fma_f32 v60, v160, v88, v28
	v_fma_f32 v61, v160, v89, v29
	v_add_f32_e64 v98, v102, 1.0
	v_add_f32_e64 v99, v103, 1.0
	v_pk_fma_f32 v[26:27], v[142:143], v[58:59], v[26:27] op_sel_hi:[0,1,1]
	v_mfma_f32_32x32x16_bf16 v[62:77], v[184:187], v[94:97], v[62:77]
	s_nop 1
	s_nop 1
	v_fma_f32 v16, v142, v48, v16
	v_fma_f32 v17, v142, v49, v17
	v_lshlrev_b32_e32 v94, 16, v158
	v_and_b32_e32 v95, 0xffff0000, v158
	v_fma_f32 v14, v142, v46, v14
	v_fma_f32 v15, v142, v47, v15
	v_pk_fma_f32 v[58:59], v[160:161], v[86:87], v[26:27] op_sel_hi:[0,1,1]
	v_pk_fma_f32 v[12:13], v[142:143], v[44:45], v[12:13] op_sel_hi:[0,1,1]
	v_pk_fma_f32 v[10:11], v[142:143], v[42:43], v[10:11] op_sel_hi:[0,1,1]
	s_nop 0
	v_pk_fma_f32 v[48:49], v[160:161], v[76:77], v[16:17] op_sel_hi:[0,1,1]
	v_rcp_f32_e32 v17, v99
	v_mul_f32_e32 v76, 0xbfb8aa3b, v94
	v_mul_f32_e32 v77, 0xbfb8aa3b, v95
	v_exp_f32_e32 v76, v76
	v_exp_f32_e32 v77, v77
	v_rcp_f32_e32 v16, v98
	s_nop 0
	v_pk_mul_f32 v[16:17], v[16:17], v[92:93]
	v_pk_add_f32 v[92:93], v[76:77], 1.0 op_sel_hi:[1,0]
; __device__ __forceinline__ float siluf_(float x) { return x * sigmoidf_(x); }
; __device__ __forceinline__ void ph_ret_chunk(unsigned char* lds_, bf16_t* Z, const bf16_t* KVF, const bf16_t* KVB, const float* decay_logit, const float* gn_w, int with_ctx, int u0, int ustep, unsigned* kvc, unsigned* barw) { PH_IDS;
;     ...
;           for (int r = 0; r < 16; ++r) { o0[r] += p0[r] * sf; o1[r] += p1[r] * sf; }
;           ret_qk(sm, r32, hi, ST_OFF + (2 + cl) * ST_SZ, qf, p0, p1);
;           const float sbk = __builtin_amdgcn_exp2f(lgb * (float)(c0 + 128 - qpos));
; #pragma unroll
;           for (int r = 0; r < 16; ++r) { o0[r] += p0[r] * sbk; o1[r] += p1[r] * sbk; } }
;         float s1 = 0.f;
; #pragma unroll
;         for (int r = 0; r < 16; ++r) s1 += o0[r] + o1[r];
;         s1 += __shfl_xor(s1, 32);
;         const float mu = s1 * (1.f / 64);
;         float s2 = 0.f;
; #pragma unroll
;         for (int r = 0; r < 16; ++r) { const float a = o0[r] - mu, c = o1[r] - mu; s2 += a * a + c * c; }
;         s2 += __shfl_xor(s2, 32);
;         const float rstd = rsqrtf(s2 * (1.f / 64) + EPS);
;         u32x2 wv[2][4];
; #pragma unroll
;         for (int g = 0; g < 4; ++g)
; #pragma unroll
;             for (int blk = 0; blk < 2; ++blk) {
;                 const int d = blk * 32 + 8 * g + 4 * hi;
;                 const u32x2 gt = gtv[2 * g + blk];
;                 const f32x4 gw = gwv[2 * g + blk];
;                 float y[4];
; #pragma unroll
;                 for (int q = 0; q < 4; ++q) { const float ov = blk ? o1[4 * g + q] : o0[4 * g + q]; const unsigned gb = q < 2 ? gt.x : gt.y; const float gv = __uint_as_float((q & 1) ? (gb & 0xffff0000u) : (gb << 16));
;                     y[q] = siluf_(gv) * ((ov - mu) * rstd * gw[q]); }
	v_pk_fma_f32 v[46:47], v[160:161], v[74:75], v[14:15] op_sel_hi:[0,1,1]
	v_pk_fma_f32 v[44:45], v[160:161], v[72:73], v[12:13] op_sel_hi:[0,1,1]
	v_pk_fma_f32 v[42:43], v[160:161], v[70:71], v[10:11] op_sel_hi:[0,1,1]
	v_pk_fma_f32 v[24:25], v[142:143], v[56:57], v[24:25] op_sel_hi:[0,1,1]
	v_rcp_f32_e32 v15, v93
	v_lshlrev_b32_e32 v96, 16, v157
	v_and_b32_e32 v97, 0xffff0000, v157
	v_mul_f32_e32 v74, 0xbfb8aa3b, v96
	v_mul_f32_e32 v75, 0xbfb8aa3b, v97
	v_exp_f32_e32 v74, v74
	v_exp_f32_e32 v75, v75
	v_rcp_f32_e32 v14, v92
	s_nop 0
	v_pk_mul_f32 v[14:15], v[14:15], v[94:95]
	v_pk_add_f32 v[92:93], v[74:75], 1.0 op_sel_hi:[1,0]
	v_pk_fma_f32 v[56:57], v[160:161], v[84:85], v[24:25] op_sel_hi:[0,1,1]
	v_pk_fma_f32 v[22:23], v[142:143], v[54:55], v[22:23] op_sel_hi:[0,1,1]
	v_pk_fma_f32 v[54:55], v[160:161], v[82:83], v[22:23] op_sel_hi:[0,1,1]
	v_pk_fma_f32 v[8:9], v[142:143], v[40:41], v[8:9] op_sel_hi:[0,1,1]
	v_rcp_f32_e32 v29, v93
	v_lshlrev_b32_e32 v88, 16, v156
	v_and_b32_e32 v89, 0xffff0000, v156
	v_mul_f32_e32 v94, 0xbfb8aa3b, v88
	v_mul_f32_e32 v95, 0xbfb8aa3b, v89
	v_exp_f32_e32 v94, v94
	v_exp_f32_e32 v95, v95
	v_rcp_f32_e32 v28, v92
	s_nop 0
	v_pk_mul_f32 v[28:29], v[28:29], v[96:97]
	v_pk_add_f32 v[92:93], v[94:95], 1.0 op_sel_hi:[1,0]
	v_pk_fma_f32 v[40:41], v[160:161], v[68:69], v[8:9] op_sel_hi:[0,1,1]
	v_pk_fma_f32 v[6:7], v[142:143], v[38:39], v[6:7] op_sel_hi:[0,1,1]
	v_pk_fma_f32 v[38:39], v[160:161], v[66:67], v[6:7] op_sel_hi:[0,1,1]
	v_pk_fma_f32 v[20:21], v[142:143], v[52:53], v[20:21] op_sel_hi:[0,1,1]
	v_rcp_f32_e32 v27, v93
	v_lshlrev_b32_e32 v86, 16, v155
	v_and_b32_e32 v87, 0xffff0000, v155
	v_mul_f32_e32 v94, 0xbfb8aa3b, v86
	v_mul_f32_e32 v95, 0xbfb8aa3b, v87
	v_exp_f32_e32 v94, v94
	v_exp_f32_e32 v95, v95
	v_rcp_f32_e32 v26, v92
	s_nop 0
	v_pk_mul_f32 v[26:27], v[26:27], v[88:89]
	v_pk_add_f32 v[92:93], v[94:95], 1.0 op_sel_hi:[1,0]
	v_lshlrev_b32_e32 v88, 16, v154
	v_and_b32_e32 v89, 0xffff0000, v154
	v_pk_fma_f32 v[20:21], v[160:161], v[80:81], v[20:21] op_sel_hi:[0,1,1]
	v_pk_fma_f32 v[18:19], v[142:143], v[50:51], v[18:19] op_sel_hi:[0,1,1]
	v_rcp_f32_e32 v13, v93
	v_pk_fma_f32 v[18:19], v[160:161], v[78:79], v[18:19] op_sel_hi:[0,1,1]
	v_mul_f32_e32 v72, 0xbfb8aa3b, v88
	v_mul_f32_e32 v73, 0xbfb8aa3b, v89
	v_exp_f32_e32 v72, v72
	v_exp_f32_e32 v73, v73
	v_rcp_f32_e32 v12, v92
	s_nop 0
	v_pk_mul_f32 v[12:13], v[12:13], v[86:87]
	v_pk_add_f32 v[86:87], v[72:73], 1.0 op_sel_hi:[1,0]
	v_pk_fma_f32 v[4:5], v[142:143], v[36:37], v[4:5] op_sel_hi:[0,1,1]
	v_pk_fma_f32 v[4:5], v[160:161], v[64:65], v[4:5] op_sel_hi:[0,1,1]
	v_pk_fma_f32 v[2:3], v[142:143], v[34:35], v[2:3] op_sel_hi:[0,1,1]
	v_pk_fma_f32 v[2:3], v[160:161], v[62:63], v[2:3] op_sel_hi:[0,1,1]
	v_rcp_f32_e32 v11, v87
	v_lshlrev_b32_e32 v92, 16, v153
	v_and_b32_e32 v93, 0xffff0000, v153
	v_mul_f32_e32 v70, 0xbfb8aa3b, v92
	v_mul_f32_e32 v71, 0xbfb8aa3b, v93
	v_exp_f32_e32 v70, v70
	v_exp_f32_e32 v71, v71
	v_rcp_f32_e32 v10, v86
	s_nop 0
	v_pk_mul_f32 v[10:11], v[10:11], v[88:89]
	v_pk_add_f32 v[86:87], v[70:71], 1.0 op_sel_hi:[1,0]
	v_pk_add_f32 v[70:71], v[42:43], v[58:59]
	v_pk_add_f32 v[72:73], v[44:45], v[60:61]
	v_pk_add_f32 v[74:75], v[46:47], v[90:91]
	v_pk_add_f32 v[76:77], v[48:49], v[32:33]
	v_rcp_f32_e32 v25, v87
	v_lshlrev_b32_e32 v84, 16, v152
	v_and_b32_e32 v85, 0xffff0000, v152
	v_mul_f32_e32 v88, 0xbfb8aa3b, v84
	v_mul_f32_e32 v89, 0xbfb8aa3b, v85
	v_exp_f32_e32 v88, v88
	v_exp_f32_e32 v89, v89
	v_rcp_f32_e32 v24, v86
	s_nop 0
	v_pk_mul_f32 v[24:25], v[24:25], v[92:93]
	v_pk_add_f32 v[86:87], v[88:89], 1.0 op_sel_hi:[1,0]
	v_rcp_f32_e32 v30, v176
	s_nop 0
	v_pk_mul_f32 v[30:31], v[30:31], v[174:175]
	v_rcp_f32_e32 v23, v87
	v_lshlrev_b32_e32 v82, 16, v151
	v_and_b32_e32 v83, 0xffff0000, v151
	v_mul_f32_e32 v88, 0xbfb8aa3b, v82
	v_mul_f32_e32 v89, 0xbfb8aa3b, v83
	v_exp_f32_e32 v88, v88
	v_exp_f32_e32 v89, v89
	v_rcp_f32_e32 v22, v86
	s_nop 0
	v_pk_mul_f32 v[22:23], v[22:23], v[84:85]
	v_pk_add_f32 v[86:87], v[88:89], 1.0 op_sel_hi:[1,0]
	v_lshlrev_b32_e32 v84, 16, v150
	v_and_b32_e32 v85, 0xffff0000, v150
	v_rcp_f32_e32 v9, v87
	v_mul_f32_e32 v68, 0xbfb8aa3b, v84
	v_mul_f32_e32 v69, 0xbfb8aa3b, v85
	v_exp_f32_e32 v68, v68
	v_exp_f32_e32 v69, v69
	v_rcp_f32_e32 v8, v86
	s_nop 0
	v_pk_mul_f32 v[8:9], v[8:9], v[82:83]
	v_pk_add_f32 v[82:83], v[68:69], 1.0 op_sel_hi:[1,0]
	v_pk_add_f32 v[68:69], v[40:41], v[56:57]
	s_nop 0
	v_rcp_f32_e32 v7, v83
	v_lshlrev_b32_e32 v66, 16, v149
	v_and_b32_e32 v67, 0xffff0000, v149
	v_mul_f32_e32 v86, 0xbfb8aa3b, v66
	v_mul_f32_e32 v87, 0xbfb8aa3b, v67
	v_exp_f32_e32 v86, v86
	v_exp_f32_e32 v87, v87
	v_rcp_f32_e32 v6, v82
	s_nop 0
	v_pk_mul_f32 v[6:7], v[6:7], v[84:85]
	v_pk_add_f32 v[82:83], v[86:87], 1.0 op_sel_hi:[1,0]
	v_pk_add_f32 v[84:85], v[38:39], v[54:55]
	s_nop 0
	v_rcp_f32_e32 v53, v83
	v_lshlrev_b32_e32 v80, 16, v148
	v_and_b32_e32 v81, 0xffff0000, v148
	v_mul_f32_e32 v86, 0xbfb8aa3b, v80
	v_mul_f32_e32 v87, 0xbfb8aa3b, v81
	v_exp_f32_e32 v86, v86
	v_exp_f32_e32 v87, v87
	v_rcp_f32_e32 v52, v82
	s_nop 0
	v_pk_mul_f32 v[52:53], v[52:53], v[66:67]
	v_pk_add_f32 v[82:83], v[86:87], 1.0 op_sel_hi:[1,0]
	s_nop 0
	s_nop 0
	v_rcp_f32_e32 v51, v83
	v_lshlrev_b32_e32 v66, 16, v147
	v_and_b32_e32 v67, 0xffff0000, v147
	v_mul_f32_e32 v78, 0xbfb8aa3b, v66
	v_mul_f32_e32 v79, 0xbfb8aa3b, v67
	v_exp_f32_e32 v78, v78
	v_exp_f32_e32 v79, v79
	v_rcp_f32_e32 v50, v82
	s_nop 0
	v_pk_mul_f32 v[50:51], v[50:51], v[80:81]
	v_pk_add_f32 v[78:79], v[78:79], 1.0 op_sel_hi:[1,0]
	s_nop 0
	s_nop 0
	v_rcp_f32_e32 v37, v79
	v_lshlrev_b32_e32 v64, 16, v146
	v_and_b32_e32 v65, 0xffff0000, v146
	v_mul_f32_e32 v80, 0xbfb8aa3b, v64
	v_mul_f32_e32 v81, 0xbfb8aa3b, v65
	v_exp_f32_e32 v80, v80
	v_exp_f32_e32 v81, v81
	v_rcp_f32_e32 v36, v78
	s_nop 0
	v_pk_mul_f32 v[36:37], v[36:37], v[66:67]
	v_pk_add_f32 v[66:67], v[80:81], 1.0 op_sel_hi:[1,0]
	v_pk_add_f32 v[78:79], v[4:5], v[20:21]
	s_nop 0
	v_pk_add_f32 v[62:63], v[2:3], v[18:19]
	v_rcp_f32_e32 v35, v67
	v_add_f32_e32 v34, 0, v62
	v_add_f32_e32 v34, v63, v34
	v_add_f32_e32 v34, v78, v34
	v_add_f32_e32 v34, v79, v34
	v_add_f32_e32 v34, v84, v34
	v_add_f32_e32 v34, v85, v34
	v_add_f32_e32 v34, v68, v34
	v_add_f32_e32 v34, v69, v34
	v_add_f32_e32 v34, v70, v34
	v_add_f32_e32 v34, v71, v34
	v_add_f32_e32 v34, v72, v34
	v_add_f32_e32 v34, v73, v34
	v_add_f32_e32 v34, v74, v34
	v_add_f32_e32 v34, v75, v34
	v_add_f32_e32 v34, v76, v34
	v_add_f32_e32 v34, v77, v34
	ds_bpermute_b32 v62, v131, v34
	s_mov_b32 s4, 0x800000
	s_waitcnt lgkmcnt(0)
; __device__ __forceinline__ float siluf_(float x) { return x * sigmoidf_(x); }
; __device__ __forceinline__ unsigned pk2n(float lo, float hi) { return __builtin_bit_cast(unsigned, __builtin_convertvector((f32v2_t){lo, hi}, bf16v2_t)); }
; __device__ __forceinline__ void ph_ret_chunk(unsigned char* lds_, bf16_t* Z, const bf16_t* KVF, const bf16_t* KVB, const float* decay_logit, const float* gn_w, int with_ctx, int u0, int ustep, unsigned* kvc, unsigned* barw) { PH_IDS;
;     ...
;         float s1 = 0.f;
; #pragma unroll
;         for (int r = 0; r < 16; ++r) s1 += o0[r] + o1[r];
;         s1 += __shfl_xor(s1, 32);
;         const float mu = s1 * (1.f / 64);
;         float s2 = 0.f;
; #pragma unroll
;         for (int r = 0; r < 16; ++r) { const float a = o0[r] - mu, c = o1[r] - mu; s2 += a * a + c * c; }
;         s2 += __shfl_xor(s2, 32);
;         const float rstd = rsqrtf(s2 * (1.f / 64) + EPS);
;         u32x2 wv[2][4];
; #pragma unroll
;         for (int g = 0; g < 4; ++g)
; #pragma unroll
;             for (int blk = 0; blk < 2; ++blk) {
;                 const int d = blk * 32 + 8 * g + 4 * hi;
;                 const u32x2 gt = gtv[2 * g + blk];
;                 const f32x4 gw = gwv[2 * g + blk];
;                 float y[4];
; #pragma unroll
;                 for (int q = 0; q < 4; ++q) { const float ov = blk ? o1[4 * g + q] : o0[4 * g + q]; const unsigned gb = q < 2 ? gt.x : gt.y; const float gv = __uint_as_float((q & 1) ? (gb & 0xffff0000u) : (gb << 16));
;                     y[q] = siluf_(gv) * ((ov - mu) * rstd * gw[q]); }
;                 wv[blk][g].x = pk2n(y[0], y[1]); wv[blk][g].y = pk2n(y[2], y[3]);
;             }
; #pragma unroll
;         for (int blk = 0; blk < 2; ++blk)
; #pragma unroll
;             for (int g = 0; g < 4; g += 2) {
;                 auto rx = __builtin_amdgcn_permlane32_swap(wv[blk][g].x, wv[blk][g + 1].x, false, false), ry = __builtin_amdgcn_permlane32_swap(wv[blk][g].y, wv[blk][g + 1].y, false, false);
;                 *(u32x4*)(zq + C_RQ + h * 64 + blk * 32 + 8 * g + 8 * hi) = (u32x4){(unsigned)rx[0], (unsigned)ry[0], (unsigned)rx[1], (unsigned)ry[1]};
;             }
	v_add_f32_e32 v34, v34, v62
	v_mul_f32_e32 v34, 0x3c800000, v34
	v_pk_add_f32 v[18:19], v[18:19], v[34:35] op_sel_hi:[1,0] neg_lo:[0,1] neg_hi:[0,1]
	v_pk_add_f32 v[2:3], v[2:3], v[34:35] op_sel_hi:[1,0] neg_lo:[0,1] neg_hi:[0,1]
	v_pk_mul_f32 v[62:63], v[18:19], v[18:19]
	v_pk_add_f32 v[20:21], v[20:21], v[34:35] op_sel_hi:[1,0] neg_lo:[0,1] neg_hi:[0,1]
	v_pk_fma_f32 v[62:63], v[2:3], v[2:3], v[62:63]
	v_pk_add_f32 v[4:5], v[4:5], v[34:35] op_sel_hi:[1,0] neg_lo:[0,1] neg_hi:[0,1]
	v_pk_mul_f32 v[68:69], v[20:21], v[20:21]
	v_pk_add_f32 v[38:39], v[38:39], v[34:35] op_sel_hi:[1,0] neg_lo:[0,1] neg_hi:[0,1]
	v_pk_fma_f32 v[68:69], v[4:5], v[4:5], v[68:69]
	v_pk_add_f32 v[54:55], v[54:55], v[34:35] op_sel_hi:[1,0] neg_lo:[0,1] neg_hi:[0,1]
	v_pk_add_f32 v[40:41], v[40:41], v[34:35] op_sel_hi:[1,0] neg_lo:[0,1] neg_hi:[0,1]
	v_pk_add_f32 v[56:57], v[56:57], v[34:35] op_sel_hi:[1,0] neg_lo:[0,1] neg_hi:[0,1]
	v_pk_add_f32 v[42:43], v[42:43], v[34:35] op_sel_hi:[1,0] neg_lo:[0,1] neg_hi:[0,1]
	v_pk_add_f32 v[58:59], v[58:59], v[34:35] op_sel_hi:[1,0] neg_lo:[0,1] neg_hi:[0,1]
	v_pk_add_f32 v[44:45], v[44:45], v[34:35] op_sel_hi:[1,0] neg_lo:[0,1] neg_hi:[0,1]
	v_pk_add_f32 v[60:61], v[60:61], v[34:35] op_sel_hi:[1,0] neg_lo:[0,1] neg_hi:[0,1]
	v_pk_add_f32 v[46:47], v[46:47], v[34:35] op_sel_hi:[1,0] neg_lo:[0,1] neg_hi:[0,1]
	v_pk_add_f32 v[78:79], v[90:91], v[34:35] op_sel_hi:[1,0] neg_lo:[0,1] neg_hi:[0,1]
	v_pk_add_f32 v[48:49], v[48:49], v[34:35] op_sel_hi:[1,0] neg_lo:[0,1] neg_hi:[0,1]
	v_pk_add_f32 v[32:33], v[32:33], v[34:35] op_sel_hi:[1,0] neg_lo:[0,1] neg_hi:[0,1]
	v_add_f32_e32 v34, v62, v63
	v_pk_mul_f32 v[70:71], v[54:55], v[54:55]
	v_add_f32_e32 v34, v68, v34
	v_pk_fma_f32 v[70:71], v[38:39], v[38:39], v[70:71]
	v_add_f32_e32 v34, v69, v34
	v_pk_mul_f32 v[72:73], v[56:57], v[56:57]
	v_add_f32_e32 v34, v70, v34
	v_pk_fma_f32 v[72:73], v[40:41], v[40:41], v[72:73]
	v_add_f32_e32 v34, v71, v34
	v_pk_mul_f32 v[74:75], v[58:59], v[58:59]
	v_add_f32_e32 v34, v72, v34
	v_pk_fma_f32 v[74:75], v[42:43], v[42:43], v[74:75]
	v_add_f32_e32 v34, v73, v34
	v_pk_mul_f32 v[76:77], v[60:61], v[60:61]
	v_add_f32_e32 v34, v74, v34
	v_pk_fma_f32 v[76:77], v[44:45], v[44:45], v[76:77]
	v_add_f32_e32 v34, v75, v34
	v_pk_mul_f32 v[80:81], v[78:79], v[78:79]
	v_add_f32_e32 v34, v76, v34
	v_pk_fma_f32 v[80:81], v[46:47], v[46:47], v[80:81]
	v_add_f32_e32 v34, v77, v34
	v_pk_mul_f32 v[82:83], v[32:33], v[32:33]
	v_add_f32_e32 v34, v80, v34
	v_pk_fma_f32 v[82:83], v[48:49], v[48:49], v[82:83]
	v_add_f32_e32 v34, v81, v34
	v_add_f32_e32 v34, v82, v34
	v_add_f32_e32 v34, v83, v34
	ds_bpermute_b32 v62, v131, v34
	s_waitcnt lgkmcnt(0)
	v_add_f32_e32 v34, v34, v62
	v_fmamk_f32 v34, v34, 0x3c800000, v207
	v_mul_f32_e32 v62, 0x4b800000, v34
	v_cmp_gt_f32_e64 s[4:5], s4, v34
	v_cndmask_b32_e64 v34, v34, v62, s[4:5]
	v_rsq_f32_e32 v62, v34
	v_rcp_f32_e32 v34, v66
	s_nop 0
	v_pk_mul_f32 v[34:35], v[34:35], v[64:65]
	v_mul_f32_e32 v63, 0x45800000, v62
	v_cndmask_b32_e64 v62, v62, v63, s[4:5]
	v_pk_mul_f32 v[2:3], v[2:3], v[62:63] op_sel_hi:[1,0]
	v_pk_mul_f32 v[4:5], v[4:5], v[62:63] op_sel_hi:[1,0]
	v_pk_mul_f32 v[2:3], v[126:127], v[2:3]
	v_pk_mul_f32 v[4:5], v[128:129], v[4:5]
	v_pk_mul_f32 v[2:3], v[34:35], v[2:3]
	v_pk_mul_f32 v[4:5], v[36:37], v[4:5]
	v_cvt_pk_bf16_f32 v2, v2, v3
	v_cvt_pk_bf16_f32 v3, v4, v5
	v_pk_mul_f32 v[4:5], v[18:19], v[62:63] op_sel_hi:[1,0]
	v_pk_mul_f32 v[18:19], v[20:21], v[62:63] op_sel_hi:[1,0]
	v_pk_mul_f32 v[4:5], v[136:137], v[4:5]
	v_pk_mul_f32 v[18:19], v[138:139], v[18:19]
	v_pk_mul_f32 v[4:5], v[50:51], v[4:5]
	v_pk_mul_f32 v[20:21], v[52:53], v[18:19]
	v_cvt_pk_bf16_f32 v18, v4, v5
	v_pk_mul_f32 v[4:5], v[38:39], v[62:63] op_sel_hi:[1,0]
	v_cvt_pk_bf16_f32 v19, v20, v21
	v_pk_mul_f32 v[4:5], v[114:115], v[4:5]
	s_nop 0
	v_pk_mul_f32 v[4:5], v[6:7], v[4:5]
	v_pk_mul_f32 v[6:7], v[40:41], v[62:63] op_sel_hi:[1,0]
	v_cvt_pk_bf16_f32 v4, v4, v5
	v_pk_mul_f32 v[6:7], v[116:117], v[6:7]
	s_nop 0
	v_permlane32_swap_b32_e32 v2, v4
	v_pk_mul_f32 v[6:7], v[8:9], v[6:7]
	v_pk_mul_f32 v[8:9], v[56:57], v[62:63] op_sel_hi:[1,0]
	v_cvt_pk_bf16_f32 v5, v6, v7
	v_pk_mul_f32 v[6:7], v[54:55], v[62:63] op_sel_hi:[1,0]
	v_pk_mul_f32 v[8:9], v[124:125], v[8:9]
	v_pk_mul_f32 v[6:7], v[122:123], v[6:7]
	v_pk_mul_f32 v[8:9], v[24:25], v[8:9]
	v_pk_mul_f32 v[6:7], v[22:23], v[6:7]
	v_cvt_pk_bf16_f32 v21, v8, v9
	v_cvt_pk_bf16_f32 v20, v6, v7
	v_pk_mul_f32 v[6:7], v[42:43], v[62:63] op_sel_hi:[1,0]
	v_pk_mul_f32 v[8:9], v[44:45], v[62:63] op_sel_hi:[1,0]
	v_pk_mul_f32 v[6:7], v[118:119], v[6:7]
	v_pk_mul_f32 v[8:9], v[120:121], v[8:9]
	v_pk_mul_f32 v[6:7], v[10:11], v[6:7]
	v_pk_mul_f32 v[8:9], v[12:13], v[8:9]
	v_cvt_pk_bf16_f32 v6, v6, v7
	v_cvt_pk_bf16_f32 v7, v8, v9
	v_pk_mul_f32 v[8:9], v[58:59], v[62:63] op_sel_hi:[1,0]
	v_pk_mul_f32 v[10:11], v[60:61], v[62:63] op_sel_hi:[1,0]
	s_waitcnt vmcnt(1)
	v_pk_mul_f32 v[8:9], v[132:133], v[8:9]
	v_pk_mul_f32 v[10:11], v[134:135], v[10:11]
	v_pk_mul_f32 v[8:9], v[26:27], v[8:9]
	v_pk_mul_f32 v[12:13], v[28:29], v[10:11]
	v_cvt_pk_bf16_f32 v10, v8, v9
	v_pk_mul_f32 v[8:9], v[46:47], v[62:63] op_sel_hi:[1,0]
	v_cvt_pk_bf16_f32 v11, v12, v13
	v_pk_mul_f32 v[8:9], v[110:111], v[8:9]
	v_pk_mul_f32 v[12:13], v[48:49], v[62:63] op_sel_hi:[1,0]
	v_pk_mul_f32 v[8:9], v[14:15], v[8:9]
	v_lshlrev_b32_e32 v14, 16, v145
	v_and_b32_e32 v15, 0xffff0000, v145
	v_mul_f32_e32 v22, 0xbfb8aa3b, v14
	v_mul_f32_e32 v23, 0xbfb8aa3b, v15
	v_exp_f32_e32 v22, v22
	v_exp_f32_e32 v23, v23
	v_pk_mul_f32 v[12:13], v[112:113], v[12:13]
	v_cvt_pk_bf16_f32 v8, v8, v9
	v_pk_mul_f32 v[12:13], v[16:17], v[12:13]
	v_pk_mul_f32 v[16:17], v[78:79], v[62:63] op_sel_hi:[1,0]
	v_cvt_pk_bf16_f32 v9, v12, v13
	v_pk_add_f32 v[12:13], v[22:23], 1.0 op_sel_hi:[1,0]
	s_waitcnt vmcnt(0)
	v_pk_mul_f32 v[16:17], v[106:107], v[16:17]
	v_pk_mul_f32 v[16:17], v[30:31], v[16:17]
	v_permlane32_swap_b32_e32 v3, v5
	v_rcp_f32_e32 v13, v13
	v_permlane32_swap_b32_e32 v6, v8
	v_rcp_f32_e32 v12, v12
	s_nop 0
	v_pk_mul_f32 v[12:13], v[12:13], v[14:15]
	v_pk_mul_f32 v[14:15], v[32:33], v[62:63] op_sel_hi:[1,0]
	v_permlane32_swap_b32_e32 v7, v9
	v_pk_mul_f32 v[14:15], v[108:109], v[14:15]
	v_permlane32_swap_b32_e32 v18, v20
	v_pk_mul_f32 v[14:15], v[12:13], v[14:15]
	v_cvt_pk_bf16_f32 v12, v16, v17
	v_cvt_pk_bf16_f32 v13, v14, v15
	v_permlane32_swap_b32_e32 v19, v21
	v_permlane32_swap_b32_e32 v10, v12
	v_permlane32_swap_b32_e32 v11, v13
	global_store_dwordx4 v[140:141], v[2:5], off offset:2880
	global_store_dwordx4 v[140:141], v[6:9], off offset:2912
	global_store_dwordx4 v[140:141], v[18:21], off offset:2944
	global_store_dwordx4 v[140:141], v[10:13], off offset:2976
	s_barrier

; __device__ __forceinline__ float sigmoidf_(float x) { return 1.f / (1.f + __expf(-x)); }
; __device__ __forceinline__ pg8::u32x4 pack8(const f32x4 a, const f32x4 b) { pg8::u32x4 w; w.x = pg8::cvt_pk_bf16(a[0], a[1]); w.y = pg8::cvt_pk_bf16(a[2], a[3]); w.z = pg8::cvt_pk_bf16(b[0], b[1]); w.w = pg8::cvt_pk_bf16(b[2], b[3]); return w; }
;     __device__ __forceinline__ void operator()(const f32x4 (&acc)[2][2][4][2], const pg8::Unit& u, int wr, int wc, int fr, int fq) const {
; #pragma unroll
;         for (int ai = 0; ai < 2; ++ai)
; #pragma unroll
;             for (int m = 0; m < 4; ++m) {
;                 const int row = u.pm * 256 + ai * 128 + wr * 64 + m * 16 + fr, col = u.pn * 128 + wc * 32 + 8 * fq;
;                 f32x4 a, b;
; #pragma unroll
;                 for (int q = 0; q < 4; ++q) { a[q] = acc[ai][0][m][0][q] * sigmoidf_(acc[ai][1][m][0][q]); b[q] = acc[ai][0][m][1][q] * sigmoidf_(acc[ai][1][m][1][q]); }
;                 *(pg8::u32x4*)(OCp + (size_t)row * 256 + col) = pack8(a, b);
;             }
;     }
.LBB0_3038:
	v_mul_f32_e32 v126, 0xbfb8aa3b, v126
	v_exp_f32_e32 v147, v126
	v_mul_f32_e32 v122, 0xbfb8aa3b, v122
	v_exp_f32_e32 v122, v122
	v_mul_f32_e32 v127, 0xbfb8aa3b, v127
	v_add_f32_e32 v148, 1.0, v147
	v_add_f32_e32 v122, 1.0, v122
	v_rcp_f32_e32 v148, v148
	v_exp_f32_e32 v127, v127
	v_mul_f32_e32 v118, v118, v148
	v_add_f32_e32 v127, 1.0, v127
	v_mul_f32_e32 v123, 0xbfb8aa3b, v123
	v_rcp_f32_e32 v122, v122
	v_exp_f32_e32 v123, v123
	v_mul_f32_e32 v114, v114, v122
	v_add_f32_e32 v123, 1.0, v123
	v_mul_f32_e32 v128, 0xbfb8aa3b, v128
	v_rcp_f32_e32 v122, v127
	v_exp_f32_e32 v128, v128
	v_mul_f32_e32 v119, v119, v122
	v_add_f32_e32 v128, 1.0, v128
	v_mul_f32_e32 v124, 0xbfb8aa3b, v124
	v_rcp_f32_e32 v122, v123
	v_exp_f32_e32 v124, v124
	v_mul_f32_e32 v115, v115, v122
	v_add_f32_e32 v124, 1.0, v124
	v_rcp_f32_e32 v122, v128
	s_nop 0
	v_mul_f32_e32 v120, v120, v122
	v_mul_f32_e32 v128, 0xbfb8aa3b, v129
	v_exp_f32_e32 v128, v128
	s_nop 0
	v_add_f32_e32 v127, 1.0, v128
	v_rcp_f32_e32 v122, v124
	v_mul_f32_e32 v124, 0xbfb8aa3b, v125
	v_exp_f32_e32 v124, v124
	v_mul_f32_e32 v122, v116, v122
	v_add_f32_e32 v124, 1.0, v124
	v_rcp_f32_e32 v116, v127
	s_nop 0
	v_mul_f32_e32 v121, v121, v116
	v_mul_f32_e32 v110, 0xbfb8aa3b, v110
	v_exp_f32_e32 v110, v110
	v_rcp_f32_e32 v116, v124
	v_add_f32_e32 v110, 1.0, v110
	v_lshl_add_u32 v126, s26, 8, v138
	v_mul_f32_e32 v123, v117, v116
	v_cvt_pk_bf16_f32 v116, v118, v119
	v_cvt_pk_bf16_f32 v117, v120, v121
	v_cvt_pk_bf16_f32 v118, v114, v115
	v_cvt_pk_bf16_f32 v119, v122, v123
	v_lshl_or_b32 v146, s58, 7, v139
	v_ashrrev_i32_e32 v127, 31, v126
	v_ashrrev_i32_e32 v147, 31, v146
	v_lshlrev_b64 v[114:115], 9, v[126:127]
	v_lshl_add_u64 v[120:121], s[10:11], 0, v[114:115]
	v_lshlrev_b64 v[114:115], 1, v[146:147]
	v_mul_f32_e32 v106, 0xbfb8aa3b, v106
	v_lshl_add_u64 v[120:121], v[120:121], 0, v[114:115]
	v_exp_f32_e32 v106, v106
	global_store_dwordx4 v[120:121], v[116:119], off
	v_mul_f32_e32 v111, 0xbfb8aa3b, v111
	v_exp_f32_e32 v111, v111
	v_add_f32_e32 v106, 1.0, v106
	v_rcp_f32_e32 v110, v110
	s_nop 0
	v_mul_f32_e32 v110, v102, v110
	v_add_f32_e32 v111, 1.0, v111
	v_mul_f32_e32 v107, 0xbfb8aa3b, v107
	v_rcp_f32_e32 v102, v106
	v_exp_f32_e32 v107, v107
	v_mul_f32_e32 v106, v98, v102
	v_add_f32_e32 v107, 1.0, v107
	v_rcp_f32_e32 v98, v111
	v_mul_f32_e32 v111, 0xbfb8aa3b, v112
	v_exp_f32_e32 v111, v111
	v_mul_f32_e32 v98, v103, v98
	v_add_f32_e32 v111, 1.0, v111
	v_rcp_f32_e32 v102, v107
	v_mul_f32_e32 v107, 0xbfb8aa3b, v108
	v_exp_f32_e32 v107, v107
	v_mul_f32_e32 v103, v99, v102
	v_add_f32_e32 v107, 1.0, v107
	v_rcp_f32_e32 v99, v111
	v_mul_f32_e32 v111, 0xbfb8aa3b, v113
	v_exp_f32_e32 v111, v111
	v_mul_f32_e32 v99, v104, v99
	v_add_f32_e32 v108, 1.0, v111
	v_rcp_f32_e32 v102, v107
	v_mul_f32_e32 v107, 0xbfb8aa3b, v109
	v_exp_f32_e32 v107, v107
	v_mul_f32_e32 v104, v100, v102
	v_add_f32_e32 v107, 1.0, v107
	v_rcp_f32_e32 v100, v108
	s_nop 0
	v_mul_f32_e32 v100, v105, v100
	v_mul_f32_e32 v94, 0xbfb8aa3b, v94
	v_exp_f32_e32 v94, v94
	v_rcp_f32_e32 v102, v107
	s_nop 0
	v_mul_f32_e32 v101, v101, v102
	v_add_f32_e32 v94, 1.0, v94
	v_or_b32_e32 v102, 16, v126
	v_cvt_pk_bf16_f32 v98, v110, v98
	v_cvt_pk_bf16_f32 v99, v99, v100
	v_cvt_pk_bf16_f32 v100, v106, v103
	v_cvt_pk_bf16_f32 v101, v104, v101
	v_ashrrev_i32_e32 v103, 31, v102
	v_lshlrev_b64 v[102:103], 9, v[102:103]
	v_lshl_add_u64 v[102:103], s[10:11], 0, v[102:103]
	v_mul_f32_e32 v90, 0xbfb8aa3b, v90
	v_lshl_add_u64 v[102:103], v[102:103], 0, v[114:115]
	v_exp_f32_e32 v90, v90
	global_store_dwordx4 v[102:103], v[98:101], off
	v_mul_f32_e32 v95, 0xbfb8aa3b, v95
	v_exp_f32_e32 v95, v95
	v_add_f32_e32 v90, 1.0, v90
	v_rcp_f32_e32 v94, v94
	s_nop 0
	v_mul_f32_e32 v94, v86, v94
	v_add_f32_e32 v95, 1.0, v95
	v_mul_f32_e32 v91, 0xbfb8aa3b, v91
	v_rcp_f32_e32 v86, v90
	v_exp_f32_e32 v91, v91
	v_mul_f32_e32 v90, v82, v86
	v_add_f32_e32 v91, 1.0, v91
	v_rcp_f32_e32 v82, v95
	v_mul_f32_e32 v95, 0xbfb8aa3b, v96
	v_exp_f32_e32 v95, v95
	v_mul_f32_e32 v82, v87, v82
	v_add_f32_e32 v95, 1.0, v95
	v_rcp_f32_e32 v86, v91
	v_mul_f32_e32 v91, 0xbfb8aa3b, v92
	v_exp_f32_e32 v91, v91
	v_mul_f32_e32 v87, v83, v86
	v_add_f32_e32 v91, 1.0, v91
	v_rcp_f32_e32 v83, v95
	v_mul_f32_e32 v95, 0xbfb8aa3b, v97
	v_exp_f32_e32 v95, v95
	v_mul_f32_e32 v83, v88, v83
	v_add_f32_e32 v92, 1.0, v95
	v_rcp_f32_e32 v86, v91
	v_mul_f32_e32 v91, 0xbfb8aa3b, v93
	v_exp_f32_e32 v91, v91
	v_mul_f32_e32 v88, v84, v86
	v_add_f32_e32 v91, 1.0, v91
	v_rcp_f32_e32 v84, v92
	s_nop 0
	v_mul_f32_e32 v84, v89, v84
	v_mul_f32_e32 v78, 0xbfb8aa3b, v78
	v_exp_f32_e32 v78, v78
	v_rcp_f32_e32 v86, v91
	s_nop 0
	v_mul_f32_e32 v85, v85, v86
	v_add_f32_e32 v78, 1.0, v78
	v_or_b32_e32 v86, 32, v126
	v_cvt_pk_bf16_f32 v82, v94, v82
	v_cvt_pk_bf16_f32 v83, v83, v84
	v_cvt_pk_bf16_f32 v84, v90, v87
	v_cvt_pk_bf16_f32 v85, v88, v85
	v_ashrrev_i32_e32 v87, 31, v86
	v_lshlrev_b64 v[86:87], 9, v[86:87]
	v_lshl_add_u64 v[86:87], s[10:11], 0, v[86:87]
	v_mul_f32_e32 v74, 0xbfb8aa3b, v74
	v_lshl_add_u64 v[86:87], v[86:87], 0, v[114:115]
	v_exp_f32_e32 v74, v74
	global_store_dwordx4 v[86:87], v[82:85], off
	v_mul_f32_e32 v79, 0xbfb8aa3b, v79
	v_exp_f32_e32 v79, v79
	v_add_f32_e32 v74, 1.0, v74
	v_rcp_f32_e32 v78, v78
	s_nop 0
	v_mul_f32_e32 v78, v70, v78
	v_add_f32_e32 v79, 1.0, v79
	v_mul_f32_e32 v75, 0xbfb8aa3b, v75
	v_rcp_f32_e32 v70, v74
	v_exp_f32_e32 v75, v75
	v_mul_f32_e32 v74, v66, v70
	v_add_f32_e32 v75, 1.0, v75
	v_rcp_f32_e32 v66, v79
	v_mul_f32_e32 v79, 0xbfb8aa3b, v80
	v_exp_f32_e32 v79, v79
	v_mul_f32_e32 v66, v71, v66
	v_add_f32_e32 v79, 1.0, v79
	v_rcp_f32_e32 v70, v75
	v_mul_f32_e32 v75, 0xbfb8aa3b, v76
; __device__ __forceinline__ float sigmoidf_(float x) { return 1.f / (1.f + __expf(-x)); }
; __device__ __forceinline__ pg8::u32x4 pack8(const f32x4 a, const f32x4 b) { pg8::u32x4 w; w.x = pg8::cvt_pk_bf16(a[0], a[1]); w.y = pg8::cvt_pk_bf16(a[2], a[3]); w.z = pg8::cvt_pk_bf16(b[0], b[1]); w.w = pg8::cvt_pk_bf16(b[2], b[3]); return w; }
;     __device__ __forceinline__ void operator()(const f32x4 (&acc)[2][2][4][2], const pg8::Unit& u, int wr, int wc, int fr, int fq) const {
; #pragma unroll
;         for (int ai = 0; ai < 2; ++ai)
; #pragma unroll
;             for (int m = 0; m < 4; ++m) {
;                 const int row = u.pm * 256 + ai * 128 + wr * 64 + m * 16 + fr, col = u.pn * 128 + wc * 32 + 8 * fq;
;                 f32x4 a, b;
; #pragma unroll
;                 for (int q = 0; q < 4; ++q) { a[q] = acc[ai][0][m][0][q] * sigmoidf_(acc[ai][1][m][0][q]); b[q] = acc[ai][0][m][1][q] * sigmoidf_(acc[ai][1][m][1][q]); }
;                 *(pg8::u32x4*)(OCp + (size_t)row * 256 + col) = pack8(a, b);
;             }
;     }
	v_exp_f32_e32 v75, v75
	v_mul_f32_e32 v71, v67, v70
	v_add_f32_e32 v75, 1.0, v75
	v_rcp_f32_e32 v67, v79
	v_mul_f32_e32 v79, 0xbfb8aa3b, v81
	v_exp_f32_e32 v79, v79
	v_mul_f32_e32 v67, v72, v67
	v_add_f32_e32 v76, 1.0, v79
	v_rcp_f32_e32 v70, v75
	v_mul_f32_e32 v75, 0xbfb8aa3b, v77
	v_exp_f32_e32 v75, v75
	v_mul_f32_e32 v72, v68, v70
	v_add_f32_e32 v75, 1.0, v75
	v_rcp_f32_e32 v68, v76
	s_nop 0
	v_mul_f32_e32 v68, v73, v68
	v_mul_f32_e32 v62, 0xbfb8aa3b, v62
	v_exp_f32_e32 v62, v62
	v_rcp_f32_e32 v70, v75
	s_nop 0
	v_mul_f32_e32 v69, v69, v70
	v_cvt_pk_bf16_f32 v66, v78, v66
	v_cvt_pk_bf16_f32 v67, v67, v68
	v_cvt_pk_bf16_f32 v68, v74, v71
	v_cvt_pk_bf16_f32 v69, v72, v69
	v_add_f32_e32 v72, 1.0, v62
	v_or_b32_e32 v70, 48, v126
	v_ashrrev_i32_e32 v71, 31, v70
	v_lshlrev_b64 v[70:71], 9, v[70:71]
	v_lshl_add_u64 v[70:71], s[10:11], 0, v[70:71]
	v_mul_f32_e32 v58, 0xbfb8aa3b, v58
	v_lshl_add_u64 v[70:71], v[70:71], 0, v[114:115]
	v_exp_f32_e32 v58, v58
	global_store_dwordx4 v[70:71], v[66:69], off
	v_mul_f32_e32 v63, 0xbfb8aa3b, v63
	v_exp_f32_e32 v63, v63
	v_add_f32_e32 v58, 1.0, v58
	v_rcp_f32_e32 v66, v72
	s_nop 0
	v_mul_f32_e32 v54, v54, v66
	v_add_f32_e32 v63, 1.0, v63
	v_mul_f32_e32 v59, 0xbfb8aa3b, v59
	v_rcp_f32_e32 v58, v58
	v_exp_f32_e32 v59, v59
	v_mul_f32_e32 v58, v50, v58
	v_add_f32_e32 v59, 1.0, v59
	v_mul_f32_e32 v64, 0xbfb8aa3b, v64
	v_rcp_f32_e32 v50, v63
	v_exp_f32_e32 v64, v64
	v_mul_f32_e32 v50, v55, v50
	v_add_f32_e32 v64, 1.0, v64
	v_mul_f32_e32 v60, 0xbfb8aa3b, v60
	v_rcp_f32_e32 v55, v59
	v_exp_f32_e32 v60, v60
	v_mul_f32_e32 v55, v51, v55
	v_add_f32_e32 v60, 1.0, v60
	v_rcp_f32_e32 v51, v64
	s_nop 0
	v_mul_f32_e32 v51, v56, v51
	v_mul_f32_e32 v64, 0xbfb8aa3b, v65
	v_exp_f32_e32 v64, v64
	s_nop 0
	v_add_f32_e32 v63, 1.0, v64
	v_rcp_f32_e32 v56, v60
	v_mul_f32_e32 v60, 0xbfb8aa3b, v61
	v_exp_f32_e32 v60, v60
	v_mul_f32_e32 v56, v52, v56
	v_add_f32_e32 v60, 1.0, v60
	v_rcp_f32_e32 v52, v63
	s_nop 0
	v_mul_f32_e32 v52, v57, v52
	v_mul_f32_e32 v46, 0xbfb8aa3b, v46
	v_exp_f32_e32 v46, v46
	v_rcp_f32_e32 v57, v60
	s_nop 0
	v_mul_f32_e32 v53, v53, v57
	v_add_f32_e32 v46, 1.0, v46
	v_add_u32_e32 v62, 0x80, v126
	v_cvt_pk_bf16_f32 v50, v54, v50
	v_cvt_pk_bf16_f32 v51, v51, v52
	v_cvt_pk_bf16_f32 v52, v58, v55
	v_cvt_pk_bf16_f32 v53, v56, v53
	v_ashrrev_i32_e32 v63, 31, v62
	v_lshlrev_b64 v[54:55], 9, v[62:63]
	v_lshl_add_u64 v[54:55], s[10:11], 0, v[54:55]
	v_mul_f32_e32 v42, 0xbfb8aa3b, v42
	v_lshl_add_u64 v[54:55], v[54:55], 0, v[114:115]
	v_exp_f32_e32 v42, v42
	global_store_dwordx4 v[54:55], v[50:53], off
	v_mul_f32_e32 v47, 0xbfb8aa3b, v47
	v_exp_f32_e32 v47, v47
	v_add_f32_e32 v42, 1.0, v42
	v_rcp_f32_e32 v46, v46
	s_nop 0
	v_mul_f32_e32 v46, v38, v46
	v_add_f32_e32 v47, 1.0, v47
	v_mul_f32_e32 v43, 0xbfb8aa3b, v43
	v_rcp_f32_e32 v38, v42
	v_exp_f32_e32 v43, v43
	v_mul_f32_e32 v42, v34, v38
	v_add_f32_e32 v43, 1.0, v43
	v_rcp_f32_e32 v34, v47
	v_mul_f32_e32 v47, 0xbfb8aa3b, v48
	v_exp_f32_e32 v47, v47
	v_mul_f32_e32 v34, v39, v34
	v_add_f32_e32 v47, 1.0, v47
	v_rcp_f32_e32 v38, v43
	v_mul_f32_e32 v43, 0xbfb8aa3b, v44
	v_exp_f32_e32 v43, v43
	v_mul_f32_e32 v39, v35, v38
	v_add_f32_e32 v43, 1.0, v43
	v_rcp_f32_e32 v35, v47
	v_mul_f32_e32 v47, 0xbfb8aa3b, v49
	v_exp_f32_e32 v47, v47
	v_mul_f32_e32 v35, v40, v35
	v_add_f32_e32 v44, 1.0, v47
	v_rcp_f32_e32 v38, v43
	v_mul_f32_e32 v43, 0xbfb8aa3b, v45
	v_exp_f32_e32 v43, v43
	v_mul_f32_e32 v40, v36, v38
	v_add_f32_e32 v43, 1.0, v43
	v_rcp_f32_e32 v36, v44
	s_nop 0
	v_mul_f32_e32 v36, v41, v36
	v_mul_f32_e32 v30, 0xbfb8aa3b, v30
	v_exp_f32_e32 v30, v30
; __device__ __forceinline__ float sigmoidf_(float x) { return 1.f / (1.f + __expf(-x)); }
; __device__ __forceinline__ pg8::u32x4 pack8(const f32x4 a, const f32x4 b) { pg8::u32x4 w; w.x = pg8::cvt_pk_bf16(a[0], a[1]); w.y = pg8::cvt_pk_bf16(a[2], a[3]); w.z = pg8::cvt_pk_bf16(b[0], b[1]); w.w = pg8::cvt_pk_bf16(b[2], b[3]); return w; }
;     __device__ __forceinline__ void operator()(const f32x4 (&acc)[2][2][4][2], const pg8::Unit& u, int wr, int wc, int fr, int fq) const {
; #pragma unroll
;         for (int ai = 0; ai < 2; ++ai)
; #pragma unroll
;             for (int m = 0; m < 4; ++m) {
;                 const int row = u.pm * 256 + ai * 128 + wr * 64 + m * 16 + fr, col = u.pn * 128 + wc * 32 + 8 * fq;
;                 f32x4 a, b;
; #pragma unroll
;                 for (int q = 0; q < 4; ++q) { a[q] = acc[ai][0][m][0][q] * sigmoidf_(acc[ai][1][m][0][q]); b[q] = acc[ai][0][m][1][q] * sigmoidf_(acc[ai][1][m][1][q]); }
;                 *(pg8::u32x4*)(OCp + (size_t)row * 256 + col) = pack8(a, b);
;             }
;     }
	v_rcp_f32_e32 v38, v43
	s_nop 0
	v_mul_f32_e32 v37, v37, v38
	v_add_f32_e32 v30, 1.0, v30
	v_add_u32_e32 v38, 0x90, v126
	v_cvt_pk_bf16_f32 v34, v46, v34
	v_cvt_pk_bf16_f32 v35, v35, v36
	v_cvt_pk_bf16_f32 v36, v42, v39
	v_cvt_pk_bf16_f32 v37, v40, v37
	v_ashrrev_i32_e32 v39, 31, v38
	v_lshlrev_b64 v[38:39], 9, v[38:39]
	v_lshl_add_u64 v[38:39], s[10:11], 0, v[38:39]
	v_mul_f32_e32 v26, 0xbfb8aa3b, v26
	v_lshl_add_u64 v[38:39], v[38:39], 0, v[114:115]
	v_exp_f32_e32 v26, v26
	global_store_dwordx4 v[38:39], v[34:37], off
	v_mul_f32_e32 v31, 0xbfb8aa3b, v31
	v_exp_f32_e32 v31, v31
	v_add_f32_e32 v26, 1.0, v26
	v_rcp_f32_e32 v30, v30
	s_nop 0
	v_mul_f32_e32 v30, v22, v30
	v_add_f32_e32 v31, 1.0, v31
	v_mul_f32_e32 v27, 0xbfb8aa3b, v27
	v_rcp_f32_e32 v22, v26
	v_exp_f32_e32 v27, v27
	v_mul_f32_e32 v26, v18, v22
	v_add_f32_e32 v27, 1.0, v27
	v_rcp_f32_e32 v18, v31
	v_mul_f32_e32 v31, 0xbfb8aa3b, v32
	v_exp_f32_e32 v31, v31
	v_mul_f32_e32 v18, v23, v18
	v_add_f32_e32 v31, 1.0, v31
	v_rcp_f32_e32 v22, v27
	v_mul_f32_e32 v27, 0xbfb8aa3b, v28
	v_exp_f32_e32 v27, v27
	v_mul_f32_e32 v23, v19, v22
	v_add_f32_e32 v27, 1.0, v27
	v_rcp_f32_e32 v19, v31
	v_mul_f32_e32 v31, 0xbfb8aa3b, v33
	v_exp_f32_e32 v31, v31
	v_mul_f32_e32 v19, v24, v19
	v_add_f32_e32 v28, 1.0, v31
	v_rcp_f32_e32 v22, v27
	v_mul_f32_e32 v27, 0xbfb8aa3b, v29
	v_exp_f32_e32 v27, v27
	v_mul_f32_e32 v24, v20, v22
	v_add_f32_e32 v27, 1.0, v27
	v_rcp_f32_e32 v20, v28
	s_nop 0
	v_mul_f32_e32 v20, v25, v20
	v_mul_f32_e32 v14, 0xbfb8aa3b, v14
	v_exp_f32_e32 v14, v14
	v_rcp_f32_e32 v22, v27
	s_nop 0
	v_mul_f32_e32 v21, v21, v22
	v_add_f32_e32 v14, 1.0, v14
	v_add_u32_e32 v22, 0xa0, v126
	v_cvt_pk_bf16_f32 v18, v30, v18
	v_cvt_pk_bf16_f32 v19, v19, v20
	v_cvt_pk_bf16_f32 v20, v26, v23
	v_cvt_pk_bf16_f32 v21, v24, v21
	v_ashrrev_i32_e32 v23, 31, v22
	v_lshlrev_b64 v[22:23], 9, v[22:23]
	v_lshl_add_u64 v[22:23], s[10:11], 0, v[22:23]
	v_mul_f32_e32 v10, 0xbfb8aa3b, v10
	v_lshl_add_u64 v[22:23], v[22:23], 0, v[114:115]
	v_exp_f32_e32 v10, v10
	global_store_dwordx4 v[22:23], v[18:21], off
	v_mul_f32_e32 v15, 0xbfb8aa3b, v15
	v_exp_f32_e32 v15, v15
	v_add_f32_e32 v10, 1.0, v10
	v_rcp_f32_e32 v14, v14
	s_nop 0
	v_mul_f32_e32 v14, v6, v14
	v_add_f32_e32 v15, 1.0, v15
	v_mul_f32_e32 v11, 0xbfb8aa3b, v11
	v_rcp_f32_e32 v6, v10
	v_exp_f32_e32 v11, v11
	v_mul_f32_e32 v10, v2, v6
	v_add_f32_e32 v11, 1.0, v11
	v_rcp_f32_e32 v2, v15
	v_mul_f32_e32 v15, 0xbfb8aa3b, v16
	v_exp_f32_e32 v15, v15
	v_mul_f32_e32 v2, v7, v2
	v_add_f32_e32 v15, 1.0, v15
	v_rcp_f32_e32 v6, v11
	v_mul_f32_e32 v11, 0xbfb8aa3b, v12
	v_exp_f32_e32 v11, v11
	v_mul_f32_e32 v7, v3, v6
	v_add_f32_e32 v11, 1.0, v11
	v_rcp_f32_e32 v3, v15
	v_mul_f32_e32 v15, 0xbfb8aa3b, v17
	v_exp_f32_e32 v15, v15
	v_mul_f32_e32 v3, v8, v3
	v_add_f32_e32 v12, 1.0, v15
	v_rcp_f32_e32 v6, v11
	v_mul_f32_e32 v11, 0xbfb8aa3b, v13
	v_exp_f32_e32 v11, v11
	v_mul_f32_e32 v8, v4, v6
	v_add_f32_e32 v11, 1.0, v11
	v_rcp_f32_e32 v4, v12
	s_nop 0
	v_mul_f32_e32 v4, v9, v4
	v_rcp_f32_e32 v6, v11
	s_nop 0
	v_mul_f32_e32 v5, v5, v6
	v_add_u32_e32 v6, 0xb0, v126
	v_cvt_pk_bf16_f32 v2, v14, v2
	v_cvt_pk_bf16_f32 v3, v3, v4
	v_cvt_pk_bf16_f32 v4, v10, v7
	v_ashrrev_i32_e32 v7, 31, v6
	v_lshlrev_b64 v[6:7], 9, v[6:7]
	v_lshl_add_u64 v[6:7], s[10:11], 0, v[6:7]
	v_lshl_add_u64 v[6:7], v[6:7], 0, v[114:115]
	s_andn2_b64 vcc, exec, s[24:25]
	s_mov_b64 s[24:25], -1
	v_cvt_pk_bf16_f32 v5, v8, v5
	global_store_dwordx4 v[6:7], v[2:5], off
	s_cbranch_vccnz .LBB0_3029
	s_andn2_b64 vcc, exec, s[8:9]
	s_cbranch_vccnz .LBB0_3028
	s_barrier
	s_branch .LBB0_3028

; template <class Epi, class Sched>
; __device__ __forceinline__ void gemm_phase(LAS unsigned char* lds, const Sched& S, const Epi& E) {
;     ...
; #pragma unroll
;         for (int a = 0; a < 2; ++a)
; #pragma unroll
;             for (int b = 0; b < 2; ++b)
; #pragma unroll
;                 for (int m = 0; m < 4; ++m)
; #pragma unroll
;                     for (int n = 0; n < 2; ++n) acc[a][b][m][n] = (f32x4){0.f, 0.f, 0.f, 0.f};
;         cur = nxt; cA = nA; cB = nB; clda = nlda; cldb = nldb; ++ui;
.LBB0_3111:
	s_ashr_i32 s7, s6, 31
	s_add_i32 s88, s86, -2
	s_lshl_b64 s[36:37], s[6:7], 7
	s_add_u32 s7, s30, 0x100
	s_addc_u32 s89, s31, 0
	v_mad_u64_u32 v[2:3], s[38:39], s6, v131, v[130:131]
	s_add_u32 s30, s34, 0x80
	s_addc_u32 s31, s35, 0
	v_mad_u64_u32 v[4:5], s[34:35], v152, s6, v[134:135]
	v_mov_b32_e32 v3, v133
	v_mov_b32_e32 v5, v133
	v_lshl_add_u64 v[138:139], s[36:37], 0, v[2:3]
	v_mov_b32_e32 v2, 0
	v_lshl_add_u64 v[136:137], s[36:37], 0, v[4:5]
	s_mov_b32 s34, 0
	v_mov_b32_e32 v3, 0
	v_mov_b64_e32 v[4:5], 0
	v_mov_b64_e32 v[6:7], 0
	v_mov_b64_e32 v[8:9], 0
	v_mov_b64_e32 v[10:11], 0
	v_mov_b64_e32 v[12:13], 0
	v_mov_b64_e32 v[14:15], 0
	v_mov_b64_e32 v[16:17], 0
	v_mov_b64_e32 v[18:19], 0
	v_mov_b64_e32 v[20:21], 0
	v_mov_b64_e32 v[22:23], 0
	v_mov_b64_e32 v[24:25], 0
	v_mov_b64_e32 v[26:27], 0
	v_mov_b64_e32 v[28:29], 0
	v_mov_b64_e32 v[30:31], 0
	v_mov_b64_e32 v[32:33], 0
	v_mov_b64_e32 v[34:35], 0
	v_mov_b64_e32 v[36:37], 0
	v_mov_b64_e32 v[38:39], 0
	v_mov_b64_e32 v[40:41], 0
	v_mov_b64_e32 v[42:43], 0
	v_mov_b64_e32 v[44:45], 0
	v_mov_b64_e32 v[46:47], 0
	v_mov_b64_e32 v[48:49], 0
	v_mov_b64_e32 v[50:51], 0
	v_mov_b64_e32 v[52:53], 0
	v_mov_b64_e32 v[54:55], 0
	v_mov_b64_e32 v[56:57], 0
	v_mov_b64_e32 v[58:59], 0
	v_mov_b64_e32 v[60:61], 0
	v_mov_b64_e32 v[62:63], 0
	v_mov_b64_e32 v[64:65], 0
	v_mov_b64_e32 v[66:67], 0
	v_mov_b64_e32 v[68:69], 0
	v_mov_b64_e32 v[70:71], 0
	v_mov_b64_e32 v[72:73], 0
	v_mov_b64_e32 v[74:75], 0
	v_mov_b64_e32 v[76:77], 0
	v_mov_b64_e32 v[78:79], 0
	v_mov_b64_e32 v[80:81], 0
	v_mov_b64_e32 v[82:83], 0
	v_mov_b64_e32 v[84:85], 0
	v_mov_b64_e32 v[86:87], 0
	v_mov_b64_e32 v[88:89], 0
	v_mov_b64_e32 v[90:91], 0
	v_mov_b64_e32 v[92:93], 0
	v_mov_b64_e32 v[94:95], 0
	v_mov_b64_e32 v[96:97], 0
	v_mov_b64_e32 v[98:99], 0
	v_mov_b64_e32 v[100:101], 0
	v_mov_b64_e32 v[102:103], 0
	v_mov_b64_e32 v[104:105], 0
	v_mov_b64_e32 v[106:107], 0
	v_mov_b64_e32 v[108:109], 0
	v_mov_b64_e32 v[110:111], 0
	v_mov_b64_e32 v[112:113], 0
	v_mov_b64_e32 v[114:115], 0
	v_mov_b64_e32 v[116:117], 0
	v_mov_b64_e32 v[118:119], 0
	v_mov_b64_e32 v[120:121], 0
	v_mov_b64_e32 v[122:123], 0
	v_mov_b64_e32 v[124:125], 0
	v_mov_b64_e32 v[126:127], 0
	v_mov_b64_e32 v[128:129], 0

; #define PG8_BAR __builtin_amdgcn_s_barrier()
; template <class Epi, class Sched>
; __device__ __forceinline__ void gemm_phase(LAS unsigned char* lds, const Sched& S, const Epi& E) {
;     ...
; #pragma unroll
;         for (int a = 0; a < 2; ++a)
; #pragma unroll
;             for (int b = 0; b < 2; ++b)
; #pragma unroll
;                 for (int m = 0; m < 4; ++m)
; #pragma unroll
;                     for (int n = 0; n < 2; ++n) acc[a][b][m][n] = (f32x4){0.f, 0.f, 0.f, 0.f};
;         cur = nxt; cA = nA; cB = nB; clda = nlda; cldb = nldb; ++ui;
;         if (wr == 1) PG8_BAR;
.LBB0_3217:
	v_mov_b32_e32 v2, 0
	s_mov_b32 s16, s34
	s_mov_b32 s14, s30
	s_mov_b64 s[42:43], s[38:39]
	s_mov_b64 s[18:19], s[36:37]
	v_mov_b32_e32 v3, 0
	v_mov_b64_e32 v[4:5], 0
	v_mov_b64_e32 v[6:7], 0
	v_mov_b64_e32 v[8:9], 0
	v_mov_b64_e32 v[10:11], 0
	v_mov_b64_e32 v[12:13], 0
	v_mov_b64_e32 v[14:15], 0
	v_mov_b64_e32 v[16:17], 0
	v_mov_b64_e32 v[18:19], 0
	v_mov_b64_e32 v[20:21], 0
	v_mov_b64_e32 v[22:23], 0
	v_mov_b64_e32 v[24:25], 0
	v_mov_b64_e32 v[26:27], 0
	v_mov_b64_e32 v[28:29], 0
	v_mov_b64_e32 v[30:31], 0
	v_mov_b64_e32 v[32:33], 0
	v_mov_b64_e32 v[34:35], 0
	v_mov_b64_e32 v[36:37], 0
	v_mov_b64_e32 v[38:39], 0
	v_mov_b64_e32 v[40:41], 0
	v_mov_b64_e32 v[42:43], 0
	v_mov_b64_e32 v[44:45], 0
	v_mov_b64_e32 v[46:47], 0
	v_mov_b64_e32 v[48:49], 0
	v_mov_b64_e32 v[50:51], 0
	v_mov_b64_e32 v[52:53], 0
	v_mov_b64_e32 v[54:55], 0
	v_mov_b64_e32 v[56:57], 0
	v_mov_b64_e32 v[58:59], 0
	v_mov_b64_e32 v[60:61], 0
	v_mov_b64_e32 v[62:63], 0
	v_mov_b64_e32 v[64:65], 0
	v_mov_b64_e32 v[66:67], 0
	v_mov_b64_e32 v[68:69], 0
	v_mov_b64_e32 v[70:71], 0
	v_mov_b64_e32 v[72:73], 0
	v_mov_b64_e32 v[74:75], 0
	v_mov_b64_e32 v[76:77], 0
	v_mov_b64_e32 v[78:79], 0
	v_mov_b64_e32 v[80:81], 0
	v_mov_b64_e32 v[82:83], 0
	v_mov_b64_e32 v[84:85], 0
	v_mov_b64_e32 v[86:87], 0
	v_mov_b64_e32 v[88:89], 0
	v_mov_b64_e32 v[90:91], 0
	v_mov_b64_e32 v[92:93], 0
	v_mov_b64_e32 v[94:95], 0
	v_mov_b64_e32 v[96:97], 0
	v_mov_b64_e32 v[98:99], 0
	v_mov_b64_e32 v[100:101], 0
	v_mov_b64_e32 v[102:103], 0
	v_mov_b64_e32 v[104:105], 0
	v_mov_b64_e32 v[106:107], 0
	v_mov_b64_e32 v[108:109], 0
	v_mov_b64_e32 v[110:111], 0
	v_mov_b64_e32 v[112:113], 0
	v_mov_b64_e32 v[114:115], 0
	v_mov_b64_e32 v[116:117], 0
	v_mov_b64_e32 v[118:119], 0
	v_mov_b64_e32 v[120:121], 0
	v_mov_b64_e32 v[122:123], 0
	v_mov_b64_e32 v[124:125], 0
	v_mov_b64_e32 v[126:127], 0
	v_mov_b64_e32 v[128:129], 0
	s_mov_b32 s79, s80

; template <class Epi, class Sched>
; __device__ __forceinline__ void gemm_phase(LAS unsigned char* lds, const Sched& S, const Epi& E) {
;     ...
; #pragma unroll
;         for (int a = 0; a < 2; ++a)
; #pragma unroll
;             for (int b = 0; b < 2; ++b)
; #pragma unroll
;                 for (int m = 0; m < 4; ++m)
; #pragma unroll
;                     for (int n = 0; n < 2; ++n) acc[a][b][m][n] = (f32x4){0.f, 0.f, 0.f, 0.f};
;         cur = nxt; cA = nA; cB = nB; clda = nlda; cldb = nldb; ++ui;
.LBB0_3416:
	s_add_u32 s15, s30, 0x100
	s_addc_u32 s17, s31, 0
	s_add_u32 s28, s28, 0x100080
	v_mov_b32_e32 v0, 0
	s_addc_u32 s29, s29, 0
	s_mov_b32 s57, -2
	v_mov_b32_e32 v1, 0
	v_mov_b64_e32 v[2:3], 0
	v_mov_b64_e32 v[4:5], 0
	v_mov_b64_e32 v[6:7], 0
	v_mov_b64_e32 v[8:9], 0
	v_mov_b64_e32 v[10:11], 0
	v_mov_b64_e32 v[12:13], 0
	v_mov_b64_e32 v[14:15], 0
	v_mov_b64_e32 v[16:17], 0
	v_mov_b64_e32 v[18:19], 0
	v_mov_b64_e32 v[20:21], 0
	v_mov_b64_e32 v[22:23], 0
	v_mov_b64_e32 v[24:25], 0
	v_mov_b64_e32 v[26:27], 0
	v_mov_b64_e32 v[28:29], 0
	v_mov_b64_e32 v[30:31], 0
	v_mov_b64_e32 v[32:33], 0
	v_mov_b64_e32 v[34:35], 0
	v_mov_b64_e32 v[36:37], 0
	v_mov_b64_e32 v[38:39], 0
	v_mov_b64_e32 v[40:41], 0
	v_mov_b64_e32 v[42:43], 0
	v_mov_b64_e32 v[44:45], 0
	v_mov_b64_e32 v[46:47], 0
	v_mov_b64_e32 v[48:49], 0
	v_mov_b64_e32 v[50:51], 0
	v_mov_b64_e32 v[52:53], 0
	v_mov_b64_e32 v[54:55], 0
	v_mov_b64_e32 v[56:57], 0
	v_mov_b64_e32 v[58:59], 0
	v_mov_b64_e32 v[60:61], 0
	v_mov_b64_e32 v[62:63], 0
	v_mov_b64_e32 v[64:65], 0
	v_mov_b64_e32 v[66:67], 0
	v_mov_b64_e32 v[68:69], 0
	v_mov_b64_e32 v[70:71], 0
	v_mov_b64_e32 v[72:73], 0
	v_mov_b64_e32 v[74:75], 0
	v_mov_b64_e32 v[76:77], 0
	v_mov_b64_e32 v[78:79], 0
	v_mov_b64_e32 v[80:81], 0
	v_mov_b64_e32 v[82:83], 0
	v_mov_b64_e32 v[84:85], 0
	v_mov_b64_e32 v[86:87], 0
	v_mov_b64_e32 v[88:89], 0
	v_mov_b64_e32 v[90:91], 0
	v_mov_b64_e32 v[92:93], 0
	v_mov_b64_e32 v[94:95], 0
	v_mov_b64_e32 v[96:97], 0
	v_mov_b64_e32 v[98:99], 0
	v_mov_b64_e32 v[100:101], 0
	v_mov_b64_e32 v[102:103], 0
	v_mov_b64_e32 v[104:105], 0
	v_mov_b64_e32 v[106:107], 0
	v_mov_b64_e32 v[108:109], 0
	v_mov_b64_e32 v[110:111], 0
	v_mov_b64_e32 v[112:113], 0
	v_mov_b64_e32 v[114:115], 0
	v_mov_b64_e32 v[116:117], 0
	v_mov_b64_e32 v[118:119], 0
	v_mov_b64_e32 v[120:121], 0
	v_mov_b64_e32 v[122:123], 0
	v_mov_b64_e32 v[124:125], 0
	v_mov_b64_e32 v[126:127], 0
